# indexer score pass: q_idx LDS fragment addresses formed once per unit instead of before every read pair
# speedup vs baseline: 1.0072x; 1.0017x over previous
; #define LAS __attribute__((address_space(3)))
; __device__ __forceinline__ unsigned fkey(float f) { const unsigned u = __float_as_uint(f); return (u & 0x80000000u) ? ~u : (u | 0x80000000u); }
; #define SEL_HADD(idx_) __hip_atomic_fetch_add(&hist[(idx_)], 1u, __ATOMIC_RELAXED, __HIP_MEMORY_SCOPE_WORKGROUP)
; __device__ __forceinline__ void sel_unit(LAS char* lds, int b, int u, const bf16_t* QI, const bf16_t* KIDX, const float* WIDX, unsigned long long* MASK) {
;     ...
;     if (tid < 128) ((LAS float*)(lds + L_W))[tid] = WIDX[(rowbase + q0 + (tid & 15)) * 8 + (tid >> 4)];
;     const LAS float* wl = (const LAS float*)(lds + L_W) + q16;
;     __syncthreads();
;     const int nj = (c - wid + 8) >> 3;
;     u32x4 sc[8][4];
; #pragma unroll
;     for (int j = 0; j < 8; ++j) {
;         if (j < nj) {
;             int t = wid + 8 * j; asm volatile("" : "+s"(t));
; #pragma unroll
;             for (int kh = 0; kh < 2; ++kh) {
;             bf16x8 kf[2][2];
; #pragma unroll
;             for (int kb = 0; kb < 2; ++kb)
; #pragma unroll
;                 for (int ks = 0; ks < 2; ++ks) kf[kb][ks] = *(const bf16x8*)(KIDX + (rowbase + 64 * t + 32 * kh + 16 * kb + q16) * 64 + 32 * ks + 8 * kg);
; #pragma unroll
;             for (int kb = 0; kb < 2; ++kb) {
;                 f32x4 s = (f32x4){0.f, 0.f, 0.f, 0.f};
; #pragma unroll
;                 for (int hh = 0; hh < 8; ++hh) {
;                     f32x4 a = (f32x4){0.f, 0.f, 0.f, 0.f};
; #pragma unroll
;                     for (int ks = 0; ks < 2; ++ks) {
;                         const bf16x8 qv = *(const LAS bf16x8*)(lds + L_QI + q16 * 1024 + (((hh * 8 + 4 * ks + kg) ^ q16) << 4));
;                         a = __builtin_amdgcn_mfma_f32_16x16x32_bf16(kf[kb][ks], qv, a, 0, 0, 0);
;                     }
;                     const float wh = wl[hh * 16];
; #pragma unroll
;                     for (int i = 0; i < 4; ++i) s[i] += wh * fmaxf(a[i], 0.f);
;                 }
;                 u32x4 kk; kk.x = fkey(s[0]); kk.y = fkey(s[1]); kk.z = fkey(s[2]); kk.w = fkey(s[3]);
;                 sc[j][2 * kh + kb] = kk;
; #pragma unroll
;                 for (int i = 0; i < 4; ++i) SEL_HADD((kk[i] >> 24) * 16 + q16);
;                 __builtin_amdgcn_sched_barrier(0);
.LBB0_656:
	s_or_b64 exec, exec, s[2:3]
	s_ashr_i32 s46, s47, 6
	s_sub_i32 s2, s34, s46
	s_add_i32 s2, s2, 8
	s_ashr_i32 s4, s2, 3
	v_bfe_u32 v2, v2, 4, 2
	v_lshl_add_u32 v60, v59, 2, 0
	v_or_b32_e32 v18, s0, v59
	s_movk_i32 s0, 0x3fc
	s_cmp_gt_i32 s4, 0
	v_lshlrev_b32_e32 v0, 4, v2
	v_mad_u32_u24 v150, v59, s0, v60
	s_movk_i32 s0, 0xfc04
	s_cselect_b64 s[22:23], -1, 0
	v_mov_b32_e32 v19, s1
	v_lshl_add_u64 v[20:21], s[62:63], 0, v[0:1]
	v_mad_i32_i24 v0, v59, s0, v150
	s_and_b64 vcc, exec, s[22:23]
	v_xor_b32_e32 v182, v2, v59
	v_bitop3_b32 v183, v2, v59, 4 bitop3:0x36
	v_add_u32_e32 v137, 0x8800, v60
	v_bitop3_b32 v184, v2, v59, 8 bitop3:0x36
	v_bitop3_b32 v185, v2, v59, 12 bitop3:0x36
	v_bitop3_b32 v179, v2, v59, 16 bitop3:0x36
	v_bitop3_b32 v180, v2, v59, 20 bitop3:0x36
	v_bitop3_b32 v176, v2, v59, 24 bitop3:0x36
	v_bitop3_b32 v159, v2, v59, 28 bitop3:0x36
	v_bitop3_b32 v158, v2, v59, 32 bitop3:0x36
	v_bitop3_b32 v157, v2, v59, 36 bitop3:0x36
	v_bitop3_b32 v156, v2, v59, 40 bitop3:0x36
	v_bitop3_b32 v155, v2, v59, 44 bitop3:0x36
	v_bitop3_b32 v154, v2, v59, 48 bitop3:0x36
	v_bitop3_b32 v153, v2, v59, 52 bitop3:0x36
	v_bitop3_b32 v152, v2, v59, 56 bitop3:0x36
	v_bitop3_b32 v151, v2, v59, 60 bitop3:0x36
	v_lshl_add_u32 v182, v182, 4, v150
	v_lshl_add_u32 v183, v183, 4, v150
	v_lshl_add_u32 v184, v184, 4, v150
	v_lshl_add_u32 v185, v185, 4, v150
	v_lshl_add_u32 v179, v179, 4, v150
	v_lshl_add_u32 v180, v180, 4, v150
	v_lshl_add_u32 v176, v176, 4, v150
	v_lshl_add_u32 v159, v159, 4, v150
	v_lshl_add_u32 v158, v158, 4, v150
	v_lshl_add_u32 v157, v157, 4, v150
	v_lshl_add_u32 v156, v156, 4, v150
	v_lshl_add_u32 v155, v155, 4, v150
	v_lshl_add_u32 v154, v154, 4, v150
	v_lshl_add_u32 v153, v153, 4, v150
	v_lshl_add_u32 v152, v152, 4, v150
	v_lshl_add_u32 v151, v151, 4, v150
	s_waitcnt lgkmcnt(0)
	s_barrier
	s_cbranch_vccz .LBB0_658
	s_mov_b32 s0, s46
	s_lshl_b32 s0, s0, 6
	s_ashr_i32 s1, s0, 31
	v_lshl_add_u64 v[2:3], v[18:19], 0, s[0:1]
	v_lshlrev_b64 v[2:3], 7, v[2:3]
	v_lshl_add_u64 v[22:23], v[20:21], 0, v[2:3]
	global_load_dwordx4 v[14:17], v[22:23], off
	global_load_dwordx4 v[10:13], v[22:23], off offset:64
	ds_read_b128 v[2:5], v182
	ds_read_b128 v[6:9], v183
	ds_read_b128 v[24:27], v184
	ds_read_b128 v[28:31], v185
	ds_read_b128 v[32:35], v179
	ds_read_b128 v[36:39], v180
	ds_read_b128 v[40:43], v176
	ds_read_b128 v[44:47], v159
	ds_read_b128 v[48:51], v158
	ds_read_b128 v[52:55], v157
	ds_read_b128 v[62:65], v156
	ds_read_b128 v[66:69], v155
	s_waitcnt vmcnt(1) lgkmcnt(11)
	v_mfma_f32_16x16x32_bf16 v[2:5], v[14:17], v[2:5], 0
	s_waitcnt lgkmcnt(9)
	v_mfma_f32_16x16x32_bf16 v[24:27], v[14:17], v[24:27], 0
	s_waitcnt lgkmcnt(7)
	v_mfma_f32_16x16x32_bf16 v[32:35], v[14:17], v[32:35], 0
	s_waitcnt lgkmcnt(5)
	v_mfma_f32_16x16x32_bf16 v[40:43], v[14:17], v[40:43], 0
	s_waitcnt lgkmcnt(3)
	v_mfma_f32_16x16x32_bf16 v[48:51], v[14:17], v[48:51], 0
	s_waitcnt vmcnt(0)
	v_mfma_f32_16x16x32_bf16 v[70:73], v[10:13], v[6:9], v[2:5]
	v_mfma_f32_16x16x32_bf16 v[24:27], v[10:13], v[28:31], v[24:27]
	v_mfma_f32_16x16x32_bf16 v[28:31], v[10:13], v[36:39], v[32:35]
	v_mfma_f32_16x16x32_bf16 v[32:35], v[10:13], v[44:47], v[40:43]
	ds_read2_b32 v[44:45], v137 offset0:80 offset1:96
	ds_read2_b32 v[46:47], v137 offset0:112 offset1:128
	s_nop 3
	s_waitcnt lgkmcnt(4)
	v_mfma_f32_16x16x32_bf16 v[36:39], v[10:13], v[52:55], v[48:51]
	s_nop 0
	ds_read2_b32 v[48:49], v137 offset0:144 offset1:160
	global_load_dwordx4 v[6:9], v[22:23], off offset:2048
	global_load_dwordx4 v[2:5], v[22:23], off offset:2112
	s_waitcnt lgkmcnt(4)
	v_mfma_f32_16x16x32_bf16 v[62:65], v[14:17], v[62:65], 0
	s_nop 0
	v_max_f32_e32 v54, v24, v24
	s_nop 0
	s_waitcnt lgkmcnt(3)
	v_mfma_f32_16x16x32_bf16 v[40:43], v[10:13], v[66:69], v[62:65]
	v_max_f32_e32 v61, v39, v39
	v_max_f32_e32 v24, 0, v73
	v_max_f32_e32 v39, 0, v25
	v_max_f32_e32 v64, 0, v26
	v_max_f32_e32 v25, 0, v27
	v_max_f32_e32 v26, 0, v31
	v_max_f32_e32 v27, 0, v35
	v_max_f32_e32 v50, v70, v70
	v_max_f32_e32 v51, v71, v71
	v_max_f32_e32 v53, 0, v37
	s_waitcnt lgkmcnt(2)
	v_mul_f32_e32 v56, v45, v64
	v_pk_mul_f32 v[64:65], v[44:45], v[24:25]
	s_waitcnt lgkmcnt(1)
	v_pk_mul_f32 v[70:71], v[46:47], v[26:27]
	ds_read_b128 v[24:27], v154
	v_max_f32_e32 v62, v40, v40
	v_max_f32_e32 v40, 0, v28
	v_max_f32_e32 v28, 0, v30
	v_max_f32_e32 v63, v41, v41
	v_max_f32_e32 v41, 0, v29
	v_max_f32_e32 v29, 0, v34
	v_max_f32_e32 v30, 0, v38
	v_mul_f32_e32 v66, v46, v28
	v_max_f32_e32 v28, 0, v42
	v_mul_f32_e32 v68, v47, v29
	s_waitcnt lgkmcnt(1)
	v_mul_f32_e32 v90, v48, v30
	v_mul_f32_e32 v92, v49, v28
	ds_read_b128 v[28:31], v153
	s_waitcnt lgkmcnt(1)
	v_mfma_f32_16x16x32_bf16 v[24:27], v[14:17], v[24:27], 0
	v_max_f32_e32 v37, 0, v51
	s_waitcnt lgkmcnt(0)
	v_mfma_f32_16x16x32_bf16 v[24:27], v[10:13], v[28:31], v[24:27]
	ds_read_b128 v[28:31], v152
	v_max_f32_e32 v51, 0, v33
	v_max_f32_e32 v55, v36, v36
	v_max_f32_e32 v36, 0, v50
	v_max_f32_e32 v50, 0, v32
	v_max_f32_e32 v32, 0, v61
	v_max_f32_e32 v33, 0, v43
	v_pk_mul_f32 v[94:95], v[48:49], v[32:33]
	ds_read_b128 v[32:35], v151
	s_waitcnt lgkmcnt(1)
	v_mfma_f32_16x16x32_bf16 v[14:17], v[14:17], v[28:31], 0
	s_nop 0
	v_max_f32_e32 v42, 0, v72
	v_max_f32_e32 v38, 0, v54
	s_waitcnt lgkmcnt(0)
	v_mfma_f32_16x16x32_bf16 v[10:13], v[10:13], v[32:35], v[14:17]
	v_max_f32_e32 v52, 0, v55
	v_max_f32_e32 v54, 0, v62
	v_max_f32_e32 v55, 0, v63
	ds_read2_b32 v[62:63], v137 offset0:176 offset1:192
	s_nop 0
	s_nop 2
	v_max_f32_e32 v28, 0, v27
	v_max_f32_e32 v29, 0, v13
	s_waitcnt lgkmcnt(0)
; #define LAS __attribute__((address_space(3)))
; __device__ __forceinline__ unsigned fkey(float f) { const unsigned u = __float_as_uint(f); return (u & 0x80000000u) ? ~u : (u | 0x80000000u); }
; #define SEL_HADD(idx_) __hip_atomic_fetch_add(&hist[(idx_)], 1u, __ATOMIC_RELAXED, __HIP_MEMORY_SCOPE_WORKGROUP)
; __device__ __forceinline__ void sel_unit(LAS char* lds, int b, int u, const bf16_t* QI, const bf16_t* KIDX, const float* WIDX, unsigned long long* MASK) {
;     ...
;     for (int j = 0; j < 8; ++j) {
;         if (j < nj) {
;             int t = wid + 8 * j; asm volatile("" : "+s"(t));
; #pragma unroll
;             for (int kh = 0; kh < 2; ++kh) {
;             bf16x8 kf[2][2];
; #pragma unroll
;             for (int kb = 0; kb < 2; ++kb)
; #pragma unroll
;                 for (int ks = 0; ks < 2; ++ks) kf[kb][ks] = *(const bf16x8*)(KIDX + (rowbase + 64 * t + 32 * kh + 16 * kb + q16) * 64 + 32 * ks + 8 * kg);
; #pragma unroll
;             for (int kb = 0; kb < 2; ++kb) {
;                 f32x4 s = (f32x4){0.f, 0.f, 0.f, 0.f};
; #pragma unroll
;                 for (int hh = 0; hh < 8; ++hh) {
;                     f32x4 a = (f32x4){0.f, 0.f, 0.f, 0.f};
; #pragma unroll
;                     for (int ks = 0; ks < 2; ++ks) {
;                         const bf16x8 qv = *(const LAS bf16x8*)(lds + L_QI + q16 * 1024 + (((hh * 8 + 4 * ks + kg) ^ q16) << 4));
;                         a = __builtin_amdgcn_mfma_f32_16x16x32_bf16(kf[kb][ks], qv, a, 0, 0, 0);
;                     }
;                     const float wh = wl[hh * 16];
; #pragma unroll
;                     for (int i = 0; i < 4; ++i) s[i] += wh * fmaxf(a[i], 0.f);
;                 }
;                 u32x4 kk; kk.x = fkey(s[0]); kk.y = fkey(s[1]); kk.z = fkey(s[2]); kk.w = fkey(s[3]);
;                 sc[j][2 * kh + kb] = kk;
; #pragma unroll
;                 for (int i = 0; i < 4; ++i) SEL_HADD((kk[i] >> 24) * 16 + q16);
;                 __builtin_amdgcn_sched_barrier(0);
	v_pk_mul_f32 v[14:15], v[62:63], v[28:29]
	v_pk_fma_f32 v[16:17], v[44:45], v[36:37], 0 op_sel_hi:[0,1,0]
	v_mov_b32_e32 v28, v45
	v_pk_fma_f32 v[16:17], v[28:29], v[38:39], v[16:17] op_sel_hi:[0,1,1]
	v_pk_fma_f32 v[16:17], v[46:47], v[40:41], v[16:17] op_sel_hi:[0,1,1]
	v_mov_b32_e32 v28, v47
	v_pk_fma_f32 v[16:17], v[28:29], v[50:51], v[16:17] op_sel_hi:[0,1,1]
	v_pk_fma_f32 v[16:17], v[48:49], v[52:53], v[16:17] op_sel_hi:[0,1,1]
	v_mov_b32_e32 v28, v49
	v_max_f32_e32 v24, 0, v24
	v_max_f32_e32 v25, 0, v25
	v_pk_fma_f32 v[16:17], v[28:29], v[54:55], v[16:17] op_sel_hi:[0,1,1]
	v_max_f32_e32 v10, 0, v10
	v_max_f32_e32 v11, 0, v11
	v_pk_fma_f32 v[16:17], v[62:63], v[24:25], v[16:17] op_sel_hi:[0,1,1]
	v_mov_b32_e32 v24, v63
	v_pk_fma_f32 v[10:11], v[24:25], v[10:11], v[16:17] op_sel_hi:[0,1,1]
	v_and_b32_e32 v17, 0x7fffffff, v11
	v_and_b32_e32 v16, 0x7fffffff, v10
	v_mul_f32_e32 v42, v44, v42
	v_xor_b32_e32 v13, -1, v11
	v_pk_add_f32 v[16:17], v[16:17], 0 neg_lo:[1,1] neg_hi:[1,1]
	v_cmp_gt_i32_e32 vcc, 0, v11
	v_mov_b32_e32 v43, v64
	v_xor_b32_e32 v24, -1, v10
	v_cndmask_b32_e32 v61, v17, v13, vcc
	v_cmp_gt_i32_e32 vcc, 0, v10
	v_pk_add_f32 v[10:11], v[42:43], 0 op_sel_hi:[1,0]
	v_mov_b32_e32 v57, v65
	v_pk_add_f32 v[10:11], v[10:11], v[56:57]
	v_mov_b32_e32 v67, v70
	v_pk_add_f32 v[10:11], v[10:11], v[66:67]
	v_mov_b32_e32 v69, v71
	v_pk_add_f32 v[10:11], v[10:11], v[68:69]
	v_mov_b32_e32 v91, v94
	v_max_f32_e32 v26, 0, v26
	v_pk_add_f32 v[10:11], v[10:11], v[90:91]
	v_mov_b32_e32 v93, v95
	v_mul_f32_e32 v26, v62, v26
	v_max_f32_e32 v12, 0, v12
	v_pk_add_f32 v[10:11], v[10:11], v[92:93]
	v_mov_b32_e32 v27, v14
	v_mul_f32_e32 v12, v63, v12
	v_pk_add_f32 v[10:11], v[10:11], v[26:27]
	v_mov_b32_e32 v13, v15
	v_pk_add_f32 v[10:11], v[10:11], v[12:13]
	v_cndmask_b32_e32 v62, v16, v24, vcc
	v_and_b32_e32 v13, 0x7fffffff, v11
	v_and_b32_e32 v12, 0x7fffffff, v10
	v_xor_b32_e32 v14, -1, v11
	v_pk_add_f32 v[12:13], v[12:13], 0 neg_lo:[1,1] neg_hi:[1,1]
	v_cmp_gt_i32_e32 vcc, 0, v11
	v_xor_b32_e32 v15, -1, v10
	s_nop 0
	v_cndmask_b32_e32 v63, v13, v14, vcc
	v_cmp_gt_i32_e32 vcc, 0, v10
	v_lshrrev_b32_e32 v10, 24, v62
	v_lshl_add_u32 v10, v10, 6, v0
	ds_add_u32 v10, v205 offset:16384
	v_lshrrev_b32_e32 v10, 24, v61
	v_cndmask_b32_e32 v64, v12, v15, vcc
	v_lshl_add_u32 v10, v10, 6, v0
	ds_add_u32 v10, v205 offset:16384
	v_lshrrev_b32_e32 v10, 24, v64
	v_lshl_add_u32 v10, v10, 6, v0
	ds_add_u32 v10, v205 offset:16384
	v_lshrrev_b32_e32 v10, 24, v63
	v_lshl_add_u32 v10, v10, 6, v0
	ds_add_u32 v10, v205 offset:16384
	ds_read_b128 v[10:13], v182
	ds_read_b128 v[14:17], v183
	ds_read_b128 v[24:27], v184
	ds_read_b128 v[28:31], v185
	ds_read2_b32 v[32:33], v137 offset0:80 offset1:96
	ds_read2_b32 v[40:41], v137 offset0:112 offset1:128
	s_waitcnt vmcnt(1) lgkmcnt(5)
	v_mfma_f32_16x16x32_bf16 v[10:13], v[6:9], v[10:13], 0
	ds_read2_b32 v[52:53], v137 offset0:144 offset1:160
	s_waitcnt vmcnt(0) lgkmcnt(5)
	v_mfma_f32_16x16x32_bf16 v[10:13], v[2:5], v[14:17], v[10:13]
	ds_read_b128 v[14:17], v179
	s_waitcnt lgkmcnt(5)
	v_mfma_f32_16x16x32_bf16 v[24:27], v[6:9], v[24:27], 0
	s_nop 4
	v_max_f32_e32 v34, 0, v10
	v_max_f32_e32 v10, 0, v12
	v_max_f32_e32 v35, 0, v11
	s_waitcnt lgkmcnt(3)
	v_mul_f32_e32 v36, v32, v10
	v_max_f32_e32 v38, 0, v13
	v_mfma_f32_16x16x32_bf16 v[10:13], v[2:5], v[28:31], v[24:27]
	s_nop 2
	ds_read_b128 v[24:27], v180
	s_waitcnt lgkmcnt(1)
	v_mfma_f32_16x16x32_bf16 v[14:17], v[6:9], v[14:17], 0
	s_nop 1
	v_max_f32_e32 v28, 0, v10
	v_max_f32_e32 v29, 0, v11
	v_max_f32_e32 v10, 0, v12
	v_mul_f32_e32 v30, v33, v10
	v_max_f32_e32 v39, 0, v13
	s_waitcnt lgkmcnt(0)
	v_mfma_f32_16x16x32_bf16 v[10:13], v[2:5], v[24:27], v[14:17]
	ds_read_b128 v[24:27], v159
	v_pk_mul_f32 v[38:39], v[32:33], v[38:39]
	s_nop 0
	ds_read_b128 v[14:17], v176
	s_waitcnt lgkmcnt(0)
	v_mfma_f32_16x16x32_bf16 v[14:17], v[6:9], v[14:17], 0
	s_nop 1
	v_max_f32_e32 v42, 0, v10
	v_max_f32_e32 v43, 0, v11
	v_max_f32_e32 v10, 0, v12
	v_mul_f32_e32 v44, v40, v10
	s_nop 0
	v_max_f32_e32 v46, 0, v13
	v_mfma_f32_16x16x32_bf16 v[10:13], v[2:5], v[24:27], v[14:17]
	ds_read_b128 v[24:27], v157
	v_mov_b32_e32 v37, v38
	v_mov_b32_e32 v31, v39
	ds_read_b128 v[14:17], v158
	s_waitcnt lgkmcnt(0)
	v_mfma_f32_16x16x32_bf16 v[14:17], v[6:9], v[14:17], 0
	s_nop 1
	v_max_f32_e32 v48, 0, v10
	v_max_f32_e32 v49, 0, v11
	v_max_f32_e32 v10, 0, v12
	v_mul_f32_e32 v50, v41, v10
	s_nop 0
	v_max_f32_e32 v47, 0, v13
	v_mfma_f32_16x16x32_bf16 v[10:13], v[2:5], v[24:27], v[14:17]
	ds_read_b128 v[24:27], v155
	v_pk_mul_f32 v[46:47], v[40:41], v[46:47]
	s_nop 0
	ds_read_b128 v[14:17], v156
	s_waitcnt lgkmcnt(0)
	v_mfma_f32_16x16x32_bf16 v[14:17], v[6:9], v[14:17], 0
	s_nop 1
	v_max_f32_e32 v54, 0, v10
	v_max_f32_e32 v55, 0, v11
	v_max_f32_e32 v10, 0, v12
	v_mul_f32_e32 v56, v52, v10
	s_nop 0
	v_max_f32_e32 v66, 0, v13
	v_mfma_f32_16x16x32_bf16 v[10:13], v[2:5], v[24:27], v[14:17]
	ds_read_b128 v[24:27], v153
	v_mov_b32_e32 v45, v46
	v_mov_b32_e32 v51, v47
	ds_read_b128 v[14:17], v154
	s_waitcnt lgkmcnt(0)
	v_mfma_f32_16x16x32_bf16 v[14:17], v[6:9], v[14:17], 0
	s_nop 1
	v_max_f32_e32 v68, 0, v10
	v_max_f32_e32 v69, 0, v11
	v_max_f32_e32 v10, 0, v12
	v_mul_f32_e32 v70, v53, v10
	s_nop 0
	v_max_f32_e32 v67, 0, v13
	v_mfma_f32_16x16x32_bf16 v[10:13], v[2:5], v[24:27], v[14:17]
	ds_read_b128 v[24:27], v151
	v_pk_mul_f32 v[90:91], v[52:53], v[66:67]
	ds_read2_b32 v[66:67], v137 offset0:176 offset1:192
	ds_read_b128 v[14:17], v152
	s_waitcnt lgkmcnt(0)
; #define LAS __attribute__((address_space(3)))
; __device__ __forceinline__ unsigned fkey(float f) { const unsigned u = __float_as_uint(f); return (u & 0x80000000u) ? ~u : (u | 0x80000000u); }
; #define SEL_HADD(idx_) __hip_atomic_fetch_add(&hist[(idx_)], 1u, __ATOMIC_RELAXED, __HIP_MEMORY_SCOPE_WORKGROUP)
; __device__ __forceinline__ void sel_unit(LAS char* lds, int b, int u, const bf16_t* QI, const bf16_t* KIDX, const float* WIDX, unsigned long long* MASK) {
;     ...
;     for (int j = 0; j < 8; ++j) {
;         if (j < nj) {
;             int t = wid + 8 * j; asm volatile("" : "+s"(t));
; #pragma unroll
;             for (int kh = 0; kh < 2; ++kh) {
;             bf16x8 kf[2][2];
; #pragma unroll
;             for (int kb = 0; kb < 2; ++kb)
; #pragma unroll
;                 for (int ks = 0; ks < 2; ++ks) kf[kb][ks] = *(const bf16x8*)(KIDX + (rowbase + 64 * t + 32 * kh + 16 * kb + q16) * 64 + 32 * ks + 8 * kg);
; #pragma unroll
;             for (int kb = 0; kb < 2; ++kb) {
;                 f32x4 s = (f32x4){0.f, 0.f, 0.f, 0.f};
; #pragma unroll
;                 for (int hh = 0; hh < 8; ++hh) {
;                     f32x4 a = (f32x4){0.f, 0.f, 0.f, 0.f};
; #pragma unroll
;                     for (int ks = 0; ks < 2; ++ks) {
;                         const bf16x8 qv = *(const LAS bf16x8*)(lds + L_QI + q16 * 1024 + (((hh * 8 + 4 * ks + kg) ^ q16) << 4));
;                         a = __builtin_amdgcn_mfma_f32_16x16x32_bf16(kf[kb][ks], qv, a, 0, 0, 0);
;                     }
;                     const float wh = wl[hh * 16];
; #pragma unroll
;                     for (int i = 0; i < 4; ++i) s[i] += wh * fmaxf(a[i], 0.f);
;                 }
;                 u32x4 kk; kk.x = fkey(s[0]); kk.y = fkey(s[1]); kk.z = fkey(s[2]); kk.w = fkey(s[3]);
;                 sc[j][2 * kh + kb] = kk;
; #pragma unroll
;                 for (int i = 0; i < 4; ++i) SEL_HADD((kk[i] >> 24) * 16 + q16);
;                 __builtin_amdgcn_sched_barrier(0);
	v_mfma_f32_16x16x32_bf16 v[6:9], v[6:9], v[14:17], 0
	s_nop 1
	s_nop 0
	v_max_f32_e32 v14, 0, v13
	s_nop 0
	v_mfma_f32_16x16x32_bf16 v[2:5], v[2:5], v[24:27], v[6:9]
	s_nop 0
	v_max_f32_e32 v10, 0, v10
	v_max_f32_e32 v11, 0, v11
	v_pk_fma_f32 v[8:9], v[32:33], v[34:35], 0 op_sel_hi:[0,1,0]
	s_nop 0
	s_nop 2
	v_max_f32_e32 v15, 0, v5
	v_pk_mul_f32 v[6:7], v[66:67], v[14:15]
	v_mov_b32_e32 v14, v33
	v_pk_fma_f32 v[8:9], v[14:15], v[28:29], v[8:9] op_sel_hi:[0,1,1]
	v_pk_fma_f32 v[8:9], v[40:41], v[42:43], v[8:9] op_sel_hi:[0,1,1]
	v_mov_b32_e32 v14, v41
	v_pk_fma_f32 v[8:9], v[14:15], v[48:49], v[8:9] op_sel_hi:[0,1,1]
	v_pk_fma_f32 v[8:9], v[52:53], v[54:55], v[8:9] op_sel_hi:[0,1,1]
	v_mov_b32_e32 v14, v53
	v_pk_fma_f32 v[8:9], v[14:15], v[68:69], v[8:9] op_sel_hi:[0,1,1]
	v_max_f32_e32 v2, 0, v2
	v_max_f32_e32 v3, 0, v3
	v_pk_fma_f32 v[8:9], v[66:67], v[10:11], v[8:9] op_sel_hi:[0,1,1]
	v_mov_b32_e32 v10, v67
	v_pk_fma_f32 v[2:3], v[10:11], v[2:3], v[8:9] op_sel_hi:[0,1,1]
	v_and_b32_e32 v9, 0x7fffffff, v3
	v_and_b32_e32 v8, 0x7fffffff, v2
	v_xor_b32_e32 v5, -1, v3
	v_pk_add_f32 v[8:9], v[8:9], 0 neg_lo:[1,1] neg_hi:[1,1]
	v_cmp_gt_i32_e32 vcc, 0, v3
	v_xor_b32_e32 v10, -1, v2
	v_mov_b32_e32 v57, v90
	v_cndmask_b32_e32 v65, v9, v5, vcc
	v_cmp_gt_i32_e32 vcc, 0, v2
	v_pk_add_f32 v[2:3], v[36:37], 0 op_sel_hi:[1,0]
	v_max_f32_e32 v12, 0, v12
	v_pk_add_f32 v[2:3], v[2:3], v[30:31]
	v_pk_add_f32 v[2:3], v[2:3], v[44:45]
	v_mov_b32_e32 v71, v91
	v_pk_add_f32 v[2:3], v[2:3], v[50:51]
	v_mul_f32_e32 v12, v66, v12
	v_pk_add_f32 v[2:3], v[2:3], v[56:57]
	v_max_f32_e32 v4, 0, v4
	v_pk_add_f32 v[2:3], v[2:3], v[70:71]
	v_mov_b32_e32 v13, v6
	v_mul_f32_e32 v4, v67, v4
	v_pk_add_f32 v[2:3], v[2:3], v[12:13]
	v_mov_b32_e32 v5, v7
	v_pk_add_f32 v[2:3], v[2:3], v[4:5]
	v_cndmask_b32_e32 v66, v8, v10, vcc
	v_and_b32_e32 v5, 0x7fffffff, v3
	v_and_b32_e32 v4, 0x7fffffff, v2
	v_xor_b32_e32 v6, -1, v3
	v_pk_add_f32 v[4:5], v[4:5], 0 neg_lo:[1,1] neg_hi:[1,1]
	v_cmp_gt_i32_e32 vcc, 0, v3
	v_xor_b32_e32 v7, -1, v2
	s_nop 0
	v_cndmask_b32_e32 v67, v5, v6, vcc
	v_cmp_gt_i32_e32 vcc, 0, v2
	v_lshrrev_b32_e32 v2, 24, v66
	v_lshl_add_u32 v2, v2, 6, v0
	ds_add_u32 v2, v205 offset:16384
	v_lshrrev_b32_e32 v2, 24, v65
	v_cndmask_b32_e32 v68, v4, v7, vcc
	v_lshl_add_u32 v2, v2, 6, v0
	ds_add_u32 v2, v205 offset:16384
	v_lshrrev_b32_e32 v2, 24, v68
	v_lshl_add_u32 v2, v2, 6, v0
	ds_add_u32 v2, v205 offset:16384
	v_lshrrev_b32_e32 v2, 24, v67
	v_lshl_add_u32 v2, v2, 6, v0
	ds_add_u32 v2, v205 offset:16384
	v_add_co_u32_e32 v2, vcc, s96, v22
	s_nop 1
	v_addc_co_u32_e32 v3, vcc, 0, v23, vcc
	global_load_dwordx4 v[14:17], v[2:3], off
	global_load_dwordx4 v[10:13], v[2:3], off offset:64
	global_load_dwordx4 v[6:9], v[2:3], off offset:2048
	s_nop 0
	global_load_dwordx4 v[2:5], v[2:3], off offset:2112
	ds_read_b128 v[22:25], v182
	ds_read_b128 v[26:29], v183
	s_waitcnt vmcnt(3) lgkmcnt(1)
	v_mfma_f32_16x16x32_bf16 v[22:25], v[14:17], v[22:25], 0
	ds_read_b128 v[32:35], v185
	ds_read_b128 v[38:41], v180
	ds_read_b128 v[44:47], v159
	s_waitcnt vmcnt(2) lgkmcnt(3)
	v_mfma_f32_16x16x32_bf16 v[26:29], v[10:13], v[26:29], v[22:25]
	ds_read_b128 v[50:53], v157
	ds_read_b128 v[90:93], v155
	ds_read_b128 v[94:97], v153
	ds_read2_b32 v[24:25], v137 offset0:80 offset1:96
	s_nop 3
	v_max_f32_e32 v26, 0, v26
	v_max_f32_e32 v27, 0, v27
	v_max_f32_e32 v22, v28, v28
	v_max_f32_e32 v23, v29, v29
	ds_read_b128 v[28:31], v184
	s_waitcnt lgkmcnt(0)
	v_mfma_f32_16x16x32_bf16 v[28:31], v[14:17], v[28:31], 0
	v_max_f32_e32 v36, 0, v23
	v_max_f32_e32 v22, 0, v22
	v_mul_f32_e32 v22, v24, v22
	v_mfma_f32_16x16x32_bf16 v[28:31], v[10:13], v[32:35], v[28:31]
	s_nop 7
	v_max_f32_e32 v32, 0, v28
	v_max_f32_e32 v33, 0, v29
	v_max_f32_e32 v23, 0, v30
	v_mul_f32_e32 v28, v25, v23
	v_max_f32_e32 v37, 0, v31
	v_pk_mul_f32 v[30:31], v[24:25], v[36:37]
	ds_read_b128 v[34:37], v179
	s_waitcnt lgkmcnt(0)
	v_mfma_f32_16x16x32_bf16 v[34:37], v[14:17], v[34:37], 0
	v_mov_b32_e32 v29, v31
	v_mfma_f32_16x16x32_bf16 v[38:41], v[10:13], v[38:41], v[34:37]
	s_nop 5
	ds_read2_b32 v[36:37], v137 offset0:112 offset1:128
	s_nop 0
	v_max_f32_e32 v38, 0, v38
	v_max_f32_e32 v39, 0, v39
	v_max_f32_e32 v23, 0, v40
	s_waitcnt lgkmcnt(0)
	v_mul_f32_e32 v34, v36, v23
	v_max_f32_e32 v23, v41, v41
	ds_read_b128 v[40:43], v176
	s_waitcnt lgkmcnt(0)
	v_mfma_f32_16x16x32_bf16 v[40:43], v[14:17], v[40:43], 0
	v_max_f32_e32 v48, 0, v23
	v_mfma_f32_16x16x32_bf16 v[40:43], v[10:13], v[44:47], v[40:43]
	s_nop 7
	v_max_f32_e32 v44, 0, v40
	v_max_f32_e32 v45, 0, v41
	v_max_f32_e32 v23, 0, v42
	v_mul_f32_e32 v40, v37, v23
	v_max_f32_e32 v49, 0, v43
	v_pk_mul_f32 v[42:43], v[36:37], v[48:49]
	ds_read_b128 v[46:49], v158
	s_waitcnt lgkmcnt(0)
	v_mfma_f32_16x16x32_bf16 v[46:49], v[14:17], v[46:49], 0
	v_mov_b32_e32 v35, v42
	v_mov_b32_e32 v41, v43
	v_mfma_f32_16x16x32_bf16 v[50:53], v[10:13], v[50:53], v[46:49]
	s_nop 4
	ds_read2_b32 v[48:49], v137 offset0:144 offset1:160
	s_nop 1
	v_max_f32_e32 v50, 0, v50
	v_max_f32_e32 v51, 0, v51
	v_max_f32_e32 v23, 0, v52
	s_waitcnt lgkmcnt(0)
	v_mul_f32_e32 v46, v48, v23
	v_max_f32_e32 v23, v53, v53
	ds_read_b128 v[52:55], v156
	s_waitcnt lgkmcnt(0)
	v_mfma_f32_16x16x32_bf16 v[52:55], v[14:17], v[52:55], 0
	v_max_f32_e32 v70, 0, v23
	v_mfma_f32_16x16x32_bf16 v[52:55], v[10:13], v[90:93], v[52:55]
	ds_read_b128 v[90:93], v154
	s_waitcnt lgkmcnt(0)
	v_mfma_f32_16x16x32_bf16 v[90:93], v[14:17], v[90:93], 0
	s_nop 4
	v_max_f32_e32 v56, 0, v52
	v_max_f32_e32 v57, 0, v53
	v_max_f32_e32 v23, 0, v54
	v_mfma_f32_16x16x32_bf16 v[90:93], v[10:13], v[94:97], v[90:93]
	v_mul_f32_e32 v52, v49, v23
	s_nop 0
	v_max_f32_e32 v71, 0, v55
	v_pk_mul_f32 v[54:55], v[48:49], v[70:71]
	ds_read2_b32 v[70:71], v137 offset0:176 offset1:192
	s_nop 2
	v_max_f32_e32 v94, 0, v90
	v_max_f32_e32 v95, 0, v91
	v_max_f32_e32 v23, 0, v92
	s_waitcnt lgkmcnt(0)
; #define LAS __attribute__((address_space(3)))
; __device__ __forceinline__ unsigned fkey(float f) { const unsigned u = __float_as_uint(f); return (u & 0x80000000u) ? ~u : (u | 0x80000000u); }
; #define SEL_HADD(idx_) __hip_atomic_fetch_add(&hist[(idx_)], 1u, __ATOMIC_RELAXED, __HIP_MEMORY_SCOPE_WORKGROUP)
; __device__ __forceinline__ void sel_unit(LAS char* lds, int b, int u, const bf16_t* QI, const bf16_t* KIDX, const float* WIDX, unsigned long long* MASK) {
;     ...
;     for (int j = 0; j < 8; ++j) {
;         if (j < nj) {
;             int t = wid + 8 * j; asm volatile("" : "+s"(t));
; #pragma unroll
;             for (int kh = 0; kh < 2; ++kh) {
;             bf16x8 kf[2][2];
; #pragma unroll
;             for (int kb = 0; kb < 2; ++kb)
; #pragma unroll
;                 for (int ks = 0; ks < 2; ++ks) kf[kb][ks] = *(const bf16x8*)(KIDX + (rowbase + 64 * t + 32 * kh + 16 * kb + q16) * 64 + 32 * ks + 8 * kg);
; #pragma unroll
;             for (int kb = 0; kb < 2; ++kb) {
;                 f32x4 s = (f32x4){0.f, 0.f, 0.f, 0.f};
; #pragma unroll
;                 for (int hh = 0; hh < 8; ++hh) {
;                     f32x4 a = (f32x4){0.f, 0.f, 0.f, 0.f};
; #pragma unroll
;                     for (int ks = 0; ks < 2; ++ks) {
;                         const bf16x8 qv = *(const LAS bf16x8*)(lds + L_QI + q16 * 1024 + (((hh * 8 + 4 * ks + kg) ^ q16) << 4));
;                         a = __builtin_amdgcn_mfma_f32_16x16x32_bf16(kf[kb][ks], qv, a, 0, 0, 0);
;                     }
;                     const float wh = wl[hh * 16];
; #pragma unroll
;                     for (int i = 0; i < 4; ++i) s[i] += wh * fmaxf(a[i], 0.f);
;                 }
;                 u32x4 kk; kk.x = fkey(s[0]); kk.y = fkey(s[1]); kk.z = fkey(s[2]); kk.w = fkey(s[3]);
;                 sc[j][2 * kh + kb] = kk;
; #pragma unroll
;                 for (int i = 0; i < 4; ++i) SEL_HADD((kk[i] >> 24) * 16 + q16);
;                 __builtin_amdgcn_sched_barrier(0);
	v_mul_f32_e32 v96, v70, v23
	v_max_f32_e32 v23, v93, v93
	ds_read_b128 v[90:93], v152
	s_waitcnt lgkmcnt(0)
	v_mfma_f32_16x16x32_bf16 v[14:17], v[14:17], v[90:93], 0
	ds_read_b128 v[90:93], v151
	v_max_f32_e32 v98, 0, v23
	v_mov_b32_e32 v47, v54
	s_waitcnt lgkmcnt(0)
	v_mfma_f32_16x16x32_bf16 v[10:13], v[10:13], v[90:93], v[14:17]
	v_mov_b32_e32 v53, v55
	s_nop 1
	v_pk_fma_f32 v[16:17], v[24:25], v[26:27], 0 op_sel_hi:[0,1,0]
	v_mov_b32_e32 v24, v25
	v_pk_fma_f32 v[16:17], v[24:25], v[32:33], v[16:17] op_sel_hi:[0,1,1]
	v_pk_fma_f32 v[16:17], v[36:37], v[38:39], v[16:17] op_sel_hi:[0,1,1]
	v_mov_b32_e32 v24, v37
	v_pk_fma_f32 v[16:17], v[24:25], v[44:45], v[16:17] op_sel_hi:[0,1,1]
	v_pk_fma_f32 v[16:17], v[48:49], v[50:51], v[16:17] op_sel_hi:[0,1,1]
	v_mov_b32_e32 v24, v49
	v_pk_fma_f32 v[16:17], v[24:25], v[56:57], v[16:17] op_sel_hi:[0,1,1]
	v_max_f32_e32 v10, 0, v10
	v_max_f32_e32 v11, 0, v11
	v_pk_fma_f32 v[16:17], v[70:71], v[94:95], v[16:17] op_sel_hi:[0,1,1]
	v_mov_b32_e32 v24, v71
	v_pk_fma_f32 v[10:11], v[24:25], v[10:11], v[16:17] op_sel_hi:[0,1,1]
	v_and_b32_e32 v17, 0x7fffffff, v11
	v_and_b32_e32 v16, 0x7fffffff, v10
	v_max_f32_e32 v99, 0, v13
	v_xor_b32_e32 v23, -1, v10
	v_pk_add_f32 v[16:17], v[16:17], 0 neg_lo:[1,1] neg_hi:[1,1]
	v_cmp_gt_i32_e32 vcc, 0, v10
	v_pk_mul_f32 v[14:15], v[70:71], v[98:99]
	v_xor_b32_e32 v13, -1, v11
	v_cndmask_b32_e32 v70, v16, v23, vcc
	v_mov_b32_e32 v23, v30
	v_cmp_gt_i32_e64 s[2:3], 0, v11
	v_pk_add_f32 v[10:11], v[22:23], 0 op_sel_hi:[1,0]
	v_pk_add_f32 v[10:11], v[10:11], v[28:29]
	v_max_f32_e32 v12, 0, v12
	v_pk_add_f32 v[10:11], v[10:11], v[34:35]
	v_mov_b32_e32 v97, v14
	v_pk_add_f32 v[10:11], v[10:11], v[40:41]
	v_mul_f32_e32 v12, v71, v12
	v_pk_add_f32 v[10:11], v[10:11], v[46:47]
	v_cndmask_b32_e64 v69, v17, v13, s[2:3]
	v_pk_add_f32 v[10:11], v[10:11], v[52:53]
	v_mov_b32_e32 v13, v15
	v_pk_add_f32 v[10:11], v[10:11], v[96:97]
	s_nop 0
	v_pk_add_f32 v[10:11], v[10:11], v[12:13]
	s_nop 0
	v_xor_b32_e32 v15, -1, v10
	v_and_b32_e32 v12, 0x7fffffff, v10
	v_cmp_gt_i32_e32 vcc, 0, v10
	v_lshrrev_b32_e32 v10, 24, v70
	v_and_b32_e32 v13, 0x7fffffff, v11
	v_lshl_add_u32 v10, v10, 6, v0
	v_pk_add_f32 v[12:13], v[12:13], 0 neg_lo:[1,1] neg_hi:[1,1]
	ds_add_u32 v10, v205 offset:16384
	v_lshrrev_b32_e32 v10, 24, v69
	v_cndmask_b32_e32 v72, v12, v15, vcc
	v_lshl_add_u32 v10, v10, 6, v0
	v_xor_b32_e32 v14, -1, v11
	v_cmp_gt_i32_e64 s[2:3], 0, v11
	ds_add_u32 v10, v205 offset:16384
	v_lshrrev_b32_e32 v10, 24, v72
	v_cndmask_b32_e64 v71, v13, v14, s[2:3]
	v_lshl_add_u32 v10, v10, 6, v0
	ds_add_u32 v10, v205 offset:16384
	v_lshrrev_b32_e32 v10, 24, v71
	v_lshl_add_u32 v10, v10, 6, v0
	ds_add_u32 v10, v205 offset:16384
	ds_read_b128 v[10:13], v182
	ds_read_b128 v[14:17], v183
	ds_read_b128 v[22:25], v184
	ds_read_b128 v[26:29], v185
	ds_read2_b32 v[48:49], v137 offset0:144 offset1:160
	s_waitcnt vmcnt(1) lgkmcnt(4)
	v_mfma_f32_16x16x32_bf16 v[10:13], v[6:9], v[10:13], 0
	ds_read_b128 v[36:39], v159
	ds_read_b128 v[42:45], v157
	s_waitcnt lgkmcnt(4)
	v_mfma_f32_16x16x32_bf16 v[22:25], v[6:9], v[22:25], 0
	s_waitcnt vmcnt(0)
	v_mfma_f32_16x16x32_bf16 v[14:17], v[2:5], v[14:17], v[10:13]
	s_waitcnt lgkmcnt(3)
	v_mfma_f32_16x16x32_bf16 v[24:27], v[2:5], v[26:29], v[22:25]
	s_nop 0
	ds_read2_b32 v[12:13], v137 offset0:80 offset1:96
	s_nop 3
	v_max_f32_e32 v30, 0, v17
	v_max_f32_e32 v14, 0, v14
	v_max_f32_e32 v24, 0, v24
	v_max_f32_e32 v25, 0, v25
	v_max_f32_e32 v11, 0, v26
	v_max_f32_e32 v15, 0, v15
	v_max_f32_e32 v10, v16, v16
	s_waitcnt lgkmcnt(0)
	v_mul_f32_e32 v16, v13, v11
	v_max_f32_e32 v11, v27, v27
	ds_read_b128 v[26:29], v179
	v_max_f32_e32 v31, 0, v11
	v_pk_mul_f32 v[22:23], v[12:13], v[30:31]
	ds_read_b128 v[30:33], v180
	s_waitcnt lgkmcnt(1)
	v_mfma_f32_16x16x32_bf16 v[26:29], v[6:9], v[26:29], 0
	v_max_f32_e32 v10, 0, v10
	v_mul_f32_e32 v10, v12, v10
	v_mov_b32_e32 v17, v23
	s_waitcnt lgkmcnt(0)
	v_mfma_f32_16x16x32_bf16 v[30:33], v[2:5], v[30:33], v[26:29]
	s_nop 2
	ds_read2_b32 v[28:29], v137 offset0:112 offset1:128
	s_nop 3
	v_max_f32_e32 v30, 0, v30
	v_max_f32_e32 v31, 0, v31
	v_max_f32_e32 v11, 0, v32
	s_waitcnt lgkmcnt(0)
	v_mul_f32_e32 v26, v28, v11
	v_max_f32_e32 v11, v33, v33
	ds_read_b128 v[32:35], v176
	s_waitcnt lgkmcnt(0)
	v_mfma_f32_16x16x32_bf16 v[32:35], v[6:9], v[32:35], 0
	v_max_f32_e32 v40, 0, v11
	v_mfma_f32_16x16x32_bf16 v[32:35], v[2:5], v[36:39], v[32:35]
	s_nop 7
	v_max_f32_e32 v36, 0, v32
	v_max_f32_e32 v37, 0, v33
	v_max_f32_e32 v11, 0, v34
	v_mul_f32_e32 v32, v29, v11
	v_max_f32_e32 v41, 0, v35
	v_pk_mul_f32 v[34:35], v[28:29], v[40:41]
	ds_read_b128 v[38:41], v158
	s_waitcnt lgkmcnt(0)
	v_mfma_f32_16x16x32_bf16 v[38:41], v[6:9], v[38:41], 0
	v_mov_b32_e32 v27, v34
	v_mov_b32_e32 v33, v35
	v_mfma_f32_16x16x32_bf16 v[38:41], v[2:5], v[42:45], v[38:41]
	ds_read_b128 v[44:47], v155
	s_nop 6
	v_max_f32_e32 v50, 0, v38
	v_max_f32_e32 v51, 0, v39
	v_max_f32_e32 v11, 0, v40
	v_mul_f32_e32 v38, v48, v11
	v_max_f32_e32 v11, v41, v41
	ds_read_b128 v[40:43], v156
	s_waitcnt lgkmcnt(0)
	v_mfma_f32_16x16x32_bf16 v[40:43], v[6:9], v[40:43], 0
	v_max_f32_e32 v52, 0, v11
	v_mfma_f32_16x16x32_bf16 v[40:43], v[2:5], v[44:47], v[40:43]
	ds_read_b128 v[44:47], v153
	s_nop 6
	v_max_f32_e32 v54, 0, v40
	v_max_f32_e32 v55, 0, v41
	v_max_f32_e32 v11, 0, v42
	v_mul_f32_e32 v56, v49, v11
	v_max_f32_e32 v11, v43, v43
	ds_read_b128 v[40:43], v154
	s_waitcnt lgkmcnt(0)
	v_mfma_f32_16x16x32_bf16 v[40:43], v[6:9], v[40:43], 0
	v_max_f32_e32 v53, 0, v11
	v_pk_mul_f32 v[52:53], v[48:49], v[52:53]
	v_mfma_f32_16x16x32_bf16 v[40:43], v[2:5], v[44:47], v[40:43]
	ds_read2_b32 v[44:45], v137 offset0:176 offset1:192
	v_mov_b32_e32 v39, v52
	v_mov_b32_e32 v57, v53
	s_nop 4
	v_max_f32_e32 v46, 0, v40
	v_max_f32_e32 v47, 0, v41
	v_max_f32_e32 v11, 0, v42
	s_waitcnt lgkmcnt(0)
; #define LAS __attribute__((address_space(3)))
; __device__ __forceinline__ unsigned fkey(float f) { const unsigned u = __float_as_uint(f); return (u & 0x80000000u) ? ~u : (u | 0x80000000u); }
; #define SEL_HADD(idx_) __hip_atomic_fetch_add(&hist[(idx_)], 1u, __ATOMIC_RELAXED, __HIP_MEMORY_SCOPE_WORKGROUP)
; __device__ __forceinline__ void sel_unit(LAS char* lds, int b, int u, const bf16_t* QI, const bf16_t* KIDX, const float* WIDX, unsigned long long* MASK) {
;     ...
;     for (int j = 0; j < 8; ++j) {
;         if (j < nj) {
;             int t = wid + 8 * j; asm volatile("" : "+s"(t));
; #pragma unroll
;             for (int kh = 0; kh < 2; ++kh) {
;             bf16x8 kf[2][2];
; #pragma unroll
;             for (int kb = 0; kb < 2; ++kb)
; #pragma unroll
;                 for (int ks = 0; ks < 2; ++ks) kf[kb][ks] = *(const bf16x8*)(KIDX + (rowbase + 64 * t + 32 * kh + 16 * kb + q16) * 64 + 32 * ks + 8 * kg);
; #pragma unroll
;             for (int kb = 0; kb < 2; ++kb) {
;                 f32x4 s = (f32x4){0.f, 0.f, 0.f, 0.f};
; #pragma unroll
;                 for (int hh = 0; hh < 8; ++hh) {
;                     f32x4 a = (f32x4){0.f, 0.f, 0.f, 0.f};
; #pragma unroll
;                     for (int ks = 0; ks < 2; ++ks) {
;                         const bf16x8 qv = *(const LAS bf16x8*)(lds + L_QI + q16 * 1024 + (((hh * 8 + 4 * ks + kg) ^ q16) << 4));
;                         a = __builtin_amdgcn_mfma_f32_16x16x32_bf16(kf[kb][ks], qv, a, 0, 0, 0);
;                     }
;                     const float wh = wl[hh * 16];
; #pragma unroll
;                     for (int i = 0; i < 4; ++i) s[i] += wh * fmaxf(a[i], 0.f);
;                 }
;                 u32x4 kk; kk.x = fkey(s[0]); kk.y = fkey(s[1]); kk.z = fkey(s[2]); kk.w = fkey(s[3]);
;                 sc[j][2 * kh + kb] = kk;
; #pragma unroll
;                 for (int i = 0; i < 4; ++i) SEL_HADD((kk[i] >> 24) * 16 + q16);
;                 __builtin_amdgcn_sched_barrier(0);
	v_mul_f32_e32 v76, v44, v11
	v_max_f32_e32 v11, v43, v43
	ds_read_b128 v[40:43], v152
	s_waitcnt lgkmcnt(0)
	v_mfma_f32_16x16x32_bf16 v[6:9], v[6:9], v[40:43], 0
	ds_read_b128 v[40:43], v151
	v_max_f32_e32 v78, 0, v11
	s_waitcnt lgkmcnt(0)
	v_mfma_f32_16x16x32_bf16 v[2:5], v[2:5], v[40:43], v[6:9]
	s_nop 3
	v_fma_f32 v8, v12, v14, 0
	v_fma_f32 v9, v12, v15, 0
	v_mov_b32_e32 v12, v13
	v_pk_fma_f32 v[8:9], v[12:13], v[24:25], v[8:9] op_sel_hi:[0,1,1]
	v_pk_fma_f32 v[8:9], v[28:29], v[30:31], v[8:9] op_sel_hi:[0,1,1]
	v_mov_b32_e32 v12, v29
	v_pk_fma_f32 v[8:9], v[12:13], v[36:37], v[8:9] op_sel_hi:[0,1,1]
	v_pk_fma_f32 v[8:9], v[48:49], v[50:51], v[8:9] op_sel_hi:[0,1,1]
	v_mov_b32_e32 v12, v49
	v_pk_fma_f32 v[8:9], v[12:13], v[54:55], v[8:9] op_sel_hi:[0,1,1]
	v_max_f32_e32 v2, 0, v2
	v_max_f32_e32 v3, 0, v3
	v_pk_fma_f32 v[8:9], v[44:45], v[46:47], v[8:9] op_sel_hi:[0,1,1]
	v_mov_b32_e32 v12, v45
	v_pk_fma_f32 v[2:3], v[12:13], v[2:3], v[8:9] op_sel_hi:[0,1,1]
	v_and_b32_e32 v9, 0x7fffffff, v3
	v_and_b32_e32 v8, 0x7fffffff, v2
	v_xor_b32_e32 v11, -1, v2
	v_pk_add_f32 v[8:9], v[8:9], 0 neg_lo:[1,1] neg_hi:[1,1]
	v_cmp_gt_i32_e32 vcc, 0, v2
	v_max_f32_e32 v79, 0, v5
	s_nop 0
	v_cndmask_b32_e32 v74, v8, v11, vcc
	v_mov_b32_e32 v11, v22
	v_xor_b32_e32 v5, -1, v3
	v_cmp_gt_i32_e64 s[2:3], 0, v3
	v_pk_add_f32 v[2:3], v[10:11], 0 op_sel_hi:[1,0]
	v_pk_add_f32 v[2:3], v[2:3], v[16:17]
	v_pk_mul_f32 v[6:7], v[44:45], v[78:79]
	v_pk_add_f32 v[2:3], v[2:3], v[26:27]
	v_max_f32_e32 v4, 0, v4
	v_pk_add_f32 v[2:3], v[2:3], v[32:33]
	v_mov_b32_e32 v77, v6
	v_pk_add_f32 v[2:3], v[2:3], v[38:39]
	v_mul_f32_e32 v4, v45, v4
	v_pk_add_f32 v[2:3], v[2:3], v[56:57]
	v_cndmask_b32_e64 v73, v9, v5, s[2:3]
	v_pk_add_f32 v[2:3], v[2:3], v[76:77]
	v_mov_b32_e32 v5, v7
	v_pk_add_f32 v[2:3], v[2:3], v[4:5]
	s_nop 0
	v_xor_b32_e32 v7, -1, v2
	v_and_b32_e32 v4, 0x7fffffff, v2
	v_cmp_gt_i32_e32 vcc, 0, v2
	v_lshrrev_b32_e32 v2, 24, v74
	v_and_b32_e32 v5, 0x7fffffff, v3
	v_lshl_add_u32 v2, v2, 6, v0
	v_pk_add_f32 v[4:5], v[4:5], 0 neg_lo:[1,1] neg_hi:[1,1]
	ds_add_u32 v2, v205 offset:16384
	v_lshrrev_b32_e32 v2, 24, v73
	v_cndmask_b32_e32 v76, v4, v7, vcc
	v_lshl_add_u32 v2, v2, 6, v0
	v_xor_b32_e32 v6, -1, v3
	v_cmp_gt_i32_e64 s[2:3], 0, v3
	ds_add_u32 v2, v205 offset:16384
	v_lshrrev_b32_e32 v2, 24, v76
	v_cndmask_b32_e64 v75, v5, v6, s[2:3]
	v_lshl_add_u32 v2, v2, 6, v0
	ds_add_u32 v2, v205 offset:16384
	v_lshrrev_b32_e32 v2, 24, v75
	v_lshl_add_u32 v2, v2, 6, v0
	ds_add_u32 v2, v205 offset:16384
.LBB0_658:
	s_cmp_gt_i32 s4, 1
	s_cselect_b64 s[18:19], -1, 0
	s_cmp_lt_i32 s4, 2
	s_cbranch_scc1 .LBB0_660
	s_add_i32 s0, s46, 8
	s_lshl_b32 s0, s0, 6
	s_ashr_i32 s1, s0, 31
	v_lshl_add_u64 v[2:3], v[18:19], 0, s[0:1]
	v_lshlrev_b64 v[2:3], 7, v[2:3]
	v_lshl_add_u64 v[22:23], v[20:21], 0, v[2:3]
	global_load_dwordx4 v[14:17], v[22:23], off
	global_load_dwordx4 v[10:13], v[22:23], off offset:64
	ds_read_b128 v[2:5], v182
	ds_read_b128 v[6:9], v183
	ds_read_b128 v[24:27], v184
	ds_read_b128 v[28:31], v185
	ds_read_b128 v[32:35], v179
	ds_read_b128 v[36:39], v180
	ds_read_b128 v[40:43], v176
	ds_read_b128 v[44:47], v159
	ds_read_b128 v[48:51], v158
	ds_read_b128 v[52:55], v157
	ds_read_b128 v[78:81], v156
	ds_read_b128 v[82:85], v155
	s_waitcnt vmcnt(1) lgkmcnt(11)
	v_mfma_f32_16x16x32_bf16 v[2:5], v[14:17], v[2:5], 0
	s_waitcnt lgkmcnt(9)
	v_mfma_f32_16x16x32_bf16 v[24:27], v[14:17], v[24:27], 0
	s_waitcnt lgkmcnt(7)
	v_mfma_f32_16x16x32_bf16 v[32:35], v[14:17], v[32:35], 0
	s_waitcnt lgkmcnt(5)
	v_mfma_f32_16x16x32_bf16 v[40:43], v[14:17], v[40:43], 0
	s_waitcnt lgkmcnt(3)
	v_mfma_f32_16x16x32_bf16 v[48:51], v[14:17], v[48:51], 0
	s_waitcnt vmcnt(0)
	v_mfma_f32_16x16x32_bf16 v[102:105], v[10:13], v[6:9], v[2:5]
	v_mfma_f32_16x16x32_bf16 v[24:27], v[10:13], v[28:31], v[24:27]
	v_mfma_f32_16x16x32_bf16 v[28:31], v[10:13], v[36:39], v[32:35]
	v_mfma_f32_16x16x32_bf16 v[32:35], v[10:13], v[44:47], v[40:43]
	ds_read2_b32 v[44:45], v137 offset0:80 offset1:96
	ds_read2_b32 v[46:47], v137 offset0:112 offset1:128
	s_nop 3
	s_waitcnt lgkmcnt(4)
	v_mfma_f32_16x16x32_bf16 v[36:39], v[10:13], v[52:55], v[48:51]
	s_nop 0
	ds_read2_b32 v[48:49], v137 offset0:144 offset1:160
	global_load_dwordx4 v[6:9], v[22:23], off offset:2048
	global_load_dwordx4 v[2:5], v[22:23], off offset:2112
	s_waitcnt lgkmcnt(4)
	v_mfma_f32_16x16x32_bf16 v[78:81], v[14:17], v[78:81], 0
	s_nop 0
	v_max_f32_e32 v54, v24, v24
	s_nop 0
	s_waitcnt lgkmcnt(3)
	v_mfma_f32_16x16x32_bf16 v[40:43], v[10:13], v[82:85], v[78:81]
	v_max_f32_e32 v77, v39, v39
	v_max_f32_e32 v24, 0, v105
	v_max_f32_e32 v39, 0, v25
	v_max_f32_e32 v80, 0, v26
	v_max_f32_e32 v25, 0, v27
	v_max_f32_e32 v26, 0, v31
	v_max_f32_e32 v27, 0, v35
	v_max_f32_e32 v53, 0, v37
	s_waitcnt lgkmcnt(2)
	v_mul_f32_e32 v56, v45, v80
	v_pk_mul_f32 v[80:81], v[44:45], v[24:25]
	s_waitcnt lgkmcnt(1)
	v_pk_mul_f32 v[86:87], v[46:47], v[26:27]
	ds_read_b128 v[24:27], v154
	v_max_f32_e32 v78, v40, v40
	v_max_f32_e32 v40, 0, v28
	v_max_f32_e32 v28, 0, v30
	v_max_f32_e32 v50, v102, v102
	v_max_f32_e32 v79, v41, v41
	v_max_f32_e32 v41, 0, v29
	v_max_f32_e32 v29, 0, v34
	v_max_f32_e32 v30, 0, v38
	v_mul_f32_e32 v82, v46, v28
	v_max_f32_e32 v28, 0, v42
	v_mul_f32_e32 v84, v47, v29
	s_waitcnt lgkmcnt(1)
	v_mul_f32_e32 v106, v48, v30
	v_mul_f32_e32 v108, v49, v28
	ds_read_b128 v[28:31], v153
	s_waitcnt lgkmcnt(1)
	v_mfma_f32_16x16x32_bf16 v[24:27], v[14:17], v[24:27], 0
	v_max_f32_e32 v51, v103, v103
	s_waitcnt lgkmcnt(0)
; #define LAS __attribute__((address_space(3)))
; __device__ __forceinline__ unsigned fkey(float f) { const unsigned u = __float_as_uint(f); return (u & 0x80000000u) ? ~u : (u | 0x80000000u); }
; #define SEL_HADD(idx_) __hip_atomic_fetch_add(&hist[(idx_)], 1u, __ATOMIC_RELAXED, __HIP_MEMORY_SCOPE_WORKGROUP)
; __device__ __forceinline__ void sel_unit(LAS char* lds, int b, int u, const bf16_t* QI, const bf16_t* KIDX, const float* WIDX, unsigned long long* MASK) {
;     ...
;     for (int j = 0; j < 8; ++j) {
;         if (j < nj) {
;             int t = wid + 8 * j; asm volatile("" : "+s"(t));
; #pragma unroll
;             for (int kh = 0; kh < 2; ++kh) {
;             bf16x8 kf[2][2];
; #pragma unroll
;             for (int kb = 0; kb < 2; ++kb)
; #pragma unroll
;                 for (int ks = 0; ks < 2; ++ks) kf[kb][ks] = *(const bf16x8*)(KIDX + (rowbase + 64 * t + 32 * kh + 16 * kb + q16) * 64 + 32 * ks + 8 * kg);
; #pragma unroll
;             for (int kb = 0; kb < 2; ++kb) {
;                 f32x4 s = (f32x4){0.f, 0.f, 0.f, 0.f};
; #pragma unroll
;                 for (int hh = 0; hh < 8; ++hh) {
;                     f32x4 a = (f32x4){0.f, 0.f, 0.f, 0.f};
; #pragma unroll
;                     for (int ks = 0; ks < 2; ++ks) {
;                         const bf16x8 qv = *(const LAS bf16x8*)(lds + L_QI + q16 * 1024 + (((hh * 8 + 4 * ks + kg) ^ q16) << 4));
;                         a = __builtin_amdgcn_mfma_f32_16x16x32_bf16(kf[kb][ks], qv, a, 0, 0, 0);
;                     }
;                     const float wh = wl[hh * 16];
; #pragma unroll
;                     for (int i = 0; i < 4; ++i) s[i] += wh * fmaxf(a[i], 0.f);
;                 }
;                 u32x4 kk; kk.x = fkey(s[0]); kk.y = fkey(s[1]); kk.z = fkey(s[2]); kk.w = fkey(s[3]);
;                 sc[j][2 * kh + kb] = kk;
; #pragma unroll
;                 for (int i = 0; i < 4; ++i) SEL_HADD((kk[i] >> 24) * 16 + q16);
;                 __builtin_amdgcn_sched_barrier(0);
	v_mfma_f32_16x16x32_bf16 v[24:27], v[10:13], v[28:31], v[24:27]
	ds_read_b128 v[28:31], v152
	v_max_f32_e32 v37, 0, v51
	v_max_f32_e32 v51, 0, v33
	v_max_f32_e32 v52, v104, v104
	v_max_f32_e32 v55, v36, v36
	v_max_f32_e32 v36, 0, v50
	v_max_f32_e32 v50, 0, v32
	v_max_f32_e32 v32, 0, v77
	v_max_f32_e32 v33, 0, v43
	v_pk_mul_f32 v[110:111], v[48:49], v[32:33]
	ds_read_b128 v[32:35], v151
	s_waitcnt lgkmcnt(1)
	v_mfma_f32_16x16x32_bf16 v[14:17], v[14:17], v[28:31], 0
	v_max_f32_e32 v42, 0, v52
	v_max_f32_e32 v38, 0, v54
	v_max_f32_e32 v52, 0, v55
	s_waitcnt lgkmcnt(0)
	v_mfma_f32_16x16x32_bf16 v[10:13], v[10:13], v[32:35], v[14:17]
	v_max_f32_e32 v54, 0, v78
	v_max_f32_e32 v55, 0, v79
	ds_read2_b32 v[78:79], v137 offset0:176 offset1:192
	s_nop 0
	v_max_f32_e32 v28, 0, v27
	s_nop 2
	v_max_f32_e32 v29, 0, v13
	s_waitcnt lgkmcnt(0)
	v_pk_mul_f32 v[14:15], v[78:79], v[28:29]
	v_pk_fma_f32 v[16:17], v[44:45], v[36:37], 0 op_sel_hi:[0,1,0]
	v_mov_b32_e32 v28, v45
	v_pk_fma_f32 v[16:17], v[28:29], v[38:39], v[16:17] op_sel_hi:[0,1,1]
	v_pk_fma_f32 v[16:17], v[46:47], v[40:41], v[16:17] op_sel_hi:[0,1,1]
	v_mov_b32_e32 v28, v47
	v_pk_fma_f32 v[16:17], v[28:29], v[50:51], v[16:17] op_sel_hi:[0,1,1]
	v_pk_fma_f32 v[16:17], v[48:49], v[52:53], v[16:17] op_sel_hi:[0,1,1]
	v_mov_b32_e32 v28, v49
	v_max_f32_e32 v24, 0, v24
	v_max_f32_e32 v25, 0, v25
	v_pk_fma_f32 v[16:17], v[28:29], v[54:55], v[16:17] op_sel_hi:[0,1,1]
	v_max_f32_e32 v10, 0, v10
	v_max_f32_e32 v11, 0, v11
	v_pk_fma_f32 v[16:17], v[78:79], v[24:25], v[16:17] op_sel_hi:[0,1,1]
	v_mov_b32_e32 v24, v79
	v_pk_fma_f32 v[10:11], v[24:25], v[10:11], v[16:17] op_sel_hi:[0,1,1]
	v_and_b32_e32 v17, 0x7fffffff, v11
	v_and_b32_e32 v16, 0x7fffffff, v10
	v_mul_f32_e32 v42, v44, v42
	v_xor_b32_e32 v13, -1, v11
	v_pk_add_f32 v[16:17], v[16:17], 0 neg_lo:[1,1] neg_hi:[1,1]
	v_cmp_gt_i32_e32 vcc, 0, v11
	v_mov_b32_e32 v43, v80
	v_xor_b32_e32 v24, -1, v10
	v_cndmask_b32_e32 v77, v17, v13, vcc
	v_cmp_gt_i32_e32 vcc, 0, v10
	v_pk_add_f32 v[10:11], v[42:43], 0 op_sel_hi:[1,0]
	v_mov_b32_e32 v57, v81
	v_pk_add_f32 v[10:11], v[10:11], v[56:57]
	v_mov_b32_e32 v83, v86
	v_pk_add_f32 v[10:11], v[10:11], v[82:83]
	v_mov_b32_e32 v85, v87
	v_pk_add_f32 v[10:11], v[10:11], v[84:85]
	v_mov_b32_e32 v107, v110
	v_max_f32_e32 v26, 0, v26
	v_pk_add_f32 v[10:11], v[10:11], v[106:107]
	v_mov_b32_e32 v109, v111
	v_mul_f32_e32 v26, v78, v26
	v_max_f32_e32 v12, 0, v12
	v_pk_add_f32 v[10:11], v[10:11], v[108:109]
	v_mov_b32_e32 v27, v14
	v_mul_f32_e32 v12, v79, v12
	v_pk_add_f32 v[10:11], v[10:11], v[26:27]
	v_mov_b32_e32 v13, v15
	v_pk_add_f32 v[10:11], v[10:11], v[12:13]
	v_cndmask_b32_e32 v78, v16, v24, vcc
	v_and_b32_e32 v13, 0x7fffffff, v11
	v_and_b32_e32 v12, 0x7fffffff, v10
	v_xor_b32_e32 v14, -1, v11
	v_pk_add_f32 v[12:13], v[12:13], 0 neg_lo:[1,1] neg_hi:[1,1]
	v_cmp_gt_i32_e32 vcc, 0, v11
	v_xor_b32_e32 v15, -1, v10
	s_nop 0
	v_cndmask_b32_e32 v79, v13, v14, vcc
	v_cmp_gt_i32_e32 vcc, 0, v10
	v_lshrrev_b32_e32 v10, 24, v78
	v_lshl_add_u32 v10, v10, 6, v0
	ds_add_u32 v10, v205 offset:16384
	v_lshrrev_b32_e32 v10, 24, v77
	v_cndmask_b32_e32 v80, v12, v15, vcc
	v_lshl_add_u32 v10, v10, 6, v0
	ds_add_u32 v10, v205 offset:16384
	v_lshrrev_b32_e32 v10, 24, v80
	v_lshl_add_u32 v10, v10, 6, v0
	ds_add_u32 v10, v205 offset:16384
	v_lshrrev_b32_e32 v10, 24, v79
	v_lshl_add_u32 v10, v10, 6, v0
	ds_add_u32 v10, v205 offset:16384
	ds_read_b128 v[10:13], v182
	ds_read_b128 v[14:17], v183
	ds_read_b128 v[24:27], v184
	ds_read_b128 v[28:31], v185
	ds_read2_b32 v[32:33], v137 offset0:80 offset1:96
	ds_read2_b32 v[40:41], v137 offset0:112 offset1:128
	s_waitcnt vmcnt(1) lgkmcnt(5)
	v_mfma_f32_16x16x32_bf16 v[10:13], v[6:9], v[10:13], 0
	ds_read2_b32 v[52:53], v137 offset0:144 offset1:160
	s_waitcnt vmcnt(0) lgkmcnt(5)
	v_mfma_f32_16x16x32_bf16 v[10:13], v[2:5], v[14:17], v[10:13]
	ds_read_b128 v[14:17], v179
	s_waitcnt lgkmcnt(5)
	v_mfma_f32_16x16x32_bf16 v[24:27], v[6:9], v[24:27], 0
	s_nop 4
	v_max_f32_e32 v34, 0, v10
	v_max_f32_e32 v10, 0, v12
	v_max_f32_e32 v35, 0, v11
	s_waitcnt lgkmcnt(3)
	v_mul_f32_e32 v36, v32, v10
	v_max_f32_e32 v38, 0, v13
	v_mfma_f32_16x16x32_bf16 v[10:13], v[2:5], v[28:31], v[24:27]
	s_nop 2
	ds_read_b128 v[24:27], v180
	s_waitcnt lgkmcnt(1)
	v_mfma_f32_16x16x32_bf16 v[14:17], v[6:9], v[14:17], 0
	s_nop 1
	v_max_f32_e32 v28, 0, v10
	v_max_f32_e32 v29, 0, v11
	v_max_f32_e32 v10, 0, v12
	v_mul_f32_e32 v30, v33, v10
	v_max_f32_e32 v39, 0, v13
	s_waitcnt lgkmcnt(0)
	v_mfma_f32_16x16x32_bf16 v[10:13], v[2:5], v[24:27], v[14:17]
	ds_read_b128 v[24:27], v159
	v_pk_mul_f32 v[38:39], v[32:33], v[38:39]
	s_nop 0
	ds_read_b128 v[14:17], v176
	s_waitcnt lgkmcnt(0)
	v_mfma_f32_16x16x32_bf16 v[14:17], v[6:9], v[14:17], 0
	s_nop 1
	v_max_f32_e32 v42, 0, v10
	v_max_f32_e32 v43, 0, v11
	v_max_f32_e32 v10, 0, v12
	v_mul_f32_e32 v44, v40, v10
	s_nop 0
	v_max_f32_e32 v46, 0, v13
	v_mfma_f32_16x16x32_bf16 v[10:13], v[2:5], v[24:27], v[14:17]
	ds_read_b128 v[24:27], v157
	v_mov_b32_e32 v37, v38
	v_mov_b32_e32 v31, v39
	ds_read_b128 v[14:17], v158
	s_waitcnt lgkmcnt(0)
	v_mfma_f32_16x16x32_bf16 v[14:17], v[6:9], v[14:17], 0
	s_nop 1
	v_max_f32_e32 v48, 0, v10
	v_max_f32_e32 v49, 0, v11
	v_max_f32_e32 v10, 0, v12
	v_mul_f32_e32 v50, v41, v10
	s_nop 0
	v_max_f32_e32 v47, 0, v13
	v_mfma_f32_16x16x32_bf16 v[10:13], v[2:5], v[24:27], v[14:17]
	ds_read_b128 v[24:27], v155
	v_pk_mul_f32 v[46:47], v[40:41], v[46:47]
	s_nop 0
	ds_read_b128 v[14:17], v156
	s_waitcnt lgkmcnt(0)
; #define LAS __attribute__((address_space(3)))
; __device__ __forceinline__ unsigned fkey(float f) { const unsigned u = __float_as_uint(f); return (u & 0x80000000u) ? ~u : (u | 0x80000000u); }
; #define SEL_HADD(idx_) __hip_atomic_fetch_add(&hist[(idx_)], 1u, __ATOMIC_RELAXED, __HIP_MEMORY_SCOPE_WORKGROUP)
; __device__ __forceinline__ void sel_unit(LAS char* lds, int b, int u, const bf16_t* QI, const bf16_t* KIDX, const float* WIDX, unsigned long long* MASK) {
;     ...
;     for (int j = 0; j < 8; ++j) {
;         if (j < nj) {
;             int t = wid + 8 * j; asm volatile("" : "+s"(t));
; #pragma unroll
;             for (int kh = 0; kh < 2; ++kh) {
;             bf16x8 kf[2][2];
; #pragma unroll
;             for (int kb = 0; kb < 2; ++kb)
; #pragma unroll
;                 for (int ks = 0; ks < 2; ++ks) kf[kb][ks] = *(const bf16x8*)(KIDX + (rowbase + 64 * t + 32 * kh + 16 * kb + q16) * 64 + 32 * ks + 8 * kg);
; #pragma unroll
;             for (int kb = 0; kb < 2; ++kb) {
;                 f32x4 s = (f32x4){0.f, 0.f, 0.f, 0.f};
; #pragma unroll
;                 for (int hh = 0; hh < 8; ++hh) {
;                     f32x4 a = (f32x4){0.f, 0.f, 0.f, 0.f};
; #pragma unroll
;                     for (int ks = 0; ks < 2; ++ks) {
;                         const bf16x8 qv = *(const LAS bf16x8*)(lds + L_QI + q16 * 1024 + (((hh * 8 + 4 * ks + kg) ^ q16) << 4));
;                         a = __builtin_amdgcn_mfma_f32_16x16x32_bf16(kf[kb][ks], qv, a, 0, 0, 0);
;                     }
;                     const float wh = wl[hh * 16];
; #pragma unroll
;                     for (int i = 0; i < 4; ++i) s[i] += wh * fmaxf(a[i], 0.f);
;                 }
;                 u32x4 kk; kk.x = fkey(s[0]); kk.y = fkey(s[1]); kk.z = fkey(s[2]); kk.w = fkey(s[3]);
;                 sc[j][2 * kh + kb] = kk;
; #pragma unroll
;                 for (int i = 0; i < 4; ++i) SEL_HADD((kk[i] >> 24) * 16 + q16);
;                 __builtin_amdgcn_sched_barrier(0);
	v_mfma_f32_16x16x32_bf16 v[14:17], v[6:9], v[14:17], 0
	s_nop 1
	v_max_f32_e32 v54, 0, v10
	v_max_f32_e32 v55, 0, v11
	v_max_f32_e32 v10, 0, v12
	v_mul_f32_e32 v56, v52, v10
	s_nop 0
	v_max_f32_e32 v82, 0, v13
	v_mfma_f32_16x16x32_bf16 v[10:13], v[2:5], v[24:27], v[14:17]
	ds_read_b128 v[24:27], v153
	v_mov_b32_e32 v45, v46
	v_mov_b32_e32 v51, v47
	ds_read_b128 v[14:17], v154
	s_waitcnt lgkmcnt(0)
	v_mfma_f32_16x16x32_bf16 v[14:17], v[6:9], v[14:17], 0
	s_nop 1
	v_max_f32_e32 v84, 0, v10
	v_max_f32_e32 v85, 0, v11
	v_max_f32_e32 v10, 0, v12
	v_mul_f32_e32 v86, v53, v10
	s_nop 0
	v_max_f32_e32 v83, 0, v13
	v_mfma_f32_16x16x32_bf16 v[10:13], v[2:5], v[24:27], v[14:17]
	ds_read_b128 v[24:27], v151
	v_pk_mul_f32 v[106:107], v[52:53], v[82:83]
	ds_read2_b32 v[82:83], v137 offset0:176 offset1:192
	ds_read_b128 v[14:17], v152
	s_waitcnt lgkmcnt(0)
	v_mfma_f32_16x16x32_bf16 v[6:9], v[6:9], v[14:17], 0
	s_nop 1
	s_nop 0
	v_max_f32_e32 v14, 0, v13
	s_nop 0
	v_mfma_f32_16x16x32_bf16 v[2:5], v[2:5], v[24:27], v[6:9]
	s_nop 0
	v_max_f32_e32 v10, 0, v10
	v_max_f32_e32 v11, 0, v11
	v_pk_fma_f32 v[8:9], v[32:33], v[34:35], 0 op_sel_hi:[0,1,0]
	s_nop 0
	s_nop 2
	v_max_f32_e32 v15, 0, v5
	v_pk_mul_f32 v[6:7], v[82:83], v[14:15]
	v_mov_b32_e32 v14, v33
	v_pk_fma_f32 v[8:9], v[14:15], v[28:29], v[8:9] op_sel_hi:[0,1,1]
	v_pk_fma_f32 v[8:9], v[40:41], v[42:43], v[8:9] op_sel_hi:[0,1,1]
	v_mov_b32_e32 v14, v41
	v_pk_fma_f32 v[8:9], v[14:15], v[48:49], v[8:9] op_sel_hi:[0,1,1]
	v_pk_fma_f32 v[8:9], v[52:53], v[54:55], v[8:9] op_sel_hi:[0,1,1]
	v_mov_b32_e32 v14, v53
	v_pk_fma_f32 v[8:9], v[14:15], v[84:85], v[8:9] op_sel_hi:[0,1,1]
	v_max_f32_e32 v2, 0, v2
	v_max_f32_e32 v3, 0, v3
	v_pk_fma_f32 v[8:9], v[82:83], v[10:11], v[8:9] op_sel_hi:[0,1,1]
	v_mov_b32_e32 v10, v83
	v_pk_fma_f32 v[2:3], v[10:11], v[2:3], v[8:9] op_sel_hi:[0,1,1]
	v_and_b32_e32 v9, 0x7fffffff, v3
	v_and_b32_e32 v8, 0x7fffffff, v2
	v_xor_b32_e32 v5, -1, v3
	v_pk_add_f32 v[8:9], v[8:9], 0 neg_lo:[1,1] neg_hi:[1,1]
	v_cmp_gt_i32_e32 vcc, 0, v3
	v_xor_b32_e32 v10, -1, v2
	v_mov_b32_e32 v57, v106
	v_cndmask_b32_e32 v81, v9, v5, vcc
	v_cmp_gt_i32_e32 vcc, 0, v2
	v_pk_add_f32 v[2:3], v[36:37], 0 op_sel_hi:[1,0]
	v_max_f32_e32 v12, 0, v12
	v_pk_add_f32 v[2:3], v[2:3], v[30:31]
	v_pk_add_f32 v[2:3], v[2:3], v[44:45]
	v_mov_b32_e32 v87, v107
	v_pk_add_f32 v[2:3], v[2:3], v[50:51]
	v_mul_f32_e32 v12, v82, v12
	v_pk_add_f32 v[2:3], v[2:3], v[56:57]
	v_max_f32_e32 v4, 0, v4
	v_pk_add_f32 v[2:3], v[2:3], v[86:87]
	v_mov_b32_e32 v13, v6
	v_mul_f32_e32 v4, v83, v4
	v_pk_add_f32 v[2:3], v[2:3], v[12:13]
	v_mov_b32_e32 v5, v7
	v_pk_add_f32 v[2:3], v[2:3], v[4:5]
	v_cndmask_b32_e32 v82, v8, v10, vcc
	v_and_b32_e32 v5, 0x7fffffff, v3
	v_and_b32_e32 v4, 0x7fffffff, v2
	v_xor_b32_e32 v6, -1, v3
	v_pk_add_f32 v[4:5], v[4:5], 0 neg_lo:[1,1] neg_hi:[1,1]
	v_cmp_gt_i32_e32 vcc, 0, v3
	v_xor_b32_e32 v7, -1, v2
	s_nop 0
	v_cndmask_b32_e32 v83, v5, v6, vcc
	v_cmp_gt_i32_e32 vcc, 0, v2
	v_lshrrev_b32_e32 v2, 24, v82
	v_lshl_add_u32 v2, v2, 6, v0
	ds_add_u32 v2, v205 offset:16384
	v_lshrrev_b32_e32 v2, 24, v81
	v_cndmask_b32_e32 v84, v4, v7, vcc
	v_lshl_add_u32 v2, v2, 6, v0
	ds_add_u32 v2, v205 offset:16384
	v_lshrrev_b32_e32 v2, 24, v84
	v_lshl_add_u32 v2, v2, 6, v0
	ds_add_u32 v2, v205 offset:16384
	v_lshrrev_b32_e32 v2, 24, v83
	v_lshl_add_u32 v2, v2, 6, v0
	ds_add_u32 v2, v205 offset:16384
	v_add_co_u32_e32 v2, vcc, s96, v22
	s_nop 1
	v_addc_co_u32_e32 v3, vcc, 0, v23, vcc
	global_load_dwordx4 v[14:17], v[2:3], off
	global_load_dwordx4 v[10:13], v[2:3], off offset:64
	global_load_dwordx4 v[6:9], v[2:3], off offset:2048
	s_nop 0
	global_load_dwordx4 v[2:5], v[2:3], off offset:2112
	ds_read_b128 v[22:25], v182
	ds_read_b128 v[26:29], v183
	s_waitcnt vmcnt(3) lgkmcnt(1)
	v_mfma_f32_16x16x32_bf16 v[22:25], v[14:17], v[22:25], 0
	ds_read_b128 v[32:35], v185
	ds_read_b128 v[38:41], v180
	ds_read_b128 v[44:47], v159
	s_waitcnt vmcnt(2) lgkmcnt(3)
	v_mfma_f32_16x16x32_bf16 v[26:29], v[10:13], v[26:29], v[22:25]
	ds_read_b128 v[50:53], v157
	ds_read_b128 v[106:109], v155
	ds_read_b128 v[110:113], v153
	ds_read2_b32 v[24:25], v137 offset0:80 offset1:96
	s_nop 3
	v_max_f32_e32 v26, 0, v26
	v_max_f32_e32 v27, 0, v27
	v_max_f32_e32 v22, v28, v28
	v_max_f32_e32 v23, v29, v29
	ds_read_b128 v[28:31], v184
	s_waitcnt lgkmcnt(0)
	v_mfma_f32_16x16x32_bf16 v[28:31], v[14:17], v[28:31], 0
	v_max_f32_e32 v36, 0, v23
	v_max_f32_e32 v22, 0, v22
	v_mul_f32_e32 v22, v24, v22
	v_mfma_f32_16x16x32_bf16 v[28:31], v[10:13], v[32:35], v[28:31]
	s_nop 7
	v_max_f32_e32 v32, 0, v28
	v_max_f32_e32 v33, 0, v29
	v_max_f32_e32 v23, 0, v30
	v_mul_f32_e32 v28, v25, v23
	v_max_f32_e32 v37, 0, v31
	v_pk_mul_f32 v[30:31], v[24:25], v[36:37]
	ds_read_b128 v[34:37], v179
	s_waitcnt lgkmcnt(0)
	v_mfma_f32_16x16x32_bf16 v[34:37], v[14:17], v[34:37], 0
	v_mov_b32_e32 v29, v31
	v_mfma_f32_16x16x32_bf16 v[38:41], v[10:13], v[38:41], v[34:37]
	s_nop 5
	ds_read2_b32 v[36:37], v137 offset0:112 offset1:128
	s_nop 0
	v_max_f32_e32 v38, 0, v38
	v_max_f32_e32 v39, 0, v39
	v_max_f32_e32 v23, 0, v40
	s_waitcnt lgkmcnt(0)
	v_mul_f32_e32 v34, v36, v23
	v_max_f32_e32 v23, v41, v41
	ds_read_b128 v[40:43], v176
	s_waitcnt lgkmcnt(0)
	v_mfma_f32_16x16x32_bf16 v[40:43], v[14:17], v[40:43], 0
	v_max_f32_e32 v48, 0, v23
	v_mfma_f32_16x16x32_bf16 v[40:43], v[10:13], v[44:47], v[40:43]
	s_nop 7
	v_max_f32_e32 v44, 0, v40
	v_max_f32_e32 v45, 0, v41
	v_max_f32_e32 v23, 0, v42
	v_mul_f32_e32 v40, v37, v23
	v_max_f32_e32 v49, 0, v43
	v_pk_mul_f32 v[42:43], v[36:37], v[48:49]
	ds_read_b128 v[46:49], v158
	s_waitcnt lgkmcnt(0)
; #define LAS __attribute__((address_space(3)))
; __device__ __forceinline__ unsigned fkey(float f) { const unsigned u = __float_as_uint(f); return (u & 0x80000000u) ? ~u : (u | 0x80000000u); }
; #define SEL_HADD(idx_) __hip_atomic_fetch_add(&hist[(idx_)], 1u, __ATOMIC_RELAXED, __HIP_MEMORY_SCOPE_WORKGROUP)
; __device__ __forceinline__ void sel_unit(LAS char* lds, int b, int u, const bf16_t* QI, const bf16_t* KIDX, const float* WIDX, unsigned long long* MASK) {
;     ...
;     for (int j = 0; j < 8; ++j) {
;         if (j < nj) {
;             int t = wid + 8 * j; asm volatile("" : "+s"(t));
; #pragma unroll
;             for (int kh = 0; kh < 2; ++kh) {
;             bf16x8 kf[2][2];
; #pragma unroll
;             for (int kb = 0; kb < 2; ++kb)
; #pragma unroll
;                 for (int ks = 0; ks < 2; ++ks) kf[kb][ks] = *(const bf16x8*)(KIDX + (rowbase + 64 * t + 32 * kh + 16 * kb + q16) * 64 + 32 * ks + 8 * kg);
; #pragma unroll
;             for (int kb = 0; kb < 2; ++kb) {
;                 f32x4 s = (f32x4){0.f, 0.f, 0.f, 0.f};
; #pragma unroll
;                 for (int hh = 0; hh < 8; ++hh) {
;                     f32x4 a = (f32x4){0.f, 0.f, 0.f, 0.f};
; #pragma unroll
;                     for (int ks = 0; ks < 2; ++ks) {
;                         const bf16x8 qv = *(const LAS bf16x8*)(lds + L_QI + q16 * 1024 + (((hh * 8 + 4 * ks + kg) ^ q16) << 4));
;                         a = __builtin_amdgcn_mfma_f32_16x16x32_bf16(kf[kb][ks], qv, a, 0, 0, 0);
;                     }
;                     const float wh = wl[hh * 16];
; #pragma unroll
;                     for (int i = 0; i < 4; ++i) s[i] += wh * fmaxf(a[i], 0.f);
;                 }
;                 u32x4 kk; kk.x = fkey(s[0]); kk.y = fkey(s[1]); kk.z = fkey(s[2]); kk.w = fkey(s[3]);
;                 sc[j][2 * kh + kb] = kk;
; #pragma unroll
;                 for (int i = 0; i < 4; ++i) SEL_HADD((kk[i] >> 24) * 16 + q16);
;                 __builtin_amdgcn_sched_barrier(0);
	v_mfma_f32_16x16x32_bf16 v[46:49], v[14:17], v[46:49], 0
	v_mov_b32_e32 v35, v42
	v_mov_b32_e32 v41, v43
	v_mfma_f32_16x16x32_bf16 v[50:53], v[10:13], v[50:53], v[46:49]
	s_nop 4
	ds_read2_b32 v[48:49], v137 offset0:144 offset1:160
	s_nop 1
	v_max_f32_e32 v50, 0, v50
	v_max_f32_e32 v51, 0, v51
	v_max_f32_e32 v23, 0, v52
	s_waitcnt lgkmcnt(0)
	v_mul_f32_e32 v46, v48, v23
	v_max_f32_e32 v23, v53, v53
	ds_read_b128 v[52:55], v156
	s_waitcnt lgkmcnt(0)
	v_mfma_f32_16x16x32_bf16 v[52:55], v[14:17], v[52:55], 0
	v_max_f32_e32 v86, 0, v23
	v_mfma_f32_16x16x32_bf16 v[52:55], v[10:13], v[106:109], v[52:55]
	ds_read_b128 v[106:109], v154
	s_waitcnt lgkmcnt(0)
	v_mfma_f32_16x16x32_bf16 v[106:109], v[14:17], v[106:109], 0
	s_nop 4
	v_max_f32_e32 v56, 0, v52
	v_max_f32_e32 v57, 0, v53
	v_max_f32_e32 v23, 0, v54
	v_mfma_f32_16x16x32_bf16 v[106:109], v[10:13], v[110:113], v[106:109]
	v_mul_f32_e32 v52, v49, v23
	s_nop 0
	v_max_f32_e32 v87, 0, v55
	v_pk_mul_f32 v[54:55], v[48:49], v[86:87]
	ds_read2_b32 v[86:87], v137 offset0:176 offset1:192
	s_nop 2
	v_max_f32_e32 v110, 0, v106
	v_max_f32_e32 v111, 0, v107
	v_max_f32_e32 v23, 0, v108
	s_waitcnt lgkmcnt(0)
	v_mul_f32_e32 v112, v86, v23
	v_max_f32_e32 v23, v109, v109
	ds_read_b128 v[106:109], v152
	s_waitcnt lgkmcnt(0)
	v_mfma_f32_16x16x32_bf16 v[14:17], v[14:17], v[106:109], 0
	ds_read_b128 v[106:109], v151
	v_max_f32_e32 v114, 0, v23
	v_mov_b32_e32 v47, v54
	s_waitcnt lgkmcnt(0)
	v_mfma_f32_16x16x32_bf16 v[10:13], v[10:13], v[106:109], v[14:17]
	v_mov_b32_e32 v53, v55
	s_nop 1
	v_pk_fma_f32 v[16:17], v[24:25], v[26:27], 0 op_sel_hi:[0,1,0]
	v_mov_b32_e32 v24, v25
	v_pk_fma_f32 v[16:17], v[24:25], v[32:33], v[16:17] op_sel_hi:[0,1,1]
	v_pk_fma_f32 v[16:17], v[36:37], v[38:39], v[16:17] op_sel_hi:[0,1,1]
	v_mov_b32_e32 v24, v37
	v_pk_fma_f32 v[16:17], v[24:25], v[44:45], v[16:17] op_sel_hi:[0,1,1]
	v_pk_fma_f32 v[16:17], v[48:49], v[50:51], v[16:17] op_sel_hi:[0,1,1]
	v_mov_b32_e32 v24, v49
	v_pk_fma_f32 v[16:17], v[24:25], v[56:57], v[16:17] op_sel_hi:[0,1,1]
	v_max_f32_e32 v10, 0, v10
	v_max_f32_e32 v11, 0, v11
	v_pk_fma_f32 v[16:17], v[86:87], v[110:111], v[16:17] op_sel_hi:[0,1,1]
	v_mov_b32_e32 v24, v87
	v_pk_fma_f32 v[10:11], v[24:25], v[10:11], v[16:17] op_sel_hi:[0,1,1]
	v_and_b32_e32 v17, 0x7fffffff, v11
	v_and_b32_e32 v16, 0x7fffffff, v10
	v_max_f32_e32 v115, 0, v13
	v_xor_b32_e32 v23, -1, v10
	v_pk_add_f32 v[16:17], v[16:17], 0 neg_lo:[1,1] neg_hi:[1,1]
	v_cmp_gt_i32_e32 vcc, 0, v10
	v_pk_mul_f32 v[14:15], v[86:87], v[114:115]
	v_xor_b32_e32 v13, -1, v11
	v_cndmask_b32_e32 v86, v16, v23, vcc
	v_mov_b32_e32 v23, v30
	v_cmp_gt_i32_e64 s[2:3], 0, v11
	v_pk_add_f32 v[10:11], v[22:23], 0 op_sel_hi:[1,0]
	v_pk_add_f32 v[10:11], v[10:11], v[28:29]
	v_max_f32_e32 v12, 0, v12
	v_pk_add_f32 v[10:11], v[10:11], v[34:35]
	v_mov_b32_e32 v113, v14
	v_pk_add_f32 v[10:11], v[10:11], v[40:41]
	v_mul_f32_e32 v12, v87, v12
	v_pk_add_f32 v[10:11], v[10:11], v[46:47]
	v_cndmask_b32_e64 v85, v17, v13, s[2:3]
	v_pk_add_f32 v[10:11], v[10:11], v[52:53]
	v_mov_b32_e32 v13, v15
	v_pk_add_f32 v[10:11], v[10:11], v[112:113]
	s_nop 0
	v_pk_add_f32 v[10:11], v[10:11], v[12:13]
	s_nop 0
	v_xor_b32_e32 v15, -1, v10
	v_and_b32_e32 v12, 0x7fffffff, v10
	v_cmp_gt_i32_e32 vcc, 0, v10
	v_lshrrev_b32_e32 v10, 24, v86
	v_and_b32_e32 v13, 0x7fffffff, v11
	v_lshl_add_u32 v10, v10, 6, v0
	v_pk_add_f32 v[12:13], v[12:13], 0 neg_lo:[1,1] neg_hi:[1,1]
	ds_add_u32 v10, v205 offset:16384
	v_lshrrev_b32_e32 v10, 24, v85
	v_cndmask_b32_e32 v88, v12, v15, vcc
	v_lshl_add_u32 v10, v10, 6, v0
	v_xor_b32_e32 v14, -1, v11
	v_cmp_gt_i32_e64 s[2:3], 0, v11
	ds_add_u32 v10, v205 offset:16384
	v_lshrrev_b32_e32 v10, 24, v88
	v_cndmask_b32_e64 v87, v13, v14, s[2:3]
	v_lshl_add_u32 v10, v10, 6, v0
	ds_add_u32 v10, v205 offset:16384
	v_lshrrev_b32_e32 v10, 24, v87
	v_lshl_add_u32 v10, v10, 6, v0
	ds_add_u32 v10, v205 offset:16384
	ds_read_b128 v[10:13], v182
	ds_read_b128 v[14:17], v183
	ds_read_b128 v[22:25], v184
	ds_read_b128 v[26:29], v185
	ds_read2_b32 v[30:31], v137 offset0:80 offset1:96
	ds_read2_b32 v[38:39], v137 offset0:112 offset1:128
	s_waitcnt vmcnt(1) lgkmcnt(5)
	v_mfma_f32_16x16x32_bf16 v[10:13], v[6:9], v[10:13], 0
	ds_read2_b32 v[50:51], v137 offset0:144 offset1:160
	s_waitcnt vmcnt(0) lgkmcnt(5)
	v_mfma_f32_16x16x32_bf16 v[10:13], v[2:5], v[14:17], v[10:13]
	ds_read_b128 v[14:17], v179
	s_waitcnt lgkmcnt(5)
	v_mfma_f32_16x16x32_bf16 v[22:25], v[6:9], v[22:25], 0
	s_nop 4
	v_max_f32_e32 v32, 0, v10
	v_max_f32_e32 v10, 0, v12
	v_max_f32_e32 v33, 0, v11
	s_waitcnt lgkmcnt(3)
	v_mul_f32_e32 v34, v30, v10
	v_max_f32_e32 v36, 0, v13
	v_mfma_f32_16x16x32_bf16 v[10:13], v[2:5], v[26:29], v[22:25]
	s_nop 2
	ds_read_b128 v[22:25], v180
	s_waitcnt lgkmcnt(1)
	v_mfma_f32_16x16x32_bf16 v[14:17], v[6:9], v[14:17], 0
	s_nop 1
	v_max_f32_e32 v26, 0, v10
	v_max_f32_e32 v27, 0, v11
	v_max_f32_e32 v10, 0, v12
	v_mul_f32_e32 v28, v31, v10
	v_max_f32_e32 v37, 0, v13
	s_waitcnt lgkmcnt(0)
	v_mfma_f32_16x16x32_bf16 v[10:13], v[2:5], v[22:25], v[14:17]
	ds_read_b128 v[22:25], v159
	ds_read2_b32 v[94:95], v137 offset0:176 offset1:192
	v_pk_mul_f32 v[36:37], v[30:31], v[36:37]
	ds_read_b128 v[14:17], v176
	s_waitcnt lgkmcnt(0)
	v_mfma_f32_16x16x32_bf16 v[14:17], v[6:9], v[14:17], 0
	s_nop 1
	v_max_f32_e32 v40, 0, v10
	v_max_f32_e32 v41, 0, v11
	v_max_f32_e32 v10, 0, v12
	v_mul_f32_e32 v42, v38, v10
	s_nop 0
	v_max_f32_e32 v44, 0, v13
	v_mfma_f32_16x16x32_bf16 v[10:13], v[2:5], v[22:25], v[14:17]
	ds_read_b128 v[22:25], v157
	v_mov_b32_e32 v35, v36
	v_mov_b32_e32 v29, v37
	ds_read_b128 v[14:17], v158
	s_waitcnt lgkmcnt(0)
; #define LAS __attribute__((address_space(3)))
; __device__ __forceinline__ unsigned fkey(float f) { const unsigned u = __float_as_uint(f); return (u & 0x80000000u) ? ~u : (u | 0x80000000u); }
; #define SEL_HADD(idx_) __hip_atomic_fetch_add(&hist[(idx_)], 1u, __ATOMIC_RELAXED, __HIP_MEMORY_SCOPE_WORKGROUP)
; __device__ __forceinline__ void sel_unit(LAS char* lds, int b, int u, const bf16_t* QI, const bf16_t* KIDX, const float* WIDX, unsigned long long* MASK) {
;     ...
;     for (int j = 0; j < 8; ++j) {
;         if (j < nj) {
;             int t = wid + 8 * j; asm volatile("" : "+s"(t));
; #pragma unroll
;             for (int kh = 0; kh < 2; ++kh) {
;             bf16x8 kf[2][2];
; #pragma unroll
;             for (int kb = 0; kb < 2; ++kb)
; #pragma unroll
;                 for (int ks = 0; ks < 2; ++ks) kf[kb][ks] = *(const bf16x8*)(KIDX + (rowbase + 64 * t + 32 * kh + 16 * kb + q16) * 64 + 32 * ks + 8 * kg);
; #pragma unroll
;             for (int kb = 0; kb < 2; ++kb) {
;                 f32x4 s = (f32x4){0.f, 0.f, 0.f, 0.f};
; #pragma unroll
;                 for (int hh = 0; hh < 8; ++hh) {
;                     f32x4 a = (f32x4){0.f, 0.f, 0.f, 0.f};
; #pragma unroll
;                     for (int ks = 0; ks < 2; ++ks) {
;                         const bf16x8 qv = *(const LAS bf16x8*)(lds + L_QI + q16 * 1024 + (((hh * 8 + 4 * ks + kg) ^ q16) << 4));
;                         a = __builtin_amdgcn_mfma_f32_16x16x32_bf16(kf[kb][ks], qv, a, 0, 0, 0);
;                     }
;                     const float wh = wl[hh * 16];
; #pragma unroll
;                     for (int i = 0; i < 4; ++i) s[i] += wh * fmaxf(a[i], 0.f);
;                 }
;                 u32x4 kk; kk.x = fkey(s[0]); kk.y = fkey(s[1]); kk.z = fkey(s[2]); kk.w = fkey(s[3]);
;                 sc[j][2 * kh + kb] = kk;
; #pragma unroll
;                 for (int i = 0; i < 4; ++i) SEL_HADD((kk[i] >> 24) * 16 + q16);
;                 __builtin_amdgcn_sched_barrier(0);
;             }
	v_mfma_f32_16x16x32_bf16 v[14:17], v[6:9], v[14:17], 0
	s_nop 1
	v_max_f32_e32 v46, 0, v10
	v_max_f32_e32 v47, 0, v11
	v_max_f32_e32 v10, 0, v12
	v_mul_f32_e32 v48, v39, v10
	s_nop 0
	v_max_f32_e32 v45, 0, v13
	v_mfma_f32_16x16x32_bf16 v[10:13], v[2:5], v[22:25], v[14:17]
	ds_read_b128 v[22:25], v155
	v_pk_mul_f32 v[44:45], v[38:39], v[44:45]
	s_nop 0
	ds_read_b128 v[14:17], v156
	s_waitcnt lgkmcnt(0)
	v_mfma_f32_16x16x32_bf16 v[14:17], v[6:9], v[14:17], 0
	s_nop 1
	v_max_f32_e32 v52, 0, v10
	v_max_f32_e32 v53, 0, v11
	v_max_f32_e32 v10, 0, v12
	v_mul_f32_e32 v54, v50, v10
	s_nop 0
	v_max_f32_e32 v56, 0, v13
	v_mfma_f32_16x16x32_bf16 v[10:13], v[2:5], v[22:25], v[14:17]
	ds_read_b128 v[22:25], v153
	v_mov_b32_e32 v43, v44
	v_mov_b32_e32 v49, v45
	ds_read_b128 v[14:17], v154
	s_waitcnt lgkmcnt(0)
	v_mfma_f32_16x16x32_bf16 v[14:17], v[6:9], v[14:17], 0
	s_nop 1
	v_max_f32_e32 v90, 0, v10
	v_max_f32_e32 v91, 0, v11
	v_max_f32_e32 v10, 0, v12
	v_mul_f32_e32 v92, v51, v10
	s_nop 0
	v_max_f32_e32 v57, 0, v13
	v_mfma_f32_16x16x32_bf16 v[10:13], v[2:5], v[22:25], v[14:17]
	ds_read_b128 v[22:25], v151
	v_pk_mul_f32 v[56:57], v[50:51], v[56:57]
	s_nop 0
	ds_read_b128 v[14:17], v152
	s_waitcnt lgkmcnt(0)
	v_mfma_f32_16x16x32_bf16 v[6:9], v[6:9], v[14:17], 0
	s_nop 1
	s_nop 0
	v_max_f32_e32 v14, 0, v13
	s_nop 0
	v_mfma_f32_16x16x32_bf16 v[2:5], v[2:5], v[22:25], v[6:9]
	s_nop 0
	v_max_f32_e32 v10, 0, v10
	v_max_f32_e32 v11, 0, v11
	v_pk_fma_f32 v[8:9], v[30:31], v[32:33], 0 op_sel_hi:[0,1,0]
	s_nop 0
	s_nop 2
	v_max_f32_e32 v15, 0, v5
	v_pk_mul_f32 v[6:7], v[94:95], v[14:15]
	v_mov_b32_e32 v14, v31
	v_pk_fma_f32 v[8:9], v[14:15], v[26:27], v[8:9] op_sel_hi:[0,1,1]
	v_pk_fma_f32 v[8:9], v[38:39], v[40:41], v[8:9] op_sel_hi:[0,1,1]
	v_mov_b32_e32 v14, v39
	v_pk_fma_f32 v[8:9], v[14:15], v[46:47], v[8:9] op_sel_hi:[0,1,1]
	v_pk_fma_f32 v[8:9], v[50:51], v[52:53], v[8:9] op_sel_hi:[0,1,1]
	v_mov_b32_e32 v14, v51
	v_pk_fma_f32 v[8:9], v[14:15], v[90:91], v[8:9] op_sel_hi:[0,1,1]
	v_max_f32_e32 v2, 0, v2
	v_max_f32_e32 v3, 0, v3
	v_pk_fma_f32 v[8:9], v[94:95], v[10:11], v[8:9] op_sel_hi:[0,1,1]
	v_mov_b32_e32 v10, v95
	v_pk_fma_f32 v[2:3], v[10:11], v[2:3], v[8:9] op_sel_hi:[0,1,1]
	v_and_b32_e32 v9, 0x7fffffff, v3
	v_and_b32_e32 v8, 0x7fffffff, v2
	v_xor_b32_e32 v5, -1, v3
	v_pk_add_f32 v[8:9], v[8:9], 0 neg_lo:[1,1] neg_hi:[1,1]
	v_cmp_gt_i32_e32 vcc, 0, v3
	v_xor_b32_e32 v10, -1, v2
	v_mov_b32_e32 v55, v56
	v_cndmask_b32_e32 v89, v9, v5, vcc
	v_cmp_gt_i32_e32 vcc, 0, v2
	v_pk_add_f32 v[2:3], v[34:35], 0 op_sel_hi:[1,0]
	v_max_f32_e32 v12, 0, v12
	v_pk_add_f32 v[2:3], v[2:3], v[28:29]
	v_pk_add_f32 v[2:3], v[2:3], v[42:43]
	v_mov_b32_e32 v93, v57
	v_pk_add_f32 v[2:3], v[2:3], v[48:49]
	v_mul_f32_e32 v12, v94, v12
	v_pk_add_f32 v[2:3], v[2:3], v[54:55]
	v_max_f32_e32 v4, 0, v4
	v_pk_add_f32 v[2:3], v[2:3], v[92:93]
	v_mov_b32_e32 v13, v6
	v_mul_f32_e32 v4, v95, v4
	v_pk_add_f32 v[2:3], v[2:3], v[12:13]
	v_mov_b32_e32 v5, v7
	v_pk_add_f32 v[2:3], v[2:3], v[4:5]
	v_cndmask_b32_e32 v90, v8, v10, vcc
	v_and_b32_e32 v5, 0x7fffffff, v3
	v_and_b32_e32 v4, 0x7fffffff, v2
	v_xor_b32_e32 v6, -1, v3
	v_pk_add_f32 v[4:5], v[4:5], 0 neg_lo:[1,1] neg_hi:[1,1]
	v_cmp_gt_i32_e32 vcc, 0, v3
	v_xor_b32_e32 v7, -1, v2
	s_nop 0
	v_cndmask_b32_e32 v91, v5, v6, vcc
	v_cmp_gt_i32_e32 vcc, 0, v2
	v_lshrrev_b32_e32 v2, 24, v90
	v_lshl_add_u32 v2, v2, 6, v0
	ds_add_u32 v2, v205 offset:16384
	v_lshrrev_b32_e32 v2, 24, v89
	v_cndmask_b32_e32 v92, v4, v7, vcc
	v_lshl_add_u32 v2, v2, 6, v0
	ds_add_u32 v2, v205 offset:16384
	v_lshrrev_b32_e32 v2, 24, v92
	v_lshl_add_u32 v2, v2, 6, v0
	ds_add_u32 v2, v205 offset:16384
	v_lshrrev_b32_e32 v2, 24, v91
	v_lshl_add_u32 v2, v2, 6, v0
	ds_add_u32 v2, v205 offset:16384
.LBB0_660:
	s_cmp_gt_i32 s4, 2
	s_cselect_b64 s[54:55], -1, 0
	s_cmp_lt_i32 s4, 3
	s_cbranch_scc1 .LBB0_662
	s_add_i32 s0, s46, 16
	s_lshl_b32 s0, s0, 6
	s_ashr_i32 s1, s0, 31
	v_lshl_add_u64 v[2:3], v[18:19], 0, s[0:1]
	v_lshlrev_b64 v[2:3], 7, v[2:3]
	v_lshl_add_u64 v[22:23], v[20:21], 0, v[2:3]
	global_load_dwordx4 v[14:17], v[22:23], off
	global_load_dwordx4 v[10:13], v[22:23], off offset:64
	ds_read_b128 v[2:5], v182
	ds_read_b128 v[6:9], v183
	ds_read_b128 v[24:27], v184
	ds_read_b128 v[28:31], v185
	ds_read_b128 v[32:35], v179
	ds_read_b128 v[36:39], v180
	ds_read_b128 v[40:43], v176
	ds_read_b128 v[44:47], v159
	ds_read_b128 v[48:51], v158
	ds_read_b128 v[52:55], v157
	ds_read_b128 v[94:97], v156
	ds_read_b128 v[98:101], v155
	s_waitcnt vmcnt(1) lgkmcnt(11)
	v_mfma_f32_16x16x32_bf16 v[2:5], v[14:17], v[2:5], 0
	s_waitcnt lgkmcnt(9)
	v_mfma_f32_16x16x32_bf16 v[24:27], v[14:17], v[24:27], 0
	s_waitcnt lgkmcnt(7)
	v_mfma_f32_16x16x32_bf16 v[32:35], v[14:17], v[32:35], 0
	s_waitcnt lgkmcnt(5)
	v_mfma_f32_16x16x32_bf16 v[40:43], v[14:17], v[40:43], 0
	s_waitcnt lgkmcnt(3)
	v_mfma_f32_16x16x32_bf16 v[48:51], v[14:17], v[48:51], 0
	s_waitcnt vmcnt(0)
	v_mfma_f32_16x16x32_bf16 v[118:121], v[10:13], v[6:9], v[2:5]
	v_mfma_f32_16x16x32_bf16 v[24:27], v[10:13], v[28:31], v[24:27]
	v_mfma_f32_16x16x32_bf16 v[28:31], v[10:13], v[36:39], v[32:35]
	v_mfma_f32_16x16x32_bf16 v[32:35], v[10:13], v[44:47], v[40:43]
	ds_read2_b32 v[44:45], v137 offset0:80 offset1:96
	ds_read2_b32 v[46:47], v137 offset0:112 offset1:128
	s_nop 3
	s_waitcnt lgkmcnt(4)
	v_mfma_f32_16x16x32_bf16 v[36:39], v[10:13], v[52:55], v[48:51]
	s_nop 0
	ds_read2_b32 v[48:49], v137 offset0:144 offset1:160
	global_load_dwordx4 v[6:9], v[22:23], off offset:2048
	global_load_dwordx4 v[2:5], v[22:23], off offset:2112
	s_waitcnt lgkmcnt(4)
	v_mfma_f32_16x16x32_bf16 v[94:97], v[14:17], v[94:97], 0
	s_nop 0
	v_max_f32_e32 v54, v24, v24
	s_nop 0
	s_waitcnt lgkmcnt(3)
; #define LAS __attribute__((address_space(3)))
; __device__ __forceinline__ unsigned fkey(float f) { const unsigned u = __float_as_uint(f); return (u & 0x80000000u) ? ~u : (u | 0x80000000u); }
; #define SEL_HADD(idx_) __hip_atomic_fetch_add(&hist[(idx_)], 1u, __ATOMIC_RELAXED, __HIP_MEMORY_SCOPE_WORKGROUP)
; __device__ __forceinline__ void sel_unit(LAS char* lds, int b, int u, const bf16_t* QI, const bf16_t* KIDX, const float* WIDX, unsigned long long* MASK) {
;     ...
;                 for (int ks = 0; ks < 2; ++ks) kf[kb][ks] = *(const bf16x8*)(KIDX + (rowbase + 64 * t + 32 * kh + 16 * kb + q16) * 64 + 32 * ks + 8 * kg);
; #pragma unroll
;             for (int kb = 0; kb < 2; ++kb) {
;                 f32x4 s = (f32x4){0.f, 0.f, 0.f, 0.f};
; #pragma unroll
;                 for (int hh = 0; hh < 8; ++hh) {
;                     f32x4 a = (f32x4){0.f, 0.f, 0.f, 0.f};
; #pragma unroll
;                     for (int ks = 0; ks < 2; ++ks) {
;                         const bf16x8 qv = *(const LAS bf16x8*)(lds + L_QI + q16 * 1024 + (((hh * 8 + 4 * ks + kg) ^ q16) << 4));
;                         a = __builtin_amdgcn_mfma_f32_16x16x32_bf16(kf[kb][ks], qv, a, 0, 0, 0);
;                     }
;                     const float wh = wl[hh * 16];
; #pragma unroll
;                     for (int i = 0; i < 4; ++i) s[i] += wh * fmaxf(a[i], 0.f);
;                 }
;                 u32x4 kk; kk.x = fkey(s[0]); kk.y = fkey(s[1]); kk.z = fkey(s[2]); kk.w = fkey(s[3]);
;                 sc[j][2 * kh + kb] = kk;
; #pragma unroll
;                 for (int i = 0; i < 4; ++i) SEL_HADD((kk[i] >> 24) * 16 + q16);
	v_mfma_f32_16x16x32_bf16 v[40:43], v[10:13], v[98:101], v[94:97]
	v_max_f32_e32 v93, v39, v39
	v_max_f32_e32 v24, 0, v121
	v_max_f32_e32 v39, 0, v25
	v_max_f32_e32 v96, 0, v26
	v_max_f32_e32 v25, 0, v27
	v_max_f32_e32 v26, 0, v31
	v_max_f32_e32 v27, 0, v35
	v_max_f32_e32 v53, 0, v37
	s_waitcnt lgkmcnt(2)
	v_mul_f32_e32 v56, v45, v96
	v_pk_mul_f32 v[96:97], v[44:45], v[24:25]
	s_waitcnt lgkmcnt(1)
	v_pk_mul_f32 v[102:103], v[46:47], v[26:27]
	ds_read_b128 v[24:27], v154
	v_max_f32_e32 v94, v40, v40
	v_max_f32_e32 v40, 0, v28
	v_max_f32_e32 v28, 0, v30
	v_max_f32_e32 v50, v118, v118
	v_max_f32_e32 v95, v41, v41
	v_max_f32_e32 v41, 0, v29
	v_max_f32_e32 v29, 0, v34
	v_max_f32_e32 v30, 0, v38
	v_mul_f32_e32 v98, v46, v28
	v_max_f32_e32 v28, 0, v42
	v_mul_f32_e32 v100, v47, v29
	s_waitcnt lgkmcnt(1)
	v_mul_f32_e32 v122, v48, v30
	v_mul_f32_e32 v124, v49, v28
	ds_read_b128 v[28:31], v153
	s_waitcnt lgkmcnt(1)
	v_mfma_f32_16x16x32_bf16 v[24:27], v[14:17], v[24:27], 0
	v_max_f32_e32 v51, v119, v119
	s_waitcnt lgkmcnt(0)
	v_mfma_f32_16x16x32_bf16 v[24:27], v[10:13], v[28:31], v[24:27]
	ds_read_b128 v[28:31], v152
	v_max_f32_e32 v37, 0, v51
	v_max_f32_e32 v51, 0, v33
	v_max_f32_e32 v52, v120, v120
	v_max_f32_e32 v55, v36, v36
	v_max_f32_e32 v36, 0, v50
	v_max_f32_e32 v50, 0, v32
	v_max_f32_e32 v32, 0, v93
	v_max_f32_e32 v33, 0, v43
	v_pk_mul_f32 v[126:127], v[48:49], v[32:33]
	ds_read_b128 v[32:35], v151
	s_waitcnt lgkmcnt(1)
	v_mfma_f32_16x16x32_bf16 v[14:17], v[14:17], v[28:31], 0
	v_max_f32_e32 v42, 0, v52
	v_max_f32_e32 v38, 0, v54
	v_max_f32_e32 v52, 0, v55
	s_waitcnt lgkmcnt(0)
	v_mfma_f32_16x16x32_bf16 v[10:13], v[10:13], v[32:35], v[14:17]
	v_max_f32_e32 v54, 0, v94
	v_max_f32_e32 v55, 0, v95
	ds_read2_b32 v[94:95], v137 offset0:176 offset1:192
	s_nop 0
	v_max_f32_e32 v28, 0, v27
	s_nop 2
	v_max_f32_e32 v29, 0, v13
	s_waitcnt lgkmcnt(0)
	v_pk_mul_f32 v[14:15], v[94:95], v[28:29]
	v_pk_fma_f32 v[16:17], v[44:45], v[36:37], 0 op_sel_hi:[0,1,0]
	v_mov_b32_e32 v28, v45
	v_pk_fma_f32 v[16:17], v[28:29], v[38:39], v[16:17] op_sel_hi:[0,1,1]
	v_pk_fma_f32 v[16:17], v[46:47], v[40:41], v[16:17] op_sel_hi:[0,1,1]
	v_mov_b32_e32 v28, v47
	v_pk_fma_f32 v[16:17], v[28:29], v[50:51], v[16:17] op_sel_hi:[0,1,1]
	v_pk_fma_f32 v[16:17], v[48:49], v[52:53], v[16:17] op_sel_hi:[0,1,1]
	v_mov_b32_e32 v28, v49
	v_max_f32_e32 v24, 0, v24
	v_max_f32_e32 v25, 0, v25
	v_pk_fma_f32 v[16:17], v[28:29], v[54:55], v[16:17] op_sel_hi:[0,1,1]
	v_max_f32_e32 v10, 0, v10
	v_max_f32_e32 v11, 0, v11
	v_pk_fma_f32 v[16:17], v[94:95], v[24:25], v[16:17] op_sel_hi:[0,1,1]
	v_mov_b32_e32 v24, v95
	v_pk_fma_f32 v[10:11], v[24:25], v[10:11], v[16:17] op_sel_hi:[0,1,1]
	v_and_b32_e32 v17, 0x7fffffff, v11
	v_and_b32_e32 v16, 0x7fffffff, v10
	v_mul_f32_e32 v42, v44, v42
	v_xor_b32_e32 v13, -1, v11
	v_pk_add_f32 v[16:17], v[16:17], 0 neg_lo:[1,1] neg_hi:[1,1]
	v_cmp_gt_i32_e32 vcc, 0, v11
	v_mov_b32_e32 v43, v96
	v_xor_b32_e32 v24, -1, v10
	v_cndmask_b32_e32 v93, v17, v13, vcc
	v_cmp_gt_i32_e32 vcc, 0, v10
	v_pk_add_f32 v[10:11], v[42:43], 0 op_sel_hi:[1,0]
	v_mov_b32_e32 v57, v97
	v_pk_add_f32 v[10:11], v[10:11], v[56:57]
	v_mov_b32_e32 v99, v102
	v_pk_add_f32 v[10:11], v[10:11], v[98:99]
	v_mov_b32_e32 v101, v103
	v_pk_add_f32 v[10:11], v[10:11], v[100:101]
	v_mov_b32_e32 v123, v126
	v_max_f32_e32 v26, 0, v26
	v_pk_add_f32 v[10:11], v[10:11], v[122:123]
	v_mov_b32_e32 v125, v127
	v_mul_f32_e32 v26, v94, v26
	v_max_f32_e32 v12, 0, v12
	v_pk_add_f32 v[10:11], v[10:11], v[124:125]
	v_mov_b32_e32 v27, v14
	v_mul_f32_e32 v12, v95, v12
	v_pk_add_f32 v[10:11], v[10:11], v[26:27]
	v_mov_b32_e32 v13, v15
	v_pk_add_f32 v[10:11], v[10:11], v[12:13]
	v_cndmask_b32_e32 v94, v16, v24, vcc
	v_and_b32_e32 v13, 0x7fffffff, v11
	v_and_b32_e32 v12, 0x7fffffff, v10
	v_xor_b32_e32 v14, -1, v11
	v_pk_add_f32 v[12:13], v[12:13], 0 neg_lo:[1,1] neg_hi:[1,1]
	v_cmp_gt_i32_e32 vcc, 0, v11
	v_xor_b32_e32 v15, -1, v10
	s_nop 0
	v_cndmask_b32_e32 v95, v13, v14, vcc
	v_cmp_gt_i32_e32 vcc, 0, v10
	v_lshrrev_b32_e32 v10, 24, v94
	v_lshl_add_u32 v10, v10, 6, v0
	ds_add_u32 v10, v205 offset:16384
	v_lshrrev_b32_e32 v10, 24, v93
	v_cndmask_b32_e32 v96, v12, v15, vcc
	v_lshl_add_u32 v10, v10, 6, v0
	ds_add_u32 v10, v205 offset:16384
	v_lshrrev_b32_e32 v10, 24, v96
	v_lshl_add_u32 v10, v10, 6, v0
	ds_add_u32 v10, v205 offset:16384
	v_lshrrev_b32_e32 v10, 24, v95
	v_lshl_add_u32 v10, v10, 6, v0
	ds_add_u32 v10, v205 offset:16384
	ds_read_b128 v[10:13], v182
	ds_read_b128 v[14:17], v183
	ds_read_b128 v[24:27], v184
	ds_read_b128 v[28:31], v185
	ds_read2_b32 v[50:51], v137 offset0:144 offset1:160
	s_waitcnt vmcnt(1) lgkmcnt(4)
	v_mfma_f32_16x16x32_bf16 v[10:13], v[6:9], v[10:13], 0
	ds_read_b128 v[38:41], v159
	ds_read_b128 v[44:47], v157
	s_waitcnt lgkmcnt(4)
	v_mfma_f32_16x16x32_bf16 v[24:27], v[6:9], v[24:27], 0
	s_waitcnt vmcnt(0)
	v_mfma_f32_16x16x32_bf16 v[14:17], v[2:5], v[14:17], v[10:13]
	s_waitcnt lgkmcnt(3)
	v_mfma_f32_16x16x32_bf16 v[26:29], v[2:5], v[28:31], v[24:27]
	s_nop 0
	ds_read2_b32 v[12:13], v137 offset0:80 offset1:96
	s_nop 3
	v_max_f32_e32 v32, 0, v17
	v_max_f32_e32 v14, 0, v14
	v_max_f32_e32 v26, 0, v26
	v_max_f32_e32 v27, 0, v27
	v_max_f32_e32 v11, 0, v28
	v_max_f32_e32 v15, 0, v15
	v_max_f32_e32 v10, v16, v16
	s_waitcnt lgkmcnt(0)
	v_mul_f32_e32 v16, v13, v11
	v_max_f32_e32 v11, v29, v29
	ds_read_b128 v[28:31], v179
	v_max_f32_e32 v33, 0, v11
	v_pk_mul_f32 v[24:25], v[12:13], v[32:33]
	ds_read_b128 v[32:35], v180
	s_waitcnt lgkmcnt(1)
	v_mfma_f32_16x16x32_bf16 v[28:31], v[6:9], v[28:31], 0
	v_max_f32_e32 v10, 0, v10
	v_mul_f32_e32 v10, v12, v10
	v_mov_b32_e32 v17, v25
	s_waitcnt lgkmcnt(0)
; #define LAS __attribute__((address_space(3)))
; __device__ __forceinline__ unsigned fkey(float f) { const unsigned u = __float_as_uint(f); return (u & 0x80000000u) ? ~u : (u | 0x80000000u); }
; #define SEL_HADD(idx_) __hip_atomic_fetch_add(&hist[(idx_)], 1u, __ATOMIC_RELAXED, __HIP_MEMORY_SCOPE_WORKGROUP)
; __device__ __forceinline__ void sel_unit(LAS char* lds, int b, int u, const bf16_t* QI, const bf16_t* KIDX, const float* WIDX, unsigned long long* MASK) {
;     ...
;                 for (int ks = 0; ks < 2; ++ks) kf[kb][ks] = *(const bf16x8*)(KIDX + (rowbase + 64 * t + 32 * kh + 16 * kb + q16) * 64 + 32 * ks + 8 * kg);
; #pragma unroll
;             for (int kb = 0; kb < 2; ++kb) {
;                 f32x4 s = (f32x4){0.f, 0.f, 0.f, 0.f};
; #pragma unroll
;                 for (int hh = 0; hh < 8; ++hh) {
;                     f32x4 a = (f32x4){0.f, 0.f, 0.f, 0.f};
; #pragma unroll
;                     for (int ks = 0; ks < 2; ++ks) {
;                         const bf16x8 qv = *(const LAS bf16x8*)(lds + L_QI + q16 * 1024 + (((hh * 8 + 4 * ks + kg) ^ q16) << 4));
;                         a = __builtin_amdgcn_mfma_f32_16x16x32_bf16(kf[kb][ks], qv, a, 0, 0, 0);
;                     }
;                     const float wh = wl[hh * 16];
; #pragma unroll
;                     for (int i = 0; i < 4; ++i) s[i] += wh * fmaxf(a[i], 0.f);
;                 }
;                 u32x4 kk; kk.x = fkey(s[0]); kk.y = fkey(s[1]); kk.z = fkey(s[2]); kk.w = fkey(s[3]);
;                 sc[j][2 * kh + kb] = kk;
; #pragma unroll
;                 for (int i = 0; i < 4; ++i) SEL_HADD((kk[i] >> 24) * 16 + q16);
	v_mfma_f32_16x16x32_bf16 v[32:35], v[2:5], v[32:35], v[28:31]
	s_nop 2
	ds_read2_b32 v[30:31], v137 offset0:112 offset1:128
	s_nop 3
	v_max_f32_e32 v32, 0, v32
	v_max_f32_e32 v33, 0, v33
	v_max_f32_e32 v11, 0, v34
	s_waitcnt lgkmcnt(0)
	v_mul_f32_e32 v28, v30, v11
	v_max_f32_e32 v11, v35, v35
	ds_read_b128 v[34:37], v176
	s_waitcnt lgkmcnt(0)
	v_mfma_f32_16x16x32_bf16 v[34:37], v[6:9], v[34:37], 0
	v_max_f32_e32 v42, 0, v11
	v_mfma_f32_16x16x32_bf16 v[34:37], v[2:5], v[38:41], v[34:37]
	s_nop 7
	v_max_f32_e32 v38, 0, v34
	v_max_f32_e32 v39, 0, v35
	v_max_f32_e32 v11, 0, v36
	v_mul_f32_e32 v34, v31, v11
	v_max_f32_e32 v43, 0, v37
	v_pk_mul_f32 v[36:37], v[30:31], v[42:43]
	ds_read_b128 v[40:43], v158
	s_waitcnt lgkmcnt(0)
	v_mfma_f32_16x16x32_bf16 v[40:43], v[6:9], v[40:43], 0
	v_mov_b32_e32 v29, v36
	v_mov_b32_e32 v35, v37
	v_mfma_f32_16x16x32_bf16 v[40:43], v[2:5], v[44:47], v[40:43]
	ds_read_b128 v[46:49], v155
	s_nop 6
	v_max_f32_e32 v52, 0, v40
	v_max_f32_e32 v53, 0, v41
	v_max_f32_e32 v11, 0, v42
	v_mul_f32_e32 v40, v50, v11
	v_max_f32_e32 v11, v43, v43
	ds_read_b128 v[42:45], v156
	s_waitcnt lgkmcnt(0)
	v_mfma_f32_16x16x32_bf16 v[42:45], v[6:9], v[42:45], 0
	v_max_f32_e32 v54, 0, v11
	v_mfma_f32_16x16x32_bf16 v[42:45], v[2:5], v[46:49], v[42:45]
	ds_read_b128 v[46:49], v153
	s_nop 6
	v_max_f32_e32 v56, 0, v42
	v_max_f32_e32 v57, 0, v43
	v_max_f32_e32 v11, 0, v44
	v_mul_f32_e32 v100, v51, v11
	v_max_f32_e32 v11, v45, v45
	ds_read_b128 v[42:45], v154
	s_waitcnt lgkmcnt(0)
	v_mfma_f32_16x16x32_bf16 v[42:45], v[6:9], v[42:45], 0
	v_max_f32_e32 v55, 0, v11
	v_pk_mul_f32 v[54:55], v[50:51], v[54:55]
	v_mfma_f32_16x16x32_bf16 v[42:45], v[2:5], v[46:49], v[42:45]
	ds_read2_b32 v[46:47], v137 offset0:176 offset1:192
	v_mov_b32_e32 v41, v54
	v_mov_b32_e32 v101, v55
	s_nop 4
	v_max_f32_e32 v48, 0, v42
	v_max_f32_e32 v49, 0, v43
	v_max_f32_e32 v11, 0, v44
	s_waitcnt lgkmcnt(0)
	v_mul_f32_e32 v102, v46, v11
	v_max_f32_e32 v11, v45, v45
	ds_read_b128 v[42:45], v152
	s_waitcnt lgkmcnt(0)
	v_mfma_f32_16x16x32_bf16 v[6:9], v[6:9], v[42:45], 0
	ds_read_b128 v[42:45], v151
	v_max_f32_e32 v98, 0, v11
	s_waitcnt lgkmcnt(0)
	v_mfma_f32_16x16x32_bf16 v[2:5], v[2:5], v[42:45], v[6:9]
	s_nop 3
	v_fma_f32 v8, v12, v14, 0
	v_fma_f32 v9, v12, v15, 0
	v_mov_b32_e32 v12, v13
	v_pk_fma_f32 v[8:9], v[12:13], v[26:27], v[8:9] op_sel_hi:[0,1,1]
	v_pk_fma_f32 v[8:9], v[30:31], v[32:33], v[8:9] op_sel_hi:[0,1,1]
	v_mov_b32_e32 v12, v31
	v_pk_fma_f32 v[8:9], v[12:13], v[38:39], v[8:9] op_sel_hi:[0,1,1]
	v_pk_fma_f32 v[8:9], v[50:51], v[52:53], v[8:9] op_sel_hi:[0,1,1]
	v_mov_b32_e32 v12, v51
	v_pk_fma_f32 v[8:9], v[12:13], v[56:57], v[8:9] op_sel_hi:[0,1,1]
	v_max_f32_e32 v2, 0, v2
	v_max_f32_e32 v3, 0, v3
	v_pk_fma_f32 v[8:9], v[46:47], v[48:49], v[8:9] op_sel_hi:[0,1,1]
	v_mov_b32_e32 v12, v47
	v_pk_fma_f32 v[2:3], v[12:13], v[2:3], v[8:9] op_sel_hi:[0,1,1]
	v_and_b32_e32 v9, 0x7fffffff, v3
	v_and_b32_e32 v8, 0x7fffffff, v2
	v_max_f32_e32 v99, 0, v5
	v_xor_b32_e32 v11, -1, v2
	v_pk_add_f32 v[8:9], v[8:9], 0 neg_lo:[1,1] neg_hi:[1,1]
	v_cmp_gt_i32_e32 vcc, 0, v2
	v_pk_mul_f32 v[6:7], v[46:47], v[98:99]
	v_xor_b32_e32 v5, -1, v3
	v_cndmask_b32_e32 v98, v8, v11, vcc
	v_mov_b32_e32 v11, v24
	v_cmp_gt_i32_e64 s[2:3], 0, v3
	v_pk_add_f32 v[2:3], v[10:11], 0 op_sel_hi:[1,0]
	v_pk_add_f32 v[2:3], v[2:3], v[16:17]
	v_max_f32_e32 v4, 0, v4
	v_pk_add_f32 v[2:3], v[2:3], v[28:29]
	v_mov_b32_e32 v103, v6
	v_pk_add_f32 v[2:3], v[2:3], v[34:35]
	v_mul_f32_e32 v4, v47, v4
	v_pk_add_f32 v[2:3], v[2:3], v[40:41]
	v_cndmask_b32_e64 v97, v9, v5, s[2:3]
	v_pk_add_f32 v[2:3], v[2:3], v[100:101]
	v_mov_b32_e32 v5, v7
	v_pk_add_f32 v[2:3], v[2:3], v[102:103]
	s_nop 0
	v_pk_add_f32 v[2:3], v[2:3], v[4:5]
	s_nop 0
	v_xor_b32_e32 v7, -1, v2
	v_and_b32_e32 v4, 0x7fffffff, v2
	v_cmp_gt_i32_e32 vcc, 0, v2
	v_lshrrev_b32_e32 v2, 24, v98
	v_and_b32_e32 v5, 0x7fffffff, v3
	v_lshl_add_u32 v2, v2, 6, v0
	v_pk_add_f32 v[4:5], v[4:5], 0 neg_lo:[1,1] neg_hi:[1,1]
	ds_add_u32 v2, v205 offset:16384
	v_lshrrev_b32_e32 v2, 24, v97
	v_cndmask_b32_e32 v100, v4, v7, vcc
	v_lshl_add_u32 v2, v2, 6, v0
	v_xor_b32_e32 v6, -1, v3
	v_cmp_gt_i32_e64 s[2:3], 0, v3
	ds_add_u32 v2, v205 offset:16384
	v_lshrrev_b32_e32 v2, 24, v100
	v_cndmask_b32_e64 v99, v5, v6, s[2:3]
	v_lshl_add_u32 v2, v2, 6, v0
	ds_add_u32 v2, v205 offset:16384
	v_lshrrev_b32_e32 v2, 24, v99
	v_lshl_add_u32 v2, v2, 6, v0
	ds_add_u32 v2, v205 offset:16384
	v_add_co_u32_e32 v2, vcc, s96, v22
	s_nop 1
	v_addc_co_u32_e32 v3, vcc, 0, v23, vcc
	global_load_dwordx4 v[14:17], v[2:3], off
	global_load_dwordx4 v[10:13], v[2:3], off offset:64
	global_load_dwordx4 v[6:9], v[2:3], off offset:2048
	s_nop 0
	global_load_dwordx4 v[2:5], v[2:3], off offset:2112
	ds_read_b128 v[22:25], v182
	ds_read_b128 v[26:29], v183
	s_waitcnt vmcnt(3) lgkmcnt(1)
	v_mfma_f32_16x16x32_bf16 v[22:25], v[14:17], v[22:25], 0
	ds_read_b128 v[32:35], v185
	ds_read_b128 v[38:41], v180
	ds_read_b128 v[44:47], v159
	s_waitcnt vmcnt(2) lgkmcnt(3)
	v_mfma_f32_16x16x32_bf16 v[26:29], v[10:13], v[26:29], v[22:25]
	ds_read_b128 v[50:53], v157
	ds_read_b128 v[122:125], v155
	ds_read_b128 v[126:129], v153
	ds_read2_b32 v[24:25], v137 offset0:80 offset1:96
	s_nop 3
	v_max_f32_e32 v26, 0, v26
	v_max_f32_e32 v27, 0, v27
	v_max_f32_e32 v22, v28, v28
	v_max_f32_e32 v23, v29, v29
	ds_read_b128 v[28:31], v184
	s_waitcnt lgkmcnt(0)
	v_mfma_f32_16x16x32_bf16 v[28:31], v[14:17], v[28:31], 0
	v_max_f32_e32 v36, 0, v23
	v_max_f32_e32 v22, 0, v22
	v_mul_f32_e32 v22, v24, v22
	v_mfma_f32_16x16x32_bf16 v[28:31], v[10:13], v[32:35], v[28:31]
	s_nop 7
	v_max_f32_e32 v32, 0, v28
	v_max_f32_e32 v33, 0, v29
	v_max_f32_e32 v23, 0, v30
	v_mul_f32_e32 v28, v25, v23
	v_max_f32_e32 v37, 0, v31
	v_pk_mul_f32 v[30:31], v[24:25], v[36:37]
	ds_read_b128 v[34:37], v179
	s_waitcnt lgkmcnt(0)
; #define LAS __attribute__((address_space(3)))
; __device__ __forceinline__ unsigned fkey(float f) { const unsigned u = __float_as_uint(f); return (u & 0x80000000u) ? ~u : (u | 0x80000000u); }
; #define SEL_HADD(idx_) __hip_atomic_fetch_add(&hist[(idx_)], 1u, __ATOMIC_RELAXED, __HIP_MEMORY_SCOPE_WORKGROUP)
; __device__ __forceinline__ void sel_unit(LAS char* lds, int b, int u, const bf16_t* QI, const bf16_t* KIDX, const float* WIDX, unsigned long long* MASK) {
;     ...
;                 for (int ks = 0; ks < 2; ++ks) kf[kb][ks] = *(const bf16x8*)(KIDX + (rowbase + 64 * t + 32 * kh + 16 * kb + q16) * 64 + 32 * ks + 8 * kg);
; #pragma unroll
;             for (int kb = 0; kb < 2; ++kb) {
;                 f32x4 s = (f32x4){0.f, 0.f, 0.f, 0.f};
; #pragma unroll
;                 for (int hh = 0; hh < 8; ++hh) {
;                     f32x4 a = (f32x4){0.f, 0.f, 0.f, 0.f};
; #pragma unroll
;                     for (int ks = 0; ks < 2; ++ks) {
;                         const bf16x8 qv = *(const LAS bf16x8*)(lds + L_QI + q16 * 1024 + (((hh * 8 + 4 * ks + kg) ^ q16) << 4));
;                         a = __builtin_amdgcn_mfma_f32_16x16x32_bf16(kf[kb][ks], qv, a, 0, 0, 0);
;                     }
;                     const float wh = wl[hh * 16];
; #pragma unroll
;                     for (int i = 0; i < 4; ++i) s[i] += wh * fmaxf(a[i], 0.f);
;                 }
;                 u32x4 kk; kk.x = fkey(s[0]); kk.y = fkey(s[1]); kk.z = fkey(s[2]); kk.w = fkey(s[3]);
;                 sc[j][2 * kh + kb] = kk;
; #pragma unroll
;                 for (int i = 0; i < 4; ++i) SEL_HADD((kk[i] >> 24) * 16 + q16);
	v_mfma_f32_16x16x32_bf16 v[34:37], v[14:17], v[34:37], 0
	v_mov_b32_e32 v29, v31
	v_mfma_f32_16x16x32_bf16 v[38:41], v[10:13], v[38:41], v[34:37]
	s_nop 5
	ds_read2_b32 v[36:37], v137 offset0:112 offset1:128
	s_nop 0
	v_max_f32_e32 v38, 0, v38
	v_max_f32_e32 v39, 0, v39
	v_max_f32_e32 v23, 0, v40
	s_waitcnt lgkmcnt(0)
	v_mul_f32_e32 v34, v36, v23
	v_max_f32_e32 v23, v41, v41
	ds_read_b128 v[40:43], v176
	s_waitcnt lgkmcnt(0)
	v_mfma_f32_16x16x32_bf16 v[40:43], v[14:17], v[40:43], 0
	v_max_f32_e32 v48, 0, v23
	v_mfma_f32_16x16x32_bf16 v[40:43], v[10:13], v[44:47], v[40:43]
	s_nop 7
	v_max_f32_e32 v44, 0, v40
	v_max_f32_e32 v45, 0, v41
	v_max_f32_e32 v23, 0, v42
	v_mul_f32_e32 v40, v37, v23
	v_max_f32_e32 v49, 0, v43
	v_pk_mul_f32 v[42:43], v[36:37], v[48:49]
	ds_read_b128 v[46:49], v158
	s_waitcnt lgkmcnt(0)
	v_mfma_f32_16x16x32_bf16 v[46:49], v[14:17], v[46:49], 0
	v_mov_b32_e32 v35, v42
	v_mov_b32_e32 v41, v43
	v_mfma_f32_16x16x32_bf16 v[50:53], v[10:13], v[50:53], v[46:49]
	s_nop 4
	ds_read2_b32 v[48:49], v137 offset0:144 offset1:160
	s_nop 1
	v_max_f32_e32 v50, 0, v50
	v_max_f32_e32 v51, 0, v51
	v_max_f32_e32 v23, 0, v52
	s_waitcnt lgkmcnt(0)
	v_mul_f32_e32 v46, v48, v23
	v_max_f32_e32 v23, v53, v53
	ds_read_b128 v[52:55], v156
	s_waitcnt lgkmcnt(0)
	v_mfma_f32_16x16x32_bf16 v[52:55], v[14:17], v[52:55], 0
	v_max_f32_e32 v102, 0, v23
	v_mfma_f32_16x16x32_bf16 v[52:55], v[10:13], v[122:125], v[52:55]
	ds_read_b128 v[122:125], v154
	s_waitcnt lgkmcnt(0)
	v_mfma_f32_16x16x32_bf16 v[122:125], v[14:17], v[122:125], 0
	s_nop 4
	v_max_f32_e32 v56, 0, v52
	v_max_f32_e32 v57, 0, v53
	v_max_f32_e32 v23, 0, v54
	v_mfma_f32_16x16x32_bf16 v[122:125], v[10:13], v[126:129], v[122:125]
	v_mul_f32_e32 v52, v49, v23
	s_nop 0
	v_max_f32_e32 v103, 0, v55
	v_pk_mul_f32 v[54:55], v[48:49], v[102:103]
	ds_read2_b32 v[102:103], v137 offset0:176 offset1:192
	s_nop 2
	v_max_f32_e32 v126, 0, v122
	v_max_f32_e32 v127, 0, v123
	v_max_f32_e32 v23, 0, v124
	s_waitcnt lgkmcnt(0)
	v_mul_f32_e32 v128, v102, v23
	v_max_f32_e32 v23, v125, v125
	ds_read_b128 v[122:125], v152
	s_waitcnt lgkmcnt(0)
	v_mfma_f32_16x16x32_bf16 v[14:17], v[14:17], v[122:125], 0
	ds_read_b128 v[122:125], v151
	v_max_f32_e32 v130, 0, v23
	v_mov_b32_e32 v47, v54
	s_waitcnt lgkmcnt(0)
	v_mfma_f32_16x16x32_bf16 v[10:13], v[10:13], v[122:125], v[14:17]
	v_mov_b32_e32 v53, v55
	s_nop 1
	v_pk_fma_f32 v[16:17], v[24:25], v[26:27], 0 op_sel_hi:[0,1,0]
	v_mov_b32_e32 v24, v25
	v_pk_fma_f32 v[16:17], v[24:25], v[32:33], v[16:17] op_sel_hi:[0,1,1]
	v_pk_fma_f32 v[16:17], v[36:37], v[38:39], v[16:17] op_sel_hi:[0,1,1]
	v_mov_b32_e32 v24, v37
	v_pk_fma_f32 v[16:17], v[24:25], v[44:45], v[16:17] op_sel_hi:[0,1,1]
	v_pk_fma_f32 v[16:17], v[48:49], v[50:51], v[16:17] op_sel_hi:[0,1,1]
	v_mov_b32_e32 v24, v49
	v_pk_fma_f32 v[16:17], v[24:25], v[56:57], v[16:17] op_sel_hi:[0,1,1]
	v_max_f32_e32 v10, 0, v10
	v_max_f32_e32 v11, 0, v11
	v_pk_fma_f32 v[16:17], v[102:103], v[126:127], v[16:17] op_sel_hi:[0,1,1]
	v_mov_b32_e32 v24, v103
	v_pk_fma_f32 v[10:11], v[24:25], v[10:11], v[16:17] op_sel_hi:[0,1,1]
	v_and_b32_e32 v17, 0x7fffffff, v11
	v_and_b32_e32 v16, 0x7fffffff, v10
	v_max_f32_e32 v131, 0, v13
	v_xor_b32_e32 v23, -1, v10
	v_pk_add_f32 v[16:17], v[16:17], 0 neg_lo:[1,1] neg_hi:[1,1]
	v_cmp_gt_i32_e32 vcc, 0, v10
	v_pk_mul_f32 v[14:15], v[102:103], v[130:131]
	v_xor_b32_e32 v13, -1, v11
	v_cndmask_b32_e32 v102, v16, v23, vcc
	v_mov_b32_e32 v23, v30
	v_cmp_gt_i32_e64 s[2:3], 0, v11
	v_pk_add_f32 v[10:11], v[22:23], 0 op_sel_hi:[1,0]
	v_pk_add_f32 v[10:11], v[10:11], v[28:29]
	v_max_f32_e32 v12, 0, v12
	v_pk_add_f32 v[10:11], v[10:11], v[34:35]
	v_mov_b32_e32 v129, v14
	v_pk_add_f32 v[10:11], v[10:11], v[40:41]
	v_mul_f32_e32 v12, v103, v12
	v_pk_add_f32 v[10:11], v[10:11], v[46:47]
	v_cndmask_b32_e64 v101, v17, v13, s[2:3]
	v_pk_add_f32 v[10:11], v[10:11], v[52:53]
	v_mov_b32_e32 v13, v15
	v_pk_add_f32 v[10:11], v[10:11], v[128:129]
	s_nop 0
	v_pk_add_f32 v[10:11], v[10:11], v[12:13]
	s_nop 0
	v_xor_b32_e32 v15, -1, v10
	v_and_b32_e32 v12, 0x7fffffff, v10
	v_cmp_gt_i32_e32 vcc, 0, v10
	v_lshrrev_b32_e32 v10, 24, v102
	v_and_b32_e32 v13, 0x7fffffff, v11
	v_lshl_add_u32 v10, v10, 6, v0
	v_pk_add_f32 v[12:13], v[12:13], 0 neg_lo:[1,1] neg_hi:[1,1]
	ds_add_u32 v10, v205 offset:16384
	v_lshrrev_b32_e32 v10, 24, v101
	v_cndmask_b32_e32 v104, v12, v15, vcc
	v_lshl_add_u32 v10, v10, 6, v0
	v_xor_b32_e32 v14, -1, v11
	v_cmp_gt_i32_e64 s[2:3], 0, v11
	ds_add_u32 v10, v205 offset:16384
	v_lshrrev_b32_e32 v10, 24, v104
	v_cndmask_b32_e64 v103, v13, v14, s[2:3]
	v_lshl_add_u32 v10, v10, 6, v0
	ds_add_u32 v10, v205 offset:16384
	v_lshrrev_b32_e32 v10, 24, v103
	v_lshl_add_u32 v10, v10, 6, v0
	ds_add_u32 v10, v205 offset:16384
	ds_read_b128 v[10:13], v182
	ds_read_b128 v[14:17], v183
	ds_read_b128 v[22:25], v184
	ds_read_b128 v[26:29], v185
	ds_read2_b32 v[30:31], v137 offset0:80 offset1:96
	ds_read2_b32 v[38:39], v137 offset0:112 offset1:128
	s_waitcnt vmcnt(1) lgkmcnt(5)
	v_mfma_f32_16x16x32_bf16 v[10:13], v[6:9], v[10:13], 0
	ds_read2_b32 v[50:51], v137 offset0:144 offset1:160
	s_waitcnt vmcnt(0) lgkmcnt(5)
	v_mfma_f32_16x16x32_bf16 v[10:13], v[2:5], v[14:17], v[10:13]
	ds_read_b128 v[14:17], v179
	s_waitcnt lgkmcnt(5)
	v_mfma_f32_16x16x32_bf16 v[22:25], v[6:9], v[22:25], 0
	s_nop 4
	v_max_f32_e32 v32, 0, v10
	v_max_f32_e32 v10, 0, v12
	v_max_f32_e32 v33, 0, v11
	s_waitcnt lgkmcnt(3)
	v_mul_f32_e32 v34, v30, v10
	v_max_f32_e32 v36, 0, v13
	v_mfma_f32_16x16x32_bf16 v[10:13], v[2:5], v[26:29], v[22:25]
	s_nop 2
	ds_read_b128 v[22:25], v180
	s_waitcnt lgkmcnt(1)
; #define LAS __attribute__((address_space(3)))
; __device__ __forceinline__ unsigned fkey(float f) { const unsigned u = __float_as_uint(f); return (u & 0x80000000u) ? ~u : (u | 0x80000000u); }
; #define SEL_HADD(idx_) __hip_atomic_fetch_add(&hist[(idx_)], 1u, __ATOMIC_RELAXED, __HIP_MEMORY_SCOPE_WORKGROUP)
; __device__ __forceinline__ void sel_unit(LAS char* lds, int b, int u, const bf16_t* QI, const bf16_t* KIDX, const float* WIDX, unsigned long long* MASK) {
;     ...
;                 for (int ks = 0; ks < 2; ++ks) kf[kb][ks] = *(const bf16x8*)(KIDX + (rowbase + 64 * t + 32 * kh + 16 * kb + q16) * 64 + 32 * ks + 8 * kg);
; #pragma unroll
;             for (int kb = 0; kb < 2; ++kb) {
;                 f32x4 s = (f32x4){0.f, 0.f, 0.f, 0.f};
; #pragma unroll
;                 for (int hh = 0; hh < 8; ++hh) {
;                     f32x4 a = (f32x4){0.f, 0.f, 0.f, 0.f};
; #pragma unroll
;                     for (int ks = 0; ks < 2; ++ks) {
;                         const bf16x8 qv = *(const LAS bf16x8*)(lds + L_QI + q16 * 1024 + (((hh * 8 + 4 * ks + kg) ^ q16) << 4));
;                         a = __builtin_amdgcn_mfma_f32_16x16x32_bf16(kf[kb][ks], qv, a, 0, 0, 0);
;                     }
;                     const float wh = wl[hh * 16];
; #pragma unroll
;                     for (int i = 0; i < 4; ++i) s[i] += wh * fmaxf(a[i], 0.f);
;                 }
;                 u32x4 kk; kk.x = fkey(s[0]); kk.y = fkey(s[1]); kk.z = fkey(s[2]); kk.w = fkey(s[3]);
;                 sc[j][2 * kh + kb] = kk;
; #pragma unroll
;                 for (int i = 0; i < 4; ++i) SEL_HADD((kk[i] >> 24) * 16 + q16);
	v_mfma_f32_16x16x32_bf16 v[14:17], v[6:9], v[14:17], 0
	s_nop 1
	v_max_f32_e32 v26, 0, v10
	v_max_f32_e32 v27, 0, v11
	v_max_f32_e32 v10, 0, v12
	v_mul_f32_e32 v28, v31, v10
	v_max_f32_e32 v37, 0, v13
	s_waitcnt lgkmcnt(0)
	v_mfma_f32_16x16x32_bf16 v[10:13], v[2:5], v[22:25], v[14:17]
	ds_read_b128 v[22:25], v159
	ds_read2_b32 v[110:111], v137 offset0:176 offset1:192
	v_pk_mul_f32 v[36:37], v[30:31], v[36:37]
	ds_read_b128 v[14:17], v176
	s_waitcnt lgkmcnt(0)
	v_mfma_f32_16x16x32_bf16 v[14:17], v[6:9], v[14:17], 0
	s_nop 1
	v_max_f32_e32 v40, 0, v10
	v_max_f32_e32 v41, 0, v11
	v_max_f32_e32 v10, 0, v12
	v_mul_f32_e32 v42, v38, v10
	s_nop 0
	v_max_f32_e32 v44, 0, v13
	v_mfma_f32_16x16x32_bf16 v[10:13], v[2:5], v[22:25], v[14:17]
	ds_read_b128 v[22:25], v157
	v_mov_b32_e32 v35, v36
	v_mov_b32_e32 v29, v37
	ds_read_b128 v[14:17], v158
	s_waitcnt lgkmcnt(0)
	v_mfma_f32_16x16x32_bf16 v[14:17], v[6:9], v[14:17], 0
	s_nop 1
	v_max_f32_e32 v46, 0, v10
	v_max_f32_e32 v47, 0, v11
	v_max_f32_e32 v10, 0, v12
	v_mul_f32_e32 v48, v39, v10
	s_nop 0
	v_max_f32_e32 v45, 0, v13
	v_mfma_f32_16x16x32_bf16 v[10:13], v[2:5], v[22:25], v[14:17]
	ds_read_b128 v[22:25], v155
	v_pk_mul_f32 v[44:45], v[38:39], v[44:45]
	s_nop 0
	ds_read_b128 v[14:17], v156
	s_waitcnt lgkmcnt(0)
	v_mfma_f32_16x16x32_bf16 v[14:17], v[6:9], v[14:17], 0
	s_nop 1
	v_max_f32_e32 v52, 0, v10
	v_max_f32_e32 v53, 0, v11
	v_max_f32_e32 v10, 0, v12
	v_mul_f32_e32 v54, v50, v10
	s_nop 0
	v_max_f32_e32 v56, 0, v13
	v_mfma_f32_16x16x32_bf16 v[10:13], v[2:5], v[22:25], v[14:17]
	ds_read_b128 v[22:25], v153
	v_mov_b32_e32 v43, v44
	v_mov_b32_e32 v49, v45
	ds_read_b128 v[14:17], v154
	s_waitcnt lgkmcnt(0)
	v_mfma_f32_16x16x32_bf16 v[14:17], v[6:9], v[14:17], 0
	s_nop 1
	v_max_f32_e32 v106, 0, v10
	v_max_f32_e32 v107, 0, v11
	v_max_f32_e32 v10, 0, v12
	v_mul_f32_e32 v108, v51, v10
	s_nop 0
	v_max_f32_e32 v57, 0, v13
	v_mfma_f32_16x16x32_bf16 v[10:13], v[2:5], v[22:25], v[14:17]
	ds_read_b128 v[22:25], v151
	v_pk_mul_f32 v[56:57], v[50:51], v[56:57]
	s_nop 0
	ds_read_b128 v[14:17], v152
	s_waitcnt lgkmcnt(0)
	v_mfma_f32_16x16x32_bf16 v[6:9], v[6:9], v[14:17], 0
	s_nop 1
	s_nop 0
	v_max_f32_e32 v14, 0, v13
	s_nop 0
	v_mfma_f32_16x16x32_bf16 v[2:5], v[2:5], v[22:25], v[6:9]
	s_nop 0
	v_max_f32_e32 v10, 0, v10
	v_max_f32_e32 v11, 0, v11
	v_pk_fma_f32 v[8:9], v[30:31], v[32:33], 0 op_sel_hi:[0,1,0]
	s_nop 0
	s_nop 2
	v_max_f32_e32 v15, 0, v5
	v_pk_mul_f32 v[6:7], v[110:111], v[14:15]
	v_mov_b32_e32 v14, v31
	v_pk_fma_f32 v[8:9], v[14:15], v[26:27], v[8:9] op_sel_hi:[0,1,1]
	v_pk_fma_f32 v[8:9], v[38:39], v[40:41], v[8:9] op_sel_hi:[0,1,1]
	v_mov_b32_e32 v14, v39
	v_pk_fma_f32 v[8:9], v[14:15], v[46:47], v[8:9] op_sel_hi:[0,1,1]
	v_pk_fma_f32 v[8:9], v[50:51], v[52:53], v[8:9] op_sel_hi:[0,1,1]
	v_mov_b32_e32 v14, v51
	v_pk_fma_f32 v[8:9], v[14:15], v[106:107], v[8:9] op_sel_hi:[0,1,1]
	v_max_f32_e32 v2, 0, v2
	v_max_f32_e32 v3, 0, v3
	v_pk_fma_f32 v[8:9], v[110:111], v[10:11], v[8:9] op_sel_hi:[0,1,1]
	v_mov_b32_e32 v10, v111
	v_pk_fma_f32 v[2:3], v[10:11], v[2:3], v[8:9] op_sel_hi:[0,1,1]
	v_and_b32_e32 v9, 0x7fffffff, v3
	v_and_b32_e32 v8, 0x7fffffff, v2
	v_xor_b32_e32 v5, -1, v3
	v_pk_add_f32 v[8:9], v[8:9], 0 neg_lo:[1,1] neg_hi:[1,1]
	v_cmp_gt_i32_e32 vcc, 0, v3
	v_xor_b32_e32 v10, -1, v2
	v_mov_b32_e32 v55, v56
	v_cndmask_b32_e32 v105, v9, v5, vcc
	v_cmp_gt_i32_e32 vcc, 0, v2
	v_pk_add_f32 v[2:3], v[34:35], 0 op_sel_hi:[1,0]
	v_max_f32_e32 v12, 0, v12
	v_pk_add_f32 v[2:3], v[2:3], v[28:29]
	v_pk_add_f32 v[2:3], v[2:3], v[42:43]
	v_mov_b32_e32 v109, v57
	v_pk_add_f32 v[2:3], v[2:3], v[48:49]
	v_mul_f32_e32 v12, v110, v12
	v_pk_add_f32 v[2:3], v[2:3], v[54:55]
	v_max_f32_e32 v4, 0, v4
	v_pk_add_f32 v[2:3], v[2:3], v[108:109]
	v_mov_b32_e32 v13, v6
	v_mul_f32_e32 v4, v111, v4
	v_pk_add_f32 v[2:3], v[2:3], v[12:13]
	v_mov_b32_e32 v5, v7
	v_pk_add_f32 v[2:3], v[2:3], v[4:5]
	v_cndmask_b32_e32 v106, v8, v10, vcc
	v_and_b32_e32 v5, 0x7fffffff, v3
	v_and_b32_e32 v4, 0x7fffffff, v2
	v_xor_b32_e32 v6, -1, v3
	v_pk_add_f32 v[4:5], v[4:5], 0 neg_lo:[1,1] neg_hi:[1,1]
	v_cmp_gt_i32_e32 vcc, 0, v3
	v_xor_b32_e32 v7, -1, v2
	s_nop 0
	v_cndmask_b32_e32 v107, v5, v6, vcc
	v_cmp_gt_i32_e32 vcc, 0, v2
	v_lshrrev_b32_e32 v2, 24, v106
	v_lshl_add_u32 v2, v2, 6, v0
	ds_add_u32 v2, v205 offset:16384
	v_lshrrev_b32_e32 v2, 24, v105
	v_cndmask_b32_e32 v108, v4, v7, vcc
	v_lshl_add_u32 v2, v2, 6, v0
	ds_add_u32 v2, v205 offset:16384
	v_lshrrev_b32_e32 v2, 24, v108
	v_lshl_add_u32 v2, v2, 6, v0
	ds_add_u32 v2, v205 offset:16384
	v_lshrrev_b32_e32 v2, 24, v107
	v_lshl_add_u32 v2, v2, 6, v0
	ds_add_u32 v2, v205 offset:16384
; #define LAS __attribute__((address_space(3)))
; __device__ __forceinline__ unsigned fkey(float f) { const unsigned u = __float_as_uint(f); return (u & 0x80000000u) ? ~u : (u | 0x80000000u); }
; #define SEL_HADD(idx_) __hip_atomic_fetch_add(&hist[(idx_)], 1u, __ATOMIC_RELAXED, __HIP_MEMORY_SCOPE_WORKGROUP)
; __device__ __forceinline__ void sel_unit(LAS char* lds, int b, int u, const bf16_t* QI, const bf16_t* KIDX, const float* WIDX, unsigned long long* MASK) {
;     ...
;     for (int j = 0; j < 8; ++j) {
;         if (j < nj) {
;             int t = wid + 8 * j; asm volatile("" : "+s"(t));
; #pragma unroll
;             for (int kh = 0; kh < 2; ++kh) {
;             bf16x8 kf[2][2];
; #pragma unroll
;             for (int kb = 0; kb < 2; ++kb)
; #pragma unroll
;                 for (int ks = 0; ks < 2; ++ks) kf[kb][ks] = *(const bf16x8*)(KIDX + (rowbase + 64 * t + 32 * kh + 16 * kb + q16) * 64 + 32 * ks + 8 * kg);
; #pragma unroll
;             for (int kb = 0; kb < 2; ++kb) {
;                 f32x4 s = (f32x4){0.f, 0.f, 0.f, 0.f};
; #pragma unroll
;                 for (int hh = 0; hh < 8; ++hh) {
;                     f32x4 a = (f32x4){0.f, 0.f, 0.f, 0.f};
; #pragma unroll
;                     for (int ks = 0; ks < 2; ++ks) {
;                         const bf16x8 qv = *(const LAS bf16x8*)(lds + L_QI + q16 * 1024 + (((hh * 8 + 4 * ks + kg) ^ q16) << 4));
;                         a = __builtin_amdgcn_mfma_f32_16x16x32_bf16(kf[kb][ks], qv, a, 0, 0, 0);
;                     }
;                     const float wh = wl[hh * 16];
; #pragma unroll
;                     for (int i = 0; i < 4; ++i) s[i] += wh * fmaxf(a[i], 0.f);
;                 }
;                 u32x4 kk; kk.x = fkey(s[0]); kk.y = fkey(s[1]); kk.z = fkey(s[2]); kk.w = fkey(s[3]);
;                 sc[j][2 * kh + kb] = kk;
; #pragma unroll
;                 for (int i = 0; i < 4; ++i) SEL_HADD((kk[i] >> 24) * 16 + q16);
;                 __builtin_amdgcn_sched_barrier(0);
;             }
.LBB0_662:
	s_cmp_gt_i32 s4, 3
	s_cselect_b64 s[56:57], -1, 0
	s_cmp_lt_i32 s4, 4
	s_cbranch_scc1 .LBB0_664
	s_add_i32 s0, s46, 24
	s_lshl_b32 s0, s0, 6
	s_ashr_i32 s1, s0, 31
	v_lshl_add_u64 v[2:3], v[18:19], 0, s[0:1]
	v_lshlrev_b64 v[2:3], 7, v[2:3]
	v_lshl_add_u64 v[22:23], v[20:21], 0, v[2:3]
	global_load_dwordx4 v[14:17], v[22:23], off
	global_load_dwordx4 v[10:13], v[22:23], off offset:64
	ds_read_b128 v[2:5], v182
	ds_read_b128 v[6:9], v183
	ds_read_b128 v[24:27], v184
	ds_read_b128 v[28:31], v185
	ds_read_b128 v[32:35], v179
	ds_read_b128 v[36:39], v180
	ds_read_b128 v[40:43], v176
	ds_read_b128 v[44:47], v159
	ds_read_b128 v[48:51], v158
	ds_read_b128 v[52:55], v157
	ds_read_b128 v[110:113], v156
	ds_read_b128 v[114:117], v155
	s_waitcnt vmcnt(1) lgkmcnt(11)
	v_mfma_f32_16x16x32_bf16 v[2:5], v[14:17], v[2:5], 0
	s_waitcnt lgkmcnt(9)
	v_mfma_f32_16x16x32_bf16 v[24:27], v[14:17], v[24:27], 0
	s_waitcnt lgkmcnt(7)
	v_mfma_f32_16x16x32_bf16 v[32:35], v[14:17], v[32:35], 0
	s_waitcnt lgkmcnt(5)
	v_mfma_f32_16x16x32_bf16 v[40:43], v[14:17], v[40:43], 0
	s_waitcnt lgkmcnt(3)
	v_mfma_f32_16x16x32_bf16 v[48:51], v[14:17], v[48:51], 0
	s_waitcnt vmcnt(0)
	v_mfma_f32_16x16x32_bf16 v[138:141], v[10:13], v[6:9], v[2:5]
	v_mfma_f32_16x16x32_bf16 v[24:27], v[10:13], v[28:31], v[24:27]
	v_mfma_f32_16x16x32_bf16 v[28:31], v[10:13], v[36:39], v[32:35]
	v_mfma_f32_16x16x32_bf16 v[32:35], v[10:13], v[44:47], v[40:43]
	ds_read2_b32 v[44:45], v137 offset0:80 offset1:96
	ds_read2_b32 v[46:47], v137 offset0:112 offset1:128
	s_nop 3
	s_waitcnt lgkmcnt(4)
	v_mfma_f32_16x16x32_bf16 v[36:39], v[10:13], v[52:55], v[48:51]
	s_nop 0
	ds_read2_b32 v[48:49], v137 offset0:144 offset1:160
	global_load_dwordx4 v[6:9], v[22:23], off offset:2048
	global_load_dwordx4 v[2:5], v[22:23], off offset:2112
	s_waitcnt lgkmcnt(4)
	v_mfma_f32_16x16x32_bf16 v[110:113], v[14:17], v[110:113], 0
	s_nop 0
	v_max_f32_e32 v54, v24, v24
	s_nop 0
	s_waitcnt lgkmcnt(3)
	v_mfma_f32_16x16x32_bf16 v[40:43], v[10:13], v[114:117], v[110:113]
	v_max_f32_e32 v109, v39, v39
	v_max_f32_e32 v24, 0, v141
	v_max_f32_e32 v39, 0, v25
	v_max_f32_e32 v112, 0, v26
	v_max_f32_e32 v25, 0, v27
	v_max_f32_e32 v26, 0, v31
	v_max_f32_e32 v27, 0, v35
	v_max_f32_e32 v53, 0, v37
	s_waitcnt lgkmcnt(2)
	v_mul_f32_e32 v56, v45, v112
	v_pk_mul_f32 v[112:113], v[44:45], v[24:25]
	s_waitcnt lgkmcnt(1)
	v_pk_mul_f32 v[118:119], v[46:47], v[26:27]
	ds_read_b128 v[24:27], v154
	v_max_f32_e32 v110, v40, v40
	v_max_f32_e32 v40, 0, v28
	v_max_f32_e32 v28, 0, v30
	v_max_f32_e32 v111, v41, v41
	v_max_f32_e32 v41, 0, v29
	v_max_f32_e32 v29, 0, v34
	v_max_f32_e32 v30, 0, v38
	v_mul_f32_e32 v114, v46, v28
	v_max_f32_e32 v28, 0, v42
	v_max_f32_e32 v50, v138, v138
	v_max_f32_e32 v52, v140, v140
	v_mul_f32_e32 v116, v47, v29
	s_waitcnt lgkmcnt(1)
	v_mul_f32_e32 v138, v48, v30
	v_mul_f32_e32 v140, v49, v28
	ds_read_b128 v[28:31], v153
	s_waitcnt lgkmcnt(1)
	v_mfma_f32_16x16x32_bf16 v[24:27], v[14:17], v[24:27], 0
	s_waitcnt lgkmcnt(0)
	v_mfma_f32_16x16x32_bf16 v[24:27], v[10:13], v[28:31], v[24:27]
	ds_read_b128 v[28:31], v152
	v_max_f32_e32 v37, 0, v139
	v_max_f32_e32 v51, 0, v33
	v_max_f32_e32 v55, v36, v36
	v_max_f32_e32 v36, 0, v50
	v_max_f32_e32 v50, 0, v32
	v_max_f32_e32 v32, 0, v109
	v_max_f32_e32 v33, 0, v43
	v_pk_mul_f32 v[142:143], v[48:49], v[32:33]
	ds_read_b128 v[32:35], v151
	s_waitcnt lgkmcnt(1)
	v_mfma_f32_16x16x32_bf16 v[14:17], v[14:17], v[28:31], 0
	v_max_f32_e32 v42, 0, v52
	v_max_f32_e32 v38, 0, v54
	v_max_f32_e32 v52, 0, v55
	s_waitcnt lgkmcnt(0)
	v_mfma_f32_16x16x32_bf16 v[10:13], v[10:13], v[32:35], v[14:17]
	v_max_f32_e32 v54, 0, v110
	v_max_f32_e32 v55, 0, v111
	ds_read2_b32 v[110:111], v137 offset0:176 offset1:192
	s_nop 0
	v_max_f32_e32 v28, 0, v27
	s_nop 2
	v_max_f32_e32 v29, 0, v13
	s_waitcnt lgkmcnt(0)
	v_pk_mul_f32 v[14:15], v[110:111], v[28:29]
	v_pk_fma_f32 v[16:17], v[44:45], v[36:37], 0 op_sel_hi:[0,1,0]
	v_mov_b32_e32 v28, v45
	v_pk_fma_f32 v[16:17], v[28:29], v[38:39], v[16:17] op_sel_hi:[0,1,1]
	v_pk_fma_f32 v[16:17], v[46:47], v[40:41], v[16:17] op_sel_hi:[0,1,1]
	v_mov_b32_e32 v28, v47
	v_pk_fma_f32 v[16:17], v[28:29], v[50:51], v[16:17] op_sel_hi:[0,1,1]
	v_pk_fma_f32 v[16:17], v[48:49], v[52:53], v[16:17] op_sel_hi:[0,1,1]
	v_mov_b32_e32 v28, v49
	v_max_f32_e32 v24, 0, v24
	v_max_f32_e32 v25, 0, v25
	v_pk_fma_f32 v[16:17], v[28:29], v[54:55], v[16:17] op_sel_hi:[0,1,1]
	v_max_f32_e32 v10, 0, v10
	v_max_f32_e32 v11, 0, v11
	v_pk_fma_f32 v[16:17], v[110:111], v[24:25], v[16:17] op_sel_hi:[0,1,1]
	v_mov_b32_e32 v24, v111
	v_pk_fma_f32 v[10:11], v[24:25], v[10:11], v[16:17] op_sel_hi:[0,1,1]
	v_and_b32_e32 v17, 0x7fffffff, v11
	v_and_b32_e32 v16, 0x7fffffff, v10
	v_mul_f32_e32 v42, v44, v42
	v_xor_b32_e32 v13, -1, v11
	v_pk_add_f32 v[16:17], v[16:17], 0 neg_lo:[1,1] neg_hi:[1,1]
	v_cmp_gt_i32_e32 vcc, 0, v11
	v_mov_b32_e32 v43, v112
	v_xor_b32_e32 v24, -1, v10
	v_cndmask_b32_e32 v109, v17, v13, vcc
	v_cmp_gt_i32_e32 vcc, 0, v10
	v_pk_add_f32 v[10:11], v[42:43], 0 op_sel_hi:[1,0]
	v_mov_b32_e32 v57, v113
	v_pk_add_f32 v[10:11], v[10:11], v[56:57]
	v_mov_b32_e32 v115, v118
	v_pk_add_f32 v[10:11], v[10:11], v[114:115]
	v_mov_b32_e32 v117, v119
	v_pk_add_f32 v[10:11], v[10:11], v[116:117]
	v_mov_b32_e32 v139, v142
	v_max_f32_e32 v26, 0, v26
	v_pk_add_f32 v[10:11], v[10:11], v[138:139]
	v_mov_b32_e32 v141, v143
	v_mul_f32_e32 v26, v110, v26
	v_max_f32_e32 v12, 0, v12
	v_pk_add_f32 v[10:11], v[10:11], v[140:141]
	v_mov_b32_e32 v27, v14
	v_mul_f32_e32 v12, v111, v12
	v_pk_add_f32 v[10:11], v[10:11], v[26:27]
	v_mov_b32_e32 v13, v15
	v_pk_add_f32 v[10:11], v[10:11], v[12:13]
	v_cndmask_b32_e32 v110, v16, v24, vcc
	v_and_b32_e32 v13, 0x7fffffff, v11
	v_and_b32_e32 v12, 0x7fffffff, v10
	v_xor_b32_e32 v14, -1, v11
	v_pk_add_f32 v[12:13], v[12:13], 0 neg_lo:[1,1] neg_hi:[1,1]
	v_cmp_gt_i32_e32 vcc, 0, v11
	v_xor_b32_e32 v15, -1, v10
	s_nop 0
	v_cndmask_b32_e32 v111, v13, v14, vcc
	v_cmp_gt_i32_e32 vcc, 0, v10
	v_lshrrev_b32_e32 v10, 24, v110
	v_lshl_add_u32 v10, v10, 6, v0
	ds_add_u32 v10, v205 offset:16384
	v_lshrrev_b32_e32 v10, 24, v109
	v_cndmask_b32_e32 v112, v12, v15, vcc
	v_lshl_add_u32 v10, v10, 6, v0
	ds_add_u32 v10, v205 offset:16384
	v_lshrrev_b32_e32 v10, 24, v112
	v_lshl_add_u32 v10, v10, 6, v0
	ds_add_u32 v10, v205 offset:16384
	v_lshrrev_b32_e32 v10, 24, v111
	v_lshl_add_u32 v10, v10, 6, v0
	ds_add_u32 v10, v205 offset:16384
	ds_read_b128 v[10:13], v182
	ds_read_b128 v[14:17], v183
	ds_read_b128 v[24:27], v184
	ds_read_b128 v[28:31], v185
	ds_read2_b32 v[32:33], v137 offset0:80 offset1:96
	ds_read2_b32 v[40:41], v137 offset0:112 offset1:128
	s_waitcnt vmcnt(1) lgkmcnt(5)
; #define LAS __attribute__((address_space(3)))
; __device__ __forceinline__ unsigned fkey(float f) { const unsigned u = __float_as_uint(f); return (u & 0x80000000u) ? ~u : (u | 0x80000000u); }
; #define SEL_HADD(idx_) __hip_atomic_fetch_add(&hist[(idx_)], 1u, __ATOMIC_RELAXED, __HIP_MEMORY_SCOPE_WORKGROUP)
; __device__ __forceinline__ void sel_unit(LAS char* lds, int b, int u, const bf16_t* QI, const bf16_t* KIDX, const float* WIDX, unsigned long long* MASK) {
;     ...
;                 for (int ks = 0; ks < 2; ++ks) kf[kb][ks] = *(const bf16x8*)(KIDX + (rowbase + 64 * t + 32 * kh + 16 * kb + q16) * 64 + 32 * ks + 8 * kg);
; #pragma unroll
;             for (int kb = 0; kb < 2; ++kb) {
;                 f32x4 s = (f32x4){0.f, 0.f, 0.f, 0.f};
; #pragma unroll
;                 for (int hh = 0; hh < 8; ++hh) {
;                     f32x4 a = (f32x4){0.f, 0.f, 0.f, 0.f};
; #pragma unroll
;                     for (int ks = 0; ks < 2; ++ks) {
;                         const bf16x8 qv = *(const LAS bf16x8*)(lds + L_QI + q16 * 1024 + (((hh * 8 + 4 * ks + kg) ^ q16) << 4));
;                         a = __builtin_amdgcn_mfma_f32_16x16x32_bf16(kf[kb][ks], qv, a, 0, 0, 0);
;                     }
;                     const float wh = wl[hh * 16];
; #pragma unroll
;                     for (int i = 0; i < 4; ++i) s[i] += wh * fmaxf(a[i], 0.f);
;                 }
;                 u32x4 kk; kk.x = fkey(s[0]); kk.y = fkey(s[1]); kk.z = fkey(s[2]); kk.w = fkey(s[3]);
;                 sc[j][2 * kh + kb] = kk;
; #pragma unroll
;                 for (int i = 0; i < 4; ++i) SEL_HADD((kk[i] >> 24) * 16 + q16);
	v_mfma_f32_16x16x32_bf16 v[10:13], v[6:9], v[10:13], 0
	ds_read2_b32 v[52:53], v137 offset0:144 offset1:160
	s_waitcnt vmcnt(0) lgkmcnt(5)
	v_mfma_f32_16x16x32_bf16 v[10:13], v[2:5], v[14:17], v[10:13]
	ds_read_b128 v[14:17], v179
	s_waitcnt lgkmcnt(5)
	v_mfma_f32_16x16x32_bf16 v[24:27], v[6:9], v[24:27], 0
	s_nop 4
	v_max_f32_e32 v34, 0, v10
	v_max_f32_e32 v10, 0, v12
	v_max_f32_e32 v35, 0, v11
	s_waitcnt lgkmcnt(3)
	v_mul_f32_e32 v36, v32, v10
	v_max_f32_e32 v38, 0, v13
	v_mfma_f32_16x16x32_bf16 v[10:13], v[2:5], v[28:31], v[24:27]
	s_nop 2
	ds_read_b128 v[24:27], v180
	s_waitcnt lgkmcnt(1)
	v_mfma_f32_16x16x32_bf16 v[14:17], v[6:9], v[14:17], 0
	s_nop 1
	v_max_f32_e32 v28, 0, v10
	v_max_f32_e32 v29, 0, v11
	v_max_f32_e32 v10, 0, v12
	v_mul_f32_e32 v30, v33, v10
	v_max_f32_e32 v39, 0, v13
	s_waitcnt lgkmcnt(0)
	v_mfma_f32_16x16x32_bf16 v[10:13], v[2:5], v[24:27], v[14:17]
	ds_read_b128 v[24:27], v159
	v_pk_mul_f32 v[38:39], v[32:33], v[38:39]
	s_nop 0
	ds_read_b128 v[14:17], v176
	s_waitcnt lgkmcnt(0)
	v_mfma_f32_16x16x32_bf16 v[14:17], v[6:9], v[14:17], 0
	s_nop 1
	v_max_f32_e32 v42, 0, v10
	v_max_f32_e32 v43, 0, v11
	v_max_f32_e32 v10, 0, v12
	v_mul_f32_e32 v44, v40, v10
	s_nop 0
	v_max_f32_e32 v46, 0, v13
	v_mfma_f32_16x16x32_bf16 v[10:13], v[2:5], v[24:27], v[14:17]
	ds_read_b128 v[24:27], v157
	v_mov_b32_e32 v37, v38
	v_mov_b32_e32 v31, v39
	ds_read_b128 v[14:17], v158
	s_waitcnt lgkmcnt(0)
	v_mfma_f32_16x16x32_bf16 v[14:17], v[6:9], v[14:17], 0
	s_nop 1
	v_max_f32_e32 v48, 0, v10
	v_max_f32_e32 v49, 0, v11
	v_max_f32_e32 v10, 0, v12
	v_mul_f32_e32 v50, v41, v10
	s_nop 0
	v_max_f32_e32 v47, 0, v13
	v_mfma_f32_16x16x32_bf16 v[10:13], v[2:5], v[24:27], v[14:17]
	ds_read_b128 v[24:27], v155
	v_pk_mul_f32 v[46:47], v[40:41], v[46:47]
	s_nop 0
	ds_read_b128 v[14:17], v156
	s_waitcnt lgkmcnt(0)
	v_mfma_f32_16x16x32_bf16 v[14:17], v[6:9], v[14:17], 0
	s_nop 1
	v_max_f32_e32 v54, 0, v10
	v_max_f32_e32 v55, 0, v11
	v_max_f32_e32 v10, 0, v12
	v_mul_f32_e32 v56, v52, v10
	s_nop 0
	v_max_f32_e32 v114, 0, v13
	v_mfma_f32_16x16x32_bf16 v[10:13], v[2:5], v[24:27], v[14:17]
	ds_read_b128 v[24:27], v153
	v_mov_b32_e32 v45, v46
	v_mov_b32_e32 v51, v47
	ds_read_b128 v[14:17], v154
	s_waitcnt lgkmcnt(0)
	v_mfma_f32_16x16x32_bf16 v[14:17], v[6:9], v[14:17], 0
	s_nop 1
	v_max_f32_e32 v116, 0, v10
	v_max_f32_e32 v117, 0, v11
	v_max_f32_e32 v10, 0, v12
	v_mul_f32_e32 v118, v53, v10
	s_nop 0
	v_max_f32_e32 v115, 0, v13
	v_mfma_f32_16x16x32_bf16 v[10:13], v[2:5], v[24:27], v[14:17]
	ds_read_b128 v[24:27], v151
	v_pk_mul_f32 v[138:139], v[52:53], v[114:115]
	ds_read2_b32 v[114:115], v137 offset0:176 offset1:192
	ds_read_b128 v[14:17], v152
	s_waitcnt lgkmcnt(0)
	v_mfma_f32_16x16x32_bf16 v[6:9], v[6:9], v[14:17], 0
	s_nop 1
	s_nop 0
	v_max_f32_e32 v14, 0, v13
	s_nop 0
	v_mfma_f32_16x16x32_bf16 v[2:5], v[2:5], v[24:27], v[6:9]
	s_nop 0
	v_max_f32_e32 v10, 0, v10
	v_max_f32_e32 v11, 0, v11
	v_pk_fma_f32 v[8:9], v[32:33], v[34:35], 0 op_sel_hi:[0,1,0]
	s_nop 0
	s_nop 2
	v_max_f32_e32 v15, 0, v5
	v_pk_mul_f32 v[6:7], v[114:115], v[14:15]
	v_mov_b32_e32 v14, v33
	v_pk_fma_f32 v[8:9], v[14:15], v[28:29], v[8:9] op_sel_hi:[0,1,1]
	v_pk_fma_f32 v[8:9], v[40:41], v[42:43], v[8:9] op_sel_hi:[0,1,1]
	v_mov_b32_e32 v14, v41
	v_pk_fma_f32 v[8:9], v[14:15], v[48:49], v[8:9] op_sel_hi:[0,1,1]
	v_pk_fma_f32 v[8:9], v[52:53], v[54:55], v[8:9] op_sel_hi:[0,1,1]
	v_mov_b32_e32 v14, v53
	v_pk_fma_f32 v[8:9], v[14:15], v[116:117], v[8:9] op_sel_hi:[0,1,1]
	v_max_f32_e32 v2, 0, v2
	v_max_f32_e32 v3, 0, v3
	v_pk_fma_f32 v[8:9], v[114:115], v[10:11], v[8:9] op_sel_hi:[0,1,1]
	v_mov_b32_e32 v10, v115
	v_pk_fma_f32 v[2:3], v[10:11], v[2:3], v[8:9] op_sel_hi:[0,1,1]
	v_and_b32_e32 v9, 0x7fffffff, v3
	v_and_b32_e32 v8, 0x7fffffff, v2
	v_xor_b32_e32 v5, -1, v3
	v_pk_add_f32 v[8:9], v[8:9], 0 neg_lo:[1,1] neg_hi:[1,1]
	v_cmp_gt_i32_e32 vcc, 0, v3
	v_xor_b32_e32 v10, -1, v2
	v_mov_b32_e32 v57, v138
	v_cndmask_b32_e32 v113, v9, v5, vcc
	v_cmp_gt_i32_e32 vcc, 0, v2
	v_pk_add_f32 v[2:3], v[36:37], 0 op_sel_hi:[1,0]
	v_max_f32_e32 v12, 0, v12
	v_pk_add_f32 v[2:3], v[2:3], v[30:31]
	v_pk_add_f32 v[2:3], v[2:3], v[44:45]
	v_mov_b32_e32 v119, v139
	v_pk_add_f32 v[2:3], v[2:3], v[50:51]
	v_mul_f32_e32 v12, v114, v12
	v_pk_add_f32 v[2:3], v[2:3], v[56:57]
	v_max_f32_e32 v4, 0, v4
	v_pk_add_f32 v[2:3], v[2:3], v[118:119]
	v_mov_b32_e32 v13, v6
	v_mul_f32_e32 v4, v115, v4
	v_pk_add_f32 v[2:3], v[2:3], v[12:13]
	v_mov_b32_e32 v5, v7
	v_pk_add_f32 v[2:3], v[2:3], v[4:5]
	v_cndmask_b32_e32 v114, v8, v10, vcc
	v_and_b32_e32 v5, 0x7fffffff, v3
	v_and_b32_e32 v4, 0x7fffffff, v2
	v_xor_b32_e32 v6, -1, v3
	v_pk_add_f32 v[4:5], v[4:5], 0 neg_lo:[1,1] neg_hi:[1,1]
	v_cmp_gt_i32_e32 vcc, 0, v3
	v_xor_b32_e32 v7, -1, v2
	s_nop 0
	v_cndmask_b32_e32 v115, v5, v6, vcc
	v_cmp_gt_i32_e32 vcc, 0, v2
	v_lshrrev_b32_e32 v2, 24, v114
	v_lshl_add_u32 v2, v2, 6, v0
	ds_add_u32 v2, v205 offset:16384
	v_lshrrev_b32_e32 v2, 24, v113
	v_cndmask_b32_e32 v116, v4, v7, vcc
	v_lshl_add_u32 v2, v2, 6, v0
	ds_add_u32 v2, v205 offset:16384
	v_lshrrev_b32_e32 v2, 24, v116
	v_lshl_add_u32 v2, v2, 6, v0
	ds_add_u32 v2, v205 offset:16384
	v_lshrrev_b32_e32 v2, 24, v115
	v_lshl_add_u32 v2, v2, 6, v0
	ds_add_u32 v2, v205 offset:16384
	v_add_co_u32_e32 v2, vcc, s96, v22
	s_nop 1
	v_addc_co_u32_e32 v3, vcc, 0, v23, vcc
	global_load_dwordx4 v[14:17], v[2:3], off
	global_load_dwordx4 v[10:13], v[2:3], off offset:64
	global_load_dwordx4 v[6:9], v[2:3], off offset:2048
	s_nop 0
	global_load_dwordx4 v[2:5], v[2:3], off offset:2112
	ds_read_b128 v[22:25], v182
	ds_read_b128 v[26:29], v183
	s_waitcnt vmcnt(3) lgkmcnt(1)
; #define LAS __attribute__((address_space(3)))
; __device__ __forceinline__ unsigned fkey(float f) { const unsigned u = __float_as_uint(f); return (u & 0x80000000u) ? ~u : (u | 0x80000000u); }
; #define SEL_HADD(idx_) __hip_atomic_fetch_add(&hist[(idx_)], 1u, __ATOMIC_RELAXED, __HIP_MEMORY_SCOPE_WORKGROUP)
; __device__ __forceinline__ void sel_unit(LAS char* lds, int b, int u, const bf16_t* QI, const bf16_t* KIDX, const float* WIDX, unsigned long long* MASK) {
;     ...
;                 for (int ks = 0; ks < 2; ++ks) kf[kb][ks] = *(const bf16x8*)(KIDX + (rowbase + 64 * t + 32 * kh + 16 * kb + q16) * 64 + 32 * ks + 8 * kg);
; #pragma unroll
;             for (int kb = 0; kb < 2; ++kb) {
;                 f32x4 s = (f32x4){0.f, 0.f, 0.f, 0.f};
; #pragma unroll
;                 for (int hh = 0; hh < 8; ++hh) {
;                     f32x4 a = (f32x4){0.f, 0.f, 0.f, 0.f};
; #pragma unroll
;                     for (int ks = 0; ks < 2; ++ks) {
;                         const bf16x8 qv = *(const LAS bf16x8*)(lds + L_QI + q16 * 1024 + (((hh * 8 + 4 * ks + kg) ^ q16) << 4));
;                         a = __builtin_amdgcn_mfma_f32_16x16x32_bf16(kf[kb][ks], qv, a, 0, 0, 0);
;                     }
;                     const float wh = wl[hh * 16];
; #pragma unroll
;                     for (int i = 0; i < 4; ++i) s[i] += wh * fmaxf(a[i], 0.f);
;                 }
;                 u32x4 kk; kk.x = fkey(s[0]); kk.y = fkey(s[1]); kk.z = fkey(s[2]); kk.w = fkey(s[3]);
;                 sc[j][2 * kh + kb] = kk;
; #pragma unroll
;                 for (int i = 0; i < 4; ++i) SEL_HADD((kk[i] >> 24) * 16 + q16);
	v_mfma_f32_16x16x32_bf16 v[22:25], v[14:17], v[22:25], 0
	ds_read_b128 v[32:35], v185
	ds_read_b128 v[38:41], v180
	ds_read_b128 v[44:47], v159
	s_waitcnt vmcnt(2) lgkmcnt(3)
	v_mfma_f32_16x16x32_bf16 v[26:29], v[10:13], v[26:29], v[22:25]
	ds_read_b128 v[50:53], v157
	ds_read_b128 v[138:141], v155
	ds_read_b128 v[142:145], v153
	ds_read2_b32 v[24:25], v137 offset0:80 offset1:96
	s_nop 3
	v_max_f32_e32 v26, 0, v26
	v_max_f32_e32 v27, 0, v27
	v_max_f32_e32 v22, v28, v28
	v_max_f32_e32 v23, v29, v29
	ds_read_b128 v[28:31], v184
	s_waitcnt lgkmcnt(0)
	v_mfma_f32_16x16x32_bf16 v[28:31], v[14:17], v[28:31], 0
	v_max_f32_e32 v36, 0, v23
	v_max_f32_e32 v22, 0, v22
	v_mul_f32_e32 v22, v24, v22
	v_mfma_f32_16x16x32_bf16 v[28:31], v[10:13], v[32:35], v[28:31]
	s_nop 7
	v_max_f32_e32 v32, 0, v28
	v_max_f32_e32 v33, 0, v29
	v_max_f32_e32 v23, 0, v30
	v_mul_f32_e32 v28, v25, v23
	v_max_f32_e32 v37, 0, v31
	v_pk_mul_f32 v[30:31], v[24:25], v[36:37]
	ds_read_b128 v[34:37], v179
	s_waitcnt lgkmcnt(0)
	v_mfma_f32_16x16x32_bf16 v[34:37], v[14:17], v[34:37], 0
	v_mov_b32_e32 v29, v31
	v_mfma_f32_16x16x32_bf16 v[38:41], v[10:13], v[38:41], v[34:37]
	s_nop 5
	ds_read2_b32 v[36:37], v137 offset0:112 offset1:128
	s_nop 0
	v_max_f32_e32 v38, 0, v38
	v_max_f32_e32 v39, 0, v39
	v_max_f32_e32 v23, 0, v40
	s_waitcnt lgkmcnt(0)
	v_mul_f32_e32 v34, v36, v23
	v_max_f32_e32 v23, v41, v41
	ds_read_b128 v[40:43], v176
	s_waitcnt lgkmcnt(0)
	v_mfma_f32_16x16x32_bf16 v[40:43], v[14:17], v[40:43], 0
	v_max_f32_e32 v48, 0, v23
	v_mfma_f32_16x16x32_bf16 v[40:43], v[10:13], v[44:47], v[40:43]
	s_nop 7
	v_max_f32_e32 v44, 0, v40
	v_max_f32_e32 v45, 0, v41
	v_max_f32_e32 v23, 0, v42
	v_mul_f32_e32 v40, v37, v23
	v_max_f32_e32 v49, 0, v43
	v_pk_mul_f32 v[42:43], v[36:37], v[48:49]
	ds_read_b128 v[46:49], v158
	s_waitcnt lgkmcnt(0)
	v_mfma_f32_16x16x32_bf16 v[46:49], v[14:17], v[46:49], 0
	v_mov_b32_e32 v35, v42
	v_mov_b32_e32 v41, v43
	v_mfma_f32_16x16x32_bf16 v[50:53], v[10:13], v[50:53], v[46:49]
	s_nop 4
	ds_read2_b32 v[48:49], v137 offset0:144 offset1:160
	s_nop 1
	v_max_f32_e32 v50, 0, v50
	v_max_f32_e32 v51, 0, v51
	v_max_f32_e32 v23, 0, v52
	s_waitcnt lgkmcnt(0)
	v_mul_f32_e32 v46, v48, v23
	v_max_f32_e32 v23, v53, v53
	ds_read_b128 v[52:55], v156
	s_waitcnt lgkmcnt(0)
	v_mfma_f32_16x16x32_bf16 v[52:55], v[14:17], v[52:55], 0
	v_max_f32_e32 v118, 0, v23
	v_mfma_f32_16x16x32_bf16 v[52:55], v[10:13], v[138:141], v[52:55]
	ds_read_b128 v[138:141], v154
	s_waitcnt lgkmcnt(0)
	v_mfma_f32_16x16x32_bf16 v[138:141], v[14:17], v[138:141], 0
	s_nop 4
	v_max_f32_e32 v56, 0, v52
	v_max_f32_e32 v57, 0, v53
	v_max_f32_e32 v23, 0, v54
	v_mfma_f32_16x16x32_bf16 v[138:141], v[10:13], v[142:145], v[138:141]
	v_mul_f32_e32 v52, v49, v23
	s_nop 0
	v_max_f32_e32 v119, 0, v55
	v_pk_mul_f32 v[54:55], v[48:49], v[118:119]
	ds_read2_b32 v[118:119], v137 offset0:176 offset1:192
	s_nop 2
	v_max_f32_e32 v142, 0, v138
	v_max_f32_e32 v143, 0, v139
	v_max_f32_e32 v23, 0, v140
	s_waitcnt lgkmcnt(0)
	v_mul_f32_e32 v144, v118, v23
	v_max_f32_e32 v23, v141, v141
	ds_read_b128 v[138:141], v152
	s_waitcnt lgkmcnt(0)
	v_mfma_f32_16x16x32_bf16 v[14:17], v[14:17], v[138:141], 0
	ds_read_b128 v[138:141], v151
	v_max_f32_e32 v146, 0, v23
	v_mov_b32_e32 v47, v54
	s_waitcnt lgkmcnt(0)
	v_mfma_f32_16x16x32_bf16 v[10:13], v[10:13], v[138:141], v[14:17]
	v_mov_b32_e32 v53, v55
	s_nop 1
	v_pk_fma_f32 v[16:17], v[24:25], v[26:27], 0 op_sel_hi:[0,1,0]
	v_mov_b32_e32 v24, v25
	v_pk_fma_f32 v[16:17], v[24:25], v[32:33], v[16:17] op_sel_hi:[0,1,1]
	v_pk_fma_f32 v[16:17], v[36:37], v[38:39], v[16:17] op_sel_hi:[0,1,1]
	v_mov_b32_e32 v24, v37
	v_pk_fma_f32 v[16:17], v[24:25], v[44:45], v[16:17] op_sel_hi:[0,1,1]
	v_pk_fma_f32 v[16:17], v[48:49], v[50:51], v[16:17] op_sel_hi:[0,1,1]
	v_mov_b32_e32 v24, v49
	v_pk_fma_f32 v[16:17], v[24:25], v[56:57], v[16:17] op_sel_hi:[0,1,1]
	v_max_f32_e32 v10, 0, v10
	v_max_f32_e32 v11, 0, v11
	v_pk_fma_f32 v[16:17], v[118:119], v[142:143], v[16:17] op_sel_hi:[0,1,1]
	v_mov_b32_e32 v24, v119
	v_pk_fma_f32 v[10:11], v[24:25], v[10:11], v[16:17] op_sel_hi:[0,1,1]
	v_and_b32_e32 v17, 0x7fffffff, v11
	v_and_b32_e32 v16, 0x7fffffff, v10
	v_max_f32_e32 v147, 0, v13
	v_xor_b32_e32 v23, -1, v10
	v_pk_add_f32 v[16:17], v[16:17], 0 neg_lo:[1,1] neg_hi:[1,1]
	v_cmp_gt_i32_e32 vcc, 0, v10
	v_pk_mul_f32 v[14:15], v[118:119], v[146:147]
	v_xor_b32_e32 v13, -1, v11
	v_cndmask_b32_e32 v118, v16, v23, vcc
	v_mov_b32_e32 v23, v30
	v_cmp_gt_i32_e64 s[2:3], 0, v11
	v_pk_add_f32 v[10:11], v[22:23], 0 op_sel_hi:[1,0]
	v_pk_add_f32 v[10:11], v[10:11], v[28:29]
	v_max_f32_e32 v12, 0, v12
	v_pk_add_f32 v[10:11], v[10:11], v[34:35]
	v_mov_b32_e32 v145, v14
	v_pk_add_f32 v[10:11], v[10:11], v[40:41]
	v_mul_f32_e32 v12, v119, v12
	v_pk_add_f32 v[10:11], v[10:11], v[46:47]
	v_cndmask_b32_e64 v117, v17, v13, s[2:3]
	v_pk_add_f32 v[10:11], v[10:11], v[52:53]
	v_mov_b32_e32 v13, v15
	v_pk_add_f32 v[10:11], v[10:11], v[144:145]
	s_nop 0
	v_pk_add_f32 v[10:11], v[10:11], v[12:13]
	s_nop 0
	v_xor_b32_e32 v15, -1, v10
	v_and_b32_e32 v12, 0x7fffffff, v10
	v_cmp_gt_i32_e32 vcc, 0, v10
	v_lshrrev_b32_e32 v10, 24, v118
	v_and_b32_e32 v13, 0x7fffffff, v11
	v_lshl_add_u32 v10, v10, 6, v0
	v_pk_add_f32 v[12:13], v[12:13], 0 neg_lo:[1,1] neg_hi:[1,1]
	ds_add_u32 v10, v205 offset:16384
	v_lshrrev_b32_e32 v10, 24, v117
	v_cndmask_b32_e32 v120, v12, v15, vcc
	v_lshl_add_u32 v10, v10, 6, v0
	v_xor_b32_e32 v14, -1, v11
	v_cmp_gt_i32_e64 s[2:3], 0, v11
	ds_add_u32 v10, v205 offset:16384
	v_lshrrev_b32_e32 v10, 24, v120
	v_cndmask_b32_e64 v119, v13, v14, s[2:3]
	v_lshl_add_u32 v10, v10, 6, v0
	ds_add_u32 v10, v205 offset:16384
	v_lshrrev_b32_e32 v10, 24, v119
	v_lshl_add_u32 v10, v10, 6, v0
	ds_add_u32 v10, v205 offset:16384
	ds_read_b128 v[10:13], v182
	ds_read_b128 v[14:17], v183
	ds_read_b128 v[22:25], v184
	ds_read_b128 v[26:29], v185
	ds_read2_b32 v[30:31], v137 offset0:80 offset1:96
	ds_read2_b32 v[38:39], v137 offset0:112 offset1:128
	s_waitcnt vmcnt(1) lgkmcnt(5)
; #define LAS __attribute__((address_space(3)))
; __device__ __forceinline__ unsigned fkey(float f) { const unsigned u = __float_as_uint(f); return (u & 0x80000000u) ? ~u : (u | 0x80000000u); }
; #define SEL_HADD(idx_) __hip_atomic_fetch_add(&hist[(idx_)], 1u, __ATOMIC_RELAXED, __HIP_MEMORY_SCOPE_WORKGROUP)
; __device__ __forceinline__ void sel_unit(LAS char* lds, int b, int u, const bf16_t* QI, const bf16_t* KIDX, const float* WIDX, unsigned long long* MASK) {
;     ...
;                 for (int ks = 0; ks < 2; ++ks) kf[kb][ks] = *(const bf16x8*)(KIDX + (rowbase + 64 * t + 32 * kh + 16 * kb + q16) * 64 + 32 * ks + 8 * kg);
; #pragma unroll
;             for (int kb = 0; kb < 2; ++kb) {
;                 f32x4 s = (f32x4){0.f, 0.f, 0.f, 0.f};
; #pragma unroll
;                 for (int hh = 0; hh < 8; ++hh) {
;                     f32x4 a = (f32x4){0.f, 0.f, 0.f, 0.f};
; #pragma unroll
;                     for (int ks = 0; ks < 2; ++ks) {
;                         const bf16x8 qv = *(const LAS bf16x8*)(lds + L_QI + q16 * 1024 + (((hh * 8 + 4 * ks + kg) ^ q16) << 4));
;                         a = __builtin_amdgcn_mfma_f32_16x16x32_bf16(kf[kb][ks], qv, a, 0, 0, 0);
;                     }
;                     const float wh = wl[hh * 16];
; #pragma unroll
;                     for (int i = 0; i < 4; ++i) s[i] += wh * fmaxf(a[i], 0.f);
;                 }
;                 u32x4 kk; kk.x = fkey(s[0]); kk.y = fkey(s[1]); kk.z = fkey(s[2]); kk.w = fkey(s[3]);
;                 sc[j][2 * kh + kb] = kk;
; #pragma unroll
;                 for (int i = 0; i < 4; ++i) SEL_HADD((kk[i] >> 24) * 16 + q16);
	v_mfma_f32_16x16x32_bf16 v[10:13], v[6:9], v[10:13], 0
	ds_read2_b32 v[50:51], v137 offset0:144 offset1:160
	s_waitcnt vmcnt(0) lgkmcnt(5)
	v_mfma_f32_16x16x32_bf16 v[10:13], v[2:5], v[14:17], v[10:13]
	ds_read_b128 v[14:17], v179
	s_waitcnt lgkmcnt(5)
	v_mfma_f32_16x16x32_bf16 v[22:25], v[6:9], v[22:25], 0
	s_nop 4
	v_max_f32_e32 v32, 0, v10
	v_max_f32_e32 v10, 0, v12
	v_max_f32_e32 v33, 0, v11
	s_waitcnt lgkmcnt(3)
	v_mul_f32_e32 v34, v30, v10
	v_max_f32_e32 v36, 0, v13
	v_mfma_f32_16x16x32_bf16 v[10:13], v[2:5], v[26:29], v[22:25]
	s_nop 2
	ds_read_b128 v[22:25], v180
	s_waitcnt lgkmcnt(1)
	v_mfma_f32_16x16x32_bf16 v[14:17], v[6:9], v[14:17], 0
	s_nop 1
	v_max_f32_e32 v26, 0, v10
	v_max_f32_e32 v27, 0, v11
	v_max_f32_e32 v10, 0, v12
	v_mul_f32_e32 v28, v31, v10
	v_max_f32_e32 v37, 0, v13
	s_waitcnt lgkmcnt(0)
	v_mfma_f32_16x16x32_bf16 v[10:13], v[2:5], v[22:25], v[14:17]
	ds_read_b128 v[22:25], v159
	ds_read2_b32 v[126:127], v137 offset0:176 offset1:192
	v_pk_mul_f32 v[36:37], v[30:31], v[36:37]
	ds_read_b128 v[14:17], v176
	s_waitcnt lgkmcnt(0)
	v_mfma_f32_16x16x32_bf16 v[14:17], v[6:9], v[14:17], 0
	s_nop 1
	v_max_f32_e32 v40, 0, v10
	v_max_f32_e32 v41, 0, v11
	v_max_f32_e32 v10, 0, v12
	v_mul_f32_e32 v42, v38, v10
	s_nop 0
	v_max_f32_e32 v44, 0, v13
	v_mfma_f32_16x16x32_bf16 v[10:13], v[2:5], v[22:25], v[14:17]
	ds_read_b128 v[22:25], v157
	v_mov_b32_e32 v35, v36
	v_mov_b32_e32 v29, v37
	ds_read_b128 v[14:17], v158
	s_waitcnt lgkmcnt(0)
	v_mfma_f32_16x16x32_bf16 v[14:17], v[6:9], v[14:17], 0
	s_nop 1
	v_max_f32_e32 v46, 0, v10
	v_max_f32_e32 v47, 0, v11
	v_max_f32_e32 v10, 0, v12
	v_mul_f32_e32 v48, v39, v10
	s_nop 0
	v_max_f32_e32 v45, 0, v13
	v_mfma_f32_16x16x32_bf16 v[10:13], v[2:5], v[22:25], v[14:17]
	ds_read_b128 v[22:25], v155
	v_pk_mul_f32 v[44:45], v[38:39], v[44:45]
	s_nop 0
	ds_read_b128 v[14:17], v156
	s_waitcnt lgkmcnt(0)
	v_mfma_f32_16x16x32_bf16 v[14:17], v[6:9], v[14:17], 0
	s_nop 1
	v_max_f32_e32 v52, 0, v10
	v_max_f32_e32 v53, 0, v11
	v_max_f32_e32 v10, 0, v12
	v_mul_f32_e32 v54, v50, v10
	s_nop 0
	v_max_f32_e32 v56, 0, v13
	v_mfma_f32_16x16x32_bf16 v[10:13], v[2:5], v[22:25], v[14:17]
	ds_read_b128 v[22:25], v153
	v_mov_b32_e32 v43, v44
	v_mov_b32_e32 v49, v45
	ds_read_b128 v[14:17], v154
	s_waitcnt lgkmcnt(0)
	v_mfma_f32_16x16x32_bf16 v[14:17], v[6:9], v[14:17], 0
	s_nop 1
	v_max_f32_e32 v122, 0, v10
	v_max_f32_e32 v123, 0, v11
	v_max_f32_e32 v10, 0, v12
	v_mul_f32_e32 v124, v51, v10
	s_nop 0
	v_max_f32_e32 v57, 0, v13
	v_mfma_f32_16x16x32_bf16 v[10:13], v[2:5], v[22:25], v[14:17]
	ds_read_b128 v[22:25], v151
	v_pk_mul_f32 v[56:57], v[50:51], v[56:57]
	s_nop 0
	ds_read_b128 v[14:17], v152
	s_waitcnt lgkmcnt(0)
	v_mfma_f32_16x16x32_bf16 v[6:9], v[6:9], v[14:17], 0
	s_nop 1
	s_nop 0
	v_max_f32_e32 v14, 0, v13
	s_nop 0
	v_mfma_f32_16x16x32_bf16 v[2:5], v[2:5], v[22:25], v[6:9]
	s_nop 0
	v_max_f32_e32 v10, 0, v10
	v_max_f32_e32 v11, 0, v11
	v_pk_fma_f32 v[8:9], v[30:31], v[32:33], 0 op_sel_hi:[0,1,0]
	s_nop 0
	s_nop 2
	v_max_f32_e32 v15, 0, v5
	v_pk_mul_f32 v[6:7], v[126:127], v[14:15]
	v_mov_b32_e32 v14, v31
	v_pk_fma_f32 v[8:9], v[14:15], v[26:27], v[8:9] op_sel_hi:[0,1,1]
	v_pk_fma_f32 v[8:9], v[38:39], v[40:41], v[8:9] op_sel_hi:[0,1,1]
	v_mov_b32_e32 v14, v39
	v_pk_fma_f32 v[8:9], v[14:15], v[46:47], v[8:9] op_sel_hi:[0,1,1]
	v_pk_fma_f32 v[8:9], v[50:51], v[52:53], v[8:9] op_sel_hi:[0,1,1]
	v_mov_b32_e32 v14, v51
	v_pk_fma_f32 v[8:9], v[14:15], v[122:123], v[8:9] op_sel_hi:[0,1,1]
	v_max_f32_e32 v2, 0, v2
	v_max_f32_e32 v3, 0, v3
	v_pk_fma_f32 v[8:9], v[126:127], v[10:11], v[8:9] op_sel_hi:[0,1,1]
	v_mov_b32_e32 v10, v127
	v_pk_fma_f32 v[2:3], v[10:11], v[2:3], v[8:9] op_sel_hi:[0,1,1]
	v_and_b32_e32 v9, 0x7fffffff, v3
	v_and_b32_e32 v8, 0x7fffffff, v2
	v_xor_b32_e32 v5, -1, v3
	v_pk_add_f32 v[8:9], v[8:9], 0 neg_lo:[1,1] neg_hi:[1,1]
	v_cmp_gt_i32_e32 vcc, 0, v3
	v_xor_b32_e32 v10, -1, v2
	v_mov_b32_e32 v55, v56
	v_cndmask_b32_e32 v121, v9, v5, vcc
	v_cmp_gt_i32_e32 vcc, 0, v2
	v_pk_add_f32 v[2:3], v[34:35], 0 op_sel_hi:[1,0]
	v_max_f32_e32 v12, 0, v12
	v_pk_add_f32 v[2:3], v[2:3], v[28:29]
	v_pk_add_f32 v[2:3], v[2:3], v[42:43]
	v_mov_b32_e32 v125, v57
	v_pk_add_f32 v[2:3], v[2:3], v[48:49]
	v_mul_f32_e32 v12, v126, v12
	v_pk_add_f32 v[2:3], v[2:3], v[54:55]
	v_max_f32_e32 v4, 0, v4
	v_pk_add_f32 v[2:3], v[2:3], v[124:125]
	v_mov_b32_e32 v13, v6
	v_mul_f32_e32 v4, v127, v4
	v_pk_add_f32 v[2:3], v[2:3], v[12:13]
	v_mov_b32_e32 v5, v7
	v_pk_add_f32 v[2:3], v[2:3], v[4:5]
	v_cndmask_b32_e32 v122, v8, v10, vcc
	v_and_b32_e32 v5, 0x7fffffff, v3
	v_and_b32_e32 v4, 0x7fffffff, v2
	v_xor_b32_e32 v6, -1, v3
	v_pk_add_f32 v[4:5], v[4:5], 0 neg_lo:[1,1] neg_hi:[1,1]
	v_cmp_gt_i32_e32 vcc, 0, v3
	v_xor_b32_e32 v7, -1, v2
	s_nop 0
	v_cndmask_b32_e32 v123, v5, v6, vcc
	v_cmp_gt_i32_e32 vcc, 0, v2
	v_lshrrev_b32_e32 v2, 24, v122
	v_lshl_add_u32 v2, v2, 6, v0
	ds_add_u32 v2, v205 offset:16384
	v_lshrrev_b32_e32 v2, 24, v121
	v_cndmask_b32_e32 v124, v4, v7, vcc
	v_lshl_add_u32 v2, v2, 6, v0
	ds_add_u32 v2, v205 offset:16384
	v_lshrrev_b32_e32 v2, 24, v124
	v_lshl_add_u32 v2, v2, 6, v0
	ds_add_u32 v2, v205 offset:16384
	v_lshrrev_b32_e32 v2, 24, v123
	v_lshl_add_u32 v2, v2, 6, v0
	ds_add_u32 v2, v205 offset:16384
; #define LAS __attribute__((address_space(3)))
; __device__ __forceinline__ unsigned fkey(float f) { const unsigned u = __float_as_uint(f); return (u & 0x80000000u) ? ~u : (u | 0x80000000u); }
; #define SEL_HADD(idx_) __hip_atomic_fetch_add(&hist[(idx_)], 1u, __ATOMIC_RELAXED, __HIP_MEMORY_SCOPE_WORKGROUP)
; __device__ __forceinline__ void sel_unit(LAS char* lds, int b, int u, const bf16_t* QI, const bf16_t* KIDX, const float* WIDX, unsigned long long* MASK) {
;     ...
;     for (int j = 0; j < 8; ++j) {
;         if (j < nj) {
;             int t = wid + 8 * j; asm volatile("" : "+s"(t));
; #pragma unroll
;             for (int kh = 0; kh < 2; ++kh) {
;             bf16x8 kf[2][2];
; #pragma unroll
;             for (int kb = 0; kb < 2; ++kb)
; #pragma unroll
;                 for (int ks = 0; ks < 2; ++ks) kf[kb][ks] = *(const bf16x8*)(KIDX + (rowbase + 64 * t + 32 * kh + 16 * kb + q16) * 64 + 32 * ks + 8 * kg);
; #pragma unroll
;             for (int kb = 0; kb < 2; ++kb) {
;                 f32x4 s = (f32x4){0.f, 0.f, 0.f, 0.f};
; #pragma unroll
;                 for (int hh = 0; hh < 8; ++hh) {
;                     f32x4 a = (f32x4){0.f, 0.f, 0.f, 0.f};
; #pragma unroll
;                     for (int ks = 0; ks < 2; ++ks) {
;                         const bf16x8 qv = *(const LAS bf16x8*)(lds + L_QI + q16 * 1024 + (((hh * 8 + 4 * ks + kg) ^ q16) << 4));
;                         a = __builtin_amdgcn_mfma_f32_16x16x32_bf16(kf[kb][ks], qv, a, 0, 0, 0);
;                     }
;                     const float wh = wl[hh * 16];
; #pragma unroll
;                     for (int i = 0; i < 4; ++i) s[i] += wh * fmaxf(a[i], 0.f);
;                 }
;                 u32x4 kk; kk.x = fkey(s[0]); kk.y = fkey(s[1]); kk.z = fkey(s[2]); kk.w = fkey(s[3]);
;                 sc[j][2 * kh + kb] = kk;
; #pragma unroll
;                 for (int i = 0; i < 4; ++i) SEL_HADD((kk[i] >> 24) * 16 + q16);
;                 __builtin_amdgcn_sched_barrier(0);
;             }
.LBB0_664:
	s_cmp_gt_i32 s4, 4
	s_cselect_b64 s[24:25], -1, 0
	s_cmp_lt_i32 s4, 5
	s_cbranch_scc1 .LBB0_666
	s_add_i32 s0, s46, 32
	s_lshl_b32 s0, s0, 6
	s_ashr_i32 s1, s0, 31
	v_lshl_add_u64 v[2:3], v[18:19], 0, s[0:1]
	v_lshlrev_b64 v[2:3], 7, v[2:3]
	v_lshl_add_u64 v[22:23], v[20:21], 0, v[2:3]
	global_load_dwordx4 v[14:17], v[22:23], off
	global_load_dwordx4 v[10:13], v[22:23], off offset:64
	ds_read_b128 v[2:5], v182
	ds_read_b128 v[6:9], v183
	ds_read_b128 v[24:27], v184
	ds_read_b128 v[28:31], v185
	ds_read_b128 v[32:35], v179
	ds_read_b128 v[36:39], v180
	ds_read_b128 v[40:43], v176
	ds_read_b128 v[44:47], v159
	ds_read_b128 v[48:51], v158
	ds_read_b128 v[52:55], v157
	ds_read_b128 v[126:129], v156
	ds_read_b128 v[130:133], v155
	s_waitcnt vmcnt(1) lgkmcnt(11)
	v_mfma_f32_16x16x32_bf16 v[2:5], v[14:17], v[2:5], 0
	s_waitcnt lgkmcnt(9)
	v_mfma_f32_16x16x32_bf16 v[24:27], v[14:17], v[24:27], 0
	s_waitcnt lgkmcnt(7)
	v_mfma_f32_16x16x32_bf16 v[32:35], v[14:17], v[32:35], 0
	s_waitcnt lgkmcnt(5)
	v_mfma_f32_16x16x32_bf16 v[40:43], v[14:17], v[40:43], 0
	s_waitcnt lgkmcnt(3)
	v_mfma_f32_16x16x32_bf16 v[48:51], v[14:17], v[48:51], 0
	s_waitcnt vmcnt(0)
	v_mfma_f32_16x16x32_bf16 v[160:163], v[10:13], v[6:9], v[2:5]
	v_mfma_f32_16x16x32_bf16 v[24:27], v[10:13], v[28:31], v[24:27]
	v_mfma_f32_16x16x32_bf16 v[28:31], v[10:13], v[36:39], v[32:35]
	v_mfma_f32_16x16x32_bf16 v[32:35], v[10:13], v[44:47], v[40:43]
	ds_read2_b32 v[44:45], v137 offset0:80 offset1:96
	ds_read2_b32 v[46:47], v137 offset0:112 offset1:128
	s_nop 3
	s_waitcnt lgkmcnt(4)
	v_mfma_f32_16x16x32_bf16 v[36:39], v[10:13], v[52:55], v[48:51]
	s_nop 0
	ds_read2_b32 v[48:49], v137 offset0:144 offset1:160
	global_load_dwordx4 v[6:9], v[22:23], off offset:2048
	global_load_dwordx4 v[2:5], v[22:23], off offset:2112
	s_waitcnt lgkmcnt(4)
	v_mfma_f32_16x16x32_bf16 v[126:129], v[14:17], v[126:129], 0
	s_nop 0
	v_max_f32_e32 v54, v24, v24
	s_nop 0
	s_waitcnt lgkmcnt(3)
	v_mfma_f32_16x16x32_bf16 v[40:43], v[10:13], v[130:133], v[126:129]
	v_max_f32_e32 v125, v39, v39
	v_max_f32_e32 v24, 0, v163
	v_max_f32_e32 v39, 0, v25
	v_max_f32_e32 v128, 0, v26
	v_max_f32_e32 v25, 0, v27
	v_max_f32_e32 v26, 0, v31
	v_max_f32_e32 v27, 0, v35
	v_max_f32_e32 v53, 0, v37
	s_waitcnt lgkmcnt(2)
	v_mul_f32_e32 v56, v45, v128
	v_pk_mul_f32 v[128:129], v[44:45], v[24:25]
	s_waitcnt lgkmcnt(1)
	v_pk_mul_f32 v[134:135], v[46:47], v[26:27]
	ds_read_b128 v[24:27], v154
	v_max_f32_e32 v126, v40, v40
	v_max_f32_e32 v40, 0, v28
	v_max_f32_e32 v28, 0, v30
	v_max_f32_e32 v127, v41, v41
	v_max_f32_e32 v41, 0, v29
	v_max_f32_e32 v29, 0, v34
	v_max_f32_e32 v30, 0, v38
	v_mul_f32_e32 v130, v46, v28
	v_max_f32_e32 v28, 0, v42
	v_max_f32_e32 v50, v160, v160
	v_max_f32_e32 v52, v162, v162
	v_mul_f32_e32 v132, v47, v29
	s_waitcnt lgkmcnt(1)
	v_mul_f32_e32 v160, v48, v30
	v_mul_f32_e32 v162, v49, v28
	ds_read_b128 v[28:31], v153
	s_waitcnt lgkmcnt(1)
	v_mfma_f32_16x16x32_bf16 v[24:27], v[14:17], v[24:27], 0
	s_waitcnt lgkmcnt(0)
	v_mfma_f32_16x16x32_bf16 v[24:27], v[10:13], v[28:31], v[24:27]
	ds_read_b128 v[28:31], v152
	v_max_f32_e32 v37, 0, v161
	v_max_f32_e32 v51, 0, v33
	v_max_f32_e32 v55, v36, v36
	v_max_f32_e32 v36, 0, v50
	v_max_f32_e32 v50, 0, v32
	v_max_f32_e32 v32, 0, v125
	v_max_f32_e32 v33, 0, v43
	v_pk_mul_f32 v[164:165], v[48:49], v[32:33]
	ds_read_b128 v[32:35], v151
	s_waitcnt lgkmcnt(1)
	v_mfma_f32_16x16x32_bf16 v[14:17], v[14:17], v[28:31], 0
	v_max_f32_e32 v42, 0, v52
	v_max_f32_e32 v38, 0, v54
	v_max_f32_e32 v52, 0, v55
	s_waitcnt lgkmcnt(0)
	v_mfma_f32_16x16x32_bf16 v[10:13], v[10:13], v[32:35], v[14:17]
	v_max_f32_e32 v54, 0, v126
	v_max_f32_e32 v55, 0, v127
	ds_read2_b32 v[126:127], v137 offset0:176 offset1:192
	s_nop 0
	v_max_f32_e32 v28, 0, v27
	s_nop 2
	v_max_f32_e32 v29, 0, v13
	s_waitcnt lgkmcnt(0)
	v_pk_mul_f32 v[14:15], v[126:127], v[28:29]
	v_pk_fma_f32 v[16:17], v[44:45], v[36:37], 0 op_sel_hi:[0,1,0]
	v_mov_b32_e32 v28, v45
	v_pk_fma_f32 v[16:17], v[28:29], v[38:39], v[16:17] op_sel_hi:[0,1,1]
	v_pk_fma_f32 v[16:17], v[46:47], v[40:41], v[16:17] op_sel_hi:[0,1,1]
	v_mov_b32_e32 v28, v47
	v_pk_fma_f32 v[16:17], v[28:29], v[50:51], v[16:17] op_sel_hi:[0,1,1]
	v_pk_fma_f32 v[16:17], v[48:49], v[52:53], v[16:17] op_sel_hi:[0,1,1]
	v_mov_b32_e32 v28, v49
	v_max_f32_e32 v24, 0, v24
	v_max_f32_e32 v25, 0, v25
	v_pk_fma_f32 v[16:17], v[28:29], v[54:55], v[16:17] op_sel_hi:[0,1,1]
	v_max_f32_e32 v10, 0, v10
	v_max_f32_e32 v11, 0, v11
	v_pk_fma_f32 v[16:17], v[126:127], v[24:25], v[16:17] op_sel_hi:[0,1,1]
	v_mov_b32_e32 v24, v127
	v_pk_fma_f32 v[10:11], v[24:25], v[10:11], v[16:17] op_sel_hi:[0,1,1]
	v_and_b32_e32 v17, 0x7fffffff, v11
	v_and_b32_e32 v16, 0x7fffffff, v10
	v_mul_f32_e32 v42, v44, v42
	v_xor_b32_e32 v13, -1, v11
	v_pk_add_f32 v[16:17], v[16:17], 0 neg_lo:[1,1] neg_hi:[1,1]
	v_cmp_gt_i32_e32 vcc, 0, v11
	v_mov_b32_e32 v43, v128
	v_xor_b32_e32 v24, -1, v10
	v_cndmask_b32_e32 v125, v17, v13, vcc
	v_cmp_gt_i32_e32 vcc, 0, v10
	v_pk_add_f32 v[10:11], v[42:43], 0 op_sel_hi:[1,0]
	v_mov_b32_e32 v57, v129
	v_pk_add_f32 v[10:11], v[10:11], v[56:57]
	v_mov_b32_e32 v131, v134
	v_pk_add_f32 v[10:11], v[10:11], v[130:131]
	v_mov_b32_e32 v133, v135
	v_pk_add_f32 v[10:11], v[10:11], v[132:133]
	v_mov_b32_e32 v161, v164
	v_max_f32_e32 v26, 0, v26
	v_pk_add_f32 v[10:11], v[10:11], v[160:161]
	v_mov_b32_e32 v163, v165
	v_mul_f32_e32 v26, v126, v26
	v_max_f32_e32 v12, 0, v12
	v_pk_add_f32 v[10:11], v[10:11], v[162:163]
	v_mov_b32_e32 v27, v14
	v_mul_f32_e32 v12, v127, v12
	v_pk_add_f32 v[10:11], v[10:11], v[26:27]
	v_mov_b32_e32 v13, v15
	v_pk_add_f32 v[10:11], v[10:11], v[12:13]
	v_cndmask_b32_e32 v126, v16, v24, vcc
	v_and_b32_e32 v13, 0x7fffffff, v11
	v_and_b32_e32 v12, 0x7fffffff, v10
	v_xor_b32_e32 v14, -1, v11
	v_pk_add_f32 v[12:13], v[12:13], 0 neg_lo:[1,1] neg_hi:[1,1]
	v_cmp_gt_i32_e32 vcc, 0, v11
	v_xor_b32_e32 v15, -1, v10
	s_nop 0
	v_cndmask_b32_e32 v127, v13, v14, vcc
	v_cmp_gt_i32_e32 vcc, 0, v10
	v_lshrrev_b32_e32 v10, 24, v126
	v_lshl_add_u32 v10, v10, 6, v0
	ds_add_u32 v10, v205 offset:16384
	v_lshrrev_b32_e32 v10, 24, v125
	v_cndmask_b32_e32 v128, v12, v15, vcc
	v_lshl_add_u32 v10, v10, 6, v0
	ds_add_u32 v10, v205 offset:16384
	v_lshrrev_b32_e32 v10, 24, v128
	v_lshl_add_u32 v10, v10, 6, v0
	ds_add_u32 v10, v205 offset:16384
	v_lshrrev_b32_e32 v10, 24, v127
	v_lshl_add_u32 v10, v10, 6, v0
	ds_add_u32 v10, v205 offset:16384
	ds_read_b128 v[10:13], v182
	ds_read_b128 v[14:17], v183
	ds_read_b128 v[24:27], v184
	ds_read_b128 v[28:31], v185
	ds_read2_b32 v[32:33], v137 offset0:80 offset1:96
	ds_read2_b32 v[40:41], v137 offset0:112 offset1:128
	s_waitcnt vmcnt(1) lgkmcnt(5)
; #define LAS __attribute__((address_space(3)))
; __device__ __forceinline__ unsigned fkey(float f) { const unsigned u = __float_as_uint(f); return (u & 0x80000000u) ? ~u : (u | 0x80000000u); }
; #define SEL_HADD(idx_) __hip_atomic_fetch_add(&hist[(idx_)], 1u, __ATOMIC_RELAXED, __HIP_MEMORY_SCOPE_WORKGROUP)
; __device__ __forceinline__ void sel_unit(LAS char* lds, int b, int u, const bf16_t* QI, const bf16_t* KIDX, const float* WIDX, unsigned long long* MASK) {
;     ...
;                 for (int ks = 0; ks < 2; ++ks) kf[kb][ks] = *(const bf16x8*)(KIDX + (rowbase + 64 * t + 32 * kh + 16 * kb + q16) * 64 + 32 * ks + 8 * kg);
; #pragma unroll
;             for (int kb = 0; kb < 2; ++kb) {
;                 f32x4 s = (f32x4){0.f, 0.f, 0.f, 0.f};
; #pragma unroll
;                 for (int hh = 0; hh < 8; ++hh) {
;                     f32x4 a = (f32x4){0.f, 0.f, 0.f, 0.f};
; #pragma unroll
;                     for (int ks = 0; ks < 2; ++ks) {
;                         const bf16x8 qv = *(const LAS bf16x8*)(lds + L_QI + q16 * 1024 + (((hh * 8 + 4 * ks + kg) ^ q16) << 4));
;                         a = __builtin_amdgcn_mfma_f32_16x16x32_bf16(kf[kb][ks], qv, a, 0, 0, 0);
;                     }
;                     const float wh = wl[hh * 16];
; #pragma unroll
;                     for (int i = 0; i < 4; ++i) s[i] += wh * fmaxf(a[i], 0.f);
;                 }
;                 u32x4 kk; kk.x = fkey(s[0]); kk.y = fkey(s[1]); kk.z = fkey(s[2]); kk.w = fkey(s[3]);
;                 sc[j][2 * kh + kb] = kk;
; #pragma unroll
;                 for (int i = 0; i < 4; ++i) SEL_HADD((kk[i] >> 24) * 16 + q16);
	v_mfma_f32_16x16x32_bf16 v[10:13], v[6:9], v[10:13], 0
	ds_read2_b32 v[52:53], v137 offset0:144 offset1:160
	s_waitcnt vmcnt(0) lgkmcnt(5)
	v_mfma_f32_16x16x32_bf16 v[10:13], v[2:5], v[14:17], v[10:13]
	ds_read_b128 v[14:17], v179
	s_waitcnt lgkmcnt(5)
	v_mfma_f32_16x16x32_bf16 v[24:27], v[6:9], v[24:27], 0
	s_nop 4
	v_max_f32_e32 v34, 0, v10
	v_max_f32_e32 v10, 0, v12
	v_max_f32_e32 v35, 0, v11
	s_waitcnt lgkmcnt(3)
	v_mul_f32_e32 v36, v32, v10
	v_max_f32_e32 v38, 0, v13
	v_mfma_f32_16x16x32_bf16 v[10:13], v[2:5], v[28:31], v[24:27]
	s_nop 2
	ds_read_b128 v[24:27], v180
	s_waitcnt lgkmcnt(1)
	v_mfma_f32_16x16x32_bf16 v[14:17], v[6:9], v[14:17], 0
	s_nop 1
	v_max_f32_e32 v28, 0, v10
	v_max_f32_e32 v29, 0, v11
	v_max_f32_e32 v10, 0, v12
	v_mul_f32_e32 v30, v33, v10
	v_max_f32_e32 v39, 0, v13
	s_waitcnt lgkmcnt(0)
	v_mfma_f32_16x16x32_bf16 v[10:13], v[2:5], v[24:27], v[14:17]
	ds_read_b128 v[24:27], v159
	v_pk_mul_f32 v[38:39], v[32:33], v[38:39]
	s_nop 0
	ds_read_b128 v[14:17], v176
	s_waitcnt lgkmcnt(0)
	v_mfma_f32_16x16x32_bf16 v[14:17], v[6:9], v[14:17], 0
	s_nop 1
	v_max_f32_e32 v42, 0, v10
	v_max_f32_e32 v43, 0, v11
	v_max_f32_e32 v10, 0, v12
	v_mul_f32_e32 v44, v40, v10
	s_nop 0
	v_max_f32_e32 v46, 0, v13
	v_mfma_f32_16x16x32_bf16 v[10:13], v[2:5], v[24:27], v[14:17]
	ds_read_b128 v[24:27], v157
	v_mov_b32_e32 v37, v38
	v_mov_b32_e32 v31, v39
	ds_read_b128 v[14:17], v158
	s_waitcnt lgkmcnt(0)
	v_mfma_f32_16x16x32_bf16 v[14:17], v[6:9], v[14:17], 0
	s_nop 1
	v_max_f32_e32 v48, 0, v10
	v_max_f32_e32 v49, 0, v11
	v_max_f32_e32 v10, 0, v12
	v_mul_f32_e32 v50, v41, v10
	s_nop 0
	v_max_f32_e32 v47, 0, v13
	v_mfma_f32_16x16x32_bf16 v[10:13], v[2:5], v[24:27], v[14:17]
	ds_read_b128 v[24:27], v155
	v_pk_mul_f32 v[46:47], v[40:41], v[46:47]
	s_nop 0
	ds_read_b128 v[14:17], v156
	s_waitcnt lgkmcnt(0)
	v_mfma_f32_16x16x32_bf16 v[14:17], v[6:9], v[14:17], 0
	s_nop 1
	v_max_f32_e32 v54, 0, v10
	v_max_f32_e32 v55, 0, v11
	v_max_f32_e32 v10, 0, v12
	v_mul_f32_e32 v56, v52, v10
	s_nop 0
	v_max_f32_e32 v130, 0, v13
	v_mfma_f32_16x16x32_bf16 v[10:13], v[2:5], v[24:27], v[14:17]
	ds_read_b128 v[24:27], v153
	v_mov_b32_e32 v45, v46
	v_mov_b32_e32 v51, v47
	ds_read_b128 v[14:17], v154
	s_waitcnt lgkmcnt(0)
	v_mfma_f32_16x16x32_bf16 v[14:17], v[6:9], v[14:17], 0
	s_nop 1
	v_max_f32_e32 v132, 0, v10
	v_max_f32_e32 v133, 0, v11
	v_max_f32_e32 v10, 0, v12
	v_mul_f32_e32 v134, v53, v10
	s_nop 0
	v_max_f32_e32 v131, 0, v13
	v_mfma_f32_16x16x32_bf16 v[10:13], v[2:5], v[24:27], v[14:17]
	ds_read_b128 v[24:27], v151
	v_pk_mul_f32 v[160:161], v[52:53], v[130:131]
	ds_read2_b32 v[130:131], v137 offset0:176 offset1:192
	ds_read_b128 v[14:17], v152
	s_waitcnt lgkmcnt(0)
	v_mfma_f32_16x16x32_bf16 v[6:9], v[6:9], v[14:17], 0
	s_nop 1
	s_nop 0
	v_max_f32_e32 v14, 0, v13
	s_nop 0
	v_mfma_f32_16x16x32_bf16 v[2:5], v[2:5], v[24:27], v[6:9]
	s_nop 0
	v_max_f32_e32 v10, 0, v10
	v_max_f32_e32 v11, 0, v11
	v_pk_fma_f32 v[8:9], v[32:33], v[34:35], 0 op_sel_hi:[0,1,0]
	s_nop 0
	s_nop 2
	v_max_f32_e32 v15, 0, v5
	v_pk_mul_f32 v[6:7], v[130:131], v[14:15]
	v_mov_b32_e32 v14, v33
	v_pk_fma_f32 v[8:9], v[14:15], v[28:29], v[8:9] op_sel_hi:[0,1,1]
	v_pk_fma_f32 v[8:9], v[40:41], v[42:43], v[8:9] op_sel_hi:[0,1,1]
	v_mov_b32_e32 v14, v41
	v_pk_fma_f32 v[8:9], v[14:15], v[48:49], v[8:9] op_sel_hi:[0,1,1]
	v_pk_fma_f32 v[8:9], v[52:53], v[54:55], v[8:9] op_sel_hi:[0,1,1]
	v_mov_b32_e32 v14, v53
	v_pk_fma_f32 v[8:9], v[14:15], v[132:133], v[8:9] op_sel_hi:[0,1,1]
	v_max_f32_e32 v2, 0, v2
	v_max_f32_e32 v3, 0, v3
	v_pk_fma_f32 v[8:9], v[130:131], v[10:11], v[8:9] op_sel_hi:[0,1,1]
	v_mov_b32_e32 v10, v131
	v_pk_fma_f32 v[2:3], v[10:11], v[2:3], v[8:9] op_sel_hi:[0,1,1]
	v_and_b32_e32 v9, 0x7fffffff, v3
	v_and_b32_e32 v8, 0x7fffffff, v2
	v_xor_b32_e32 v5, -1, v3
	v_pk_add_f32 v[8:9], v[8:9], 0 neg_lo:[1,1] neg_hi:[1,1]
	v_cmp_gt_i32_e32 vcc, 0, v3
	v_xor_b32_e32 v10, -1, v2
	v_mov_b32_e32 v57, v160
	v_cndmask_b32_e32 v129, v9, v5, vcc
	v_cmp_gt_i32_e32 vcc, 0, v2
	v_pk_add_f32 v[2:3], v[36:37], 0 op_sel_hi:[1,0]
	v_max_f32_e32 v12, 0, v12
	v_pk_add_f32 v[2:3], v[2:3], v[30:31]
	v_pk_add_f32 v[2:3], v[2:3], v[44:45]
	v_mov_b32_e32 v135, v161
	v_pk_add_f32 v[2:3], v[2:3], v[50:51]
	v_mul_f32_e32 v12, v130, v12
	v_pk_add_f32 v[2:3], v[2:3], v[56:57]
	v_max_f32_e32 v4, 0, v4
	v_pk_add_f32 v[2:3], v[2:3], v[134:135]
	v_mov_b32_e32 v13, v6
	v_mul_f32_e32 v4, v131, v4
	v_pk_add_f32 v[2:3], v[2:3], v[12:13]
	v_mov_b32_e32 v5, v7
	v_pk_add_f32 v[2:3], v[2:3], v[4:5]
	v_cndmask_b32_e32 v130, v8, v10, vcc
	v_and_b32_e32 v5, 0x7fffffff, v3
	v_and_b32_e32 v4, 0x7fffffff, v2
	v_xor_b32_e32 v6, -1, v3
	v_pk_add_f32 v[4:5], v[4:5], 0 neg_lo:[1,1] neg_hi:[1,1]
	v_cmp_gt_i32_e32 vcc, 0, v3
	v_xor_b32_e32 v7, -1, v2
	s_nop 0
	v_cndmask_b32_e32 v131, v5, v6, vcc
	v_cmp_gt_i32_e32 vcc, 0, v2
	v_lshrrev_b32_e32 v2, 24, v130
	v_lshl_add_u32 v2, v2, 6, v0
	ds_add_u32 v2, v205 offset:16384
	v_lshrrev_b32_e32 v2, 24, v129
	v_cndmask_b32_e32 v132, v4, v7, vcc
	v_lshl_add_u32 v2, v2, 6, v0
	ds_add_u32 v2, v205 offset:16384
	v_lshrrev_b32_e32 v2, 24, v132
	v_lshl_add_u32 v2, v2, 6, v0
	ds_add_u32 v2, v205 offset:16384
	v_lshrrev_b32_e32 v2, 24, v131
	v_lshl_add_u32 v2, v2, 6, v0
	ds_add_u32 v2, v205 offset:16384
	v_add_co_u32_e32 v2, vcc, s96, v22
	s_nop 1
	v_addc_co_u32_e32 v3, vcc, 0, v23, vcc
	global_load_dwordx4 v[14:17], v[2:3], off
	global_load_dwordx4 v[10:13], v[2:3], off offset:64
	global_load_dwordx4 v[6:9], v[2:3], off offset:2048
	s_nop 0
	global_load_dwordx4 v[2:5], v[2:3], off offset:2112
	ds_read_b128 v[22:25], v182
	ds_read_b128 v[26:29], v183
	s_waitcnt vmcnt(3) lgkmcnt(1)
; #define LAS __attribute__((address_space(3)))
; __device__ __forceinline__ unsigned fkey(float f) { const unsigned u = __float_as_uint(f); return (u & 0x80000000u) ? ~u : (u | 0x80000000u); }
; #define SEL_HADD(idx_) __hip_atomic_fetch_add(&hist[(idx_)], 1u, __ATOMIC_RELAXED, __HIP_MEMORY_SCOPE_WORKGROUP)
; __device__ __forceinline__ void sel_unit(LAS char* lds, int b, int u, const bf16_t* QI, const bf16_t* KIDX, const float* WIDX, unsigned long long* MASK) {
;     ...
;                 for (int ks = 0; ks < 2; ++ks) kf[kb][ks] = *(const bf16x8*)(KIDX + (rowbase + 64 * t + 32 * kh + 16 * kb + q16) * 64 + 32 * ks + 8 * kg);
; #pragma unroll
;             for (int kb = 0; kb < 2; ++kb) {
;                 f32x4 s = (f32x4){0.f, 0.f, 0.f, 0.f};
; #pragma unroll
;                 for (int hh = 0; hh < 8; ++hh) {
;                     f32x4 a = (f32x4){0.f, 0.f, 0.f, 0.f};
; #pragma unroll
;                     for (int ks = 0; ks < 2; ++ks) {
;                         const bf16x8 qv = *(const LAS bf16x8*)(lds + L_QI + q16 * 1024 + (((hh * 8 + 4 * ks + kg) ^ q16) << 4));
;                         a = __builtin_amdgcn_mfma_f32_16x16x32_bf16(kf[kb][ks], qv, a, 0, 0, 0);
;                     }
;                     const float wh = wl[hh * 16];
; #pragma unroll
;                     for (int i = 0; i < 4; ++i) s[i] += wh * fmaxf(a[i], 0.f);
;                 }
;                 u32x4 kk; kk.x = fkey(s[0]); kk.y = fkey(s[1]); kk.z = fkey(s[2]); kk.w = fkey(s[3]);
;                 sc[j][2 * kh + kb] = kk;
; #pragma unroll
;                 for (int i = 0; i < 4; ++i) SEL_HADD((kk[i] >> 24) * 16 + q16);
	v_mfma_f32_16x16x32_bf16 v[22:25], v[14:17], v[22:25], 0
	ds_read_b128 v[32:35], v185
	ds_read_b128 v[38:41], v180
	ds_read_b128 v[44:47], v159
	s_waitcnt vmcnt(2) lgkmcnt(3)
	v_mfma_f32_16x16x32_bf16 v[26:29], v[10:13], v[26:29], v[22:25]
	ds_read_b128 v[50:53], v157
	ds_read_b128 v[160:163], v155
	ds_read_b128 v[164:167], v153
	ds_read2_b32 v[24:25], v137 offset0:80 offset1:96
	s_nop 3
	v_max_f32_e32 v26, 0, v26
	v_max_f32_e32 v27, 0, v27
	v_max_f32_e32 v22, v28, v28
	v_max_f32_e32 v23, v29, v29
	ds_read_b128 v[28:31], v184
	s_waitcnt lgkmcnt(0)
	v_mfma_f32_16x16x32_bf16 v[28:31], v[14:17], v[28:31], 0
	v_max_f32_e32 v36, 0, v23
	v_max_f32_e32 v22, 0, v22
	v_mul_f32_e32 v22, v24, v22
	v_mfma_f32_16x16x32_bf16 v[28:31], v[10:13], v[32:35], v[28:31]
	s_nop 7
	v_max_f32_e32 v32, 0, v28
	v_max_f32_e32 v33, 0, v29
	v_max_f32_e32 v23, 0, v30
	v_mul_f32_e32 v28, v25, v23
	v_max_f32_e32 v37, 0, v31
	v_pk_mul_f32 v[30:31], v[24:25], v[36:37]
	ds_read_b128 v[34:37], v179
	s_waitcnt lgkmcnt(0)
	v_mfma_f32_16x16x32_bf16 v[34:37], v[14:17], v[34:37], 0
	v_mov_b32_e32 v29, v31
	v_mfma_f32_16x16x32_bf16 v[38:41], v[10:13], v[38:41], v[34:37]
	s_nop 5
	ds_read2_b32 v[36:37], v137 offset0:112 offset1:128
	s_nop 0
	v_max_f32_e32 v38, 0, v38
	v_max_f32_e32 v39, 0, v39
	v_max_f32_e32 v23, 0, v40
	s_waitcnt lgkmcnt(0)
	v_mul_f32_e32 v34, v36, v23
	v_max_f32_e32 v23, v41, v41
	ds_read_b128 v[40:43], v176
	s_waitcnt lgkmcnt(0)
	v_mfma_f32_16x16x32_bf16 v[40:43], v[14:17], v[40:43], 0
	v_max_f32_e32 v48, 0, v23
	v_mfma_f32_16x16x32_bf16 v[40:43], v[10:13], v[44:47], v[40:43]
	s_nop 7
	v_max_f32_e32 v44, 0, v40
	v_max_f32_e32 v45, 0, v41
	v_max_f32_e32 v23, 0, v42
	v_mul_f32_e32 v40, v37, v23
	v_max_f32_e32 v49, 0, v43
	v_pk_mul_f32 v[42:43], v[36:37], v[48:49]
	ds_read_b128 v[46:49], v158
	s_waitcnt lgkmcnt(0)
	v_mfma_f32_16x16x32_bf16 v[46:49], v[14:17], v[46:49], 0
	v_mov_b32_e32 v35, v42
	v_mov_b32_e32 v41, v43
	v_mfma_f32_16x16x32_bf16 v[50:53], v[10:13], v[50:53], v[46:49]
	s_nop 4
	ds_read2_b32 v[48:49], v137 offset0:144 offset1:160
	s_nop 1
	v_max_f32_e32 v50, 0, v50
	v_max_f32_e32 v51, 0, v51
	v_max_f32_e32 v23, 0, v52
	s_waitcnt lgkmcnt(0)
	v_mul_f32_e32 v46, v48, v23
	v_max_f32_e32 v23, v53, v53
	ds_read_b128 v[52:55], v156
	s_waitcnt lgkmcnt(0)
	v_mfma_f32_16x16x32_bf16 v[52:55], v[14:17], v[52:55], 0
	v_max_f32_e32 v134, 0, v23
	v_mfma_f32_16x16x32_bf16 v[52:55], v[10:13], v[160:163], v[52:55]
	ds_read_b128 v[160:163], v154
	s_waitcnt lgkmcnt(0)
	v_mfma_f32_16x16x32_bf16 v[160:163], v[14:17], v[160:163], 0
	s_nop 4
	v_max_f32_e32 v56, 0, v52
	v_max_f32_e32 v57, 0, v53
	v_max_f32_e32 v23, 0, v54
	v_mfma_f32_16x16x32_bf16 v[160:163], v[10:13], v[164:167], v[160:163]
	v_mul_f32_e32 v52, v49, v23
	s_nop 0
	v_max_f32_e32 v135, 0, v55
	v_pk_mul_f32 v[54:55], v[48:49], v[134:135]
	ds_read2_b32 v[134:135], v137 offset0:176 offset1:192
	s_nop 2
	v_max_f32_e32 v164, 0, v160
	v_max_f32_e32 v165, 0, v161
	v_max_f32_e32 v23, 0, v162
	s_waitcnt lgkmcnt(0)
	v_mul_f32_e32 v166, v134, v23
	v_max_f32_e32 v23, v163, v163
	ds_read_b128 v[160:163], v152
	s_waitcnt lgkmcnt(0)
	v_mfma_f32_16x16x32_bf16 v[14:17], v[14:17], v[160:163], 0
	ds_read_b128 v[160:163], v151
	v_max_f32_e32 v168, 0, v23
	v_mov_b32_e32 v47, v54
	s_waitcnt lgkmcnt(0)
	v_mfma_f32_16x16x32_bf16 v[10:13], v[10:13], v[160:163], v[14:17]
	v_mov_b32_e32 v53, v55
	s_nop 1
	v_pk_fma_f32 v[16:17], v[24:25], v[26:27], 0 op_sel_hi:[0,1,0]
	v_mov_b32_e32 v24, v25
	v_pk_fma_f32 v[16:17], v[24:25], v[32:33], v[16:17] op_sel_hi:[0,1,1]
	v_pk_fma_f32 v[16:17], v[36:37], v[38:39], v[16:17] op_sel_hi:[0,1,1]
	v_mov_b32_e32 v24, v37
	v_pk_fma_f32 v[16:17], v[24:25], v[44:45], v[16:17] op_sel_hi:[0,1,1]
	v_pk_fma_f32 v[16:17], v[48:49], v[50:51], v[16:17] op_sel_hi:[0,1,1]
	v_mov_b32_e32 v24, v49
	v_pk_fma_f32 v[16:17], v[24:25], v[56:57], v[16:17] op_sel_hi:[0,1,1]
	v_max_f32_e32 v10, 0, v10
	v_max_f32_e32 v11, 0, v11
	v_pk_fma_f32 v[16:17], v[134:135], v[164:165], v[16:17] op_sel_hi:[0,1,1]
	v_mov_b32_e32 v24, v135
	v_pk_fma_f32 v[10:11], v[24:25], v[10:11], v[16:17] op_sel_hi:[0,1,1]
	v_and_b32_e32 v17, 0x7fffffff, v11
	v_and_b32_e32 v16, 0x7fffffff, v10
	v_max_f32_e32 v169, 0, v13
	v_xor_b32_e32 v23, -1, v10
	v_pk_add_f32 v[16:17], v[16:17], 0 neg_lo:[1,1] neg_hi:[1,1]
	v_cmp_gt_i32_e32 vcc, 0, v10
	v_pk_mul_f32 v[14:15], v[134:135], v[168:169]
	v_xor_b32_e32 v13, -1, v11
	v_cndmask_b32_e32 v134, v16, v23, vcc
	v_mov_b32_e32 v23, v30
	v_cmp_gt_i32_e64 s[2:3], 0, v11
	v_pk_add_f32 v[10:11], v[22:23], 0 op_sel_hi:[1,0]
	v_pk_add_f32 v[10:11], v[10:11], v[28:29]
	v_max_f32_e32 v12, 0, v12
	v_pk_add_f32 v[10:11], v[10:11], v[34:35]
	v_mov_b32_e32 v167, v14
	v_pk_add_f32 v[10:11], v[10:11], v[40:41]
	v_mul_f32_e32 v12, v135, v12
	v_pk_add_f32 v[10:11], v[10:11], v[46:47]
	v_cndmask_b32_e64 v133, v17, v13, s[2:3]
	v_pk_add_f32 v[10:11], v[10:11], v[52:53]
	v_mov_b32_e32 v13, v15
	v_pk_add_f32 v[10:11], v[10:11], v[166:167]
	s_nop 0
	v_pk_add_f32 v[10:11], v[10:11], v[12:13]
	s_nop 0
	v_xor_b32_e32 v15, -1, v10
	v_and_b32_e32 v12, 0x7fffffff, v10
	v_cmp_gt_i32_e32 vcc, 0, v10
	v_lshrrev_b32_e32 v10, 24, v134
	v_and_b32_e32 v13, 0x7fffffff, v11
	v_lshl_add_u32 v10, v10, 6, v0
	v_pk_add_f32 v[12:13], v[12:13], 0 neg_lo:[1,1] neg_hi:[1,1]
	ds_add_u32 v10, v205 offset:16384
	v_lshrrev_b32_e32 v10, 24, v133
	v_cndmask_b32_e32 v136, v12, v15, vcc
	v_lshl_add_u32 v10, v10, 6, v0
	v_xor_b32_e32 v14, -1, v11
	v_cmp_gt_i32_e64 s[2:3], 0, v11
	ds_add_u32 v10, v205 offset:16384
	v_lshrrev_b32_e32 v10, 24, v136
	v_cndmask_b32_e64 v135, v13, v14, s[2:3]
	v_lshl_add_u32 v10, v10, 6, v0
	ds_add_u32 v10, v205 offset:16384
	v_lshrrev_b32_e32 v10, 24, v135
	v_lshl_add_u32 v10, v10, 6, v0
	ds_add_u32 v10, v205 offset:16384
	ds_read_b128 v[10:13], v182
	ds_read_b128 v[14:17], v183
	ds_read_b128 v[22:25], v184
	ds_read_b128 v[26:29], v185
	ds_read2_b32 v[30:31], v137 offset0:80 offset1:96
	ds_read2_b32 v[38:39], v137 offset0:112 offset1:128
	s_waitcnt vmcnt(1) lgkmcnt(5)
; #define LAS __attribute__((address_space(3)))
; __device__ __forceinline__ unsigned fkey(float f) { const unsigned u = __float_as_uint(f); return (u & 0x80000000u) ? ~u : (u | 0x80000000u); }
; #define SEL_HADD(idx_) __hip_atomic_fetch_add(&hist[(idx_)], 1u, __ATOMIC_RELAXED, __HIP_MEMORY_SCOPE_WORKGROUP)
; __device__ __forceinline__ void sel_unit(LAS char* lds, int b, int u, const bf16_t* QI, const bf16_t* KIDX, const float* WIDX, unsigned long long* MASK) {
;     ...
;                 for (int ks = 0; ks < 2; ++ks) kf[kb][ks] = *(const bf16x8*)(KIDX + (rowbase + 64 * t + 32 * kh + 16 * kb + q16) * 64 + 32 * ks + 8 * kg);
; #pragma unroll
;             for (int kb = 0; kb < 2; ++kb) {
;                 f32x4 s = (f32x4){0.f, 0.f, 0.f, 0.f};
; #pragma unroll
;                 for (int hh = 0; hh < 8; ++hh) {
;                     f32x4 a = (f32x4){0.f, 0.f, 0.f, 0.f};
; #pragma unroll
;                     for (int ks = 0; ks < 2; ++ks) {
;                         const bf16x8 qv = *(const LAS bf16x8*)(lds + L_QI + q16 * 1024 + (((hh * 8 + 4 * ks + kg) ^ q16) << 4));
;                         a = __builtin_amdgcn_mfma_f32_16x16x32_bf16(kf[kb][ks], qv, a, 0, 0, 0);
;                     }
;                     const float wh = wl[hh * 16];
; #pragma unroll
;                     for (int i = 0; i < 4; ++i) s[i] += wh * fmaxf(a[i], 0.f);
;                 }
;                 u32x4 kk; kk.x = fkey(s[0]); kk.y = fkey(s[1]); kk.z = fkey(s[2]); kk.w = fkey(s[3]);
;                 sc[j][2 * kh + kb] = kk;
; #pragma unroll
;                 for (int i = 0; i < 4; ++i) SEL_HADD((kk[i] >> 24) * 16 + q16);
	v_mfma_f32_16x16x32_bf16 v[10:13], v[6:9], v[10:13], 0
	ds_read2_b32 v[50:51], v137 offset0:144 offset1:160
	s_waitcnt vmcnt(0) lgkmcnt(5)
	v_mfma_f32_16x16x32_bf16 v[10:13], v[2:5], v[14:17], v[10:13]
	ds_read_b128 v[14:17], v179
	s_waitcnt lgkmcnt(5)
	v_mfma_f32_16x16x32_bf16 v[22:25], v[6:9], v[22:25], 0
	s_nop 4
	v_max_f32_e32 v32, 0, v10
	v_max_f32_e32 v10, 0, v12
	v_max_f32_e32 v33, 0, v11
	s_waitcnt lgkmcnt(3)
	v_mul_f32_e32 v34, v30, v10
	v_max_f32_e32 v36, 0, v13
	v_mfma_f32_16x16x32_bf16 v[10:13], v[2:5], v[26:29], v[22:25]
	s_nop 2
	ds_read_b128 v[22:25], v180
	s_waitcnt lgkmcnt(1)
	v_mfma_f32_16x16x32_bf16 v[14:17], v[6:9], v[14:17], 0
	s_nop 1
	v_max_f32_e32 v26, 0, v10
	v_max_f32_e32 v27, 0, v11
	v_max_f32_e32 v10, 0, v12
	v_mul_f32_e32 v28, v31, v10
	v_max_f32_e32 v37, 0, v13
	s_waitcnt lgkmcnt(0)
	v_mfma_f32_16x16x32_bf16 v[10:13], v[2:5], v[22:25], v[14:17]
	ds_read_b128 v[22:25], v159
	ds_read2_b32 v[142:143], v137 offset0:176 offset1:192
	v_pk_mul_f32 v[36:37], v[30:31], v[36:37]
	ds_read_b128 v[14:17], v176
	s_waitcnt lgkmcnt(0)
	v_mfma_f32_16x16x32_bf16 v[14:17], v[6:9], v[14:17], 0
	s_nop 1
	v_max_f32_e32 v40, 0, v10
	v_max_f32_e32 v41, 0, v11
	v_max_f32_e32 v10, 0, v12
	v_mul_f32_e32 v42, v38, v10
	s_nop 0
	v_max_f32_e32 v44, 0, v13
	v_mfma_f32_16x16x32_bf16 v[10:13], v[2:5], v[22:25], v[14:17]
	ds_read_b128 v[22:25], v157
	v_mov_b32_e32 v35, v36
	v_mov_b32_e32 v29, v37
	ds_read_b128 v[14:17], v158
	s_waitcnt lgkmcnt(0)
	v_mfma_f32_16x16x32_bf16 v[14:17], v[6:9], v[14:17], 0
	s_nop 1
	v_max_f32_e32 v46, 0, v10
	v_max_f32_e32 v47, 0, v11
	v_max_f32_e32 v10, 0, v12
	v_mul_f32_e32 v48, v39, v10
	s_nop 0
	v_max_f32_e32 v45, 0, v13
	v_mfma_f32_16x16x32_bf16 v[10:13], v[2:5], v[22:25], v[14:17]
	ds_read_b128 v[22:25], v155
	v_pk_mul_f32 v[44:45], v[38:39], v[44:45]
	s_nop 0
	ds_read_b128 v[14:17], v156
	s_waitcnt lgkmcnt(0)
	v_mfma_f32_16x16x32_bf16 v[14:17], v[6:9], v[14:17], 0
	s_nop 1
	v_max_f32_e32 v52, 0, v10
	v_max_f32_e32 v53, 0, v11
	v_max_f32_e32 v10, 0, v12
	v_mul_f32_e32 v54, v50, v10
	s_nop 0
	v_max_f32_e32 v56, 0, v13
	v_mfma_f32_16x16x32_bf16 v[10:13], v[2:5], v[22:25], v[14:17]
	ds_read_b128 v[22:25], v153
	v_mov_b32_e32 v43, v44
	v_mov_b32_e32 v49, v45
	ds_read_b128 v[14:17], v154
	s_waitcnt lgkmcnt(0)
	v_mfma_f32_16x16x32_bf16 v[14:17], v[6:9], v[14:17], 0
	s_nop 1
	v_max_f32_e32 v138, 0, v10
	v_max_f32_e32 v139, 0, v11
	v_max_f32_e32 v10, 0, v12
	v_mul_f32_e32 v140, v51, v10
	s_nop 0
	v_max_f32_e32 v57, 0, v13
	v_mfma_f32_16x16x32_bf16 v[10:13], v[2:5], v[22:25], v[14:17]
	ds_read_b128 v[22:25], v151
	v_pk_mul_f32 v[56:57], v[50:51], v[56:57]
	s_nop 0
	ds_read_b128 v[14:17], v152
	s_waitcnt lgkmcnt(0)
	v_mfma_f32_16x16x32_bf16 v[6:9], v[6:9], v[14:17], 0
	s_nop 1
	s_nop 0
	v_max_f32_e32 v14, 0, v13
	s_nop 0
	v_mfma_f32_16x16x32_bf16 v[2:5], v[2:5], v[22:25], v[6:9]
	s_nop 0
	v_max_f32_e32 v10, 0, v10
	v_max_f32_e32 v11, 0, v11
	v_pk_fma_f32 v[8:9], v[30:31], v[32:33], 0 op_sel_hi:[0,1,0]
	s_nop 0
	s_nop 2
	v_max_f32_e32 v15, 0, v5
	v_pk_mul_f32 v[6:7], v[142:143], v[14:15]
	v_mov_b32_e32 v14, v31
	v_pk_fma_f32 v[8:9], v[14:15], v[26:27], v[8:9] op_sel_hi:[0,1,1]
	v_pk_fma_f32 v[8:9], v[38:39], v[40:41], v[8:9] op_sel_hi:[0,1,1]
	v_mov_b32_e32 v14, v39
	v_pk_fma_f32 v[8:9], v[14:15], v[46:47], v[8:9] op_sel_hi:[0,1,1]
	v_pk_fma_f32 v[8:9], v[50:51], v[52:53], v[8:9] op_sel_hi:[0,1,1]
	v_mov_b32_e32 v14, v51
	v_pk_fma_f32 v[8:9], v[14:15], v[138:139], v[8:9] op_sel_hi:[0,1,1]
	v_max_f32_e32 v2, 0, v2
	v_max_f32_e32 v3, 0, v3
	v_pk_fma_f32 v[8:9], v[142:143], v[10:11], v[8:9] op_sel_hi:[0,1,1]
	v_mov_b32_e32 v10, v143
	v_pk_fma_f32 v[2:3], v[10:11], v[2:3], v[8:9] op_sel_hi:[0,1,1]
	v_and_b32_e32 v9, 0x7fffffff, v3
	v_and_b32_e32 v8, 0x7fffffff, v2
	v_xor_b32_e32 v5, -1, v3
	v_pk_add_f32 v[8:9], v[8:9], 0 neg_lo:[1,1] neg_hi:[1,1]
	v_cmp_gt_i32_e32 vcc, 0, v3
	v_xor_b32_e32 v10, -1, v2
	v_mov_b32_e32 v55, v56
	v_cndmask_b32_e32 v138, v9, v5, vcc
	v_cmp_gt_i32_e32 vcc, 0, v2
	v_pk_add_f32 v[2:3], v[34:35], 0 op_sel_hi:[1,0]
	v_max_f32_e32 v12, 0, v12
	v_pk_add_f32 v[2:3], v[2:3], v[28:29]
	v_pk_add_f32 v[2:3], v[2:3], v[42:43]
	v_mov_b32_e32 v141, v57
	v_pk_add_f32 v[2:3], v[2:3], v[48:49]
	v_mul_f32_e32 v12, v142, v12
	v_pk_add_f32 v[2:3], v[2:3], v[54:55]
	v_max_f32_e32 v4, 0, v4
	v_pk_add_f32 v[2:3], v[2:3], v[140:141]
	v_mov_b32_e32 v13, v6
	v_mul_f32_e32 v4, v143, v4
	v_pk_add_f32 v[2:3], v[2:3], v[12:13]
	v_mov_b32_e32 v5, v7
	v_pk_add_f32 v[2:3], v[2:3], v[4:5]
	v_cndmask_b32_e32 v139, v8, v10, vcc
	v_and_b32_e32 v5, 0x7fffffff, v3
	v_and_b32_e32 v4, 0x7fffffff, v2
	v_xor_b32_e32 v6, -1, v3
	v_pk_add_f32 v[4:5], v[4:5], 0 neg_lo:[1,1] neg_hi:[1,1]
	v_cmp_gt_i32_e32 vcc, 0, v3
	v_xor_b32_e32 v7, -1, v2
	s_nop 0
	v_cndmask_b32_e32 v140, v5, v6, vcc
	v_cmp_gt_i32_e32 vcc, 0, v2
	v_lshrrev_b32_e32 v2, 24, v139
	v_lshl_add_u32 v2, v2, 6, v0
	ds_add_u32 v2, v205 offset:16384
	v_lshrrev_b32_e32 v2, 24, v138
	v_cndmask_b32_e32 v141, v4, v7, vcc
	v_lshl_add_u32 v2, v2, 6, v0
	ds_add_u32 v2, v205 offset:16384
	v_lshrrev_b32_e32 v2, 24, v141
	v_lshl_add_u32 v2, v2, 6, v0
	ds_add_u32 v2, v205 offset:16384
	v_lshrrev_b32_e32 v2, 24, v140
	v_lshl_add_u32 v2, v2, 6, v0
	ds_add_u32 v2, v205 offset:16384
; #define LAS __attribute__((address_space(3)))
; __device__ __forceinline__ unsigned fkey(float f) { const unsigned u = __float_as_uint(f); return (u & 0x80000000u) ? ~u : (u | 0x80000000u); }
; #define SEL_HADD(idx_) __hip_atomic_fetch_add(&hist[(idx_)], 1u, __ATOMIC_RELAXED, __HIP_MEMORY_SCOPE_WORKGROUP)
; __device__ __forceinline__ void sel_unit(LAS char* lds, int b, int u, const bf16_t* QI, const bf16_t* KIDX, const float* WIDX, unsigned long long* MASK) {
;     ...
;     for (int j = 0; j < 8; ++j) {
;         if (j < nj) {
;             int t = wid + 8 * j; asm volatile("" : "+s"(t));
; #pragma unroll
;             for (int kh = 0; kh < 2; ++kh) {
;             bf16x8 kf[2][2];
; #pragma unroll
;             for (int kb = 0; kb < 2; ++kb)
; #pragma unroll
;                 for (int ks = 0; ks < 2; ++ks) kf[kb][ks] = *(const bf16x8*)(KIDX + (rowbase + 64 * t + 32 * kh + 16 * kb + q16) * 64 + 32 * ks + 8 * kg);
; #pragma unroll
;             for (int kb = 0; kb < 2; ++kb) {
;                 f32x4 s = (f32x4){0.f, 0.f, 0.f, 0.f};
; #pragma unroll
;                 for (int hh = 0; hh < 8; ++hh) {
;                     f32x4 a = (f32x4){0.f, 0.f, 0.f, 0.f};
; #pragma unroll
;                     for (int ks = 0; ks < 2; ++ks) {
;                         const bf16x8 qv = *(const LAS bf16x8*)(lds + L_QI + q16 * 1024 + (((hh * 8 + 4 * ks + kg) ^ q16) << 4));
;                         a = __builtin_amdgcn_mfma_f32_16x16x32_bf16(kf[kb][ks], qv, a, 0, 0, 0);
;                     }
;                     const float wh = wl[hh * 16];
; #pragma unroll
;                     for (int i = 0; i < 4; ++i) s[i] += wh * fmaxf(a[i], 0.f);
;                 }
;                 u32x4 kk; kk.x = fkey(s[0]); kk.y = fkey(s[1]); kk.z = fkey(s[2]); kk.w = fkey(s[3]);
;                 sc[j][2 * kh + kb] = kk;
; #pragma unroll
;                 for (int i = 0; i < 4; ++i) SEL_HADD((kk[i] >> 24) * 16 + q16);
;                 __builtin_amdgcn_sched_barrier(0);
;             }
.LBB0_666:
	s_cmp_gt_i32 s4, 5
	s_cselect_b64 s[48:49], -1, 0
	s_cmp_lt_i32 s4, 6
	s_cbranch_scc1 .LBB0_668
	s_add_i32 s0, s46, 40
	s_lshl_b32 s0, s0, 6
	s_ashr_i32 s1, s0, 31
	v_lshl_add_u64 v[2:3], v[18:19], 0, s[0:1]
	v_lshlrev_b64 v[2:3], 7, v[2:3]
	v_lshl_add_u64 v[22:23], v[20:21], 0, v[2:3]
	global_load_dwordx4 v[14:17], v[22:23], off
	global_load_dwordx4 v[10:13], v[22:23], off offset:64
	ds_read_b128 v[2:5], v182
	ds_read_b128 v[6:9], v183
	ds_read_b128 v[24:27], v184
	ds_read_b128 v[28:31], v185
	ds_read_b128 v[32:35], v179
	ds_read_b128 v[36:39], v180
	ds_read_b128 v[40:43], v176
	ds_read_b128 v[44:47], v159
	ds_read_b128 v[48:51], v158
	ds_read_b128 v[52:55], v157
	ds_read_b128 v[142:145], v156
	ds_read_b128 v[146:149], v155
	s_waitcnt vmcnt(1) lgkmcnt(11)
	v_mfma_f32_16x16x32_bf16 v[2:5], v[14:17], v[2:5], 0
	s_waitcnt lgkmcnt(9)
	v_mfma_f32_16x16x32_bf16 v[24:27], v[14:17], v[24:27], 0
	s_waitcnt lgkmcnt(7)
	v_mfma_f32_16x16x32_bf16 v[32:35], v[14:17], v[32:35], 0
	s_waitcnt lgkmcnt(5)
	v_mfma_f32_16x16x32_bf16 v[40:43], v[14:17], v[40:43], 0
	s_waitcnt lgkmcnt(3)
	v_mfma_f32_16x16x32_bf16 v[48:51], v[14:17], v[48:51], 0
	s_waitcnt vmcnt(0)
	v_mfma_f32_16x16x32_bf16 v[160:163], v[10:13], v[6:9], v[2:5]
	v_mfma_f32_16x16x32_bf16 v[24:27], v[10:13], v[28:31], v[24:27]
	v_mfma_f32_16x16x32_bf16 v[28:31], v[10:13], v[36:39], v[32:35]
	v_mfma_f32_16x16x32_bf16 v[32:35], v[10:13], v[44:47], v[40:43]
	ds_read2_b32 v[44:45], v137 offset0:80 offset1:96
	ds_read2_b32 v[46:47], v137 offset0:112 offset1:128
	s_nop 3
	s_waitcnt lgkmcnt(4)
	v_mfma_f32_16x16x32_bf16 v[36:39], v[10:13], v[52:55], v[48:51]
	ds_read2_b32 v[48:49], v137 offset0:144 offset1:160
	global_load_dwordx4 v[6:9], v[22:23], off offset:2048
	global_load_dwordx4 v[2:5], v[22:23], off offset:2112
	s_waitcnt lgkmcnt(4)
	v_mfma_f32_16x16x32_bf16 v[142:145], v[14:17], v[142:145], 0
	s_nop 0
	s_nop 0
	v_max_f32_e32 v54, v24, v24
	s_waitcnt lgkmcnt(3)
	v_mfma_f32_16x16x32_bf16 v[40:43], v[10:13], v[146:149], v[142:145]
	s_nop 0
	s_nop 0
	v_max_f32_e32 v24, 0, v163
	v_max_f32_e32 v142, v39, v39
	v_max_f32_e32 v39, 0, v25
	s_nop 2
	v_max_f32_e32 v145, 0, v26
	v_max_f32_e32 v25, 0, v27
	v_max_f32_e32 v26, 0, v31
	v_max_f32_e32 v27, 0, v35
	v_max_f32_e32 v50, v160, v160
	v_max_f32_e32 v51, v161, v161
	v_max_f32_e32 v147, v42, v42
	v_max_f32_e32 v42, 0, v162
	v_max_f32_e32 v52, 0, v36
	v_max_f32_e32 v53, 0, v37
	v_max_f32_e32 v55, 0, v41
	s_waitcnt lgkmcnt(2)
	v_mul_f32_e32 v56, v45, v145
	v_pk_mul_f32 v[144:145], v[44:45], v[24:25]
	s_waitcnt lgkmcnt(1)
	v_pk_mul_f32 v[160:161], v[46:47], v[26:27]
	ds_read_b128 v[24:27], v154
	v_max_f32_e32 v143, v40, v40
	v_max_f32_e32 v40, 0, v28
	v_max_f32_e32 v28, 0, v30
	v_max_f32_e32 v41, 0, v29
	v_max_f32_e32 v29, 0, v34
	v_max_f32_e32 v30, 0, v38
	v_mul_f32_e32 v146, v46, v28
	v_max_f32_e32 v28, 0, v147
	v_mul_f32_e32 v148, v47, v29
	s_waitcnt lgkmcnt(1)
	v_mul_f32_e32 v162, v48, v30
	v_mul_f32_e32 v164, v49, v28
	ds_read_b128 v[28:31], v153
	s_waitcnt lgkmcnt(1)
	v_mfma_f32_16x16x32_bf16 v[24:27], v[14:17], v[24:27], 0
	v_max_f32_e32 v37, 0, v51
	s_waitcnt lgkmcnt(0)
	v_mfma_f32_16x16x32_bf16 v[24:27], v[10:13], v[28:31], v[24:27]
	ds_read_b128 v[28:31], v152
	v_max_f32_e32 v51, 0, v33
	v_max_f32_e32 v36, 0, v50
	v_max_f32_e32 v50, 0, v32
	v_max_f32_e32 v32, 0, v142
	v_max_f32_e32 v33, 0, v43
	v_pk_mul_f32 v[166:167], v[48:49], v[32:33]
	ds_read_b128 v[32:35], v151
	s_waitcnt lgkmcnt(1)
	v_mfma_f32_16x16x32_bf16 v[14:17], v[14:17], v[28:31], 0
	v_max_f32_e32 v38, 0, v54
	v_max_f32_e32 v54, 0, v143
	ds_read2_b32 v[142:143], v137 offset0:176 offset1:192
	s_waitcnt lgkmcnt(1)
	v_mfma_f32_16x16x32_bf16 v[10:13], v[10:13], v[32:35], v[14:17]
	s_nop 0
	v_max_f32_e32 v28, 0, v27
	s_nop 0
	v_pk_fma_f32 v[16:17], v[44:45], v[36:37], 0 op_sel_hi:[0,1,0]
	s_nop 0
	s_nop 2
	v_max_f32_e32 v29, 0, v13
	s_waitcnt lgkmcnt(0)
	v_pk_mul_f32 v[14:15], v[142:143], v[28:29]
	v_mov_b32_e32 v28, v45
	v_pk_fma_f32 v[16:17], v[28:29], v[38:39], v[16:17] op_sel_hi:[0,1,1]
	v_pk_fma_f32 v[16:17], v[46:47], v[40:41], v[16:17] op_sel_hi:[0,1,1]
	v_mov_b32_e32 v28, v47
	v_pk_fma_f32 v[16:17], v[28:29], v[50:51], v[16:17] op_sel_hi:[0,1,1]
	v_pk_fma_f32 v[16:17], v[48:49], v[52:53], v[16:17] op_sel_hi:[0,1,1]
	v_mov_b32_e32 v28, v49
	v_max_f32_e32 v24, 0, v24
	v_max_f32_e32 v25, 0, v25
	v_pk_fma_f32 v[16:17], v[28:29], v[54:55], v[16:17] op_sel_hi:[0,1,1]
	v_max_f32_e32 v10, 0, v10
	v_max_f32_e32 v11, 0, v11
	v_pk_fma_f32 v[16:17], v[142:143], v[24:25], v[16:17] op_sel_hi:[0,1,1]
	v_mov_b32_e32 v24, v143
	v_pk_fma_f32 v[10:11], v[24:25], v[10:11], v[16:17] op_sel_hi:[0,1,1]
	v_and_b32_e32 v17, 0x7fffffff, v11
	v_and_b32_e32 v16, 0x7fffffff, v10
	v_mul_f32_e32 v42, v44, v42
	v_max_f32_e32 v26, 0, v26
	v_xor_b32_e32 v13, -1, v11
	v_pk_add_f32 v[16:17], v[16:17], 0 neg_lo:[1,1] neg_hi:[1,1]
	v_cmp_gt_i32_e32 vcc, 0, v11
	v_mov_b32_e32 v43, v144
	v_mul_f32_e32 v26, v142, v26
	v_xor_b32_e32 v24, -1, v10
	v_cndmask_b32_e32 v142, v17, v13, vcc
	v_cmp_gt_i32_e32 vcc, 0, v10
	v_pk_add_f32 v[10:11], v[42:43], 0 op_sel_hi:[1,0]
	v_mov_b32_e32 v57, v145
	v_pk_add_f32 v[10:11], v[10:11], v[56:57]
	v_mov_b32_e32 v147, v160
	v_pk_add_f32 v[10:11], v[10:11], v[146:147]
	v_mov_b32_e32 v149, v161
	v_pk_add_f32 v[10:11], v[10:11], v[148:149]
	v_mov_b32_e32 v163, v166
	v_pk_add_f32 v[10:11], v[10:11], v[162:163]
	v_mov_b32_e32 v165, v167
	v_max_f32_e32 v12, 0, v12
	v_pk_add_f32 v[10:11], v[10:11], v[164:165]
	v_mov_b32_e32 v27, v14
	v_mul_f32_e32 v12, v143, v12
	v_pk_add_f32 v[10:11], v[10:11], v[26:27]
	v_mov_b32_e32 v13, v15
	v_pk_add_f32 v[10:11], v[10:11], v[12:13]
	v_cndmask_b32_e32 v143, v16, v24, vcc
	v_and_b32_e32 v13, 0x7fffffff, v11
	v_and_b32_e32 v12, 0x7fffffff, v10
	v_xor_b32_e32 v14, -1, v11
	v_pk_add_f32 v[12:13], v[12:13], 0 neg_lo:[1,1] neg_hi:[1,1]
	v_cmp_gt_i32_e32 vcc, 0, v11
	v_xor_b32_e32 v15, -1, v10
	s_nop 0
	v_cndmask_b32_e32 v144, v13, v14, vcc
	v_cmp_gt_i32_e32 vcc, 0, v10
	v_lshrrev_b32_e32 v10, 24, v143
	v_lshl_add_u32 v10, v10, 6, v0
	ds_add_u32 v10, v205 offset:16384
	v_lshrrev_b32_e32 v10, 24, v142
	v_cndmask_b32_e32 v145, v12, v15, vcc
	v_lshl_add_u32 v10, v10, 6, v0
	ds_add_u32 v10, v205 offset:16384
	v_lshrrev_b32_e32 v10, 24, v145
	v_lshl_add_u32 v10, v10, 6, v0
	ds_add_u32 v10, v205 offset:16384
	v_lshrrev_b32_e32 v10, 24, v144
	v_lshl_add_u32 v10, v10, 6, v0
	ds_add_u32 v10, v205 offset:16384
	ds_read_b128 v[10:13], v182
	ds_read_b128 v[14:17], v183
	ds_read_b128 v[24:27], v184
	ds_read_b128 v[28:31], v185
	ds_read2_b32 v[32:33], v137 offset0:80 offset1:96
	ds_read2_b32 v[40:41], v137 offset0:112 offset1:128
	s_waitcnt vmcnt(1) lgkmcnt(5)
; #define LAS __attribute__((address_space(3)))
; __device__ __forceinline__ unsigned fkey(float f) { const unsigned u = __float_as_uint(f); return (u & 0x80000000u) ? ~u : (u | 0x80000000u); }
; #define SEL_HADD(idx_) __hip_atomic_fetch_add(&hist[(idx_)], 1u, __ATOMIC_RELAXED, __HIP_MEMORY_SCOPE_WORKGROUP)
; __device__ __forceinline__ void sel_unit(LAS char* lds, int b, int u, const bf16_t* QI, const bf16_t* KIDX, const float* WIDX, unsigned long long* MASK) {
;     ...
;                 for (int ks = 0; ks < 2; ++ks) kf[kb][ks] = *(const bf16x8*)(KIDX + (rowbase + 64 * t + 32 * kh + 16 * kb + q16) * 64 + 32 * ks + 8 * kg);
; #pragma unroll
;             for (int kb = 0; kb < 2; ++kb) {
;                 f32x4 s = (f32x4){0.f, 0.f, 0.f, 0.f};
; #pragma unroll
;                 for (int hh = 0; hh < 8; ++hh) {
;                     f32x4 a = (f32x4){0.f, 0.f, 0.f, 0.f};
; #pragma unroll
;                     for (int ks = 0; ks < 2; ++ks) {
;                         const bf16x8 qv = *(const LAS bf16x8*)(lds + L_QI + q16 * 1024 + (((hh * 8 + 4 * ks + kg) ^ q16) << 4));
;                         a = __builtin_amdgcn_mfma_f32_16x16x32_bf16(kf[kb][ks], qv, a, 0, 0, 0);
;                     }
;                     const float wh = wl[hh * 16];
; #pragma unroll
;                     for (int i = 0; i < 4; ++i) s[i] += wh * fmaxf(a[i], 0.f);
;                 }
;                 u32x4 kk; kk.x = fkey(s[0]); kk.y = fkey(s[1]); kk.z = fkey(s[2]); kk.w = fkey(s[3]);
;                 sc[j][2 * kh + kb] = kk;
; #pragma unroll
;                 for (int i = 0; i < 4; ++i) SEL_HADD((kk[i] >> 24) * 16 + q16);
	v_mfma_f32_16x16x32_bf16 v[10:13], v[6:9], v[10:13], 0
	ds_read2_b32 v[52:53], v137 offset0:144 offset1:160
	s_waitcnt vmcnt(0) lgkmcnt(5)
	v_mfma_f32_16x16x32_bf16 v[10:13], v[2:5], v[14:17], v[10:13]
	ds_read_b128 v[14:17], v179
	s_waitcnt lgkmcnt(5)
	v_mfma_f32_16x16x32_bf16 v[24:27], v[6:9], v[24:27], 0
	s_nop 4
	v_max_f32_e32 v34, 0, v10
	v_max_f32_e32 v10, 0, v12
	v_max_f32_e32 v35, 0, v11
	s_waitcnt lgkmcnt(3)
	v_mul_f32_e32 v36, v32, v10
	v_max_f32_e32 v38, 0, v13
	v_mfma_f32_16x16x32_bf16 v[10:13], v[2:5], v[28:31], v[24:27]
	s_nop 2
	ds_read_b128 v[24:27], v180
	s_waitcnt lgkmcnt(1)
	v_mfma_f32_16x16x32_bf16 v[14:17], v[6:9], v[14:17], 0
	s_nop 1
	v_max_f32_e32 v28, 0, v10
	v_max_f32_e32 v29, 0, v11
	v_max_f32_e32 v10, 0, v12
	v_mul_f32_e32 v30, v33, v10
	v_max_f32_e32 v39, 0, v13
	s_waitcnt lgkmcnt(0)
	v_mfma_f32_16x16x32_bf16 v[10:13], v[2:5], v[24:27], v[14:17]
	ds_read_b128 v[24:27], v159
	v_pk_mul_f32 v[38:39], v[32:33], v[38:39]
	s_nop 0
	ds_read_b128 v[14:17], v176
	s_waitcnt lgkmcnt(0)
	v_mfma_f32_16x16x32_bf16 v[14:17], v[6:9], v[14:17], 0
	s_nop 1
	v_max_f32_e32 v42, 0, v10
	v_max_f32_e32 v43, 0, v11
	v_max_f32_e32 v10, 0, v12
	v_mul_f32_e32 v44, v40, v10
	s_nop 0
	v_max_f32_e32 v46, 0, v13
	v_mfma_f32_16x16x32_bf16 v[10:13], v[2:5], v[24:27], v[14:17]
	ds_read_b128 v[24:27], v157
	v_mov_b32_e32 v37, v38
	v_mov_b32_e32 v31, v39
	ds_read_b128 v[14:17], v158
	s_waitcnt lgkmcnt(0)
	v_mfma_f32_16x16x32_bf16 v[14:17], v[6:9], v[14:17], 0
	s_nop 1
	v_max_f32_e32 v48, 0, v10
	v_max_f32_e32 v49, 0, v11
	v_max_f32_e32 v10, 0, v12
	v_mul_f32_e32 v50, v41, v10
	s_nop 0
	v_max_f32_e32 v47, 0, v13
	v_mfma_f32_16x16x32_bf16 v[10:13], v[2:5], v[24:27], v[14:17]
	ds_read_b128 v[24:27], v155
	v_pk_mul_f32 v[46:47], v[40:41], v[46:47]
	s_nop 0
	ds_read_b128 v[14:17], v156
	s_waitcnt lgkmcnt(0)
	v_mfma_f32_16x16x32_bf16 v[14:17], v[6:9], v[14:17], 0
	s_nop 1
	v_max_f32_e32 v54, 0, v10
	v_max_f32_e32 v55, 0, v11
	v_max_f32_e32 v10, 0, v12
	v_mul_f32_e32 v56, v52, v10
	s_nop 0
	v_max_f32_e32 v146, 0, v13
	v_mfma_f32_16x16x32_bf16 v[10:13], v[2:5], v[24:27], v[14:17]
	ds_read_b128 v[24:27], v153
	v_mov_b32_e32 v45, v46
	v_mov_b32_e32 v51, v47
	ds_read_b128 v[14:17], v154
	s_waitcnt lgkmcnt(0)
	v_mfma_f32_16x16x32_bf16 v[14:17], v[6:9], v[14:17], 0
	s_nop 1
	v_max_f32_e32 v148, 0, v10
	v_max_f32_e32 v149, 0, v11
	v_max_f32_e32 v10, 0, v12
	v_mul_f32_e32 v160, v53, v10
	s_nop 0
	v_max_f32_e32 v147, 0, v13
	v_mfma_f32_16x16x32_bf16 v[10:13], v[2:5], v[24:27], v[14:17]
	ds_read_b128 v[24:27], v151
	v_pk_mul_f32 v[162:163], v[52:53], v[146:147]
	ds_read2_b32 v[146:147], v137 offset0:176 offset1:192
	ds_read_b128 v[14:17], v152
	s_waitcnt lgkmcnt(0)
	v_mfma_f32_16x16x32_bf16 v[6:9], v[6:9], v[14:17], 0
	s_nop 1
	s_nop 0
	v_max_f32_e32 v14, 0, v13
	s_nop 0
	v_mfma_f32_16x16x32_bf16 v[2:5], v[2:5], v[24:27], v[6:9]
	s_nop 0
	v_max_f32_e32 v10, 0, v10
	v_max_f32_e32 v11, 0, v11
	v_pk_fma_f32 v[8:9], v[32:33], v[34:35], 0 op_sel_hi:[0,1,0]
	s_nop 0
	s_nop 2
	v_max_f32_e32 v15, 0, v5
	v_pk_mul_f32 v[6:7], v[146:147], v[14:15]
	v_mov_b32_e32 v14, v33
	v_pk_fma_f32 v[8:9], v[14:15], v[28:29], v[8:9] op_sel_hi:[0,1,1]
	v_pk_fma_f32 v[8:9], v[40:41], v[42:43], v[8:9] op_sel_hi:[0,1,1]
	v_mov_b32_e32 v14, v41
	v_pk_fma_f32 v[8:9], v[14:15], v[48:49], v[8:9] op_sel_hi:[0,1,1]
	v_pk_fma_f32 v[8:9], v[52:53], v[54:55], v[8:9] op_sel_hi:[0,1,1]
	v_mov_b32_e32 v14, v53
	v_pk_fma_f32 v[8:9], v[14:15], v[148:149], v[8:9] op_sel_hi:[0,1,1]
	v_max_f32_e32 v2, 0, v2
	v_max_f32_e32 v3, 0, v3
	v_pk_fma_f32 v[8:9], v[146:147], v[10:11], v[8:9] op_sel_hi:[0,1,1]
	v_mov_b32_e32 v10, v147
	v_pk_fma_f32 v[2:3], v[10:11], v[2:3], v[8:9] op_sel_hi:[0,1,1]
	v_and_b32_e32 v9, 0x7fffffff, v3
	v_and_b32_e32 v8, 0x7fffffff, v2
	v_max_f32_e32 v12, 0, v12
	v_xor_b32_e32 v5, -1, v3
	v_pk_add_f32 v[8:9], v[8:9], 0 neg_lo:[1,1] neg_hi:[1,1]
	v_cmp_gt_i32_e32 vcc, 0, v3
	v_mul_f32_e32 v12, v146, v12
	v_xor_b32_e32 v10, -1, v2
	v_cndmask_b32_e32 v146, v9, v5, vcc
	v_cmp_gt_i32_e32 vcc, 0, v2
	v_pk_add_f32 v[2:3], v[36:37], 0 op_sel_hi:[1,0]
	v_mov_b32_e32 v57, v162
	v_pk_add_f32 v[2:3], v[2:3], v[30:31]
	v_pk_add_f32 v[2:3], v[2:3], v[44:45]
	v_mov_b32_e32 v161, v163
	v_pk_add_f32 v[2:3], v[2:3], v[50:51]
	v_max_f32_e32 v4, 0, v4
	v_pk_add_f32 v[2:3], v[2:3], v[56:57]
	v_mov_b32_e32 v13, v6
	v_pk_add_f32 v[2:3], v[2:3], v[160:161]
	v_mul_f32_e32 v4, v147, v4
	v_pk_add_f32 v[2:3], v[2:3], v[12:13]
	v_mov_b32_e32 v5, v7
	v_pk_add_f32 v[2:3], v[2:3], v[4:5]
	v_cndmask_b32_e32 v147, v8, v10, vcc
	v_and_b32_e32 v5, 0x7fffffff, v3
	v_and_b32_e32 v4, 0x7fffffff, v2
	v_xor_b32_e32 v6, -1, v3
	v_pk_add_f32 v[4:5], v[4:5], 0 neg_lo:[1,1] neg_hi:[1,1]
	v_cmp_gt_i32_e32 vcc, 0, v3
	v_xor_b32_e32 v7, -1, v2
	s_nop 0
	v_cndmask_b32_e32 v148, v5, v6, vcc
	v_cmp_gt_i32_e32 vcc, 0, v2
	v_lshrrev_b32_e32 v2, 24, v147
	v_lshl_add_u32 v2, v2, 6, v0
	ds_add_u32 v2, v205 offset:16384
	v_lshrrev_b32_e32 v2, 24, v146
	v_cndmask_b32_e32 v149, v4, v7, vcc
	v_lshl_add_u32 v2, v2, 6, v0
	ds_add_u32 v2, v205 offset:16384
	v_lshrrev_b32_e32 v2, 24, v149
	v_lshl_add_u32 v2, v2, 6, v0
	ds_add_u32 v2, v205 offset:16384
	v_lshrrev_b32_e32 v2, 24, v148
	v_lshl_add_u32 v2, v2, 6, v0
	ds_add_u32 v2, v205 offset:16384
	v_add_co_u32_e32 v2, vcc, s96, v22
	s_nop 1
	v_addc_co_u32_e32 v3, vcc, 0, v23, vcc
	global_load_dwordx4 v[14:17], v[2:3], off
	global_load_dwordx4 v[10:13], v[2:3], off offset:64
	global_load_dwordx4 v[6:9], v[2:3], off offset:2048
	s_nop 0
	global_load_dwordx4 v[2:5], v[2:3], off offset:2112
	ds_read_b128 v[22:25], v182
	ds_read_b128 v[26:29], v183
	s_waitcnt vmcnt(3) lgkmcnt(1)
; #define LAS __attribute__((address_space(3)))
; __device__ __forceinline__ unsigned fkey(float f) { const unsigned u = __float_as_uint(f); return (u & 0x80000000u) ? ~u : (u | 0x80000000u); }
; #define SEL_HADD(idx_) __hip_atomic_fetch_add(&hist[(idx_)], 1u, __ATOMIC_RELAXED, __HIP_MEMORY_SCOPE_WORKGROUP)
; __device__ __forceinline__ void sel_unit(LAS char* lds, int b, int u, const bf16_t* QI, const bf16_t* KIDX, const float* WIDX, unsigned long long* MASK) {
;     ...
;                 for (int ks = 0; ks < 2; ++ks) kf[kb][ks] = *(const bf16x8*)(KIDX + (rowbase + 64 * t + 32 * kh + 16 * kb + q16) * 64 + 32 * ks + 8 * kg);
; #pragma unroll
;             for (int kb = 0; kb < 2; ++kb) {
;                 f32x4 s = (f32x4){0.f, 0.f, 0.f, 0.f};
; #pragma unroll
;                 for (int hh = 0; hh < 8; ++hh) {
;                     f32x4 a = (f32x4){0.f, 0.f, 0.f, 0.f};
; #pragma unroll
;                     for (int ks = 0; ks < 2; ++ks) {
;                         const bf16x8 qv = *(const LAS bf16x8*)(lds + L_QI + q16 * 1024 + (((hh * 8 + 4 * ks + kg) ^ q16) << 4));
;                         a = __builtin_amdgcn_mfma_f32_16x16x32_bf16(kf[kb][ks], qv, a, 0, 0, 0);
;                     }
;                     const float wh = wl[hh * 16];
; #pragma unroll
;                     for (int i = 0; i < 4; ++i) s[i] += wh * fmaxf(a[i], 0.f);
;                 }
;                 u32x4 kk; kk.x = fkey(s[0]); kk.y = fkey(s[1]); kk.z = fkey(s[2]); kk.w = fkey(s[3]);
;                 sc[j][2 * kh + kb] = kk;
; #pragma unroll
;                 for (int i = 0; i < 4; ++i) SEL_HADD((kk[i] >> 24) * 16 + q16);
	v_mfma_f32_16x16x32_bf16 v[22:25], v[14:17], v[22:25], 0
	ds_read_b128 v[32:35], v185
	ds_read_b128 v[38:41], v180
	ds_read_b128 v[44:47], v159
	s_waitcnt vmcnt(2) lgkmcnt(3)
	v_mfma_f32_16x16x32_bf16 v[26:29], v[10:13], v[26:29], v[22:25]
	ds_read_b128 v[50:53], v157
	ds_read_b128 v[160:163], v155
	s_nop 0
	ds_read2_b32 v[24:25], v137 offset0:80 offset1:96
	s_nop 3
	v_max_f32_e32 v26, 0, v26
	v_max_f32_e32 v27, 0, v27
	v_max_f32_e32 v22, v28, v28
	v_max_f32_e32 v23, v29, v29
	ds_read_b128 v[28:31], v184
	s_waitcnt lgkmcnt(0)
	v_mfma_f32_16x16x32_bf16 v[28:31], v[14:17], v[28:31], 0
	v_max_f32_e32 v36, 0, v23
	v_max_f32_e32 v22, 0, v22
	v_mul_f32_e32 v22, v24, v22
	v_mfma_f32_16x16x32_bf16 v[28:31], v[10:13], v[32:35], v[28:31]
	s_nop 7
	v_max_f32_e32 v32, 0, v28
	v_max_f32_e32 v33, 0, v29
	v_max_f32_e32 v23, 0, v30
	v_mul_f32_e32 v28, v25, v23
	v_max_f32_e32 v37, 0, v31
	v_pk_mul_f32 v[30:31], v[24:25], v[36:37]
	ds_read_b128 v[34:37], v179
	s_waitcnt lgkmcnt(0)
	v_mfma_f32_16x16x32_bf16 v[34:37], v[14:17], v[34:37], 0
	v_mov_b32_e32 v29, v31
	v_mfma_f32_16x16x32_bf16 v[38:41], v[10:13], v[38:41], v[34:37]
	s_nop 5
	ds_read2_b32 v[36:37], v137 offset0:112 offset1:128
	s_nop 0
	v_max_f32_e32 v38, 0, v38
	v_max_f32_e32 v39, 0, v39
	v_max_f32_e32 v23, 0, v40
	s_waitcnt lgkmcnt(0)
	v_mul_f32_e32 v34, v36, v23
	v_max_f32_e32 v23, v41, v41
	ds_read_b128 v[40:43], v176
	s_waitcnt lgkmcnt(0)
	v_mfma_f32_16x16x32_bf16 v[40:43], v[14:17], v[40:43], 0
	v_max_f32_e32 v48, 0, v23
	v_mfma_f32_16x16x32_bf16 v[40:43], v[10:13], v[44:47], v[40:43]
	s_nop 7
	v_max_f32_e32 v44, 0, v40
	v_max_f32_e32 v45, 0, v41
	v_max_f32_e32 v23, 0, v42
	v_mul_f32_e32 v40, v37, v23
	v_max_f32_e32 v49, 0, v43
	v_pk_mul_f32 v[42:43], v[36:37], v[48:49]
	ds_read_b128 v[46:49], v158
	s_waitcnt lgkmcnt(0)
	v_mfma_f32_16x16x32_bf16 v[46:49], v[14:17], v[46:49], 0
	v_mov_b32_e32 v35, v42
	v_mov_b32_e32 v41, v43
	v_mfma_f32_16x16x32_bf16 v[50:53], v[10:13], v[50:53], v[46:49]
	s_nop 4
	ds_read2_b32 v[48:49], v137 offset0:144 offset1:160
	s_nop 1
	v_max_f32_e32 v50, 0, v50
	v_max_f32_e32 v51, 0, v51
	v_max_f32_e32 v23, 0, v52
	s_waitcnt lgkmcnt(0)
	v_mul_f32_e32 v46, v48, v23
	v_max_f32_e32 v23, v53, v53
	ds_read_b128 v[52:55], v156
	s_waitcnt lgkmcnt(0)
	v_mfma_f32_16x16x32_bf16 v[52:55], v[14:17], v[52:55], 0
	v_max_f32_e32 v164, 0, v23
	v_mfma_f32_16x16x32_bf16 v[52:55], v[10:13], v[160:163], v[52:55]
	ds_read_b128 v[160:163], v154
	s_nop 6
	v_max_f32_e32 v56, 0, v52
	v_max_f32_e32 v57, 0, v53
	v_max_f32_e32 v23, 0, v54
	v_mul_f32_e32 v52, v49, v23
	v_max_f32_e32 v165, 0, v55
	v_pk_mul_f32 v[54:55], v[48:49], v[164:165]
	ds_read_b128 v[164:167], v153
	s_waitcnt lgkmcnt(1)
	v_mfma_f32_16x16x32_bf16 v[160:163], v[14:17], v[160:163], 0
	v_mov_b32_e32 v47, v54
	v_mov_b32_e32 v53, v55
	s_waitcnt lgkmcnt(0)
	v_mfma_f32_16x16x32_bf16 v[160:163], v[10:13], v[164:167], v[160:163]
	ds_read2_b32 v[164:165], v137 offset0:176 offset1:192
	s_nop 6
	v_max_f32_e32 v166, 0, v160
	v_max_f32_e32 v167, 0, v161
	v_max_f32_e32 v23, 0, v162
	s_waitcnt lgkmcnt(0)
	v_mul_f32_e32 v168, v164, v23
	v_max_f32_e32 v23, v163, v163
	ds_read_b128 v[160:163], v152
	s_waitcnt lgkmcnt(0)
	v_mfma_f32_16x16x32_bf16 v[14:17], v[14:17], v[160:163], 0
	ds_read_b128 v[160:163], v151
	v_max_f32_e32 v170, 0, v23
	s_waitcnt lgkmcnt(0)
	v_mfma_f32_16x16x32_bf16 v[10:13], v[10:13], v[160:163], v[14:17]
	s_nop 3
	v_fma_f32 v16, v24, v26, 0
	v_fma_f32 v17, v24, v27, 0
	v_mov_b32_e32 v24, v25
	v_pk_fma_f32 v[16:17], v[24:25], v[32:33], v[16:17] op_sel_hi:[0,1,1]
	v_pk_fma_f32 v[16:17], v[36:37], v[38:39], v[16:17] op_sel_hi:[0,1,1]
	v_mov_b32_e32 v24, v37
	v_pk_fma_f32 v[16:17], v[24:25], v[44:45], v[16:17] op_sel_hi:[0,1,1]
	v_pk_fma_f32 v[16:17], v[48:49], v[50:51], v[16:17] op_sel_hi:[0,1,1]
	v_mov_b32_e32 v24, v49
	v_pk_fma_f32 v[16:17], v[24:25], v[56:57], v[16:17] op_sel_hi:[0,1,1]
	v_max_f32_e32 v10, 0, v10
	v_max_f32_e32 v11, 0, v11
	v_pk_fma_f32 v[16:17], v[164:165], v[166:167], v[16:17] op_sel_hi:[0,1,1]
	v_mov_b32_e32 v24, v165
	v_pk_fma_f32 v[10:11], v[24:25], v[10:11], v[16:17] op_sel_hi:[0,1,1]
	v_and_b32_e32 v17, 0x7fffffff, v11
	v_and_b32_e32 v16, 0x7fffffff, v10
	v_xor_b32_e32 v23, -1, v10
	v_pk_add_f32 v[16:17], v[16:17], 0 neg_lo:[1,1] neg_hi:[1,1]
	v_cmp_gt_i32_e32 vcc, 0, v10
	v_max_f32_e32 v171, 0, v13
	s_nop 0
	v_cndmask_b32_e32 v178, v16, v23, vcc
	v_mov_b32_e32 v23, v30
	v_xor_b32_e32 v13, -1, v11
	v_cmp_gt_i32_e64 s[2:3], 0, v11
	v_pk_add_f32 v[10:11], v[22:23], 0 op_sel_hi:[1,0]
	v_pk_add_f32 v[10:11], v[10:11], v[28:29]
	v_pk_mul_f32 v[14:15], v[164:165], v[170:171]
	v_pk_add_f32 v[10:11], v[10:11], v[34:35]
	v_max_f32_e32 v12, 0, v12
	v_pk_add_f32 v[10:11], v[10:11], v[40:41]
	v_mov_b32_e32 v169, v14
	v_pk_add_f32 v[10:11], v[10:11], v[46:47]
	v_mul_f32_e32 v12, v165, v12
	v_pk_add_f32 v[10:11], v[10:11], v[52:53]
	v_cndmask_b32_e64 v177, v17, v13, s[2:3]
	v_pk_add_f32 v[10:11], v[10:11], v[168:169]
	v_mov_b32_e32 v13, v15
	v_pk_add_f32 v[10:11], v[10:11], v[12:13]
	s_nop 0
	v_xor_b32_e32 v15, -1, v10
	v_and_b32_e32 v12, 0x7fffffff, v10
	v_cmp_gt_i32_e32 vcc, 0, v10
	v_lshrrev_b32_e32 v10, 24, v178
	v_and_b32_e32 v13, 0x7fffffff, v11
	v_lshl_add_u32 v10, v10, 6, v0
	v_pk_add_f32 v[12:13], v[12:13], 0 neg_lo:[1,1] neg_hi:[1,1]
	ds_add_u32 v10, v205 offset:16384
	v_lshrrev_b32_e32 v10, 24, v177
	v_cndmask_b32_e32 v186, v12, v15, vcc
	v_lshl_add_u32 v10, v10, 6, v0
	v_xor_b32_e32 v14, -1, v11
	v_cmp_gt_i32_e64 s[2:3], 0, v11
	ds_add_u32 v10, v205 offset:16384
	v_lshrrev_b32_e32 v10, 24, v186
	v_cndmask_b32_e64 v181, v13, v14, s[2:3]
	v_lshl_add_u32 v10, v10, 6, v0
	ds_add_u32 v10, v205 offset:16384
	v_lshrrev_b32_e32 v10, 24, v181
	v_lshl_add_u32 v10, v10, 6, v0
	ds_add_u32 v10, v205 offset:16384
	ds_read_b128 v[10:13], v182
	ds_read_b128 v[14:17], v183
	ds_read_b128 v[22:25], v184
	ds_read_b128 v[26:29], v185
	ds_read2_b32 v[30:31], v137 offset0:80 offset1:96
	ds_read2_b32 v[38:39], v137 offset0:112 offset1:128
	s_waitcnt vmcnt(1) lgkmcnt(5)
; #define LAS __attribute__((address_space(3)))
; __device__ __forceinline__ unsigned fkey(float f) { const unsigned u = __float_as_uint(f); return (u & 0x80000000u) ? ~u : (u | 0x80000000u); }
; #define SEL_HADD(idx_) __hip_atomic_fetch_add(&hist[(idx_)], 1u, __ATOMIC_RELAXED, __HIP_MEMORY_SCOPE_WORKGROUP)
; __device__ __forceinline__ void sel_unit(LAS char* lds, int b, int u, const bf16_t* QI, const bf16_t* KIDX, const float* WIDX, unsigned long long* MASK) {
;     ...
;                 for (int ks = 0; ks < 2; ++ks) kf[kb][ks] = *(const bf16x8*)(KIDX + (rowbase + 64 * t + 32 * kh + 16 * kb + q16) * 64 + 32 * ks + 8 * kg);
; #pragma unroll
;             for (int kb = 0; kb < 2; ++kb) {
;                 f32x4 s = (f32x4){0.f, 0.f, 0.f, 0.f};
; #pragma unroll
;                 for (int hh = 0; hh < 8; ++hh) {
;                     f32x4 a = (f32x4){0.f, 0.f, 0.f, 0.f};
; #pragma unroll
;                     for (int ks = 0; ks < 2; ++ks) {
;                         const bf16x8 qv = *(const LAS bf16x8*)(lds + L_QI + q16 * 1024 + (((hh * 8 + 4 * ks + kg) ^ q16) << 4));
;                         a = __builtin_amdgcn_mfma_f32_16x16x32_bf16(kf[kb][ks], qv, a, 0, 0, 0);
;                     }
;                     const float wh = wl[hh * 16];
; #pragma unroll
;                     for (int i = 0; i < 4; ++i) s[i] += wh * fmaxf(a[i], 0.f);
;                 }
;                 u32x4 kk; kk.x = fkey(s[0]); kk.y = fkey(s[1]); kk.z = fkey(s[2]); kk.w = fkey(s[3]);
;                 sc[j][2 * kh + kb] = kk;
; #pragma unroll
;                 for (int i = 0; i < 4; ++i) SEL_HADD((kk[i] >> 24) * 16 + q16);
	v_mfma_f32_16x16x32_bf16 v[10:13], v[6:9], v[10:13], 0
	ds_read2_b32 v[50:51], v137 offset0:144 offset1:160
	ds_read2_b32 v[164:165], v137 offset0:176 offset1:192
	s_waitcnt vmcnt(0) lgkmcnt(6)
	v_mfma_f32_16x16x32_bf16 v[10:13], v[2:5], v[14:17], v[10:13]
	ds_read_b128 v[14:17], v179
	s_waitcnt lgkmcnt(6)
	v_mfma_f32_16x16x32_bf16 v[22:25], v[6:9], v[22:25], 0
	s_nop 4
	v_max_f32_e32 v32, 0, v10
	v_max_f32_e32 v10, 0, v12
	v_max_f32_e32 v33, 0, v11
	s_waitcnt lgkmcnt(4)
	v_mul_f32_e32 v34, v30, v10
	v_max_f32_e32 v36, 0, v13
	v_mfma_f32_16x16x32_bf16 v[10:13], v[2:5], v[26:29], v[22:25]
	s_nop 2
	ds_read_b128 v[22:25], v180
	s_waitcnt lgkmcnt(1)
	v_mfma_f32_16x16x32_bf16 v[14:17], v[6:9], v[14:17], 0
	s_nop 1
	v_max_f32_e32 v26, 0, v10
	v_max_f32_e32 v27, 0, v11
	v_max_f32_e32 v10, 0, v12
	v_mul_f32_e32 v28, v31, v10
	v_max_f32_e32 v37, 0, v13
	s_waitcnt lgkmcnt(0)
	v_mfma_f32_16x16x32_bf16 v[10:13], v[2:5], v[22:25], v[14:17]
	ds_read_b128 v[22:25], v159
	v_pk_mul_f32 v[36:37], v[30:31], v[36:37]
	s_nop 0
	ds_read_b128 v[14:17], v176
	s_waitcnt lgkmcnt(0)
	v_mfma_f32_16x16x32_bf16 v[14:17], v[6:9], v[14:17], 0
	s_nop 1
	v_max_f32_e32 v40, 0, v10
	v_max_f32_e32 v41, 0, v11
	v_max_f32_e32 v10, 0, v12
	v_mul_f32_e32 v42, v38, v10
	s_nop 0
	v_max_f32_e32 v44, 0, v13
	v_mfma_f32_16x16x32_bf16 v[10:13], v[2:5], v[22:25], v[14:17]
	ds_read_b128 v[22:25], v157
	v_mov_b32_e32 v35, v36
	v_mov_b32_e32 v29, v37
	ds_read_b128 v[14:17], v158
	s_waitcnt lgkmcnt(0)
	v_mfma_f32_16x16x32_bf16 v[14:17], v[6:9], v[14:17], 0
	s_nop 1
	v_max_f32_e32 v46, 0, v10
	v_max_f32_e32 v47, 0, v11
	v_max_f32_e32 v10, 0, v12
	v_mul_f32_e32 v48, v39, v10
	s_nop 0
	v_max_f32_e32 v45, 0, v13
	v_mfma_f32_16x16x32_bf16 v[10:13], v[2:5], v[22:25], v[14:17]
	ds_read_b128 v[22:25], v155
	v_pk_mul_f32 v[44:45], v[38:39], v[44:45]
	s_nop 0
	ds_read_b128 v[14:17], v156
	s_waitcnt lgkmcnt(0)
	v_mfma_f32_16x16x32_bf16 v[14:17], v[6:9], v[14:17], 0
	s_nop 1
	v_max_f32_e32 v52, 0, v10
	v_max_f32_e32 v53, 0, v11
	v_max_f32_e32 v10, 0, v12
	v_mul_f32_e32 v54, v50, v10
	s_nop 0
	v_max_f32_e32 v56, 0, v13
	v_mfma_f32_16x16x32_bf16 v[10:13], v[2:5], v[22:25], v[14:17]
	ds_read_b128 v[22:25], v153
	v_mov_b32_e32 v43, v44
	v_mov_b32_e32 v49, v45
	ds_read_b128 v[14:17], v154
	s_waitcnt lgkmcnt(0)
	v_mfma_f32_16x16x32_bf16 v[14:17], v[6:9], v[14:17], 0
	s_nop 1
	v_max_f32_e32 v160, 0, v10
	v_max_f32_e32 v161, 0, v11
	v_max_f32_e32 v10, 0, v12
	v_mul_f32_e32 v162, v51, v10
	s_nop 0
	v_max_f32_e32 v57, 0, v13
	v_mfma_f32_16x16x32_bf16 v[10:13], v[2:5], v[22:25], v[14:17]
	ds_read_b128 v[22:25], v151
	v_pk_mul_f32 v[56:57], v[50:51], v[56:57]
	s_nop 0
	ds_read_b128 v[14:17], v152
	s_waitcnt lgkmcnt(0)
	v_mfma_f32_16x16x32_bf16 v[6:9], v[6:9], v[14:17], 0
	s_nop 1
	s_nop 0
	v_max_f32_e32 v14, 0, v13
	s_nop 0
	v_mfma_f32_16x16x32_bf16 v[2:5], v[2:5], v[22:25], v[6:9]
	s_nop 0
	v_max_f32_e32 v10, 0, v10
	v_max_f32_e32 v11, 0, v11
	v_pk_fma_f32 v[8:9], v[30:31], v[32:33], 0 op_sel_hi:[0,1,0]
	s_nop 0
	s_nop 2
	v_max_f32_e32 v15, 0, v5
	v_pk_mul_f32 v[6:7], v[164:165], v[14:15]
	v_mov_b32_e32 v14, v31
	v_pk_fma_f32 v[8:9], v[14:15], v[26:27], v[8:9] op_sel_hi:[0,1,1]
	v_pk_fma_f32 v[8:9], v[38:39], v[40:41], v[8:9] op_sel_hi:[0,1,1]
	v_mov_b32_e32 v14, v39
	v_pk_fma_f32 v[8:9], v[14:15], v[46:47], v[8:9] op_sel_hi:[0,1,1]
	v_pk_fma_f32 v[8:9], v[50:51], v[52:53], v[8:9] op_sel_hi:[0,1,1]
	v_mov_b32_e32 v14, v51
	v_pk_fma_f32 v[8:9], v[14:15], v[160:161], v[8:9] op_sel_hi:[0,1,1]
	v_max_f32_e32 v2, 0, v2
	v_max_f32_e32 v3, 0, v3
	v_pk_fma_f32 v[8:9], v[164:165], v[10:11], v[8:9] op_sel_hi:[0,1,1]
	v_mov_b32_e32 v10, v165
	v_pk_fma_f32 v[2:3], v[10:11], v[2:3], v[8:9] op_sel_hi:[0,1,1]
	v_and_b32_e32 v9, 0x7fffffff, v3
	v_and_b32_e32 v8, 0x7fffffff, v2
	v_xor_b32_e32 v5, -1, v3
	v_pk_add_f32 v[8:9], v[8:9], 0 neg_lo:[1,1] neg_hi:[1,1]
	v_cmp_gt_i32_e32 vcc, 0, v3
	v_xor_b32_e32 v10, -1, v2
	v_mov_b32_e32 v55, v56
	v_cndmask_b32_e32 v187, v9, v5, vcc
	v_cmp_gt_i32_e32 vcc, 0, v2
	v_pk_add_f32 v[2:3], v[34:35], 0 op_sel_hi:[1,0]
	v_max_f32_e32 v12, 0, v12
	v_pk_add_f32 v[2:3], v[2:3], v[28:29]
	v_pk_add_f32 v[2:3], v[2:3], v[42:43]
	v_mov_b32_e32 v163, v57
	v_pk_add_f32 v[2:3], v[2:3], v[48:49]
	v_mul_f32_e32 v12, v164, v12
	v_pk_add_f32 v[2:3], v[2:3], v[54:55]
	v_max_f32_e32 v4, 0, v4
	v_pk_add_f32 v[2:3], v[2:3], v[162:163]
	v_mov_b32_e32 v13, v6
	v_mul_f32_e32 v4, v165, v4
	v_pk_add_f32 v[2:3], v[2:3], v[12:13]
	v_mov_b32_e32 v5, v7
	v_pk_add_f32 v[2:3], v[2:3], v[4:5]
	v_cndmask_b32_e32 v188, v8, v10, vcc
	v_and_b32_e32 v5, 0x7fffffff, v3
	v_and_b32_e32 v4, 0x7fffffff, v2
	v_xor_b32_e32 v6, -1, v3
	v_pk_add_f32 v[4:5], v[4:5], 0 neg_lo:[1,1] neg_hi:[1,1]
	v_cmp_gt_i32_e32 vcc, 0, v3
	v_xor_b32_e32 v7, -1, v2
	s_nop 0
	v_cndmask_b32_e32 v189, v5, v6, vcc
	v_cmp_gt_i32_e32 vcc, 0, v2
	v_lshrrev_b32_e32 v2, 24, v188
	v_lshl_add_u32 v2, v2, 6, v0
	ds_add_u32 v2, v205 offset:16384
	v_lshrrev_b32_e32 v2, 24, v187
	v_cndmask_b32_e32 v190, v4, v7, vcc
	v_lshl_add_u32 v2, v2, 6, v0
	ds_add_u32 v2, v205 offset:16384
	v_lshrrev_b32_e32 v2, 24, v190
	v_lshl_add_u32 v2, v2, 6, v0
	ds_add_u32 v2, v205 offset:16384
	v_lshrrev_b32_e32 v2, 24, v189
	v_lshl_add_u32 v2, v2, 6, v0
	ds_add_u32 v2, v205 offset:16384
; #define LAS __attribute__((address_space(3)))
; __device__ __forceinline__ unsigned fkey(float f) { const unsigned u = __float_as_uint(f); return (u & 0x80000000u) ? ~u : (u | 0x80000000u); }
; #define SEL_HADD(idx_) __hip_atomic_fetch_add(&hist[(idx_)], 1u, __ATOMIC_RELAXED, __HIP_MEMORY_SCOPE_WORKGROUP)
; __device__ __forceinline__ void sel_unit(LAS char* lds, int b, int u, const bf16_t* QI, const bf16_t* KIDX, const float* WIDX, unsigned long long* MASK) {
;     ...
;     for (int j = 0; j < 8; ++j) {
;         if (j < nj) {
;             int t = wid + 8 * j; asm volatile("" : "+s"(t));
; #pragma unroll
;             for (int kh = 0; kh < 2; ++kh) {
;             bf16x8 kf[2][2];
; #pragma unroll
;             for (int kb = 0; kb < 2; ++kb)
; #pragma unroll
;                 for (int ks = 0; ks < 2; ++ks) kf[kb][ks] = *(const bf16x8*)(KIDX + (rowbase + 64 * t + 32 * kh + 16 * kb + q16) * 64 + 32 * ks + 8 * kg);
; #pragma unroll
;             for (int kb = 0; kb < 2; ++kb) {
;                 f32x4 s = (f32x4){0.f, 0.f, 0.f, 0.f};
; #pragma unroll
;                 for (int hh = 0; hh < 8; ++hh) {
;                     f32x4 a = (f32x4){0.f, 0.f, 0.f, 0.f};
; #pragma unroll
;                     for (int ks = 0; ks < 2; ++ks) {
;                         const bf16x8 qv = *(const LAS bf16x8*)(lds + L_QI + q16 * 1024 + (((hh * 8 + 4 * ks + kg) ^ q16) << 4));
;                         a = __builtin_amdgcn_mfma_f32_16x16x32_bf16(kf[kb][ks], qv, a, 0, 0, 0);
;                     }
;                     const float wh = wl[hh * 16];
; #pragma unroll
;                     for (int i = 0; i < 4; ++i) s[i] += wh * fmaxf(a[i], 0.f);
;                 }
;                 u32x4 kk; kk.x = fkey(s[0]); kk.y = fkey(s[1]); kk.z = fkey(s[2]); kk.w = fkey(s[3]);
;                 sc[j][2 * kh + kb] = kk;
; #pragma unroll
;                 for (int i = 0; i < 4; ++i) SEL_HADD((kk[i] >> 24) * 16 + q16);
;                 __builtin_amdgcn_sched_barrier(0);
.LBB0_668:
	s_cmp_gt_i32 s4, 6
	s_cselect_b64 s[0:1], -1, 0
	s_cmp_lt_i32 s4, 7
	s_cbranch_scc1 .LBB0_670
	s_add_i32 s2, s46, 48
	s_lshl_b32 s2, s2, 6
	s_ashr_i32 s3, s2, 31
	v_lshl_add_u64 v[2:3], v[18:19], 0, s[2:3]
	v_lshlrev_b64 v[2:3], 7, v[2:3]
	v_lshl_add_u64 v[22:23], v[20:21], 0, v[2:3]
	global_load_dwordx4 v[14:17], v[22:23], off
	global_load_dwordx4 v[10:13], v[22:23], off offset:64
	ds_read_b128 v[2:5], v182
	ds_read_b128 v[6:9], v183
	ds_read_b128 v[24:27], v184
	ds_read_b128 v[28:31], v185
	ds_read_b128 v[32:35], v179
	ds_read_b128 v[36:39], v180
	ds_read_b128 v[40:43], v176
	ds_read_b128 v[44:47], v159
	ds_read_b128 v[48:51], v158
	ds_read_b128 v[52:55], v157
	ds_read_b128 v[160:163], v156
	ds_read_b128 v[164:167], v155
	s_waitcnt vmcnt(1) lgkmcnt(11)
	v_mfma_f32_16x16x32_bf16 v[2:5], v[14:17], v[2:5], 0
	s_waitcnt lgkmcnt(9)
	v_mfma_f32_16x16x32_bf16 v[24:27], v[14:17], v[24:27], 0
	s_waitcnt lgkmcnt(7)
	v_mfma_f32_16x16x32_bf16 v[32:35], v[14:17], v[32:35], 0
	s_waitcnt lgkmcnt(5)
	v_mfma_f32_16x16x32_bf16 v[40:43], v[14:17], v[40:43], 0
	s_waitcnt lgkmcnt(3)
	v_mfma_f32_16x16x32_bf16 v[48:51], v[14:17], v[48:51], 0
	s_waitcnt vmcnt(0)
	v_mfma_f32_16x16x32_bf16 v[168:171], v[10:13], v[6:9], v[2:5]
	v_mfma_f32_16x16x32_bf16 v[24:27], v[10:13], v[28:31], v[24:27]
	v_mfma_f32_16x16x32_bf16 v[28:31], v[10:13], v[36:39], v[32:35]
	v_mfma_f32_16x16x32_bf16 v[32:35], v[10:13], v[44:47], v[40:43]
	ds_read2_b32 v[44:45], v137 offset0:80 offset1:96
	ds_read2_b32 v[46:47], v137 offset0:112 offset1:128
	s_nop 3
	s_waitcnt lgkmcnt(4)
	v_mfma_f32_16x16x32_bf16 v[36:39], v[10:13], v[52:55], v[48:51]
	ds_read2_b32 v[48:49], v137 offset0:144 offset1:160
	global_load_dwordx4 v[6:9], v[22:23], off offset:2048
	global_load_dwordx4 v[2:5], v[22:23], off offset:2112
	s_waitcnt lgkmcnt(4)
	v_mfma_f32_16x16x32_bf16 v[160:163], v[14:17], v[160:163], 0
	s_nop 0
	s_nop 0
	v_max_f32_e32 v54, v24, v24
	s_waitcnt lgkmcnt(3)
	v_mfma_f32_16x16x32_bf16 v[40:43], v[10:13], v[164:167], v[160:163]
	s_nop 0
	v_max_f32_e32 v24, 0, v171
	v_max_f32_e32 v164, 0, v26
	v_max_f32_e32 v160, v39, v39
	v_max_f32_e32 v39, 0, v25
	s_nop 2
	v_max_f32_e32 v25, 0, v27
	v_max_f32_e32 v26, 0, v31
	v_max_f32_e32 v27, 0, v35
	v_max_f32_e32 v55, v36, v36
	v_max_f32_e32 v57, v38, v38
	v_max_f32_e32 v36, 0, v168
	v_max_f32_e32 v38, 0, v54
	v_max_f32_e32 v50, 0, v32
	v_max_f32_e32 v32, 0, v160
	v_max_f32_e32 v54, 0, v40
	s_waitcnt lgkmcnt(2)
	v_pk_mul_f32 v[160:161], v[44:45], v[24:25]
	s_waitcnt lgkmcnt(1)
	v_pk_mul_f32 v[166:167], v[46:47], v[26:27]
	ds_read_b128 v[24:27], v154
	v_max_f32_e32 v162, v41, v41
	v_max_f32_e32 v163, v42, v42
	v_max_f32_e32 v40, 0, v28
	v_max_f32_e32 v28, 0, v30
	v_max_f32_e32 v42, 0, v170
	v_max_f32_e32 v41, 0, v29
	v_max_f32_e32 v29, 0, v34
	v_max_f32_e32 v52, 0, v55
	v_max_f32_e32 v30, 0, v57
	v_max_f32_e32 v55, 0, v162
	v_mul_f32_e32 v162, v46, v28
	v_max_f32_e32 v28, 0, v163
	v_max_f32_e32 v53, 0, v37
	v_mul_f32_e32 v56, v45, v164
	v_mul_f32_e32 v164, v47, v29
	s_waitcnt lgkmcnt(1)
	v_mul_f32_e32 v168, v48, v30
	v_mul_f32_e32 v170, v49, v28
	ds_read_b128 v[28:31], v153
	s_waitcnt lgkmcnt(1)
	v_mfma_f32_16x16x32_bf16 v[24:27], v[14:17], v[24:27], 0
	v_max_f32_e32 v37, 0, v169
	s_waitcnt lgkmcnt(0)
	v_mfma_f32_16x16x32_bf16 v[24:27], v[10:13], v[28:31], v[24:27]
	ds_read_b128 v[28:31], v152
	v_max_f32_e32 v51, 0, v33
	v_max_f32_e32 v33, 0, v43
	v_pk_mul_f32 v[172:173], v[48:49], v[32:33]
	ds_read_b128 v[32:35], v151
	s_waitcnt lgkmcnt(1)
	v_mfma_f32_16x16x32_bf16 v[14:17], v[14:17], v[28:31], 0
	ds_read2_b32 v[174:175], v137 offset0:176 offset1:192
	s_nop 0
	v_max_f32_e32 v28, 0, v27
	s_waitcnt lgkmcnt(1)
	v_mfma_f32_16x16x32_bf16 v[10:13], v[10:13], v[32:35], v[14:17]
	s_nop 0
	s_nop 0
	v_max_f32_e32 v24, 0, v24
	v_pk_fma_f32 v[16:17], v[44:45], v[36:37], 0 op_sel_hi:[0,1,0]
	v_max_f32_e32 v25, 0, v25
	s_nop 2
	v_max_f32_e32 v29, 0, v13
	s_waitcnt lgkmcnt(0)
	v_pk_mul_f32 v[14:15], v[174:175], v[28:29]
	v_mov_b32_e32 v28, v45
	v_pk_fma_f32 v[16:17], v[28:29], v[38:39], v[16:17] op_sel_hi:[0,1,1]
	v_pk_fma_f32 v[16:17], v[46:47], v[40:41], v[16:17] op_sel_hi:[0,1,1]
	v_mov_b32_e32 v28, v47
	v_pk_fma_f32 v[16:17], v[28:29], v[50:51], v[16:17] op_sel_hi:[0,1,1]
	v_pk_fma_f32 v[16:17], v[48:49], v[52:53], v[16:17] op_sel_hi:[0,1,1]
	v_mov_b32_e32 v28, v49
	v_pk_fma_f32 v[16:17], v[28:29], v[54:55], v[16:17] op_sel_hi:[0,1,1]
	v_max_f32_e32 v10, 0, v10
	v_max_f32_e32 v11, 0, v11
	v_pk_fma_f32 v[16:17], v[174:175], v[24:25], v[16:17] op_sel_hi:[0,1,1]
	v_mov_b32_e32 v24, v175
	v_pk_fma_f32 v[10:11], v[24:25], v[10:11], v[16:17] op_sel_hi:[0,1,1]
	v_and_b32_e32 v17, 0x7fffffff, v11
	v_and_b32_e32 v16, 0x7fffffff, v10
	v_mul_f32_e32 v42, v44, v42
	v_xor_b32_e32 v13, -1, v11
	v_pk_add_f32 v[16:17], v[16:17], 0 neg_lo:[1,1] neg_hi:[1,1]
	v_cmp_gt_i32_e32 vcc, 0, v11
	v_mov_b32_e32 v43, v160
	v_xor_b32_e32 v24, -1, v10
	v_cndmask_b32_e32 v191, v17, v13, vcc
	v_cmp_gt_i32_e32 vcc, 0, v10
	v_pk_add_f32 v[10:11], v[42:43], 0 op_sel_hi:[1,0]
	v_mov_b32_e32 v57, v161
	v_pk_add_f32 v[10:11], v[10:11], v[56:57]
	v_mov_b32_e32 v163, v166
	v_pk_add_f32 v[10:11], v[10:11], v[162:163]
	v_mov_b32_e32 v165, v167
	v_pk_add_f32 v[10:11], v[10:11], v[164:165]
	v_mov_b32_e32 v169, v172
	v_max_f32_e32 v26, 0, v26
	v_pk_add_f32 v[10:11], v[10:11], v[168:169]
	v_mov_b32_e32 v171, v173
	v_mul_f32_e32 v26, v174, v26
	v_max_f32_e32 v12, 0, v12
	v_pk_add_f32 v[10:11], v[10:11], v[170:171]
	v_mov_b32_e32 v27, v14
	v_mul_f32_e32 v12, v175, v12
	v_pk_add_f32 v[10:11], v[10:11], v[26:27]
	v_mov_b32_e32 v13, v15
	v_pk_add_f32 v[10:11], v[10:11], v[12:13]
	v_cndmask_b32_e32 v192, v16, v24, vcc
	v_and_b32_e32 v13, 0x7fffffff, v11
	v_and_b32_e32 v12, 0x7fffffff, v10
	v_xor_b32_e32 v14, -1, v11
	v_pk_add_f32 v[12:13], v[12:13], 0 neg_lo:[1,1] neg_hi:[1,1]
	v_cmp_gt_i32_e32 vcc, 0, v11
	v_xor_b32_e32 v15, -1, v10
	s_nop 0
	v_cndmask_b32_e32 v193, v13, v14, vcc
	v_cmp_gt_i32_e32 vcc, 0, v10
	v_lshrrev_b32_e32 v10, 24, v192
	v_lshl_add_u32 v10, v10, 6, v0
	ds_add_u32 v10, v205 offset:16384
	v_lshrrev_b32_e32 v10, 24, v191
	v_cndmask_b32_e32 v194, v12, v15, vcc
	v_lshl_add_u32 v10, v10, 6, v0
	ds_add_u32 v10, v205 offset:16384
	v_lshrrev_b32_e32 v10, 24, v194
	v_lshl_add_u32 v10, v10, 6, v0
	ds_add_u32 v10, v205 offset:16384
	v_lshrrev_b32_e32 v10, 24, v193
	v_lshl_add_u32 v10, v10, 6, v0
	ds_add_u32 v10, v205 offset:16384
	ds_read_b128 v[10:13], v182
	ds_read_b128 v[14:17], v183
	ds_read_b128 v[24:27], v184
	ds_read_b128 v[28:31], v185
	ds_read2_b32 v[32:33], v137 offset0:80 offset1:96
	ds_read2_b32 v[40:41], v137 offset0:112 offset1:128
	s_waitcnt vmcnt(1) lgkmcnt(5)
; #define LAS __attribute__((address_space(3)))
; __device__ __forceinline__ unsigned fkey(float f) { const unsigned u = __float_as_uint(f); return (u & 0x80000000u) ? ~u : (u | 0x80000000u); }
; #define SEL_HADD(idx_) __hip_atomic_fetch_add(&hist[(idx_)], 1u, __ATOMIC_RELAXED, __HIP_MEMORY_SCOPE_WORKGROUP)
; __device__ __forceinline__ void sel_unit(LAS char* lds, int b, int u, const bf16_t* QI, const bf16_t* KIDX, const float* WIDX, unsigned long long* MASK) {
;     ...
;             for (int kh = 0; kh < 2; ++kh) {
;             bf16x8 kf[2][2];
; #pragma unroll
;             for (int kb = 0; kb < 2; ++kb)
; #pragma unroll
;                 for (int ks = 0; ks < 2; ++ks) kf[kb][ks] = *(const bf16x8*)(KIDX + (rowbase + 64 * t + 32 * kh + 16 * kb + q16) * 64 + 32 * ks + 8 * kg);
; #pragma unroll
;             for (int kb = 0; kb < 2; ++kb) {
;                 f32x4 s = (f32x4){0.f, 0.f, 0.f, 0.f};
; #pragma unroll
;                 for (int hh = 0; hh < 8; ++hh) {
;                     f32x4 a = (f32x4){0.f, 0.f, 0.f, 0.f};
; #pragma unroll
;                     for (int ks = 0; ks < 2; ++ks) {
;                         const bf16x8 qv = *(const LAS bf16x8*)(lds + L_QI + q16 * 1024 + (((hh * 8 + 4 * ks + kg) ^ q16) << 4));
;                         a = __builtin_amdgcn_mfma_f32_16x16x32_bf16(kf[kb][ks], qv, a, 0, 0, 0);
;                     }
;                     const float wh = wl[hh * 16];
; #pragma unroll
;                     for (int i = 0; i < 4; ++i) s[i] += wh * fmaxf(a[i], 0.f);
;                 }
;                 u32x4 kk; kk.x = fkey(s[0]); kk.y = fkey(s[1]); kk.z = fkey(s[2]); kk.w = fkey(s[3]);
;                 sc[j][2 * kh + kb] = kk;
; #pragma unroll
;                 for (int i = 0; i < 4; ++i) SEL_HADD((kk[i] >> 24) * 16 + q16);
;                 __builtin_amdgcn_sched_barrier(0);
	v_mfma_f32_16x16x32_bf16 v[10:13], v[6:9], v[10:13], 0
	ds_read2_b32 v[52:53], v137 offset0:144 offset1:160
	ds_read2_b32 v[166:167], v137 offset0:176 offset1:192
	s_waitcnt vmcnt(0) lgkmcnt(6)
	v_mfma_f32_16x16x32_bf16 v[10:13], v[2:5], v[14:17], v[10:13]
	ds_read_b128 v[14:17], v179
	s_waitcnt lgkmcnt(6)
	v_mfma_f32_16x16x32_bf16 v[24:27], v[6:9], v[24:27], 0
	s_nop 4
	v_max_f32_e32 v34, 0, v10
	v_max_f32_e32 v10, 0, v12
	v_max_f32_e32 v35, 0, v11
	s_waitcnt lgkmcnt(4)
	v_mul_f32_e32 v36, v32, v10
	v_max_f32_e32 v38, 0, v13
	v_mfma_f32_16x16x32_bf16 v[10:13], v[2:5], v[28:31], v[24:27]
	s_nop 2
	ds_read_b128 v[24:27], v180
	s_waitcnt lgkmcnt(1)
	v_mfma_f32_16x16x32_bf16 v[14:17], v[6:9], v[14:17], 0
	s_nop 1
	v_max_f32_e32 v28, 0, v10
	v_max_f32_e32 v29, 0, v11
	v_max_f32_e32 v10, 0, v12
	v_mul_f32_e32 v30, v33, v10
	v_max_f32_e32 v39, 0, v13
	s_waitcnt lgkmcnt(0)
	v_mfma_f32_16x16x32_bf16 v[10:13], v[2:5], v[24:27], v[14:17]
	ds_read_b128 v[24:27], v159
	v_pk_mul_f32 v[38:39], v[32:33], v[38:39]
	s_nop 0
	ds_read_b128 v[14:17], v176
	s_waitcnt lgkmcnt(0)
	v_mfma_f32_16x16x32_bf16 v[14:17], v[6:9], v[14:17], 0
	s_nop 1
	v_max_f32_e32 v42, 0, v10
	v_max_f32_e32 v43, 0, v11
	v_max_f32_e32 v10, 0, v12
	v_mul_f32_e32 v44, v40, v10
	s_nop 0
	v_max_f32_e32 v46, 0, v13
	v_mfma_f32_16x16x32_bf16 v[10:13], v[2:5], v[24:27], v[14:17]
	ds_read_b128 v[24:27], v157
	v_mov_b32_e32 v37, v38
	v_mov_b32_e32 v31, v39
	ds_read_b128 v[14:17], v158
	s_waitcnt lgkmcnt(0)
	v_mfma_f32_16x16x32_bf16 v[14:17], v[6:9], v[14:17], 0
	s_nop 1
	v_max_f32_e32 v48, 0, v10
	v_max_f32_e32 v49, 0, v11
	v_max_f32_e32 v10, 0, v12
	v_mul_f32_e32 v50, v41, v10
	s_nop 0
	v_max_f32_e32 v47, 0, v13
	v_mfma_f32_16x16x32_bf16 v[10:13], v[2:5], v[24:27], v[14:17]
	ds_read_b128 v[24:27], v155
	v_pk_mul_f32 v[46:47], v[40:41], v[46:47]
	s_nop 0
	ds_read_b128 v[14:17], v156
	s_waitcnt lgkmcnt(0)
	v_mfma_f32_16x16x32_bf16 v[14:17], v[6:9], v[14:17], 0
	s_nop 1
	v_max_f32_e32 v54, 0, v10
	v_max_f32_e32 v55, 0, v11
	v_max_f32_e32 v10, 0, v12
	v_mul_f32_e32 v56, v52, v10
	s_nop 0
	v_max_f32_e32 v160, 0, v13
	v_mfma_f32_16x16x32_bf16 v[10:13], v[2:5], v[24:27], v[14:17]
	ds_read_b128 v[24:27], v153
	v_mov_b32_e32 v45, v46
	v_mov_b32_e32 v51, v47
	ds_read_b128 v[14:17], v154
	s_waitcnt lgkmcnt(0)
	v_mfma_f32_16x16x32_bf16 v[14:17], v[6:9], v[14:17], 0
	s_nop 1
	v_max_f32_e32 v162, 0, v10
	v_max_f32_e32 v163, 0, v11
	v_max_f32_e32 v10, 0, v12
	v_mul_f32_e32 v164, v53, v10
	s_nop 0
	v_max_f32_e32 v161, 0, v13
	v_mfma_f32_16x16x32_bf16 v[10:13], v[2:5], v[24:27], v[14:17]
	ds_read_b128 v[24:27], v151
	v_pk_mul_f32 v[160:161], v[52:53], v[160:161]
	s_nop 0
	ds_read_b128 v[14:17], v152
	s_waitcnt lgkmcnt(0)
	v_mfma_f32_16x16x32_bf16 v[6:9], v[6:9], v[14:17], 0
	s_nop 1
	s_nop 0
	v_max_f32_e32 v14, 0, v13
	s_nop 0
	v_mfma_f32_16x16x32_bf16 v[2:5], v[2:5], v[24:27], v[6:9]
	s_nop 0
	v_max_f32_e32 v10, 0, v10
	v_max_f32_e32 v11, 0, v11
	v_pk_fma_f32 v[8:9], v[32:33], v[34:35], 0 op_sel_hi:[0,1,0]
	s_nop 0
	s_nop 2
	v_max_f32_e32 v15, 0, v5
	v_pk_mul_f32 v[6:7], v[166:167], v[14:15]
	v_mov_b32_e32 v14, v33
	v_pk_fma_f32 v[8:9], v[14:15], v[28:29], v[8:9] op_sel_hi:[0,1,1]
	v_pk_fma_f32 v[8:9], v[40:41], v[42:43], v[8:9] op_sel_hi:[0,1,1]
	v_mov_b32_e32 v14, v41
	v_pk_fma_f32 v[8:9], v[14:15], v[48:49], v[8:9] op_sel_hi:[0,1,1]
	v_pk_fma_f32 v[8:9], v[52:53], v[54:55], v[8:9] op_sel_hi:[0,1,1]
	v_mov_b32_e32 v14, v53
	v_pk_fma_f32 v[8:9], v[14:15], v[162:163], v[8:9] op_sel_hi:[0,1,1]
	v_max_f32_e32 v2, 0, v2
	v_max_f32_e32 v3, 0, v3
	v_pk_fma_f32 v[8:9], v[166:167], v[10:11], v[8:9] op_sel_hi:[0,1,1]
	v_mov_b32_e32 v10, v167
	v_pk_fma_f32 v[2:3], v[10:11], v[2:3], v[8:9] op_sel_hi:[0,1,1]
	v_and_b32_e32 v9, 0x7fffffff, v3
	v_and_b32_e32 v8, 0x7fffffff, v2
	v_xor_b32_e32 v5, -1, v3
	v_pk_add_f32 v[8:9], v[8:9], 0 neg_lo:[1,1] neg_hi:[1,1]
	v_cmp_gt_i32_e32 vcc, 0, v3
	v_xor_b32_e32 v10, -1, v2
	v_mov_b32_e32 v57, v160
	v_cndmask_b32_e32 v195, v9, v5, vcc
	v_cmp_gt_i32_e32 vcc, 0, v2
	v_pk_add_f32 v[2:3], v[36:37], 0 op_sel_hi:[1,0]
	v_max_f32_e32 v12, 0, v12
	v_pk_add_f32 v[2:3], v[2:3], v[30:31]
	v_pk_add_f32 v[2:3], v[2:3], v[44:45]
	v_mov_b32_e32 v165, v161
	v_pk_add_f32 v[2:3], v[2:3], v[50:51]
	v_mul_f32_e32 v12, v166, v12
	v_pk_add_f32 v[2:3], v[2:3], v[56:57]
	v_max_f32_e32 v4, 0, v4
	v_pk_add_f32 v[2:3], v[2:3], v[164:165]
	v_mov_b32_e32 v13, v6
	v_mul_f32_e32 v4, v167, v4
	v_pk_add_f32 v[2:3], v[2:3], v[12:13]
	v_mov_b32_e32 v5, v7
	v_pk_add_f32 v[2:3], v[2:3], v[4:5]
	v_cndmask_b32_e32 v196, v8, v10, vcc
	v_and_b32_e32 v5, 0x7fffffff, v3
	v_and_b32_e32 v4, 0x7fffffff, v2
	v_xor_b32_e32 v6, -1, v3
	v_pk_add_f32 v[4:5], v[4:5], 0 neg_lo:[1,1] neg_hi:[1,1]
	v_cmp_gt_i32_e32 vcc, 0, v3
	v_xor_b32_e32 v7, -1, v2
	s_nop 0
	v_cndmask_b32_e32 v197, v5, v6, vcc
	v_cmp_gt_i32_e32 vcc, 0, v2
	v_lshrrev_b32_e32 v2, 24, v196
	v_lshl_add_u32 v2, v2, 6, v0
	ds_add_u32 v2, v205 offset:16384
	v_lshrrev_b32_e32 v2, 24, v195
	v_cndmask_b32_e32 v198, v4, v7, vcc
	v_lshl_add_u32 v2, v2, 6, v0
	ds_add_u32 v2, v205 offset:16384
	v_lshrrev_b32_e32 v2, 24, v198
	v_lshl_add_u32 v2, v2, 6, v0
	ds_add_u32 v2, v205 offset:16384
	v_lshrrev_b32_e32 v2, 24, v197
	v_lshl_add_u32 v2, v2, 6, v0
	ds_add_u32 v2, v205 offset:16384
	v_add_co_u32_e32 v2, vcc, s96, v22
	s_nop 1
	v_addc_co_u32_e32 v3, vcc, 0, v23, vcc
	global_load_dwordx4 v[14:17], v[2:3], off
	global_load_dwordx4 v[10:13], v[2:3], off offset:64
	global_load_dwordx4 v[6:9], v[2:3], off offset:2048
	s_nop 0
	global_load_dwordx4 v[2:5], v[2:3], off offset:2112
	ds_read_b128 v[22:25], v182
	ds_read_b128 v[26:29], v183
	s_waitcnt vmcnt(3) lgkmcnt(1)
; #define LAS __attribute__((address_space(3)))
; __device__ __forceinline__ unsigned fkey(float f) { const unsigned u = __float_as_uint(f); return (u & 0x80000000u) ? ~u : (u | 0x80000000u); }
; #define SEL_HADD(idx_) __hip_atomic_fetch_add(&hist[(idx_)], 1u, __ATOMIC_RELAXED, __HIP_MEMORY_SCOPE_WORKGROUP)
; __device__ __forceinline__ void sel_unit(LAS char* lds, int b, int u, const bf16_t* QI, const bf16_t* KIDX, const float* WIDX, unsigned long long* MASK) {
;     ...
;             for (int kh = 0; kh < 2; ++kh) {
;             bf16x8 kf[2][2];
; #pragma unroll
;             for (int kb = 0; kb < 2; ++kb)
; #pragma unroll
;                 for (int ks = 0; ks < 2; ++ks) kf[kb][ks] = *(const bf16x8*)(KIDX + (rowbase + 64 * t + 32 * kh + 16 * kb + q16) * 64 + 32 * ks + 8 * kg);
; #pragma unroll
;             for (int kb = 0; kb < 2; ++kb) {
;                 f32x4 s = (f32x4){0.f, 0.f, 0.f, 0.f};
; #pragma unroll
;                 for (int hh = 0; hh < 8; ++hh) {
;                     f32x4 a = (f32x4){0.f, 0.f, 0.f, 0.f};
; #pragma unroll
;                     for (int ks = 0; ks < 2; ++ks) {
;                         const bf16x8 qv = *(const LAS bf16x8*)(lds + L_QI + q16 * 1024 + (((hh * 8 + 4 * ks + kg) ^ q16) << 4));
;                         a = __builtin_amdgcn_mfma_f32_16x16x32_bf16(kf[kb][ks], qv, a, 0, 0, 0);
;                     }
;                     const float wh = wl[hh * 16];
; #pragma unroll
;                     for (int i = 0; i < 4; ++i) s[i] += wh * fmaxf(a[i], 0.f);
;                 }
;                 u32x4 kk; kk.x = fkey(s[0]); kk.y = fkey(s[1]); kk.z = fkey(s[2]); kk.w = fkey(s[3]);
;                 sc[j][2 * kh + kb] = kk;
; #pragma unroll
;                 for (int i = 0; i < 4; ++i) SEL_HADD((kk[i] >> 24) * 16 + q16);
;                 __builtin_amdgcn_sched_barrier(0);
	v_mfma_f32_16x16x32_bf16 v[22:25], v[14:17], v[22:25], 0
	ds_read_b128 v[32:35], v185
	ds_read_b128 v[38:41], v180
	ds_read_b128 v[44:47], v159
	s_waitcnt vmcnt(2) lgkmcnt(3)
	v_mfma_f32_16x16x32_bf16 v[26:29], v[10:13], v[26:29], v[22:25]
	ds_read_b128 v[50:53], v157
	ds_read_b128 v[160:163], v155
	s_nop 0
	ds_read2_b32 v[24:25], v137 offset0:80 offset1:96
	s_nop 3
	v_max_f32_e32 v26, 0, v26
	v_max_f32_e32 v27, 0, v27
	v_max_f32_e32 v22, v28, v28
	v_max_f32_e32 v23, v29, v29
	ds_read_b128 v[28:31], v184
	s_waitcnt lgkmcnt(0)
	v_mfma_f32_16x16x32_bf16 v[28:31], v[14:17], v[28:31], 0
	v_max_f32_e32 v36, 0, v23
	v_max_f32_e32 v22, 0, v22
	v_mul_f32_e32 v22, v24, v22
	v_mfma_f32_16x16x32_bf16 v[28:31], v[10:13], v[32:35], v[28:31]
	s_nop 7
	v_max_f32_e32 v32, 0, v28
	v_max_f32_e32 v33, 0, v29
	v_max_f32_e32 v23, 0, v30
	v_mul_f32_e32 v28, v25, v23
	v_max_f32_e32 v37, 0, v31
	v_pk_mul_f32 v[30:31], v[24:25], v[36:37]
	ds_read_b128 v[34:37], v179
	s_waitcnt lgkmcnt(0)
	v_mfma_f32_16x16x32_bf16 v[34:37], v[14:17], v[34:37], 0
	v_mov_b32_e32 v29, v31
	v_mfma_f32_16x16x32_bf16 v[38:41], v[10:13], v[38:41], v[34:37]
	s_nop 5
	ds_read2_b32 v[36:37], v137 offset0:112 offset1:128
	s_nop 0
	v_max_f32_e32 v38, 0, v38
	v_max_f32_e32 v39, 0, v39
	v_max_f32_e32 v23, 0, v40
	s_waitcnt lgkmcnt(0)
	v_mul_f32_e32 v34, v36, v23
	v_max_f32_e32 v23, v41, v41
	ds_read_b128 v[40:43], v176
	s_waitcnt lgkmcnt(0)
	v_mfma_f32_16x16x32_bf16 v[40:43], v[14:17], v[40:43], 0
	v_max_f32_e32 v48, 0, v23
	v_mfma_f32_16x16x32_bf16 v[40:43], v[10:13], v[44:47], v[40:43]
	s_nop 7
	v_max_f32_e32 v44, 0, v40
	v_max_f32_e32 v45, 0, v41
	v_max_f32_e32 v23, 0, v42
	v_mul_f32_e32 v40, v37, v23
	v_max_f32_e32 v49, 0, v43
	v_pk_mul_f32 v[42:43], v[36:37], v[48:49]
	ds_read_b128 v[46:49], v158
	s_waitcnt lgkmcnt(0)
	v_mfma_f32_16x16x32_bf16 v[46:49], v[14:17], v[46:49], 0
	v_mov_b32_e32 v35, v42
	v_mov_b32_e32 v41, v43
	v_mfma_f32_16x16x32_bf16 v[50:53], v[10:13], v[50:53], v[46:49]
	s_nop 4
	ds_read2_b32 v[48:49], v137 offset0:144 offset1:160
	s_nop 1
	v_max_f32_e32 v50, 0, v50
	v_max_f32_e32 v51, 0, v51
	v_max_f32_e32 v23, 0, v52
	s_waitcnt lgkmcnt(0)
	v_mul_f32_e32 v46, v48, v23
	v_max_f32_e32 v23, v53, v53
	ds_read_b128 v[52:55], v156
	s_waitcnt lgkmcnt(0)
	v_mfma_f32_16x16x32_bf16 v[52:55], v[14:17], v[52:55], 0
	v_max_f32_e32 v164, 0, v23
	v_mfma_f32_16x16x32_bf16 v[52:55], v[10:13], v[160:163], v[52:55]
	ds_read_b128 v[160:163], v154
	s_nop 6
	v_max_f32_e32 v56, 0, v52
	v_max_f32_e32 v57, 0, v53
	v_max_f32_e32 v23, 0, v54
	v_mul_f32_e32 v52, v49, v23
	v_max_f32_e32 v165, 0, v55
	v_pk_mul_f32 v[54:55], v[48:49], v[164:165]
	ds_read_b128 v[164:167], v153
	s_waitcnt lgkmcnt(1)
	v_mfma_f32_16x16x32_bf16 v[160:163], v[14:17], v[160:163], 0
	v_mov_b32_e32 v47, v54
	v_mov_b32_e32 v53, v55
	s_waitcnt lgkmcnt(0)
	v_mfma_f32_16x16x32_bf16 v[160:163], v[10:13], v[164:167], v[160:163]
	ds_read2_b32 v[164:165], v137 offset0:176 offset1:192
	s_nop 6
	v_max_f32_e32 v166, 0, v160
	v_max_f32_e32 v167, 0, v161
	v_max_f32_e32 v23, 0, v162
	s_waitcnt lgkmcnt(0)
	v_mul_f32_e32 v168, v164, v23
	v_max_f32_e32 v23, v163, v163
	ds_read_b128 v[160:163], v152
	s_waitcnt lgkmcnt(0)
	v_mfma_f32_16x16x32_bf16 v[14:17], v[14:17], v[160:163], 0
	ds_read_b128 v[160:163], v151
	v_max_f32_e32 v170, 0, v23
	s_waitcnt lgkmcnt(0)
	v_mfma_f32_16x16x32_bf16 v[10:13], v[10:13], v[160:163], v[14:17]
	s_nop 3
	v_fma_f32 v16, v24, v26, 0
	v_fma_f32 v17, v24, v27, 0
	v_mov_b32_e32 v24, v25
	v_pk_fma_f32 v[16:17], v[24:25], v[32:33], v[16:17] op_sel_hi:[0,1,1]
	v_pk_fma_f32 v[16:17], v[36:37], v[38:39], v[16:17] op_sel_hi:[0,1,1]
	v_mov_b32_e32 v24, v37
	v_pk_fma_f32 v[16:17], v[24:25], v[44:45], v[16:17] op_sel_hi:[0,1,1]
	v_pk_fma_f32 v[16:17], v[48:49], v[50:51], v[16:17] op_sel_hi:[0,1,1]
	v_mov_b32_e32 v24, v49
	v_pk_fma_f32 v[16:17], v[24:25], v[56:57], v[16:17] op_sel_hi:[0,1,1]
	v_max_f32_e32 v10, 0, v10
	v_max_f32_e32 v11, 0, v11
	v_pk_fma_f32 v[16:17], v[164:165], v[166:167], v[16:17] op_sel_hi:[0,1,1]
	v_mov_b32_e32 v24, v165
	v_pk_fma_f32 v[10:11], v[24:25], v[10:11], v[16:17] op_sel_hi:[0,1,1]
	v_and_b32_e32 v17, 0x7fffffff, v11
	v_and_b32_e32 v16, 0x7fffffff, v10
	v_xor_b32_e32 v23, -1, v10
	v_pk_add_f32 v[16:17], v[16:17], 0 neg_lo:[1,1] neg_hi:[1,1]
	v_cmp_gt_i32_e32 vcc, 0, v10
	v_max_f32_e32 v171, 0, v13
	s_nop 0
	v_cndmask_b32_e32 v57, v16, v23, vcc
	v_mov_b32_e32 v23, v30
	v_xor_b32_e32 v13, -1, v11
	v_cmp_gt_i32_e64 s[2:3], 0, v11
	v_pk_add_f32 v[10:11], v[22:23], 0 op_sel_hi:[1,0]
	v_pk_add_f32 v[10:11], v[10:11], v[28:29]
	v_pk_mul_f32 v[14:15], v[164:165], v[170:171]
	v_pk_add_f32 v[10:11], v[10:11], v[34:35]
	v_max_f32_e32 v12, 0, v12
	v_pk_add_f32 v[10:11], v[10:11], v[40:41]
	v_mov_b32_e32 v169, v14
	v_pk_add_f32 v[10:11], v[10:11], v[46:47]
	v_mul_f32_e32 v12, v165, v12
	v_pk_add_f32 v[10:11], v[10:11], v[52:53]
	v_cndmask_b32_e64 v56, v17, v13, s[2:3]
	v_pk_add_f32 v[10:11], v[10:11], v[168:169]
	v_mov_b32_e32 v13, v15
	v_pk_add_f32 v[10:11], v[10:11], v[12:13]
	s_nop 0
	v_xor_b32_e32 v15, -1, v10
	v_and_b32_e32 v12, 0x7fffffff, v10
	v_cmp_gt_i32_e32 vcc, 0, v10
	v_lshrrev_b32_e32 v10, 24, v57
	v_and_b32_e32 v13, 0x7fffffff, v11
	v_lshl_add_u32 v10, v10, 6, v0
	v_pk_add_f32 v[12:13], v[12:13], 0 neg_lo:[1,1] neg_hi:[1,1]
	ds_add_u32 v10, v205 offset:16384
	v_lshrrev_b32_e32 v10, 24, v56
	v_cndmask_b32_e32 v55, v12, v15, vcc
	v_lshl_add_u32 v10, v10, 6, v0
	v_xor_b32_e32 v14, -1, v11
	v_cmp_gt_i32_e64 s[2:3], 0, v11
	ds_add_u32 v10, v205 offset:16384
	v_lshrrev_b32_e32 v10, 24, v55
	v_cndmask_b32_e64 v54, v13, v14, s[2:3]
	v_lshl_add_u32 v10, v10, 6, v0
	ds_add_u32 v10, v205 offset:16384
	v_lshrrev_b32_e32 v10, 24, v54
	v_lshl_add_u32 v10, v10, 6, v0
	ds_add_u32 v10, v205 offset:16384
	ds_read_b128 v[10:13], v182
	ds_read_b128 v[14:17], v183
	ds_read_b128 v[22:25], v184
	ds_read_b128 v[26:29], v185
	ds_read2_b32 v[30:31], v137 offset0:80 offset1:96
	ds_read2_b32 v[38:39], v137 offset0:112 offset1:128
	s_waitcnt vmcnt(1) lgkmcnt(5)
; #define LAS __attribute__((address_space(3)))
; __device__ __forceinline__ unsigned fkey(float f) { const unsigned u = __float_as_uint(f); return (u & 0x80000000u) ? ~u : (u | 0x80000000u); }
; #define SEL_HADD(idx_) __hip_atomic_fetch_add(&hist[(idx_)], 1u, __ATOMIC_RELAXED, __HIP_MEMORY_SCOPE_WORKGROUP)
; __device__ __forceinline__ void sel_unit(LAS char* lds, int b, int u, const bf16_t* QI, const bf16_t* KIDX, const float* WIDX, unsigned long long* MASK) {
;     ...
;             for (int kh = 0; kh < 2; ++kh) {
;             bf16x8 kf[2][2];
; #pragma unroll
;             for (int kb = 0; kb < 2; ++kb)
; #pragma unroll
;                 for (int ks = 0; ks < 2; ++ks) kf[kb][ks] = *(const bf16x8*)(KIDX + (rowbase + 64 * t + 32 * kh + 16 * kb + q16) * 64 + 32 * ks + 8 * kg);
; #pragma unroll
;             for (int kb = 0; kb < 2; ++kb) {
;                 f32x4 s = (f32x4){0.f, 0.f, 0.f, 0.f};
; #pragma unroll
;                 for (int hh = 0; hh < 8; ++hh) {
;                     f32x4 a = (f32x4){0.f, 0.f, 0.f, 0.f};
; #pragma unroll
;                     for (int ks = 0; ks < 2; ++ks) {
;                         const bf16x8 qv = *(const LAS bf16x8*)(lds + L_QI + q16 * 1024 + (((hh * 8 + 4 * ks + kg) ^ q16) << 4));
;                         a = __builtin_amdgcn_mfma_f32_16x16x32_bf16(kf[kb][ks], qv, a, 0, 0, 0);
;                     }
;                     const float wh = wl[hh * 16];
; #pragma unroll
;                     for (int i = 0; i < 4; ++i) s[i] += wh * fmaxf(a[i], 0.f);
;                 }
;                 u32x4 kk; kk.x = fkey(s[0]); kk.y = fkey(s[1]); kk.z = fkey(s[2]); kk.w = fkey(s[3]);
;                 sc[j][2 * kh + kb] = kk;
; #pragma unroll
;                 for (int i = 0; i < 4; ++i) SEL_HADD((kk[i] >> 24) * 16 + q16);
;                 __builtin_amdgcn_sched_barrier(0);
	v_mfma_f32_16x16x32_bf16 v[10:13], v[6:9], v[10:13], 0
	ds_read2_b32 v[50:51], v137 offset0:144 offset1:160
	ds_read2_b32 v[168:169], v137 offset0:176 offset1:192
	s_waitcnt vmcnt(0) lgkmcnt(6)
	v_mfma_f32_16x16x32_bf16 v[10:13], v[2:5], v[14:17], v[10:13]
	ds_read_b128 v[14:17], v179
	s_waitcnt lgkmcnt(6)
	v_mfma_f32_16x16x32_bf16 v[22:25], v[6:9], v[22:25], 0
	s_nop 4
	v_max_f32_e32 v32, 0, v10
	v_max_f32_e32 v10, 0, v12
	v_max_f32_e32 v33, 0, v11
	s_waitcnt lgkmcnt(4)
	v_mul_f32_e32 v34, v30, v10
	v_max_f32_e32 v36, 0, v13
	v_mfma_f32_16x16x32_bf16 v[10:13], v[2:5], v[26:29], v[22:25]
	s_nop 2
	ds_read_b128 v[22:25], v180
	s_waitcnt lgkmcnt(1)
	v_mfma_f32_16x16x32_bf16 v[14:17], v[6:9], v[14:17], 0
	s_nop 1
	v_max_f32_e32 v26, 0, v10
	v_max_f32_e32 v27, 0, v11
	v_max_f32_e32 v10, 0, v12
	v_mul_f32_e32 v28, v31, v10
	v_max_f32_e32 v37, 0, v13
	s_waitcnt lgkmcnt(0)
	v_mfma_f32_16x16x32_bf16 v[10:13], v[2:5], v[22:25], v[14:17]
	ds_read_b128 v[22:25], v159
	v_pk_mul_f32 v[36:37], v[30:31], v[36:37]
	s_nop 0
	ds_read_b128 v[14:17], v176
	s_waitcnt lgkmcnt(0)
	v_mfma_f32_16x16x32_bf16 v[14:17], v[6:9], v[14:17], 0
	s_nop 1
	v_max_f32_e32 v40, 0, v10
	v_max_f32_e32 v41, 0, v11
	v_max_f32_e32 v10, 0, v12
	v_mul_f32_e32 v42, v38, v10
	s_nop 0
	v_max_f32_e32 v44, 0, v13
	v_mfma_f32_16x16x32_bf16 v[10:13], v[2:5], v[22:25], v[14:17]
	ds_read_b128 v[22:25], v157
	v_mov_b32_e32 v35, v36
	v_mov_b32_e32 v29, v37
	ds_read_b128 v[14:17], v158
	s_waitcnt lgkmcnt(0)
	v_mfma_f32_16x16x32_bf16 v[14:17], v[6:9], v[14:17], 0
	s_nop 1
	v_max_f32_e32 v46, 0, v10
	v_max_f32_e32 v47, 0, v11
	v_max_f32_e32 v10, 0, v12
	v_mul_f32_e32 v48, v39, v10
	s_nop 0
	v_max_f32_e32 v45, 0, v13
	v_mfma_f32_16x16x32_bf16 v[10:13], v[2:5], v[22:25], v[14:17]
	ds_read_b128 v[22:25], v155
	v_pk_mul_f32 v[44:45], v[38:39], v[44:45]
	s_nop 0
	ds_read_b128 v[14:17], v156
	s_waitcnt lgkmcnt(0)
	v_mfma_f32_16x16x32_bf16 v[14:17], v[6:9], v[14:17], 0
	s_nop 1
	v_max_f32_e32 v52, 0, v10
	v_max_f32_e32 v53, 0, v11
	v_max_f32_e32 v10, 0, v12
	v_mul_f32_e32 v160, v50, v10
	s_nop 0
	v_max_f32_e32 v162, 0, v13
	v_mfma_f32_16x16x32_bf16 v[10:13], v[2:5], v[22:25], v[14:17]
	ds_read_b128 v[22:25], v153
	v_mov_b32_e32 v43, v44
	v_mov_b32_e32 v49, v45
	ds_read_b128 v[14:17], v154
	s_waitcnt lgkmcnt(0)
	v_mfma_f32_16x16x32_bf16 v[14:17], v[6:9], v[14:17], 0
	s_nop 1
	v_max_f32_e32 v164, 0, v10
	v_max_f32_e32 v165, 0, v11
	v_max_f32_e32 v10, 0, v12
	v_mul_f32_e32 v166, v51, v10
	s_nop 0
	v_max_f32_e32 v163, 0, v13
	v_mfma_f32_16x16x32_bf16 v[10:13], v[2:5], v[22:25], v[14:17]
	ds_read_b128 v[22:25], v151
	v_pk_mul_f32 v[162:163], v[50:51], v[162:163]
	s_nop 0
	ds_read_b128 v[14:17], v152
	s_waitcnt lgkmcnt(0)
	v_mfma_f32_16x16x32_bf16 v[6:9], v[6:9], v[14:17], 0
	s_nop 1
	s_nop 0
	v_max_f32_e32 v14, 0, v13
	s_nop 0
	v_mfma_f32_16x16x32_bf16 v[2:5], v[2:5], v[22:25], v[6:9]
	s_nop 0
	v_max_f32_e32 v10, 0, v10
	v_max_f32_e32 v11, 0, v11
	v_pk_fma_f32 v[8:9], v[30:31], v[32:33], 0 op_sel_hi:[0,1,0]
	s_nop 0
	s_nop 2
	v_max_f32_e32 v15, 0, v5
	v_pk_mul_f32 v[6:7], v[168:169], v[14:15]
	v_mov_b32_e32 v14, v31
	v_pk_fma_f32 v[8:9], v[14:15], v[26:27], v[8:9] op_sel_hi:[0,1,1]
	v_pk_fma_f32 v[8:9], v[38:39], v[40:41], v[8:9] op_sel_hi:[0,1,1]
	v_mov_b32_e32 v14, v39
	v_pk_fma_f32 v[8:9], v[14:15], v[46:47], v[8:9] op_sel_hi:[0,1,1]
	v_pk_fma_f32 v[8:9], v[50:51], v[52:53], v[8:9] op_sel_hi:[0,1,1]
	v_mov_b32_e32 v14, v51
	v_pk_fma_f32 v[8:9], v[14:15], v[164:165], v[8:9] op_sel_hi:[0,1,1]
	v_max_f32_e32 v2, 0, v2
	v_max_f32_e32 v3, 0, v3
	v_pk_fma_f32 v[8:9], v[168:169], v[10:11], v[8:9] op_sel_hi:[0,1,1]
	v_mov_b32_e32 v10, v169
	v_pk_fma_f32 v[2:3], v[10:11], v[2:3], v[8:9] op_sel_hi:[0,1,1]
	v_and_b32_e32 v9, 0x7fffffff, v3
	v_and_b32_e32 v8, 0x7fffffff, v2
	v_xor_b32_e32 v5, -1, v3
	v_pk_add_f32 v[8:9], v[8:9], 0 neg_lo:[1,1] neg_hi:[1,1]
	v_cmp_gt_i32_e32 vcc, 0, v3
	v_xor_b32_e32 v10, -1, v2
	v_mov_b32_e32 v161, v162
	v_cndmask_b32_e32 v199, v9, v5, vcc
	v_cmp_gt_i32_e32 vcc, 0, v2
	v_pk_add_f32 v[2:3], v[34:35], 0 op_sel_hi:[1,0]
	v_max_f32_e32 v12, 0, v12
	v_pk_add_f32 v[2:3], v[2:3], v[28:29]
	v_pk_add_f32 v[2:3], v[2:3], v[42:43]
	v_mov_b32_e32 v167, v163
	v_pk_add_f32 v[2:3], v[2:3], v[48:49]
	v_mul_f32_e32 v12, v168, v12
	v_pk_add_f32 v[2:3], v[2:3], v[160:161]
	v_max_f32_e32 v4, 0, v4
	v_pk_add_f32 v[2:3], v[2:3], v[166:167]
	v_mov_b32_e32 v13, v6
	v_mul_f32_e32 v4, v169, v4
	v_pk_add_f32 v[2:3], v[2:3], v[12:13]
	v_mov_b32_e32 v5, v7
	v_pk_add_f32 v[2:3], v[2:3], v[4:5]
	v_cndmask_b32_e32 v218, v8, v10, vcc
	v_and_b32_e32 v5, 0x7fffffff, v3
	v_and_b32_e32 v4, 0x7fffffff, v2
	v_xor_b32_e32 v6, -1, v3
	v_pk_add_f32 v[4:5], v[4:5], 0 neg_lo:[1,1] neg_hi:[1,1]
	v_cmp_gt_i32_e32 vcc, 0, v3
	v_xor_b32_e32 v7, -1, v2
	s_nop 0
	v_cndmask_b32_e32 v219, v5, v6, vcc
	v_cmp_gt_i32_e32 vcc, 0, v2
	v_lshrrev_b32_e32 v2, 24, v218
	v_lshl_add_u32 v2, v2, 6, v0
	ds_add_u32 v2, v205 offset:16384
	v_lshrrev_b32_e32 v2, 24, v199
	v_cndmask_b32_e32 v220, v4, v7, vcc
	v_lshl_add_u32 v2, v2, 6, v0
	ds_add_u32 v2, v205 offset:16384
	v_lshrrev_b32_e32 v2, 24, v220
	v_lshl_add_u32 v2, v2, 6, v0
	ds_add_u32 v2, v205 offset:16384
	v_lshrrev_b32_e32 v2, 24, v219
	v_lshl_add_u32 v2, v2, 6, v0
	ds_add_u32 v2, v205 offset:16384
; #define LAS __attribute__((address_space(3)))
; __device__ __forceinline__ unsigned fkey(float f) { const unsigned u = __float_as_uint(f); return (u & 0x80000000u) ? ~u : (u | 0x80000000u); }
; #define SEL_HADD(idx_) __hip_atomic_fetch_add(&hist[(idx_)], 1u, __ATOMIC_RELAXED, __HIP_MEMORY_SCOPE_WORKGROUP)
; __device__ __forceinline__ void sel_unit(LAS char* lds, int b, int u, const bf16_t* QI, const bf16_t* KIDX, const float* WIDX, unsigned long long* MASK) {
;     ...
;     for (int j = 0; j < 8; ++j) {
;         if (j < nj) {
;             int t = wid + 8 * j; asm volatile("" : "+s"(t));
; #pragma unroll
;             for (int kh = 0; kh < 2; ++kh) {
;             bf16x8 kf[2][2];
; #pragma unroll
;             for (int kb = 0; kb < 2; ++kb)
; #pragma unroll
;                 for (int ks = 0; ks < 2; ++ks) kf[kb][ks] = *(const bf16x8*)(KIDX + (rowbase + 64 * t + 32 * kh + 16 * kb + q16) * 64 + 32 * ks + 8 * kg);
; #pragma unroll
;             for (int kb = 0; kb < 2; ++kb) {
;                 f32x4 s = (f32x4){0.f, 0.f, 0.f, 0.f};
; #pragma unroll
;                 for (int hh = 0; hh < 8; ++hh) {
;                     f32x4 a = (f32x4){0.f, 0.f, 0.f, 0.f};
; #pragma unroll
;                     for (int ks = 0; ks < 2; ++ks) {
;                         const bf16x8 qv = *(const LAS bf16x8*)(lds + L_QI + q16 * 1024 + (((hh * 8 + 4 * ks + kg) ^ q16) << 4));
;                         a = __builtin_amdgcn_mfma_f32_16x16x32_bf16(kf[kb][ks], qv, a, 0, 0, 0);
;                     }
;                     const float wh = wl[hh * 16];
; #pragma unroll
;                     for (int i = 0; i < 4; ++i) s[i] += wh * fmaxf(a[i], 0.f);
;                 }
;                 u32x4 kk; kk.x = fkey(s[0]); kk.y = fkey(s[1]); kk.z = fkey(s[2]); kk.w = fkey(s[3]);
;                 sc[j][2 * kh + kb] = kk;
; #pragma unroll
;                 for (int i = 0; i < 4; ++i) SEL_HADD((kk[i] >> 24) * 16 + q16);
;                 __builtin_amdgcn_sched_barrier(0);
.LBB0_670:
	s_cmp_gt_i32 s4, 7
	s_cselect_b64 s[26:27], -1, 0
	s_cmp_lt_i32 s4, 8
	s_cbranch_scc1 .LBB0_672
	s_add_i32 s2, s46, 56
	s_lshl_b32 s2, s2, 6
	s_ashr_i32 s3, s2, 31
	v_lshl_add_u64 v[2:3], v[18:19], 0, s[2:3]
	v_lshlrev_b64 v[2:3], 7, v[2:3]
	v_lshl_add_u64 v[18:19], v[20:21], 0, v[2:3]
	global_load_dwordx4 v[14:17], v[18:19], off
	global_load_dwordx4 v[10:13], v[18:19], off offset:64
	ds_read_b128 v[2:5], v182
	ds_read_b128 v[6:9], v183
	ds_read_b128 v[20:23], v184
	ds_read_b128 v[24:27], v185
	ds_read_b128 v[28:31], v179
	ds_read_b128 v[32:35], v180
	ds_read_b128 v[36:39], v176
	ds_read_b128 v[40:43], v159
	ds_read_b128 v[44:47], v158
	ds_read_b128 v[48:51], v157
	ds_read_b128 v[160:163], v156
	ds_read_b128 v[164:167], v155
	s_waitcnt vmcnt(1) lgkmcnt(11)
	v_mfma_f32_16x16x32_bf16 v[2:5], v[14:17], v[2:5], 0
	s_waitcnt lgkmcnt(9)
	v_mfma_f32_16x16x32_bf16 v[20:23], v[14:17], v[20:23], 0
	s_waitcnt lgkmcnt(7)
	v_mfma_f32_16x16x32_bf16 v[28:31], v[14:17], v[28:31], 0
	s_waitcnt lgkmcnt(5)
	v_mfma_f32_16x16x32_bf16 v[36:39], v[14:17], v[36:39], 0
	s_waitcnt lgkmcnt(3)
	v_mfma_f32_16x16x32_bf16 v[44:47], v[14:17], v[44:47], 0
	s_waitcnt vmcnt(0)
	v_mfma_f32_16x16x32_bf16 v[168:171], v[10:13], v[6:9], v[2:5]
	v_mfma_f32_16x16x32_bf16 v[20:23], v[10:13], v[24:27], v[20:23]
	v_mfma_f32_16x16x32_bf16 v[24:27], v[10:13], v[32:35], v[28:31]
	v_mfma_f32_16x16x32_bf16 v[28:31], v[10:13], v[40:43], v[36:39]
	ds_read2_b32 v[40:41], v137 offset0:80 offset1:96
	ds_read2_b32 v[42:43], v137 offset0:112 offset1:128
	s_nop 3
	s_waitcnt lgkmcnt(4)
	v_mfma_f32_16x16x32_bf16 v[32:35], v[10:13], v[48:51], v[44:47]
	ds_read2_b32 v[44:45], v137 offset0:144 offset1:160
	global_load_dwordx4 v[6:9], v[18:19], off offset:2048
	global_load_dwordx4 v[2:5], v[18:19], off offset:2112
	s_waitcnt lgkmcnt(4)
	v_mfma_f32_16x16x32_bf16 v[160:163], v[14:17], v[160:163], 0
	s_nop 0
	s_nop 0
	v_max_f32_e32 v50, v20, v20
	s_waitcnt lgkmcnt(3)
	v_mfma_f32_16x16x32_bf16 v[36:39], v[10:13], v[164:167], v[160:163]
	s_nop 0
	v_max_f32_e32 v20, 0, v171
	v_max_f32_e32 v164, 0, v22
	v_max_f32_e32 v160, v35, v35
	v_max_f32_e32 v35, 0, v21
	s_nop 2
	v_max_f32_e32 v21, 0, v23
	v_max_f32_e32 v22, 0, v27
	v_max_f32_e32 v23, 0, v31
	v_max_f32_e32 v51, v32, v32
	v_max_f32_e32 v53, v34, v34
	v_max_f32_e32 v32, 0, v168
	v_max_f32_e32 v34, 0, v50
	v_max_f32_e32 v46, 0, v28
	v_max_f32_e32 v28, 0, v160
	v_max_f32_e32 v50, 0, v36
	s_waitcnt lgkmcnt(2)
	v_pk_mul_f32 v[160:161], v[40:41], v[20:21]
	s_waitcnt lgkmcnt(1)
	v_pk_mul_f32 v[166:167], v[42:43], v[22:23]
	ds_read_b128 v[20:23], v154
	v_max_f32_e32 v162, v37, v37
	v_max_f32_e32 v163, v38, v38
	v_max_f32_e32 v36, 0, v24
	v_max_f32_e32 v24, 0, v26
	v_max_f32_e32 v38, 0, v170
	v_max_f32_e32 v37, 0, v25
	v_max_f32_e32 v25, 0, v30
	v_max_f32_e32 v48, 0, v51
	v_max_f32_e32 v26, 0, v53
	v_max_f32_e32 v51, 0, v162
	v_mul_f32_e32 v162, v42, v24
	v_max_f32_e32 v24, 0, v163
	v_max_f32_e32 v49, 0, v33
	v_mul_f32_e32 v52, v41, v164
	v_mul_f32_e32 v164, v43, v25
	s_waitcnt lgkmcnt(1)
	v_mul_f32_e32 v168, v44, v26
	v_mul_f32_e32 v170, v45, v24
	ds_read_b128 v[24:27], v153
	s_waitcnt lgkmcnt(1)
	v_mfma_f32_16x16x32_bf16 v[20:23], v[14:17], v[20:23], 0
	v_max_f32_e32 v33, 0, v169
	s_waitcnt lgkmcnt(0)
	v_mfma_f32_16x16x32_bf16 v[20:23], v[10:13], v[24:27], v[20:23]
	ds_read_b128 v[24:27], v152
	v_max_f32_e32 v47, 0, v29
	v_max_f32_e32 v29, 0, v39
	v_pk_mul_f32 v[172:173], v[44:45], v[28:29]
	ds_read_b128 v[28:31], v151
	s_waitcnt lgkmcnt(1)
	v_mfma_f32_16x16x32_bf16 v[14:17], v[14:17], v[24:27], 0
	ds_read2_b32 v[174:175], v137 offset0:176 offset1:192
	s_nop 0
	v_max_f32_e32 v24, 0, v23
	s_waitcnt lgkmcnt(1)
	v_mfma_f32_16x16x32_bf16 v[10:13], v[10:13], v[28:31], v[14:17]
	s_nop 0
	s_nop 0
	v_max_f32_e32 v20, 0, v20
	v_pk_fma_f32 v[16:17], v[40:41], v[32:33], 0 op_sel_hi:[0,1,0]
	v_max_f32_e32 v21, 0, v21
	s_nop 2
	v_max_f32_e32 v25, 0, v13
	s_waitcnt lgkmcnt(0)
	v_pk_mul_f32 v[14:15], v[174:175], v[24:25]
	v_mov_b32_e32 v24, v41
	v_pk_fma_f32 v[16:17], v[24:25], v[34:35], v[16:17] op_sel_hi:[0,1,1]
	v_pk_fma_f32 v[16:17], v[42:43], v[36:37], v[16:17] op_sel_hi:[0,1,1]
	v_mov_b32_e32 v24, v43
	v_pk_fma_f32 v[16:17], v[24:25], v[46:47], v[16:17] op_sel_hi:[0,1,1]
	v_pk_fma_f32 v[16:17], v[44:45], v[48:49], v[16:17] op_sel_hi:[0,1,1]
	v_mov_b32_e32 v24, v45
	v_pk_fma_f32 v[16:17], v[24:25], v[50:51], v[16:17] op_sel_hi:[0,1,1]
	v_max_f32_e32 v10, 0, v10
	v_max_f32_e32 v11, 0, v11
	v_pk_fma_f32 v[16:17], v[174:175], v[20:21], v[16:17] op_sel_hi:[0,1,1]
	v_mov_b32_e32 v20, v175
	v_pk_fma_f32 v[10:11], v[20:21], v[10:11], v[16:17] op_sel_hi:[0,1,1]
	v_and_b32_e32 v17, 0x7fffffff, v11
	v_and_b32_e32 v16, 0x7fffffff, v10
	v_mul_f32_e32 v38, v40, v38
	v_xor_b32_e32 v13, -1, v11
	v_pk_add_f32 v[16:17], v[16:17], 0 neg_lo:[1,1] neg_hi:[1,1]
	v_cmp_gt_i32_e32 vcc, 0, v11
	v_mov_b32_e32 v39, v160
	v_xor_b32_e32 v20, -1, v10
	v_cndmask_b32_e32 v221, v17, v13, vcc
	v_cmp_gt_i32_e32 vcc, 0, v10
	v_pk_add_f32 v[10:11], v[38:39], 0 op_sel_hi:[1,0]
	v_mov_b32_e32 v53, v161
	v_pk_add_f32 v[10:11], v[10:11], v[52:53]
	v_mov_b32_e32 v163, v166
	v_pk_add_f32 v[10:11], v[10:11], v[162:163]
	v_mov_b32_e32 v165, v167
	v_pk_add_f32 v[10:11], v[10:11], v[164:165]
	v_mov_b32_e32 v169, v172
	v_max_f32_e32 v22, 0, v22
	v_pk_add_f32 v[10:11], v[10:11], v[168:169]
	v_mov_b32_e32 v171, v173
	v_mul_f32_e32 v22, v174, v22
	v_max_f32_e32 v12, 0, v12
	v_pk_add_f32 v[10:11], v[10:11], v[170:171]
	v_mov_b32_e32 v23, v14
	v_mul_f32_e32 v12, v175, v12
	v_pk_add_f32 v[10:11], v[10:11], v[22:23]
	v_mov_b32_e32 v13, v15
	v_pk_add_f32 v[10:11], v[10:11], v[12:13]
	v_cndmask_b32_e32 v222, v16, v20, vcc
	v_and_b32_e32 v13, 0x7fffffff, v11
	v_and_b32_e32 v12, 0x7fffffff, v10
	v_xor_b32_e32 v14, -1, v11
	v_pk_add_f32 v[12:13], v[12:13], 0 neg_lo:[1,1] neg_hi:[1,1]
	v_cmp_gt_i32_e32 vcc, 0, v11
	v_xor_b32_e32 v15, -1, v10
	s_nop 0
	v_cndmask_b32_e32 v223, v13, v14, vcc
	v_cmp_gt_i32_e32 vcc, 0, v10
	v_lshrrev_b32_e32 v10, 24, v222
	v_lshl_add_u32 v10, v10, 6, v0
	ds_add_u32 v10, v205 offset:16384
	v_lshrrev_b32_e32 v10, 24, v221
	v_cndmask_b32_e32 v224, v12, v15, vcc
	v_lshl_add_u32 v10, v10, 6, v0
	ds_add_u32 v10, v205 offset:16384
	v_lshrrev_b32_e32 v10, 24, v224
	v_lshl_add_u32 v10, v10, 6, v0
	ds_add_u32 v10, v205 offset:16384
	v_lshrrev_b32_e32 v10, 24, v223
	v_lshl_add_u32 v10, v10, 6, v0
	ds_add_u32 v10, v205 offset:16384
	ds_read_b128 v[10:13], v182
	ds_read_b128 v[14:17], v183
	ds_read_b128 v[20:23], v184
	ds_read_b128 v[24:27], v185
	ds_read2_b32 v[28:29], v137 offset0:80 offset1:96
	ds_read2_b32 v[36:37], v137 offset0:112 offset1:128
	s_waitcnt vmcnt(1) lgkmcnt(5)
; #define LAS __attribute__((address_space(3)))
; __device__ __forceinline__ unsigned fkey(float f) { const unsigned u = __float_as_uint(f); return (u & 0x80000000u) ? ~u : (u | 0x80000000u); }
; #define SEL_HADD(idx_) __hip_atomic_fetch_add(&hist[(idx_)], 1u, __ATOMIC_RELAXED, __HIP_MEMORY_SCOPE_WORKGROUP)
; __device__ __forceinline__ void sel_unit(LAS char* lds, int b, int u, const bf16_t* QI, const bf16_t* KIDX, const float* WIDX, unsigned long long* MASK) {
;     ...
;             for (int kh = 0; kh < 2; ++kh) {
;             bf16x8 kf[2][2];
; #pragma unroll
;             for (int kb = 0; kb < 2; ++kb)
; #pragma unroll
;                 for (int ks = 0; ks < 2; ++ks) kf[kb][ks] = *(const bf16x8*)(KIDX + (rowbase + 64 * t + 32 * kh + 16 * kb + q16) * 64 + 32 * ks + 8 * kg);
; #pragma unroll
;             for (int kb = 0; kb < 2; ++kb) {
;                 f32x4 s = (f32x4){0.f, 0.f, 0.f, 0.f};
; #pragma unroll
;                 for (int hh = 0; hh < 8; ++hh) {
;                     f32x4 a = (f32x4){0.f, 0.f, 0.f, 0.f};
; #pragma unroll
;                     for (int ks = 0; ks < 2; ++ks) {
;                         const bf16x8 qv = *(const LAS bf16x8*)(lds + L_QI + q16 * 1024 + (((hh * 8 + 4 * ks + kg) ^ q16) << 4));
;                         a = __builtin_amdgcn_mfma_f32_16x16x32_bf16(kf[kb][ks], qv, a, 0, 0, 0);
;                     }
;                     const float wh = wl[hh * 16];
; #pragma unroll
;                     for (int i = 0; i < 4; ++i) s[i] += wh * fmaxf(a[i], 0.f);
;                 }
;                 u32x4 kk; kk.x = fkey(s[0]); kk.y = fkey(s[1]); kk.z = fkey(s[2]); kk.w = fkey(s[3]);
;                 sc[j][2 * kh + kb] = kk;
; #pragma unroll
;                 for (int i = 0; i < 4; ++i) SEL_HADD((kk[i] >> 24) * 16 + q16);
;                 __builtin_amdgcn_sched_barrier(0);
	v_mfma_f32_16x16x32_bf16 v[10:13], v[6:9], v[10:13], 0
	ds_read2_b32 v[48:49], v137 offset0:144 offset1:160
	ds_read2_b32 v[166:167], v137 offset0:176 offset1:192
	s_waitcnt vmcnt(0) lgkmcnt(6)
	v_mfma_f32_16x16x32_bf16 v[10:13], v[2:5], v[14:17], v[10:13]
	ds_read_b128 v[14:17], v179
	s_waitcnt lgkmcnt(6)
	v_mfma_f32_16x16x32_bf16 v[20:23], v[6:9], v[20:23], 0
	s_nop 4
	v_max_f32_e32 v30, 0, v10
	v_max_f32_e32 v10, 0, v12
	v_max_f32_e32 v31, 0, v11
	s_waitcnt lgkmcnt(4)
	v_mul_f32_e32 v32, v28, v10
	v_max_f32_e32 v34, 0, v13
	v_mfma_f32_16x16x32_bf16 v[10:13], v[2:5], v[24:27], v[20:23]
	s_nop 2
	ds_read_b128 v[20:23], v180
	s_waitcnt lgkmcnt(1)
	v_mfma_f32_16x16x32_bf16 v[14:17], v[6:9], v[14:17], 0
	s_nop 1
	v_max_f32_e32 v24, 0, v10
	v_max_f32_e32 v25, 0, v11
	v_max_f32_e32 v10, 0, v12
	v_mul_f32_e32 v26, v29, v10
	v_max_f32_e32 v35, 0, v13
	s_waitcnt lgkmcnt(0)
	v_mfma_f32_16x16x32_bf16 v[10:13], v[2:5], v[20:23], v[14:17]
	ds_read_b128 v[20:23], v159
	v_pk_mul_f32 v[34:35], v[28:29], v[34:35]
	s_nop 0
	ds_read_b128 v[14:17], v176
	s_waitcnt lgkmcnt(0)
	v_mfma_f32_16x16x32_bf16 v[14:17], v[6:9], v[14:17], 0
	s_nop 1
	v_max_f32_e32 v38, 0, v10
	v_max_f32_e32 v39, 0, v11
	v_max_f32_e32 v10, 0, v12
	v_mul_f32_e32 v40, v36, v10
	s_nop 0
	v_max_f32_e32 v42, 0, v13
	v_mfma_f32_16x16x32_bf16 v[10:13], v[2:5], v[20:23], v[14:17]
	ds_read_b128 v[20:23], v157
	v_mov_b32_e32 v33, v34
	v_mov_b32_e32 v27, v35
	ds_read_b128 v[14:17], v158
	s_waitcnt lgkmcnt(0)
	v_mfma_f32_16x16x32_bf16 v[14:17], v[6:9], v[14:17], 0
	s_nop 1
	v_max_f32_e32 v44, 0, v10
	v_max_f32_e32 v45, 0, v11
	v_max_f32_e32 v10, 0, v12
	v_mul_f32_e32 v46, v37, v10
	s_nop 0
	v_max_f32_e32 v43, 0, v13
	v_mfma_f32_16x16x32_bf16 v[10:13], v[2:5], v[20:23], v[14:17]
	ds_read_b128 v[20:23], v155
	v_pk_mul_f32 v[42:43], v[36:37], v[42:43]
	s_nop 0
	ds_read_b128 v[14:17], v156
	s_waitcnt lgkmcnt(0)
	v_mfma_f32_16x16x32_bf16 v[14:17], v[6:9], v[14:17], 0
	s_nop 1
	v_max_f32_e32 v50, 0, v10
	v_max_f32_e32 v51, 0, v11
	v_max_f32_e32 v10, 0, v12
	v_mul_f32_e32 v52, v48, v10
	s_nop 0
	v_max_f32_e32 v160, 0, v13
	v_mfma_f32_16x16x32_bf16 v[10:13], v[2:5], v[20:23], v[14:17]
	ds_read_b128 v[20:23], v153
	v_mov_b32_e32 v41, v42
	v_mov_b32_e32 v47, v43
	ds_read_b128 v[14:17], v154
	s_waitcnt lgkmcnt(0)
	v_mfma_f32_16x16x32_bf16 v[14:17], v[6:9], v[14:17], 0
	s_nop 1
	v_max_f32_e32 v162, 0, v10
	v_max_f32_e32 v163, 0, v11
	v_max_f32_e32 v10, 0, v12
	v_mul_f32_e32 v164, v49, v10
	s_nop 0
	v_max_f32_e32 v161, 0, v13
	v_mfma_f32_16x16x32_bf16 v[10:13], v[2:5], v[20:23], v[14:17]
	ds_read_b128 v[20:23], v151
	v_pk_mul_f32 v[160:161], v[48:49], v[160:161]
	s_nop 0
	ds_read_b128 v[14:17], v152
	s_waitcnt lgkmcnt(0)
	v_mfma_f32_16x16x32_bf16 v[6:9], v[6:9], v[14:17], 0
	s_nop 1
	s_nop 0
	v_max_f32_e32 v14, 0, v13
	s_nop 0
	v_mfma_f32_16x16x32_bf16 v[2:5], v[2:5], v[20:23], v[6:9]
	s_nop 0
	v_max_f32_e32 v10, 0, v10
	v_max_f32_e32 v11, 0, v11
	v_pk_fma_f32 v[8:9], v[28:29], v[30:31], 0 op_sel_hi:[0,1,0]
	s_nop 0
	s_nop 2
	v_max_f32_e32 v15, 0, v5
	v_pk_mul_f32 v[6:7], v[166:167], v[14:15]
	v_mov_b32_e32 v14, v29
	v_pk_fma_f32 v[8:9], v[14:15], v[24:25], v[8:9] op_sel_hi:[0,1,1]
	v_pk_fma_f32 v[8:9], v[36:37], v[38:39], v[8:9] op_sel_hi:[0,1,1]
	v_mov_b32_e32 v14, v37
	v_pk_fma_f32 v[8:9], v[14:15], v[44:45], v[8:9] op_sel_hi:[0,1,1]
	v_pk_fma_f32 v[8:9], v[48:49], v[50:51], v[8:9] op_sel_hi:[0,1,1]
	v_mov_b32_e32 v14, v49
	v_pk_fma_f32 v[8:9], v[14:15], v[162:163], v[8:9] op_sel_hi:[0,1,1]
	v_max_f32_e32 v2, 0, v2
	v_max_f32_e32 v3, 0, v3
	v_pk_fma_f32 v[8:9], v[166:167], v[10:11], v[8:9] op_sel_hi:[0,1,1]
	v_mov_b32_e32 v10, v167
	v_pk_fma_f32 v[2:3], v[10:11], v[2:3], v[8:9] op_sel_hi:[0,1,1]
	v_and_b32_e32 v9, 0x7fffffff, v3
	v_and_b32_e32 v8, 0x7fffffff, v2
	v_xor_b32_e32 v5, -1, v3
	v_pk_add_f32 v[8:9], v[8:9], 0 neg_lo:[1,1] neg_hi:[1,1]
	v_cmp_gt_i32_e32 vcc, 0, v3
	v_xor_b32_e32 v10, -1, v2
	v_mov_b32_e32 v53, v160
	v_cndmask_b32_e32 v225, v9, v5, vcc
	v_cmp_gt_i32_e32 vcc, 0, v2
	v_pk_add_f32 v[2:3], v[32:33], 0 op_sel_hi:[1,0]
	v_max_f32_e32 v12, 0, v12
	v_pk_add_f32 v[2:3], v[2:3], v[26:27]
	v_pk_add_f32 v[2:3], v[2:3], v[40:41]
	v_mov_b32_e32 v165, v161
	v_pk_add_f32 v[2:3], v[2:3], v[46:47]
	v_mul_f32_e32 v12, v166, v12
	v_pk_add_f32 v[2:3], v[2:3], v[52:53]
	v_max_f32_e32 v4, 0, v4
	v_pk_add_f32 v[2:3], v[2:3], v[164:165]
	v_mov_b32_e32 v13, v6
	v_mul_f32_e32 v4, v167, v4
	v_pk_add_f32 v[2:3], v[2:3], v[12:13]
	v_mov_b32_e32 v5, v7
	v_pk_add_f32 v[2:3], v[2:3], v[4:5]
	v_cndmask_b32_e32 v226, v8, v10, vcc
	v_and_b32_e32 v5, 0x7fffffff, v3
	v_and_b32_e32 v4, 0x7fffffff, v2
	v_xor_b32_e32 v6, -1, v3
	v_pk_add_f32 v[4:5], v[4:5], 0 neg_lo:[1,1] neg_hi:[1,1]
	v_cmp_gt_i32_e32 vcc, 0, v3
	v_xor_b32_e32 v7, -1, v2
	s_nop 0
	v_cndmask_b32_e32 v227, v5, v6, vcc
	v_cmp_gt_i32_e32 vcc, 0, v2
	v_lshrrev_b32_e32 v2, 24, v226
	v_lshl_add_u32 v2, v2, 6, v0
	ds_add_u32 v2, v205 offset:16384
	v_lshrrev_b32_e32 v2, 24, v225
	v_cndmask_b32_e32 v228, v4, v7, vcc
	v_lshl_add_u32 v2, v2, 6, v0
	ds_add_u32 v2, v205 offset:16384
	v_lshrrev_b32_e32 v2, 24, v228
	v_lshl_add_u32 v2, v2, 6, v0
	ds_add_u32 v2, v205 offset:16384
	v_lshrrev_b32_e32 v2, 24, v227
	v_lshl_add_u32 v2, v2, 6, v0
	ds_add_u32 v2, v205 offset:16384
	v_add_co_u32_e32 v2, vcc, s96, v18
	s_nop 1
	v_addc_co_u32_e32 v3, vcc, 0, v19, vcc
	global_load_dwordx4 v[14:17], v[2:3], off
	global_load_dwordx4 v[10:13], v[2:3], off offset:64
	global_load_dwordx4 v[6:9], v[2:3], off offset:2048
	s_nop 0
	global_load_dwordx4 v[2:5], v[2:3], off offset:2112
	ds_read_b128 v[18:21], v182
	ds_read_b128 v[22:25], v183
	s_waitcnt vmcnt(3) lgkmcnt(1)
; #define LAS __attribute__((address_space(3)))
; __device__ __forceinline__ unsigned fkey(float f) { const unsigned u = __float_as_uint(f); return (u & 0x80000000u) ? ~u : (u | 0x80000000u); }
; #define SEL_HADD(idx_) __hip_atomic_fetch_add(&hist[(idx_)], 1u, __ATOMIC_RELAXED, __HIP_MEMORY_SCOPE_WORKGROUP)
; __device__ __forceinline__ void sel_unit(LAS char* lds, int b, int u, const bf16_t* QI, const bf16_t* KIDX, const float* WIDX, unsigned long long* MASK) {
;     ...
;             for (int kh = 0; kh < 2; ++kh) {
;             bf16x8 kf[2][2];
; #pragma unroll
;             for (int kb = 0; kb < 2; ++kb)
; #pragma unroll
;                 for (int ks = 0; ks < 2; ++ks) kf[kb][ks] = *(const bf16x8*)(KIDX + (rowbase + 64 * t + 32 * kh + 16 * kb + q16) * 64 + 32 * ks + 8 * kg);
; #pragma unroll
;             for (int kb = 0; kb < 2; ++kb) {
;                 f32x4 s = (f32x4){0.f, 0.f, 0.f, 0.f};
; #pragma unroll
;                 for (int hh = 0; hh < 8; ++hh) {
;                     f32x4 a = (f32x4){0.f, 0.f, 0.f, 0.f};
; #pragma unroll
;                     for (int ks = 0; ks < 2; ++ks) {
;                         const bf16x8 qv = *(const LAS bf16x8*)(lds + L_QI + q16 * 1024 + (((hh * 8 + 4 * ks + kg) ^ q16) << 4));
;                         a = __builtin_amdgcn_mfma_f32_16x16x32_bf16(kf[kb][ks], qv, a, 0, 0, 0);
;                     }
;                     const float wh = wl[hh * 16];
; #pragma unroll
;                     for (int i = 0; i < 4; ++i) s[i] += wh * fmaxf(a[i], 0.f);
;                 }
;                 u32x4 kk; kk.x = fkey(s[0]); kk.y = fkey(s[1]); kk.z = fkey(s[2]); kk.w = fkey(s[3]);
;                 sc[j][2 * kh + kb] = kk;
; #pragma unroll
;                 for (int i = 0; i < 4; ++i) SEL_HADD((kk[i] >> 24) * 16 + q16);
;                 __builtin_amdgcn_sched_barrier(0);
	v_mfma_f32_16x16x32_bf16 v[18:21], v[14:17], v[18:21], 0
	ds_read_b128 v[28:31], v185
	ds_read_b128 v[34:37], v180
	ds_read_b128 v[40:43], v159
	s_waitcnt vmcnt(2) lgkmcnt(3)
	v_mfma_f32_16x16x32_bf16 v[22:25], v[10:13], v[22:25], v[18:21]
	ds_read_b128 v[46:49], v157
	ds_read_b128 v[160:163], v155
	s_nop 0
	ds_read2_b32 v[20:21], v137 offset0:80 offset1:96
	s_nop 3
	v_max_f32_e32 v22, 0, v22
	v_max_f32_e32 v23, 0, v23
	v_max_f32_e32 v18, v24, v24
	v_max_f32_e32 v19, v25, v25
	ds_read_b128 v[24:27], v184
	s_waitcnt lgkmcnt(0)
	v_mfma_f32_16x16x32_bf16 v[24:27], v[14:17], v[24:27], 0
	v_max_f32_e32 v32, 0, v19
	v_max_f32_e32 v18, 0, v18
	v_mul_f32_e32 v18, v20, v18
	v_mfma_f32_16x16x32_bf16 v[24:27], v[10:13], v[28:31], v[24:27]
	s_nop 7
	v_max_f32_e32 v28, 0, v24
	v_max_f32_e32 v29, 0, v25
	v_max_f32_e32 v19, 0, v26
	v_mul_f32_e32 v24, v21, v19
	v_max_f32_e32 v33, 0, v27
	v_pk_mul_f32 v[26:27], v[20:21], v[32:33]
	ds_read_b128 v[30:33], v179
	s_waitcnt lgkmcnt(0)
	v_mfma_f32_16x16x32_bf16 v[30:33], v[14:17], v[30:33], 0
	v_mov_b32_e32 v25, v27
	v_mfma_f32_16x16x32_bf16 v[34:37], v[10:13], v[34:37], v[30:33]
	s_nop 5
	ds_read2_b32 v[32:33], v137 offset0:112 offset1:128
	s_nop 0
	v_max_f32_e32 v34, 0, v34
	v_max_f32_e32 v35, 0, v35
	v_max_f32_e32 v19, 0, v36
	s_waitcnt lgkmcnt(0)
	v_mul_f32_e32 v30, v32, v19
	v_max_f32_e32 v19, v37, v37
	ds_read_b128 v[36:39], v176
	s_waitcnt lgkmcnt(0)
	v_mfma_f32_16x16x32_bf16 v[36:39], v[14:17], v[36:39], 0
	v_max_f32_e32 v44, 0, v19
	v_mfma_f32_16x16x32_bf16 v[36:39], v[10:13], v[40:43], v[36:39]
	s_nop 7
	v_max_f32_e32 v40, 0, v36
	v_max_f32_e32 v41, 0, v37
	v_max_f32_e32 v19, 0, v38
	v_mul_f32_e32 v36, v33, v19
	v_max_f32_e32 v45, 0, v39
	v_pk_mul_f32 v[38:39], v[32:33], v[44:45]
	ds_read_b128 v[42:45], v158
	s_waitcnt lgkmcnt(0)
	v_mfma_f32_16x16x32_bf16 v[42:45], v[14:17], v[42:45], 0
	v_mov_b32_e32 v31, v38
	v_mov_b32_e32 v37, v39
	v_mfma_f32_16x16x32_bf16 v[46:49], v[10:13], v[46:49], v[42:45]
	s_nop 4
	ds_read2_b32 v[44:45], v137 offset0:144 offset1:160
	s_nop 1
	v_max_f32_e32 v46, 0, v46
	v_max_f32_e32 v47, 0, v47
	v_max_f32_e32 v19, 0, v48
	s_waitcnt lgkmcnt(0)
	v_mul_f32_e32 v42, v44, v19
	v_max_f32_e32 v19, v49, v49
	ds_read_b128 v[48:51], v156
	s_waitcnt lgkmcnt(0)
	v_mfma_f32_16x16x32_bf16 v[48:51], v[14:17], v[48:51], 0
	v_max_f32_e32 v164, 0, v19
	v_mfma_f32_16x16x32_bf16 v[48:51], v[10:13], v[160:163], v[48:51]
	ds_read_b128 v[160:163], v154
	s_nop 6
	v_max_f32_e32 v52, 0, v48
	v_max_f32_e32 v53, 0, v49
	v_max_f32_e32 v19, 0, v50
	v_mul_f32_e32 v48, v45, v19
	v_max_f32_e32 v165, 0, v51
	v_pk_mul_f32 v[50:51], v[44:45], v[164:165]
	ds_read_b128 v[164:167], v153
	s_waitcnt lgkmcnt(1)
	v_mfma_f32_16x16x32_bf16 v[160:163], v[14:17], v[160:163], 0
	v_mov_b32_e32 v43, v50
	v_mov_b32_e32 v49, v51
	s_waitcnt lgkmcnt(0)
	v_mfma_f32_16x16x32_bf16 v[160:163], v[10:13], v[164:167], v[160:163]
	ds_read2_b32 v[164:165], v137 offset0:176 offset1:192
	s_nop 6
	v_max_f32_e32 v166, 0, v160
	v_max_f32_e32 v167, 0, v161
	v_max_f32_e32 v19, 0, v162
	s_waitcnt lgkmcnt(0)
	v_mul_f32_e32 v168, v164, v19
	v_max_f32_e32 v19, v163, v163
	ds_read_b128 v[160:163], v152
	s_waitcnt lgkmcnt(0)
	v_mfma_f32_16x16x32_bf16 v[14:17], v[14:17], v[160:163], 0
	ds_read_b128 v[160:163], v151
	v_max_f32_e32 v170, 0, v19
	s_waitcnt lgkmcnt(0)
	v_mfma_f32_16x16x32_bf16 v[10:13], v[10:13], v[160:163], v[14:17]
	s_nop 3
	v_fma_f32 v16, v20, v22, 0
	v_fma_f32 v17, v20, v23, 0
	v_mov_b32_e32 v20, v21
	v_pk_fma_f32 v[16:17], v[20:21], v[28:29], v[16:17] op_sel_hi:[0,1,1]
	v_pk_fma_f32 v[16:17], v[32:33], v[34:35], v[16:17] op_sel_hi:[0,1,1]
	v_mov_b32_e32 v20, v33
	v_pk_fma_f32 v[16:17], v[20:21], v[40:41], v[16:17] op_sel_hi:[0,1,1]
	v_pk_fma_f32 v[16:17], v[44:45], v[46:47], v[16:17] op_sel_hi:[0,1,1]
	v_mov_b32_e32 v20, v45
	v_pk_fma_f32 v[16:17], v[20:21], v[52:53], v[16:17] op_sel_hi:[0,1,1]
	v_max_f32_e32 v10, 0, v10
	v_max_f32_e32 v11, 0, v11
	v_pk_fma_f32 v[16:17], v[164:165], v[166:167], v[16:17] op_sel_hi:[0,1,1]
	v_mov_b32_e32 v20, v165
	v_pk_fma_f32 v[10:11], v[20:21], v[10:11], v[16:17] op_sel_hi:[0,1,1]
	v_and_b32_e32 v17, 0x7fffffff, v11
	v_and_b32_e32 v16, 0x7fffffff, v10
	v_xor_b32_e32 v19, -1, v10
	v_pk_add_f32 v[16:17], v[16:17], 0 neg_lo:[1,1] neg_hi:[1,1]
	v_cmp_gt_i32_e32 vcc, 0, v10
	v_max_f32_e32 v171, 0, v13
	v_xor_b32_e32 v13, -1, v11
	v_cmp_gt_i32_e64 s[2:3], 0, v11
	v_cndmask_b32_e32 v11, v16, v19, vcc
	v_mov_b32_e32 v19, v26
	v_cndmask_b32_e64 v10, v17, v13, s[2:3]
	v_pk_add_f32 v[16:17], v[18:19], 0 op_sel_hi:[1,0]
	v_pk_add_f32 v[16:17], v[16:17], v[24:25]
	v_pk_mul_f32 v[14:15], v[164:165], v[170:171]
	v_pk_add_f32 v[16:17], v[16:17], v[30:31]
	v_max_f32_e32 v12, 0, v12
	v_pk_add_f32 v[16:17], v[16:17], v[36:37]
	v_mov_b32_e32 v169, v14
	v_pk_add_f32 v[16:17], v[16:17], v[42:43]
	v_mul_f32_e32 v12, v165, v12
	v_pk_add_f32 v[16:17], v[16:17], v[48:49]
	v_mov_b32_e32 v13, v15
	v_pk_add_f32 v[16:17], v[16:17], v[168:169]
	s_nop 0
	v_pk_add_f32 v[12:13], v[16:17], v[12:13]
	s_nop 0
	v_and_b32_e32 v15, 0x7fffffff, v13
	v_and_b32_e32 v14, 0x7fffffff, v12
	v_xor_b32_e32 v17, -1, v12
	v_pk_add_f32 v[14:15], v[14:15], 0 neg_lo:[1,1] neg_hi:[1,1]
	v_cmp_gt_i32_e32 vcc, 0, v12
	v_xor_b32_e32 v16, -1, v13
	v_cmp_gt_i32_e64 s[2:3], 0, v13
	v_cndmask_b32_e32 v13, v14, v17, vcc
	v_lshrrev_b32_e32 v14, 24, v11
	v_lshl_add_u32 v14, v14, 6, v0
	ds_add_u32 v14, v205 offset:16384
	v_lshrrev_b32_e32 v14, 24, v10
	v_lshl_add_u32 v14, v14, 6, v0
	ds_add_u32 v14, v205 offset:16384
	v_lshrrev_b32_e32 v14, 24, v13
	v_cndmask_b32_e64 v12, v15, v16, s[2:3]
	v_lshl_add_u32 v14, v14, 6, v0
	ds_add_u32 v14, v205 offset:16384
	v_lshrrev_b32_e32 v14, 24, v12
	v_lshl_add_u32 v14, v14, 6, v0
	ds_add_u32 v14, v205 offset:16384
	ds_read_b128 v[14:17], v182
	ds_read_b128 v[18:21], v183
	ds_read_b128 v[22:25], v184
	ds_read_b128 v[26:29], v185
	ds_read2_b32 v[30:31], v137 offset0:80 offset1:96
	ds_read2_b32 v[38:39], v137 offset0:112 offset1:128
	s_waitcnt vmcnt(1) lgkmcnt(5)
; #define LAS __attribute__((address_space(3)))
; __device__ __forceinline__ unsigned fkey(float f) { const unsigned u = __float_as_uint(f); return (u & 0x80000000u) ? ~u : (u | 0x80000000u); }
; #define SEL_HADD(idx_) __hip_atomic_fetch_add(&hist[(idx_)], 1u, __ATOMIC_RELAXED, __HIP_MEMORY_SCOPE_WORKGROUP)
; __device__ __forceinline__ void sel_unit(LAS char* lds, int b, int u, const bf16_t* QI, const bf16_t* KIDX, const float* WIDX, unsigned long long* MASK) {
;     ...
;             for (int kh = 0; kh < 2; ++kh) {
;             bf16x8 kf[2][2];
; #pragma unroll
;             for (int kb = 0; kb < 2; ++kb)
; #pragma unroll
;                 for (int ks = 0; ks < 2; ++ks) kf[kb][ks] = *(const bf16x8*)(KIDX + (rowbase + 64 * t + 32 * kh + 16 * kb + q16) * 64 + 32 * ks + 8 * kg);
; #pragma unroll
;             for (int kb = 0; kb < 2; ++kb) {
;                 f32x4 s = (f32x4){0.f, 0.f, 0.f, 0.f};
; #pragma unroll
;                 for (int hh = 0; hh < 8; ++hh) {
;                     f32x4 a = (f32x4){0.f, 0.f, 0.f, 0.f};
; #pragma unroll
;                     for (int ks = 0; ks < 2; ++ks) {
;                         const bf16x8 qv = *(const LAS bf16x8*)(lds + L_QI + q16 * 1024 + (((hh * 8 + 4 * ks + kg) ^ q16) << 4));
;                         a = __builtin_amdgcn_mfma_f32_16x16x32_bf16(kf[kb][ks], qv, a, 0, 0, 0);
;                     }
;                     const float wh = wl[hh * 16];
; #pragma unroll
;                     for (int i = 0; i < 4; ++i) s[i] += wh * fmaxf(a[i], 0.f);
;                 }
;                 u32x4 kk; kk.x = fkey(s[0]); kk.y = fkey(s[1]); kk.z = fkey(s[2]); kk.w = fkey(s[3]);
;                 sc[j][2 * kh + kb] = kk;
; #pragma unroll
;                 for (int i = 0; i < 4; ++i) SEL_HADD((kk[i] >> 24) * 16 + q16);
;                 __builtin_amdgcn_sched_barrier(0);
	v_mfma_f32_16x16x32_bf16 v[14:17], v[6:9], v[14:17], 0
	ds_read2_b32 v[50:51], v137 offset0:144 offset1:160
	ds_read2_b32 v[162:163], v137 offset0:176 offset1:192
	s_waitcnt vmcnt(0) lgkmcnt(6)
	v_mfma_f32_16x16x32_bf16 v[14:17], v[2:5], v[18:21], v[14:17]
	ds_read_b128 v[18:21], v179
	s_waitcnt lgkmcnt(6)
	v_mfma_f32_16x16x32_bf16 v[22:25], v[6:9], v[22:25], 0
	s_nop 4
	v_max_f32_e32 v32, 0, v14
	v_max_f32_e32 v14, 0, v16
	v_max_f32_e32 v33, 0, v15
	s_waitcnt lgkmcnt(4)
	v_mul_f32_e32 v34, v30, v14
	v_max_f32_e32 v36, 0, v17
	v_mfma_f32_16x16x32_bf16 v[14:17], v[2:5], v[26:29], v[22:25]
	s_nop 2
	ds_read_b128 v[22:25], v180
	s_waitcnt lgkmcnt(1)
	v_mfma_f32_16x16x32_bf16 v[18:21], v[6:9], v[18:21], 0
	s_nop 1
	v_max_f32_e32 v26, 0, v14
	v_max_f32_e32 v27, 0, v15
	v_max_f32_e32 v14, 0, v16
	v_mul_f32_e32 v28, v31, v14
	v_max_f32_e32 v37, 0, v17
	s_waitcnt lgkmcnt(0)
	v_mfma_f32_16x16x32_bf16 v[14:17], v[2:5], v[22:25], v[18:21]
	ds_read_b128 v[22:25], v159
	v_pk_mul_f32 v[36:37], v[30:31], v[36:37]
	s_nop 0
	ds_read_b128 v[18:21], v176
	s_waitcnt lgkmcnt(0)
	v_mfma_f32_16x16x32_bf16 v[18:21], v[6:9], v[18:21], 0
	s_nop 1
	v_max_f32_e32 v40, 0, v14
	v_max_f32_e32 v41, 0, v15
	v_max_f32_e32 v14, 0, v16
	v_mul_f32_e32 v42, v38, v14
	s_nop 0
	v_max_f32_e32 v44, 0, v17
	v_mfma_f32_16x16x32_bf16 v[14:17], v[2:5], v[22:25], v[18:21]
	ds_read_b128 v[22:25], v157
	v_mov_b32_e32 v35, v36
	v_mov_b32_e32 v29, v37
	ds_read_b128 v[18:21], v158
	s_waitcnt lgkmcnt(0)
	v_mfma_f32_16x16x32_bf16 v[18:21], v[6:9], v[18:21], 0
	s_nop 1
	v_max_f32_e32 v46, 0, v14
	v_max_f32_e32 v47, 0, v15
	v_max_f32_e32 v14, 0, v16
	v_mul_f32_e32 v48, v39, v14
	s_nop 0
	v_max_f32_e32 v45, 0, v17
	v_mfma_f32_16x16x32_bf16 v[14:17], v[2:5], v[22:25], v[18:21]
	ds_read_b128 v[22:25], v155
	v_pk_mul_f32 v[44:45], v[38:39], v[44:45]
	s_nop 0
	ds_read_b128 v[18:21], v156
	s_waitcnt lgkmcnt(0)
	v_mfma_f32_16x16x32_bf16 v[18:21], v[6:9], v[18:21], 0
	s_nop 1
	v_max_f32_e32 v52, 0, v14
	v_max_f32_e32 v53, 0, v15
	v_max_f32_e32 v14, 0, v16
	v_mul_f32_e32 v156, v50, v14
	s_nop 0
	v_max_f32_e32 v158, 0, v17
	v_mfma_f32_16x16x32_bf16 v[14:17], v[2:5], v[22:25], v[18:21]
	ds_read_b128 v[22:25], v153
	v_mov_b32_e32 v43, v44
	v_mov_b32_e32 v49, v45
	ds_read_b128 v[18:21], v154
	s_waitcnt lgkmcnt(0)
	v_mfma_f32_16x16x32_bf16 v[18:21], v[6:9], v[18:21], 0
	s_nop 1
	v_max_f32_e32 v160, 0, v14
	v_max_f32_e32 v161, 0, v15
	v_max_f32_e32 v14, 0, v16
	v_mul_f32_e32 v154, v51, v14
	s_nop 0
	v_max_f32_e32 v159, 0, v17
	v_mfma_f32_16x16x32_bf16 v[14:17], v[2:5], v[22:25], v[18:21]
	ds_read_b128 v[22:25], v151
	v_pk_mul_f32 v[158:159], v[50:51], v[158:159]
	s_nop 0
	ds_read_b128 v[18:21], v152
	s_waitcnt lgkmcnt(0)
	v_mfma_f32_16x16x32_bf16 v[6:9], v[6:9], v[18:21], 0
	s_nop 1
	s_nop 0
	v_max_f32_e32 v18, 0, v17
	s_nop 0
	v_mfma_f32_16x16x32_bf16 v[2:5], v[2:5], v[22:25], v[6:9]
	s_nop 0
	v_max_f32_e32 v14, 0, v14
	v_max_f32_e32 v15, 0, v15
	v_pk_fma_f32 v[8:9], v[30:31], v[32:33], 0 op_sel_hi:[0,1,0]
	s_nop 0
	s_nop 2
	v_max_f32_e32 v19, 0, v5
	v_pk_mul_f32 v[6:7], v[162:163], v[18:19]
	v_mov_b32_e32 v18, v31
	v_pk_fma_f32 v[8:9], v[18:19], v[26:27], v[8:9] op_sel_hi:[0,1,1]
	v_pk_fma_f32 v[8:9], v[38:39], v[40:41], v[8:9] op_sel_hi:[0,1,1]
	v_mov_b32_e32 v18, v39
	v_pk_fma_f32 v[8:9], v[18:19], v[46:47], v[8:9] op_sel_hi:[0,1,1]
	v_pk_fma_f32 v[8:9], v[50:51], v[52:53], v[8:9] op_sel_hi:[0,1,1]
	v_mov_b32_e32 v18, v51
	v_pk_fma_f32 v[8:9], v[18:19], v[160:161], v[8:9] op_sel_hi:[0,1,1]
	v_max_f32_e32 v2, 0, v2
	v_max_f32_e32 v3, 0, v3
	v_pk_fma_f32 v[8:9], v[162:163], v[14:15], v[8:9] op_sel_hi:[0,1,1]
	v_mov_b32_e32 v14, v163
	v_pk_fma_f32 v[2:3], v[14:15], v[2:3], v[8:9] op_sel_hi:[0,1,1]
	v_and_b32_e32 v9, 0x7fffffff, v3
	v_and_b32_e32 v8, 0x7fffffff, v2
	v_xor_b32_e32 v5, -1, v3
	v_pk_add_f32 v[8:9], v[8:9], 0 neg_lo:[1,1] neg_hi:[1,1]
	v_cmp_gt_i32_e32 vcc, 0, v3
	v_xor_b32_e32 v15, -1, v2
	v_mov_b32_e32 v157, v158
	v_cndmask_b32_e32 v14, v9, v5, vcc
	v_cmp_gt_i32_e32 vcc, 0, v2
	v_pk_add_f32 v[2:3], v[34:35], 0 op_sel_hi:[1,0]
	v_max_f32_e32 v16, 0, v16
	v_pk_add_f32 v[2:3], v[2:3], v[28:29]
	v_pk_add_f32 v[2:3], v[2:3], v[42:43]
	v_mov_b32_e32 v155, v159
	v_pk_add_f32 v[2:3], v[2:3], v[48:49]
	v_mul_f32_e32 v16, v162, v16
	v_pk_add_f32 v[2:3], v[2:3], v[156:157]
	v_max_f32_e32 v4, 0, v4
	v_pk_add_f32 v[2:3], v[2:3], v[154:155]
	v_mov_b32_e32 v17, v6
	v_mul_f32_e32 v4, v163, v4
	v_pk_add_f32 v[2:3], v[2:3], v[16:17]
	v_mov_b32_e32 v5, v7
	v_pk_add_f32 v[2:3], v[2:3], v[4:5]
	v_cndmask_b32_e32 v15, v8, v15, vcc
	v_and_b32_e32 v5, 0x7fffffff, v3
	v_and_b32_e32 v4, 0x7fffffff, v2
	v_xor_b32_e32 v6, -1, v3
	v_pk_add_f32 v[4:5], v[4:5], 0 neg_lo:[1,1] neg_hi:[1,1]
	v_cmp_gt_i32_e32 vcc, 0, v3
	v_xor_b32_e32 v7, -1, v2
	s_nop 0
	v_cndmask_b32_e32 v16, v5, v6, vcc
	v_cmp_gt_i32_e32 vcc, 0, v2
	v_lshrrev_b32_e32 v2, 24, v15
	v_lshl_add_u32 v2, v2, 6, v0
	ds_add_u32 v2, v205 offset:16384
	v_lshrrev_b32_e32 v2, 24, v14
	v_cndmask_b32_e32 v17, v4, v7, vcc
	v_lshl_add_u32 v2, v2, 6, v0
	ds_add_u32 v2, v205 offset:16384
	v_lshrrev_b32_e32 v2, 24, v17
	v_lshl_add_u32 v2, v2, 6, v0
	ds_add_u32 v2, v205 offset:16384
	v_lshrrev_b32_e32 v2, 24, v16
	v_lshl_add_u32 v2, v2, 6, v0
	ds_add_u32 v2, v205 offset:16384
